# speedup vs baseline: 1.0563x; 1.0182x over previous
.LBB0_384:
	s_or_b64 exec, exec, s[6:7]
	v_ashrrev_i32_e32 v71, 31, v70
	v_lshlrev_b64 v[90:91], 11, v[70:71]
	v_lshl_add_u64 v[40:41], v[66:67], 0, v[90:91]
	global_load_dwordx4 v[96:99], v[40:41], off
	v_add_u32_e32 v40, 1, v70
	v_add_u32_e32 v50, 3, v70
	v_add_u32_e32 v46, 2, v70
	v_ashrrev_i32_e32 v41, 31, v40
	v_ashrrev_i32_e32 v51, 31, v50
	v_pk_fma_f32 v[56:57], v[32:33], v[56:57], v[36:37]
	v_pk_fma_f32 v[58:59], v[34:35], v[60:61], v[38:39]
	v_pk_fma_f32 v[44:45], v[24:25], v[44:45], v[28:29]
	v_ashrrev_i32_e32 v47, 31, v46
	v_lshlrev_b64 v[92:93], 11, v[40:41]
	v_lshlrev_b64 v[40:41], 11, v[50:51]
	v_pk_fma_f32 v[56:57], v[0:1], v[88:89], v[56:57]
	v_pk_fma_f32 v[58:59], v[2:3], v[54:55], v[58:59]
	v_pk_fma_f32 v[44:45], v[8:9], v[76:77], v[44:45]
	v_lshlrev_b64 v[82:83], 11, v[46:47]
	v_lshl_add_u64 v[74:75], v[66:67], 0, v[92:93]
	v_lshl_add_u64 v[84:85], v[66:67], 0, v[40:41]
	v_pk_fma_f32 v[50:51], v[4:5], v[78:79], v[56:57]
	v_pk_fma_f32 v[100:101], v[6:7], v[52:53], v[58:59]
	v_pk_fma_f32 v[102:103], v[12:13], v[72:73], v[44:45]
	v_lshl_add_u64 v[80:81], v[66:67], 0, v[82:83]
	global_load_dwordx4 v[60:63], v[74:75], off
	global_load_dwordx4 v[56:59], v[80:81], off
	global_load_dwordx4 v[44:47], v[84:85], off
	v_pk_fma_f32 v[86:87], v[26:27], v[86:87], v[30:31]
	v_pk_fma_f32 v[54:55], v[34:35], v[54:55], v[38:39]
	v_pk_fma_f32 v[86:87], v[10:11], v[48:49], v[86:87]
	v_pk_fma_f32 v[54:55], v[2:3], v[52:53], v[54:55]
	v_pk_fma_f32 v[86:87], v[14:15], v[42:43], v[86:87]
	v_pk_fma_f32 v[48:49], v[26:27], v[48:49], v[30:31]
	v_pk_fma_f32 v[52:53], v[34:35], v[52:53], v[38:39]
	v_pk_fma_f32 v[48:49], v[10:11], v[42:43], v[48:49]
	v_pk_fma_f32 v[42:43], v[26:27], v[42:43], v[30:31]
	v_add_u32_e32 v94, s2, v94
	v_lshl_add_u64 v[40:41], v[68:69], 0, v[40:41]
	v_add_u32_e32 v70, s3, v70
	s_waitcnt vmcnt(3)
	v_lshlrev_b32_e32 v85, 16, v97
	v_lshlrev_b32_e32 v84, 16, v96
	v_and_b32_e32 v81, 0xffff0000, v97
	v_and_b32_e32 v80, 0xffff0000, v96
	v_pk_fma_f32 v[96:97], v[16:17], v[84:85], v[50:51]
	v_pk_fma_f32 v[100:101], v[18:19], v[80:81], v[100:101]
	v_mul_f32_e32 v50, 0xbfb8aa3b, v96
	v_mul_f32_e32 v71, 0xbfb8aa3b, v97
	v_exp_f32_e32 v104, v50
	v_exp_f32_e32 v105, v71
	v_mul_f32_e32 v51, 0xbfb8aa3b, v100
	v_mul_f32_e32 v95, 0xbfb8aa3b, v101
	v_exp_f32_e32 v106, v51
	v_exp_f32_e32 v107, v95
	v_lshlrev_b32_e32 v75, 16, v99
	v_lshlrev_b32_e32 v74, 16, v98
	v_and_b32_e32 v51, 0xffff0000, v99
	v_and_b32_e32 v50, 0xffff0000, v98
	v_pk_add_f32 v[98:99], v[104:105], 1.0 op_sel_hi:[1,0]
	v_pk_add_f32 v[104:105], v[106:107], 1.0 op_sel_hi:[1,0]
	s_mov_b64 vcc, s[4:5]
	s_mov_b64 vcc, s[6:7]
	v_rcp_f32_e32 v95, v98
	s_nop 0
	v_mul_f32_e32 v95, v96, v95
	s_mov_b64 vcc, s[8:9]
	v_rcp_f32_e32 v71, v99
	s_nop 0
	v_mul_f32_e32 v71, v97, v71
	v_rcp_f32_e32 v96, v105
	s_nop 0
	v_mul_f32_e32 v96, v101, v96
	v_cvt_pk_bf16_f32 v71, v95, v71
	v_rcp_f32_e32 v97, v104
	s_nop 0
	v_mul_f32_e32 v95, v100, v97
	v_cvt_pk_bf16_f32 v95, v95, v96
	v_and_b32_e32 v96, 0xffff0000, v95
	v_lshlrev_b32_e32 v95, 16, v95
	v_pk_fma_f32 v[98:99], v[20:21], v[74:75], v[102:103]
	v_or_b32_sdwa v97, v96, v71 dst_sel:DWORD dst_unused:UNUSED_PAD src0_sel:DWORD src1_sel:WORD_1
	v_or_b32_sdwa v96, v95, v71 dst_sel:DWORD dst_unused:UNUSED_PAD src0_sel:DWORD src1_sel:WORD_0
	v_mul_f32_e32 v71, 0xbfb8aa3b, v98
	v_exp_f32_e32 v100, v71
	v_mul_f32_e32 v71, 0xbfb8aa3b, v99
	v_exp_f32_e32 v101, v71
	v_pk_fma_f32 v[86:87], v[22:23], v[50:51], v[86:87]
	v_pk_fma_f32 v[54:55], v[6:7], v[80:81], v[54:55]
	v_mul_f32_e32 v102, 0xbfb8aa3b, v86
	v_pk_add_f32 v[100:101], v[100:101], 1.0 op_sel_hi:[1,0]
	v_exp_f32_e32 v102, v102
	v_pk_fma_f32 v[48:49], v[14:15], v[50:51], v[48:49]
	v_pk_fma_f32 v[52:53], v[2:3], v[80:81], v[52:53]
	v_pk_fma_f32 v[42:43], v[10:11], v[50:51], v[42:43]
	v_rcp_f32_e32 v71, v101
	s_nop 0
	v_mul_f32_e32 v71, v99, v71
	v_mul_f32_e32 v101, 0xbfb8aa3b, v87
	v_exp_f32_e32 v103, v101
	s_nop 0
	v_pk_add_f32 v[102:103], v[102:103], 1.0 op_sel_hi:[1,0]
	v_rcp_f32_e32 v95, v100
	s_nop 0
	v_mul_f32_e32 v95, v98, v95
	v_rcp_f32_e32 v98, v103
	s_nop 0
	v_mul_f32_e32 v87, v87, v98
	v_cvt_pk_bf16_f32 v71, v95, v71
	v_rcp_f32_e32 v98, v102
	s_nop 0
	v_mul_f32_e32 v86, v86, v98
	v_cvt_pk_bf16_f32 v86, v86, v87
	v_and_b32_e32 v87, 0xffff0000, v86
	v_lshlrev_b32_e32 v86, 16, v86
	v_or_b32_sdwa v99, v87, v71 dst_sel:DWORD dst_unused:UNUSED_PAD src0_sel:DWORD src1_sel:WORD_1
	v_or_b32_sdwa v98, v86, v71 dst_sel:DWORD dst_unused:UNUSED_PAD src0_sel:DWORD src1_sel:WORD_0
	v_lshl_add_u64 v[86:87], v[68:69], 0, v[90:91]
	global_store_dwordx4 v[86:87], v[96:99], off
	v_pk_fma_f32 v[86:87], v[32:33], v[88:89], v[36:37]
	s_waitcnt vmcnt(3)
	v_lshlrev_b32_e32 v91, 16, v61
	v_pk_fma_f32 v[86:87], v[0:1], v[78:79], v[86:87]
	v_lshlrev_b32_e32 v90, 16, v60
	v_pk_fma_f32 v[86:87], v[4:5], v[84:85], v[86:87]
	v_and_b32_e32 v61, 0xffff0000, v61
	v_pk_fma_f32 v[86:87], v[16:17], v[90:91], v[86:87]
	v_and_b32_e32 v60, 0xffff0000, v60
	v_mul_f32_e32 v71, 0xbfb8aa3b, v86
	v_exp_f32_e32 v88, v71
	v_mul_f32_e32 v71, 0xbfb8aa3b, v87
	v_exp_f32_e32 v89, v71
	v_pk_fma_f32 v[54:55], v[18:19], v[60:61], v[54:55]
	v_pk_fma_f32 v[52:53], v[6:7], v[60:61], v[52:53]
	v_mul_f32_e32 v96, 0xbfb8aa3b, v54
	v_pk_add_f32 v[88:89], v[88:89], 1.0 op_sel_hi:[1,0]
	v_exp_f32_e32 v96, v96
	v_pk_fma_f32 v[50:51], v[26:27], v[50:51], v[30:31]
	v_mul_f32_e32 v95, 0xbfb8aa3b, v55
	v_exp_f32_e32 v97, v95
	v_rcp_f32_e32 v71, v89
	s_nop 0
	v_mul_f32_e32 v71, v87, v71
	v_pk_add_f32 v[96:97], v[96:97], 1.0 op_sel_hi:[1,0]
	v_rcp_f32_e32 v87, v88
	s_nop 0
	v_mul_f32_e32 v86, v86, v87
	v_rcp_f32_e32 v87, v97
	s_nop 0
	v_mul_f32_e32 v55, v55, v87
	v_cvt_pk_bf16_f32 v71, v86, v71
	v_rcp_f32_e32 v87, v96
	s_nop 0
	v_mul_f32_e32 v54, v54, v87
	v_cvt_pk_bf16_f32 v54, v54, v55
	v_and_b32_e32 v55, 0xffff0000, v54
	v_lshlrev_b32_e32 v54, 16, v54
	v_or_b32_sdwa v97, v55, v71 dst_sel:DWORD dst_unused:UNUSED_PAD src0_sel:DWORD src1_sel:WORD_1
	v_or_b32_sdwa v96, v54, v71 dst_sel:DWORD dst_unused:UNUSED_PAD src0_sel:DWORD src1_sel:WORD_0
	v_lshlrev_b32_e32 v87, 16, v63
	v_lshlrev_b32_e32 v86, 16, v62
	v_and_b32_e32 v55, 0xffff0000, v63
	v_and_b32_e32 v54, 0xffff0000, v62
	v_pk_fma_f32 v[62:63], v[24:25], v[76:77], v[28:29]
	v_pk_fma_f32 v[48:49], v[22:23], v[54:55], v[48:49]
	v_pk_fma_f32 v[62:63], v[8:9], v[72:73], v[62:63]
	v_mul_f32_e32 v88, 0xbfb8aa3b, v48
	v_pk_fma_f32 v[62:63], v[12:13], v[74:75], v[62:63]
	v_exp_f32_e32 v88, v88
	v_pk_fma_f32 v[62:63], v[20:21], v[86:87], v[62:63]
	v_pk_fma_f32 v[42:43], v[14:15], v[54:55], v[42:43]
	v_mul_f32_e32 v71, 0xbfb8aa3b, v62
	v_exp_f32_e32 v76, v71
	v_mul_f32_e32 v71, 0xbfb8aa3b, v63
	v_exp_f32_e32 v77, v71
	v_pk_fma_f32 v[50:51], v[10:11], v[54:55], v[50:51]
	v_pk_add_f32 v[76:77], v[76:77], 1.0 op_sel_hi:[1,0]
	s_nop 0
	s_nop 0
	v_mul_f32_e32 v89, 0xbfb8aa3b, v49
	v_rcp_f32_e32 v71, v77
	s_nop 0
	v_mul_f32_e32 v63, v63, v71
	v_exp_f32_e32 v89, v89
	s_nop 0
	v_pk_add_f32 v[88:89], v[88:89], 1.0 op_sel_hi:[1,0]
	v_rcp_f32_e32 v71, v76
	s_nop 0
	v_mul_f32_e32 v62, v62, v71
	v_cvt_pk_bf16_f32 v62, v62, v63
	v_rcp_f32_e32 v71, v89
	s_nop 0
	v_mul_f32_e32 v49, v49, v71
	s_waitcnt vmcnt(2)
	v_and_b32_e32 v63, 0xffff0000, v57
	v_rcp_f32_e32 v71, v88
	s_nop 0
	v_mul_f32_e32 v48, v48, v71
	v_cvt_pk_bf16_f32 v48, v48, v49
	v_and_b32_e32 v49, 0xffff0000, v48
	v_lshlrev_b32_e32 v48, 16, v48
	v_or_b32_sdwa v99, v49, v62 dst_sel:DWORD dst_unused:UNUSED_PAD src0_sel:DWORD src1_sel:WORD_1
	v_or_b32_sdwa v98, v48, v62 dst_sel:DWORD dst_unused:UNUSED_PAD src0_sel:DWORD src1_sel:WORD_0
	v_lshl_add_u64 v[48:49], v[68:69], 0, v[92:93]
	global_store_dwordx4 v[48:49], v[96:99], off
	v_lshlrev_b32_e32 v49, 16, v57
	v_lshlrev_b32_e32 v48, 16, v56
	v_and_b32_e32 v62, 0xffff0000, v56
	v_pk_fma_f32 v[56:57], v[32:33], v[78:79], v[36:37]
	v_pk_fma_f32 v[52:53], v[18:19], v[62:63], v[52:53]
	v_pk_fma_f32 v[56:57], v[0:1], v[84:85], v[56:57]
	v_mul_f32_e32 v78, 0xbfb8aa3b, v52
	v_pk_fma_f32 v[56:57], v[4:5], v[90:91], v[56:57]
	v_exp_f32_e32 v78, v78
	v_pk_fma_f32 v[56:57], v[16:17], v[48:49], v[56:57]
	s_nop 0
	v_mul_f32_e32 v71, 0xbfb8aa3b, v56
	v_exp_f32_e32 v76, v71
	v_mul_f32_e32 v71, 0xbfb8aa3b, v57
	v_exp_f32_e32 v77, v71
	s_nop 0
	v_pk_add_f32 v[76:77], v[76:77], 1.0 op_sel_hi:[1,0]
	s_nop 0
	s_nop 0
	v_mul_f32_e32 v79, 0xbfb8aa3b, v53
	v_rcp_f32_e32 v71, v77
	s_nop 0
	v_mul_f32_e32 v57, v57, v71
	v_exp_f32_e32 v79, v79
	s_nop 0
	v_pk_add_f32 v[78:79], v[78:79], 1.0 op_sel_hi:[1,0]
	v_rcp_f32_e32 v71, v76
	s_nop 0
	v_mul_f32_e32 v56, v56, v71
	v_cvt_pk_bf16_f32 v56, v56, v57
	v_rcp_f32_e32 v71, v79
	s_nop 0
	v_mul_f32_e32 v53, v53, v71
	v_rcp_f32_e32 v71, v78
	s_nop 0
	v_mul_f32_e32 v52, v52, v71
	v_cvt_pk_bf16_f32 v52, v52, v53
	v_and_b32_e32 v53, 0xffff0000, v52
	v_lshlrev_b32_e32 v52, 16, v52
	v_or_b32_sdwa v57, v53, v56 dst_sel:DWORD dst_unused:UNUSED_PAD src0_sel:DWORD src1_sel:WORD_1
	v_or_b32_sdwa v56, v52, v56 dst_sel:DWORD dst_unused:UNUSED_PAD src0_sel:DWORD src1_sel:WORD_0
	v_lshlrev_b32_e32 v53, 16, v59
	v_lshlrev_b32_e32 v52, 16, v58
	v_and_b32_e32 v77, 0xffff0000, v59
	v_and_b32_e32 v76, 0xffff0000, v58
	v_pk_fma_f32 v[58:59], v[24:25], v[72:73], v[28:29]
	v_pk_fma_f32 v[42:43], v[22:23], v[76:77], v[42:43]
	v_pk_fma_f32 v[58:59], v[8:9], v[74:75], v[58:59]
	v_mul_f32_e32 v78, 0xbfb8aa3b, v42
	v_pk_fma_f32 v[58:59], v[12:13], v[86:87], v[58:59]
	v_exp_f32_e32 v78, v78
	v_pk_fma_f32 v[58:59], v[20:21], v[52:53], v[58:59]
	v_pk_fma_f32 v[50:51], v[14:15], v[76:77], v[50:51]
	v_mul_f32_e32 v71, 0xbfb8aa3b, v58
	v_exp_f32_e32 v72, v71
	v_mul_f32_e32 v71, 0xbfb8aa3b, v59
	v_exp_f32_e32 v73, v71
	s_nop 0
	v_pk_add_f32 v[72:73], v[72:73], 1.0 op_sel_hi:[1,0]
	s_nop 0
	s_nop 0
	v_mul_f32_e32 v79, 0xbfb8aa3b, v43
	v_rcp_f32_e32 v71, v73
	s_nop 0
	v_mul_f32_e32 v59, v59, v71
	v_exp_f32_e32 v79, v79
	s_nop 0
	v_pk_add_f32 v[78:79], v[78:79], 1.0 op_sel_hi:[1,0]
	v_rcp_f32_e32 v71, v72
	s_nop 0
	v_mul_f32_e32 v58, v58, v71
	v_cvt_pk_bf16_f32 v58, v58, v59
	v_rcp_f32_e32 v71, v79
	s_nop 0
	v_mul_f32_e32 v43, v43, v71
	v_rcp_f32_e32 v71, v78
	s_nop 0
	v_mul_f32_e32 v42, v42, v71
	v_cvt_pk_bf16_f32 v42, v42, v43
	v_and_b32_e32 v43, 0xffff0000, v42
	v_lshlrev_b32_e32 v42, 16, v42
	v_or_b32_sdwa v59, v43, v58 dst_sel:DWORD dst_unused:UNUSED_PAD src0_sel:DWORD src1_sel:WORD_1
	v_or_b32_sdwa v58, v42, v58 dst_sel:DWORD dst_unused:UNUSED_PAD src0_sel:DWORD src1_sel:WORD_0
	v_lshl_add_u64 v[42:43], v[68:69], 0, v[82:83]
	global_store_dwordx4 v[42:43], v[56:59], off
	s_waitcnt vmcnt(3)
	v_and_b32_e32 v43, 0xffff0000, v45
	v_and_b32_e32 v42, 0xffff0000, v44
	v_pk_fma_f32 v[56:57], v[32:33], v[84:85], v[36:37]
	v_lshlrev_b32_e32 v45, 16, v45
	v_pk_fma_f32 v[56:57], v[0:1], v[90:91], v[56:57]
	v_lshlrev_b32_e32 v44, 16, v44
	v_pk_fma_f32 v[48:49], v[4:5], v[48:49], v[56:57]
	v_pk_fma_f32 v[56:57], v[34:35], v[80:81], v[38:39]
	v_pk_fma_f32 v[44:45], v[16:17], v[44:45], v[48:49]
	v_pk_fma_f32 v[56:57], v[2:3], v[60:61], v[56:57]
	v_mul_f32_e32 v48, 0xbfb8aa3b, v44
	v_mul_f32_e32 v49, 0xbfb8aa3b, v45
	v_exp_f32_e32 v48, v48
	v_exp_f32_e32 v49, v49
	v_pk_fma_f32 v[56:57], v[6:7], v[62:63], v[56:57]
	v_pk_add_f32 v[48:49], v[48:49], 1.0 op_sel_hi:[1,0]
	s_nop 0
	v_pk_fma_f32 v[42:43], v[18:19], v[42:43], v[56:57]
	v_mul_f32_e32 v56, 0xbfb8aa3b, v42
	v_rcp_f32_e32 v57, v49
	s_nop 0
	v_mul_f32_e32 v45, v45, v57
	v_mul_f32_e32 v57, 0xbfb8aa3b, v43
	v_exp_f32_e32 v56, v56
	v_exp_f32_e32 v57, v57
	s_nop 0
	v_pk_add_f32 v[56:57], v[56:57], 1.0 op_sel_hi:[1,0]
	v_rcp_f32_e32 v49, v48
	s_nop 0
	v_mul_f32_e32 v44, v44, v49
	v_cvt_pk_bf16_f32 v44, v44, v45
	v_rcp_f32_e32 v48, v57
	s_nop 0
	v_mul_f32_e32 v43, v43, v48
	v_and_b32_e32 v45, 0xffff0000, v47
	v_rcp_f32_e32 v48, v56
	s_nop 0
	v_mul_f32_e32 v42, v42, v48
	v_cvt_pk_bf16_f32 v42, v42, v43
	v_pk_fma_f32 v[48:49], v[24:25], v[74:75], v[28:29]
	v_and_b32_e32 v43, 0xffff0000, v42
	v_lshlrev_b32_e32 v42, 16, v42
	v_pk_fma_f32 v[48:49], v[8:9], v[86:87], v[48:49]
	v_or_b32_sdwa v43, v43, v44 dst_sel:DWORD dst_unused:UNUSED_PAD src0_sel:DWORD src1_sel:WORD_1
	v_or_b32_sdwa v42, v42, v44 dst_sel:DWORD dst_unused:UNUSED_PAD src0_sel:DWORD src1_sel:WORD_0
	v_and_b32_e32 v44, 0xffff0000, v46
	v_lshlrev_b32_e32 v47, 16, v47
	v_lshlrev_b32_e32 v46, 16, v46
	v_pk_fma_f32 v[48:49], v[12:13], v[52:53], v[48:49]
	v_pk_fma_f32 v[44:45], v[22:23], v[44:45], v[50:51]
	v_pk_fma_f32 v[46:47], v[20:21], v[46:47], v[48:49]
	v_mul_f32_e32 v50, 0xbfb8aa3b, v44
	v_mul_f32_e32 v48, 0xbfb8aa3b, v46
	v_mul_f32_e32 v49, 0xbfb8aa3b, v47
	v_exp_f32_e32 v48, v48
	v_exp_f32_e32 v49, v49
	v_exp_f32_e32 v50, v50
	v_pk_add_f32 v[48:49], v[48:49], 1.0 op_sel_hi:[1,0]
	s_nop 0
	s_nop 0
	v_rcp_f32_e32 v51, v49
	s_nop 0
	v_mul_f32_e32 v47, v47, v51
	v_mul_f32_e32 v51, 0xbfb8aa3b, v45
	v_exp_f32_e32 v51, v51
	s_nop 0
	v_pk_add_f32 v[50:51], v[50:51], 1.0 op_sel_hi:[1,0]
	v_rcp_f32_e32 v49, v48
	s_nop 0
	v_mul_f32_e32 v46, v46, v49
	v_cvt_pk_bf16_f32 v46, v46, v47
	v_rcp_f32_e32 v48, v51
	s_nop 0
	v_mul_f32_e32 v45, v45, v48
	v_rcp_f32_e32 v48, v50
	s_nop 0
	v_mul_f32_e32 v44, v44, v48
	v_cvt_pk_bf16_f32 v44, v44, v45
	v_and_b32_e32 v45, 0xffff0000, v44
	v_lshlrev_b32_e32 v44, 16, v44
	v_cmp_lt_i32_e32 vcc, s22, v94
	v_or_b32_sdwa v45, v45, v46 dst_sel:DWORD dst_unused:UNUSED_PAD src0_sel:DWORD src1_sel:WORD_1
	v_or_b32_sdwa v44, v44, v46 dst_sel:DWORD dst_unused:UNUSED_PAD src0_sel:DWORD src1_sel:WORD_0
	s_or_b64 s[16:17], vcc, s[16:17]
	global_store_dwordx4 v[40:41], v[42:45], off
	s_andn2_b64 exec, exec, s[16:17]
	s_cbranch_execz .LBB0_406

.LBB0_651:
	s_or_b64 exec, exec, s[76:77]
	s_waitcnt lgkmcnt(0)
	s_barrier
	s_and_saveexec_b64 s[70:71], s[14:15]
	s_xor_b64 s[76:77], exec, s[70:71]
	s_cbranch_execz .LBB0_656
	ds_read_b128 v[194:197], v173
	ds_read_b128 v[198:201], v173 offset:16
	s_waitcnt lgkmcnt(1)
	v_lshlrev_b32_e32 v122, 16, v194
	v_and_b32_e32 v193, 0xffff0000, v194
	v_lshlrev_b32_e32 v194, 16, v195
	v_and_b32_e32 v195, 0xffff0000, v195
	v_lshlrev_b32_e32 v202, 16, v196
	v_and_b32_e32 v196, 0xffff0000, v196
	v_lshlrev_b32_e32 v203, 16, v197
	v_and_b32_e32 v197, 0xffff0000, v197
	v_add_f32_e32 v122, v122, v193
	v_add_f32_e32 v193, v194, v195
	v_add_f32_e32 v122, v122, v193
	v_add_f32_e32 v193, v202, v196
	v_add_f32_e32 v194, v203, v197
	v_add_f32_e32 v193, v193, v194
	v_add_f32_e32 v122, v122, v193
	s_waitcnt lgkmcnt(0)
	v_lshlrev_b32_e32 v193, 16, v198
	v_and_b32_e32 v194, 0xffff0000, v198
	v_lshlrev_b32_e32 v195, 16, v199
	v_and_b32_e32 v196, 0xffff0000, v199
	v_lshlrev_b32_e32 v197, 16, v200
	v_and_b32_e32 v198, 0xffff0000, v200
	v_lshlrev_b32_e32 v199, 16, v201
	v_and_b32_e32 v200, 0xffff0000, v201
	v_add_f32_e32 v193, v193, v194
	v_add_f32_e32 v194, v195, v196
	v_add_f32_e32 v193, v193, v194
	v_add_f32_e32 v194, v197, v198
	v_add_f32_e32 v195, v199, v200
	v_add_f32_e32 v194, v194, v195
	v_add_f32_e32 v122, 0, v122
	v_add_f32_e32 v193, v193, v194
	v_add_f32_e32 v122, v122, v193
	v_xor_b32_e32 v193, 1, v129
	v_add_u32_e32 v194, 64, v130
	v_cmp_lt_i32_e32 vcc, v193, v194
	s_nop 1
	v_cndmask_b32_e32 v193, v129, v193, vcc
	v_lshlrev_b32_e32 v193, 2, v193
	ds_bpermute_b32 v193, v193, v122
	s_waitcnt lgkmcnt(0)
	v_add_f32_e32 v122, v122, v193
	v_xor_b32_e32 v193, 2, v129
	v_cmp_lt_i32_e32 vcc, v193, v194
	s_nop 1
	v_cndmask_b32_e32 v193, v129, v193, vcc
	v_lshlrev_b32_e32 v193, 2, v193
	ds_bpermute_b32 v193, v193, v122
	s_and_saveexec_b64 s[78:79], s[12:13]
	s_cbranch_execz .LBB0_654
	v_lshl_add_u32 v194, v153, 2, s69
	ds_read_b32 v196, v155
	ds_read2st64_b32 v[194:195], v194 offset0:2 offset1:3
	s_waitcnt lgkmcnt(2)
	v_add_f32_e32 v122, v122, v193
	s_waitcnt lgkmcnt(0)
	v_fmac_f32_e32 v122, v194, v196
	v_max_f32_e32 v193, v195, v195
	v_max_f32_e64 v122, |v122|, v193
	v_rcp_f32_e32 v122, v122
	s_nop 0
	ds_write_b32 v156, v122

.LBB0_1268:
	s_and_saveexec_b64 s[14:15], s[16:17]
	s_cbranch_execz .LBB0_1209
	s_mul_i32 s2, s18, 0x78
	s_mul_hi_i32 s3, s18, 0x78
	s_add_u32 s2, s0, s2
	s_addc_u32 s3, s1, s3
	s_load_dwordx2 s[4:5], s[2:3], 0x1e8
	s_nop 0
	s_load_dwordx2 s[2:3], s[2:3], 0x220
	v_mov_b32_e32 v12, v64
	v_mov_b32_e32 v13, v66
	s_waitcnt lgkmcnt(0)
	v_mov_b64_e32 v[2:3], s[4:5]
	v_mad_u64_u32 v[2:3], s[4:5], v182, s68, v[2:3]
	v_mov_b32_e32 v0, v3
	v_mad_u64_u32 v[4:5], s[4:5], v183, s68, v[0:1]
	v_mov_b32_e32 v3, v4
	s_lshl_b64 s[4:5], s[82:83], 1
	v_lshl_add_u64 v[4:5], v[2:3], 0, s[4:5]
	s_nop 0
	v_rcp_f32_e32 v2, v187
	s_nop 0
	v_lshlrev_b64 v[6:7], 11, v[182:183]
	v_lshlrev_b32_e32 v0, 3, v221
	v_lshl_add_u64 v[6:7], s[2:3], 0, v[6:7]
	v_lshl_add_u64 v[8:9], v[4:5], 0, v[0:1]
	s_mov_b64 s[2:3], 0x1580
	v_lshl_add_u64 v[4:5], v[8:9], 0, s[2:3]
	v_add_co_u32_e32 v8, vcc, s89, v8
	v_lshl_add_u64 v[6:7], v[6:7], 0, s[4:5]
	s_nop 0
	v_addc_co_u32_e32 v9, vcc, 0, v9, vcc
	global_load_dwordx2 v[8:9], v[8:9], off offset:1408
	v_lshl_add_u64 v[6:7], v[6:7], 0, v[0:1]
	s_waitcnt vmcnt(0)
	v_and_b32_e32 v15, 0xffff0000, v8
	v_lshlrev_b32_e32 v3, 16, v9
	v_lshlrev_b32_e32 v11, 16, v8
	v_and_b32_e32 v14, 0xffff0000, v9
	v_mul_f32_e32 v9, 0xbfb8aa3b, v15
	v_mul_f32_e32 v8, 0xbfb8aa3b, v11
	v_exp_f32_e32 v10, v9
	v_mul_f32_e32 v9, 0xbfb8aa3b, v3
	v_exp_f32_e32 v8, v8
	v_exp_f32_e32 v9, v9
	v_pk_mul_f32 v[12:13], v[12:13], v[2:3] op_sel_hi:[1,0]
	v_pk_add_f32 v[8:9], v[8:9], 1.0 op_sel_hi:[1,0]
	s_nop 0
	s_nop 0
	v_rcp_f32_e32 v64, v9
	s_nop 0
	v_mul_f32_e32 v9, v3, v64
	s_nop 0
	v_rcp_f32_e32 v3, v8
	s_nop 0
	v_mul_f32_e32 v8, v11, v3
	v_mov_b32_e32 v66, v65
	v_pk_mul_f32 v[8:9], v[12:13], v[8:9]
	v_pk_mul_f32 v[12:13], v[66:67], v[2:3] op_sel_hi:[1,0]
	v_mul_f32_e32 v3, 0xbfb8aa3b, v14
	v_exp_f32_e32 v11, v3
	s_nop 0
	v_pk_add_f32 v[10:11], v[10:11], 1.0 op_sel_hi:[1,0]
	s_nop 0
	s_nop 0
	v_rcp_f32_e32 v3, v11
	s_nop 0
	v_mul_f32_e32 v11, v14, v3
	s_nop 0
	v_rcp_f32_e32 v3, v10
	s_nop 0
	v_mul_f32_e32 v10, v15, v3
	v_pk_mul_f32 v[10:11], v[12:13], v[10:11]
	v_cvt_pk_bf16_f32 v3, v8, v9
	v_cvt_pk_bf16_f32 v8, v10, v11
	v_and_b32_e32 v9, 0xffff0000, v8
	v_lshlrev_b32_e32 v8, 16, v8
	v_or_b32_sdwa v9, v9, v3 dst_sel:DWORD dst_unused:UNUSED_PAD src0_sel:DWORD src1_sel:WORD_1
	v_or_b32_sdwa v8, v8, v3 dst_sel:DWORD dst_unused:UNUSED_PAD src0_sel:DWORD src1_sel:WORD_0
	global_store_dwordx2 v[6:7], v[8:9], off
	global_load_dwordx2 v[8:9], v[4:5], off offset:16
	v_mov_b32_e32 v12, v68
	v_mov_b32_e32 v13, v70
	v_mov_b32_e32 v70, v69
	s_waitcnt vmcnt(0)
	v_and_b32_e32 v15, 0xffff0000, v8
	v_lshlrev_b32_e32 v0, 16, v9
	v_lshlrev_b32_e32 v3, 16, v8
	v_and_b32_e32 v14, 0xffff0000, v9
	v_mul_f32_e32 v9, 0xbfb8aa3b, v15
	v_mul_f32_e32 v8, 0xbfb8aa3b, v3
	v_exp_f32_e32 v10, v9
	v_mul_f32_e32 v9, 0xbfb8aa3b, v0
	v_exp_f32_e32 v8, v8
	v_exp_f32_e32 v9, v9
	v_pk_mul_f32 v[12:13], v[12:13], v[2:3] op_sel_hi:[1,0]
	v_pk_add_f32 v[8:9], v[8:9], 1.0 op_sel_hi:[1,0]
	s_nop 0
	s_nop 0
	v_rcp_f32_e32 v11, v9
	s_nop 0
	v_mul_f32_e32 v9, v0, v11
	s_nop 0
	v_rcp_f32_e32 v0, v8
	s_nop 0
	v_mul_f32_e32 v8, v3, v0
	v_mul_f32_e32 v0, 0xbfb8aa3b, v14
	v_exp_f32_e32 v11, v0
	v_pk_mul_f32 v[8:9], v[12:13], v[8:9]
	v_pk_mul_f32 v[12:13], v[70:71], v[2:3] op_sel_hi:[1,0]
	v_pk_add_f32 v[10:11], v[10:11], 1.0 op_sel_hi:[1,0]
	s_nop 0
	s_nop 0
	v_rcp_f32_e32 v0, v11
	s_nop 0
	v_mul_f32_e32 v11, v14, v0
	s_nop 0
	v_rcp_f32_e32 v0, v10
	s_nop 0
	v_mul_f32_e32 v10, v15, v0
	v_pk_mul_f32 v[10:11], v[12:13], v[10:11]
	v_cvt_pk_bf16_f32 v0, v8, v9
	v_cvt_pk_bf16_f32 v3, v10, v11
	v_and_b32_e32 v8, 0xffff0000, v3
	v_lshlrev_b32_e32 v3, 16, v3
	v_or_b32_sdwa v9, v8, v0 dst_sel:DWORD dst_unused:UNUSED_PAD src0_sel:DWORD src1_sel:WORD_1
	v_or_b32_sdwa v8, v3, v0 dst_sel:DWORD dst_unused:UNUSED_PAD src0_sel:DWORD src1_sel:WORD_0
	global_store_dwordx2 v[6:7], v[8:9], off offset:16
	global_load_dwordx2 v[8:9], v[4:5], off offset:32
	v_mov_b32_e32 v12, v72
	v_mov_b32_e32 v13, v74
	v_mov_b32_e32 v74, v73
	s_waitcnt vmcnt(0)
	v_and_b32_e32 v15, 0xffff0000, v8
	v_lshlrev_b32_e32 v0, 16, v9
	v_lshlrev_b32_e32 v3, 16, v8
	v_and_b32_e32 v14, 0xffff0000, v9
	v_mul_f32_e32 v9, 0xbfb8aa3b, v15
	v_mul_f32_e32 v8, 0xbfb8aa3b, v3
	v_exp_f32_e32 v10, v9
	v_mul_f32_e32 v9, 0xbfb8aa3b, v0
	v_exp_f32_e32 v8, v8
	v_exp_f32_e32 v9, v9
	v_pk_mul_f32 v[12:13], v[12:13], v[2:3] op_sel_hi:[1,0]
	v_pk_add_f32 v[8:9], v[8:9], 1.0 op_sel_hi:[1,0]
	s_nop 0
	s_nop 0
	v_rcp_f32_e32 v11, v9
	s_nop 0
	v_mul_f32_e32 v9, v0, v11
	s_nop 0
	v_rcp_f32_e32 v0, v8
	s_nop 0
	v_mul_f32_e32 v8, v3, v0
	v_mul_f32_e32 v0, 0xbfb8aa3b, v14
	v_exp_f32_e32 v11, v0
	v_pk_mul_f32 v[8:9], v[12:13], v[8:9]
	v_pk_mul_f32 v[12:13], v[74:75], v[2:3] op_sel_hi:[1,0]
	v_pk_add_f32 v[10:11], v[10:11], 1.0 op_sel_hi:[1,0]
	s_nop 0
	s_nop 0
	v_rcp_f32_e32 v0, v11
	s_nop 0
	v_mul_f32_e32 v11, v14, v0
	s_nop 0
	v_rcp_f32_e32 v0, v10
	s_nop 0
	v_mul_f32_e32 v10, v15, v0
	v_pk_mul_f32 v[10:11], v[12:13], v[10:11]
	v_cvt_pk_bf16_f32 v0, v8, v9
	v_cvt_pk_bf16_f32 v3, v10, v11
	v_and_b32_e32 v8, 0xffff0000, v3
	v_lshlrev_b32_e32 v3, 16, v3
	v_or_b32_sdwa v9, v8, v0 dst_sel:DWORD dst_unused:UNUSED_PAD src0_sel:DWORD src1_sel:WORD_1
	v_or_b32_sdwa v8, v3, v0 dst_sel:DWORD dst_unused:UNUSED_PAD src0_sel:DWORD src1_sel:WORD_0
	global_store_dwordx2 v[6:7], v[8:9], off offset:32
	global_load_dwordx2 v[8:9], v[4:5], off offset:48
	v_mov_b32_e32 v12, v76
	v_mov_b32_e32 v13, v78
	v_mov_b32_e32 v78, v77
	s_waitcnt vmcnt(0)
	v_and_b32_e32 v15, 0xffff0000, v8
	v_lshlrev_b32_e32 v0, 16, v9
	v_lshlrev_b32_e32 v3, 16, v8
	v_and_b32_e32 v14, 0xffff0000, v9
	v_mul_f32_e32 v9, 0xbfb8aa3b, v15
	v_mul_f32_e32 v8, 0xbfb8aa3b, v3
	v_exp_f32_e32 v10, v9
	v_mul_f32_e32 v9, 0xbfb8aa3b, v0
	v_exp_f32_e32 v8, v8
	v_exp_f32_e32 v9, v9
	v_pk_mul_f32 v[12:13], v[12:13], v[2:3] op_sel_hi:[1,0]
	v_pk_add_f32 v[8:9], v[8:9], 1.0 op_sel_hi:[1,0]
	s_nop 0
	s_nop 0
	v_rcp_f32_e32 v11, v9
	s_nop 0
	v_mul_f32_e32 v9, v0, v11
	s_nop 0
	v_rcp_f32_e32 v0, v8
	s_nop 0
	v_mul_f32_e32 v8, v3, v0
	v_mul_f32_e32 v0, 0xbfb8aa3b, v14
	v_exp_f32_e32 v11, v0
	v_pk_mul_f32 v[8:9], v[12:13], v[8:9]
	v_pk_mul_f32 v[12:13], v[78:79], v[2:3] op_sel_hi:[1,0]
	v_pk_add_f32 v[10:11], v[10:11], 1.0 op_sel_hi:[1,0]
	s_nop 0
	s_nop 0
	v_rcp_f32_e32 v0, v11
	s_nop 0
	v_mul_f32_e32 v11, v14, v0
	s_nop 0
	v_rcp_f32_e32 v0, v10
	s_nop 0
	v_mul_f32_e32 v10, v15, v0
	v_pk_mul_f32 v[10:11], v[12:13], v[10:11]
	v_cvt_pk_bf16_f32 v0, v8, v9
	v_cvt_pk_bf16_f32 v3, v10, v11
	v_and_b32_e32 v8, 0xffff0000, v3
	v_lshlrev_b32_e32 v3, 16, v3
	v_or_b32_sdwa v9, v8, v0 dst_sel:DWORD dst_unused:UNUSED_PAD src0_sel:DWORD src1_sel:WORD_1
	v_or_b32_sdwa v8, v3, v0 dst_sel:DWORD dst_unused:UNUSED_PAD src0_sel:DWORD src1_sel:WORD_0
	global_store_dwordx2 v[6:7], v[8:9], off offset:48
	global_load_dwordx2 v[8:9], v[4:5], off offset:64
	v_mov_b32_e32 v12, v48
	v_mov_b32_e32 v13, v50
	s_waitcnt vmcnt(0)
	v_and_b32_e32 v15, 0xffff0000, v8
	v_lshlrev_b32_e32 v0, 16, v9
	v_lshlrev_b32_e32 v3, 16, v8
	v_and_b32_e32 v14, 0xffff0000, v9
	v_mul_f32_e32 v9, 0xbfb8aa3b, v15
	v_mul_f32_e32 v8, 0xbfb8aa3b, v3
	v_exp_f32_e32 v10, v9
	v_mul_f32_e32 v9, 0xbfb8aa3b, v0
	v_exp_f32_e32 v8, v8
	v_exp_f32_e32 v9, v9
	v_pk_mul_f32 v[12:13], v[12:13], v[2:3] op_sel_hi:[1,0]
	v_pk_add_f32 v[8:9], v[8:9], 1.0 op_sel_hi:[1,0]
	s_nop 0
	s_nop 0
	v_rcp_f32_e32 v11, v9
	s_nop 0
	v_mul_f32_e32 v9, v0, v11
	s_nop 0
	v_rcp_f32_e32 v0, v8
	s_nop 0
	v_mul_f32_e32 v8, v3, v0
	v_mul_f32_e32 v0, 0xbfb8aa3b, v14
	v_exp_f32_e32 v11, v0
	v_mov_b32_e32 v50, v49
	v_pk_mul_f32 v[8:9], v[12:13], v[8:9]
	v_pk_mul_f32 v[12:13], v[50:51], v[2:3] op_sel_hi:[1,0]
	v_pk_add_f32 v[10:11], v[10:11], 1.0 op_sel_hi:[1,0]
	s_nop 0
	s_nop 0
	v_rcp_f32_e32 v0, v11
	s_nop 0
	v_mul_f32_e32 v11, v14, v0
	s_nop 0
	v_rcp_f32_e32 v0, v10
	s_nop 0
	v_mul_f32_e32 v10, v15, v0
	v_pk_mul_f32 v[10:11], v[12:13], v[10:11]
	v_cvt_pk_bf16_f32 v0, v8, v9
	v_cvt_pk_bf16_f32 v3, v10, v11
	v_and_b32_e32 v8, 0xffff0000, v3
	v_lshlrev_b32_e32 v3, 16, v3
	v_or_b32_sdwa v9, v8, v0 dst_sel:DWORD dst_unused:UNUSED_PAD src0_sel:DWORD src1_sel:WORD_1
	v_or_b32_sdwa v8, v3, v0 dst_sel:DWORD dst_unused:UNUSED_PAD src0_sel:DWORD src1_sel:WORD_0
	global_store_dwordx2 v[6:7], v[8:9], off offset:64
	global_load_dwordx2 v[8:9], v[4:5], off offset:80
	v_mov_b32_e32 v12, v52
	v_mov_b32_e32 v13, v54
	v_mov_b32_e32 v54, v53
	s_waitcnt vmcnt(0)
	v_and_b32_e32 v15, 0xffff0000, v8
	v_lshlrev_b32_e32 v0, 16, v9
	v_lshlrev_b32_e32 v3, 16, v8
	v_and_b32_e32 v14, 0xffff0000, v9
	v_mul_f32_e32 v9, 0xbfb8aa3b, v15
	v_mul_f32_e32 v8, 0xbfb8aa3b, v3
	v_exp_f32_e32 v10, v9
	v_mul_f32_e32 v9, 0xbfb8aa3b, v0
	v_exp_f32_e32 v8, v8
	v_exp_f32_e32 v9, v9
	v_pk_mul_f32 v[12:13], v[12:13], v[2:3] op_sel_hi:[1,0]
	v_pk_add_f32 v[8:9], v[8:9], 1.0 op_sel_hi:[1,0]
	s_nop 0
	s_nop 0
	v_rcp_f32_e32 v11, v9
	s_nop 0
	v_mul_f32_e32 v9, v0, v11
	s_nop 0
	v_rcp_f32_e32 v0, v8
	s_nop 0
	v_mul_f32_e32 v8, v3, v0
	v_mul_f32_e32 v0, 0xbfb8aa3b, v14
	v_exp_f32_e32 v11, v0
	v_pk_mul_f32 v[8:9], v[12:13], v[8:9]
	v_pk_mul_f32 v[12:13], v[54:55], v[2:3] op_sel_hi:[1,0]
	v_pk_add_f32 v[10:11], v[10:11], 1.0 op_sel_hi:[1,0]
	s_nop 0
	s_nop 0
	v_rcp_f32_e32 v0, v11
	s_nop 0
	v_mul_f32_e32 v11, v14, v0
	s_nop 0
	v_rcp_f32_e32 v0, v10
	s_nop 0
	v_mul_f32_e32 v10, v15, v0
	v_pk_mul_f32 v[10:11], v[12:13], v[10:11]
	v_cvt_pk_bf16_f32 v0, v8, v9
	v_cvt_pk_bf16_f32 v3, v10, v11
	v_and_b32_e32 v8, 0xffff0000, v3
	v_lshlrev_b32_e32 v3, 16, v3
	v_or_b32_sdwa v9, v8, v0 dst_sel:DWORD dst_unused:UNUSED_PAD src0_sel:DWORD src1_sel:WORD_1
	v_or_b32_sdwa v8, v3, v0 dst_sel:DWORD dst_unused:UNUSED_PAD src0_sel:DWORD src1_sel:WORD_0
	global_store_dwordx2 v[6:7], v[8:9], off offset:80
	global_load_dwordx2 v[8:9], v[4:5], off offset:96
	v_mov_b32_e32 v12, v56
	v_mov_b32_e32 v13, v58
	v_mov_b32_e32 v58, v57
	s_waitcnt vmcnt(0)
	v_and_b32_e32 v15, 0xffff0000, v8
	v_lshlrev_b32_e32 v0, 16, v9
	v_lshlrev_b32_e32 v3, 16, v8
	v_and_b32_e32 v14, 0xffff0000, v9
	v_mul_f32_e32 v9, 0xbfb8aa3b, v15
	v_mul_f32_e32 v8, 0xbfb8aa3b, v3
	v_exp_f32_e32 v10, v9
	v_mul_f32_e32 v9, 0xbfb8aa3b, v0
	v_exp_f32_e32 v8, v8
	v_exp_f32_e32 v9, v9
	v_pk_mul_f32 v[12:13], v[12:13], v[2:3] op_sel_hi:[1,0]
	v_pk_add_f32 v[8:9], v[8:9], 1.0 op_sel_hi:[1,0]
	s_nop 0
	s_nop 0
	v_rcp_f32_e32 v11, v9
	s_nop 0
	v_mul_f32_e32 v9, v0, v11
	s_nop 0
	v_rcp_f32_e32 v0, v8
	s_nop 0
	v_mul_f32_e32 v8, v3, v0
	v_mul_f32_e32 v0, 0xbfb8aa3b, v14
	v_exp_f32_e32 v11, v0
	v_pk_mul_f32 v[8:9], v[12:13], v[8:9]
	v_pk_mul_f32 v[12:13], v[58:59], v[2:3] op_sel_hi:[1,0]
	v_pk_add_f32 v[10:11], v[10:11], 1.0 op_sel_hi:[1,0]
	s_nop 0
	s_nop 0
	v_rcp_f32_e32 v0, v11
	s_nop 0
	v_mul_f32_e32 v11, v14, v0
	s_nop 0
	v_rcp_f32_e32 v0, v10
	s_nop 0
	v_mul_f32_e32 v10, v15, v0
	v_pk_mul_f32 v[10:11], v[12:13], v[10:11]
	v_cvt_pk_bf16_f32 v0, v8, v9
	v_cvt_pk_bf16_f32 v3, v10, v11
	v_and_b32_e32 v8, 0xffff0000, v3
	v_lshlrev_b32_e32 v3, 16, v3
	v_or_b32_sdwa v9, v8, v0 dst_sel:DWORD dst_unused:UNUSED_PAD src0_sel:DWORD src1_sel:WORD_1
	v_or_b32_sdwa v8, v3, v0 dst_sel:DWORD dst_unused:UNUSED_PAD src0_sel:DWORD src1_sel:WORD_0
	global_store_dwordx2 v[6:7], v[8:9], off offset:96
	global_load_dwordx2 v[8:9], v[4:5], off offset:112
	v_mov_b32_e32 v12, v60
	v_mov_b32_e32 v13, v62
	v_mov_b32_e32 v62, v61
	s_waitcnt vmcnt(0)
	v_and_b32_e32 v15, 0xffff0000, v8
	v_lshlrev_b32_e32 v0, 16, v9
	v_lshlrev_b32_e32 v3, 16, v8
	v_and_b32_e32 v14, 0xffff0000, v9
	v_mul_f32_e32 v9, 0xbfb8aa3b, v15
	v_mul_f32_e32 v8, 0xbfb8aa3b, v3
	v_exp_f32_e32 v10, v9
	v_mul_f32_e32 v9, 0xbfb8aa3b, v0
	v_exp_f32_e32 v8, v8
	v_exp_f32_e32 v9, v9
	v_pk_mul_f32 v[12:13], v[12:13], v[2:3] op_sel_hi:[1,0]
	v_pk_add_f32 v[8:9], v[8:9], 1.0 op_sel_hi:[1,0]
	s_nop 0
	s_nop 0
	v_rcp_f32_e32 v11, v9
	s_nop 0
	v_mul_f32_e32 v9, v0, v11
	s_nop 0
	v_rcp_f32_e32 v0, v8
	s_nop 0
	v_mul_f32_e32 v8, v3, v0
	v_mul_f32_e32 v0, 0xbfb8aa3b, v14
	v_exp_f32_e32 v11, v0
	v_pk_mul_f32 v[8:9], v[12:13], v[8:9]
	v_pk_mul_f32 v[12:13], v[62:63], v[2:3] op_sel_hi:[1,0]
	v_pk_add_f32 v[10:11], v[10:11], 1.0 op_sel_hi:[1,0]
	s_nop 0
	s_nop 0
	v_rcp_f32_e32 v0, v11
	s_nop 0
	v_mul_f32_e32 v11, v14, v0
	s_nop 0
	v_rcp_f32_e32 v0, v10
	s_nop 0
	v_mul_f32_e32 v10, v15, v0
	v_pk_mul_f32 v[10:11], v[12:13], v[10:11]
	v_cvt_pk_bf16_f32 v0, v8, v9
	v_cvt_pk_bf16_f32 v3, v10, v11
	v_and_b32_e32 v8, 0xffff0000, v3
	v_lshlrev_b32_e32 v3, 16, v3
	v_or_b32_sdwa v9, v8, v0 dst_sel:DWORD dst_unused:UNUSED_PAD src0_sel:DWORD src1_sel:WORD_1
	v_or_b32_sdwa v8, v3, v0 dst_sel:DWORD dst_unused:UNUSED_PAD src0_sel:DWORD src1_sel:WORD_0
	global_store_dwordx2 v[6:7], v[8:9], off offset:112
	global_load_dwordx2 v[8:9], v[4:5], off offset:128
	v_mov_b32_e32 v12, v32
	v_mov_b32_e32 v13, v34
	s_waitcnt vmcnt(0)
	v_and_b32_e32 v15, 0xffff0000, v8
	v_lshlrev_b32_e32 v0, 16, v9
	v_lshlrev_b32_e32 v3, 16, v8
	v_and_b32_e32 v14, 0xffff0000, v9
	v_mul_f32_e32 v9, 0xbfb8aa3b, v15
	v_mul_f32_e32 v8, 0xbfb8aa3b, v3
	v_exp_f32_e32 v10, v9
	v_mul_f32_e32 v9, 0xbfb8aa3b, v0
	v_exp_f32_e32 v8, v8
	v_exp_f32_e32 v9, v9
	v_pk_mul_f32 v[12:13], v[12:13], v[2:3] op_sel_hi:[1,0]
	v_pk_add_f32 v[8:9], v[8:9], 1.0 op_sel_hi:[1,0]
	s_nop 0
	s_nop 0
	v_rcp_f32_e32 v11, v9
	s_nop 0
	v_mul_f32_e32 v9, v0, v11
	s_nop 0
	v_rcp_f32_e32 v0, v8
	s_nop 0
	v_mul_f32_e32 v8, v3, v0
	v_mul_f32_e32 v0, 0xbfb8aa3b, v14
	v_exp_f32_e32 v11, v0
	v_mov_b32_e32 v34, v33
	v_pk_mul_f32 v[8:9], v[12:13], v[8:9]
	v_pk_mul_f32 v[12:13], v[34:35], v[2:3] op_sel_hi:[1,0]
	v_pk_add_f32 v[10:11], v[10:11], 1.0 op_sel_hi:[1,0]
	s_nop 0
	s_nop 0
	v_rcp_f32_e32 v0, v11
	s_nop 0
	v_mul_f32_e32 v11, v14, v0
	s_nop 0
	v_rcp_f32_e32 v0, v10
	s_nop 0
	v_mul_f32_e32 v10, v15, v0
	v_pk_mul_f32 v[10:11], v[12:13], v[10:11]
	v_cvt_pk_bf16_f32 v0, v8, v9
	v_cvt_pk_bf16_f32 v3, v10, v11
	v_and_b32_e32 v8, 0xffff0000, v3
	v_lshlrev_b32_e32 v3, 16, v3
	v_or_b32_sdwa v9, v8, v0 dst_sel:DWORD dst_unused:UNUSED_PAD src0_sel:DWORD src1_sel:WORD_1
	v_or_b32_sdwa v8, v3, v0 dst_sel:DWORD dst_unused:UNUSED_PAD src0_sel:DWORD src1_sel:WORD_0
	global_store_dwordx2 v[6:7], v[8:9], off offset:128
	global_load_dwordx2 v[8:9], v[4:5], off offset:144
	v_mov_b32_e32 v12, v36
	v_mov_b32_e32 v13, v38
	v_mov_b32_e32 v38, v37
	s_waitcnt vmcnt(0)
	v_and_b32_e32 v15, 0xffff0000, v8
	v_lshlrev_b32_e32 v0, 16, v9
	v_lshlrev_b32_e32 v3, 16, v8
	v_and_b32_e32 v14, 0xffff0000, v9
	v_mul_f32_e32 v9, 0xbfb8aa3b, v15
	v_mul_f32_e32 v8, 0xbfb8aa3b, v3
	v_exp_f32_e32 v10, v9
	v_mul_f32_e32 v9, 0xbfb8aa3b, v0
	v_exp_f32_e32 v8, v8
	v_exp_f32_e32 v9, v9
	v_pk_mul_f32 v[12:13], v[12:13], v[2:3] op_sel_hi:[1,0]
	v_pk_add_f32 v[8:9], v[8:9], 1.0 op_sel_hi:[1,0]
	s_nop 0
	s_nop 0
	v_rcp_f32_e32 v11, v9
	s_nop 0
	v_mul_f32_e32 v9, v0, v11
	s_nop 0
	v_rcp_f32_e32 v0, v8
	s_nop 0
	v_mul_f32_e32 v8, v3, v0
	v_mul_f32_e32 v0, 0xbfb8aa3b, v14
	v_exp_f32_e32 v11, v0
	v_pk_mul_f32 v[8:9], v[12:13], v[8:9]
	v_pk_mul_f32 v[12:13], v[38:39], v[2:3] op_sel_hi:[1,0]
	v_pk_add_f32 v[10:11], v[10:11], 1.0 op_sel_hi:[1,0]
	s_nop 0
	s_nop 0
	v_rcp_f32_e32 v0, v11
	s_nop 0
	v_mul_f32_e32 v11, v14, v0
	s_nop 0
	v_rcp_f32_e32 v0, v10
	s_nop 0
	v_mul_f32_e32 v10, v15, v0
	v_pk_mul_f32 v[10:11], v[12:13], v[10:11]
	v_cvt_pk_bf16_f32 v0, v8, v9
	v_cvt_pk_bf16_f32 v3, v10, v11
	v_and_b32_e32 v8, 0xffff0000, v3
	v_lshlrev_b32_e32 v3, 16, v3
	v_or_b32_sdwa v9, v8, v0 dst_sel:DWORD dst_unused:UNUSED_PAD src0_sel:DWORD src1_sel:WORD_1
	v_or_b32_sdwa v8, v3, v0 dst_sel:DWORD dst_unused:UNUSED_PAD src0_sel:DWORD src1_sel:WORD_0
	global_store_dwordx2 v[6:7], v[8:9], off offset:144
	global_load_dwordx2 v[8:9], v[4:5], off offset:160
	v_mov_b32_e32 v12, v40
	v_mov_b32_e32 v13, v42
	v_mov_b32_e32 v42, v41
	s_waitcnt vmcnt(0)
	v_and_b32_e32 v15, 0xffff0000, v8
	v_lshlrev_b32_e32 v0, 16, v9
	v_lshlrev_b32_e32 v3, 16, v8
	v_and_b32_e32 v14, 0xffff0000, v9
	v_mul_f32_e32 v9, 0xbfb8aa3b, v15
	v_mul_f32_e32 v8, 0xbfb8aa3b, v3
	v_exp_f32_e32 v10, v9
	v_mul_f32_e32 v9, 0xbfb8aa3b, v0
	v_exp_f32_e32 v8, v8
	v_exp_f32_e32 v9, v9
	v_pk_mul_f32 v[12:13], v[12:13], v[2:3] op_sel_hi:[1,0]
	v_pk_add_f32 v[8:9], v[8:9], 1.0 op_sel_hi:[1,0]
	s_nop 0
	s_nop 0
	v_rcp_f32_e32 v11, v9
	s_nop 0
	v_mul_f32_e32 v9, v0, v11
	s_nop 0
	v_rcp_f32_e32 v0, v8
	s_nop 0
	v_mul_f32_e32 v8, v3, v0
	v_mul_f32_e32 v0, 0xbfb8aa3b, v14
	v_exp_f32_e32 v11, v0
	v_pk_mul_f32 v[8:9], v[12:13], v[8:9]
	v_pk_mul_f32 v[12:13], v[42:43], v[2:3] op_sel_hi:[1,0]
	v_pk_add_f32 v[10:11], v[10:11], 1.0 op_sel_hi:[1,0]
	s_nop 0
	s_nop 0
	v_rcp_f32_e32 v0, v11
	s_nop 0
	v_mul_f32_e32 v11, v14, v0
	s_nop 0
	v_rcp_f32_e32 v0, v10
	s_nop 0
	v_mul_f32_e32 v10, v15, v0
	v_pk_mul_f32 v[10:11], v[12:13], v[10:11]
	v_cvt_pk_bf16_f32 v0, v8, v9
	v_cvt_pk_bf16_f32 v3, v10, v11
	v_and_b32_e32 v8, 0xffff0000, v3
	v_lshlrev_b32_e32 v3, 16, v3
	v_or_b32_sdwa v9, v8, v0 dst_sel:DWORD dst_unused:UNUSED_PAD src0_sel:DWORD src1_sel:WORD_1
	v_or_b32_sdwa v8, v3, v0 dst_sel:DWORD dst_unused:UNUSED_PAD src0_sel:DWORD src1_sel:WORD_0
	global_store_dwordx2 v[6:7], v[8:9], off offset:160
	global_load_dwordx2 v[8:9], v[4:5], off offset:176
	v_mov_b32_e32 v12, v44
	v_mov_b32_e32 v13, v46
	v_mov_b32_e32 v46, v45
	s_waitcnt vmcnt(0)
	v_and_b32_e32 v15, 0xffff0000, v8
	v_lshlrev_b32_e32 v0, 16, v9
	v_lshlrev_b32_e32 v3, 16, v8
	v_and_b32_e32 v14, 0xffff0000, v9
	v_mul_f32_e32 v9, 0xbfb8aa3b, v15
	v_mul_f32_e32 v8, 0xbfb8aa3b, v3
	v_exp_f32_e32 v10, v9
	v_mul_f32_e32 v9, 0xbfb8aa3b, v0
	v_exp_f32_e32 v8, v8
	v_exp_f32_e32 v9, v9
	v_pk_mul_f32 v[12:13], v[12:13], v[2:3] op_sel_hi:[1,0]
	v_pk_add_f32 v[8:9], v[8:9], 1.0 op_sel_hi:[1,0]
	s_nop 0
	s_nop 0
	v_rcp_f32_e32 v11, v9
	s_nop 0
	v_mul_f32_e32 v9, v0, v11
	s_nop 0
	v_rcp_f32_e32 v0, v8
	s_nop 0
	v_mul_f32_e32 v8, v3, v0
	v_mul_f32_e32 v0, 0xbfb8aa3b, v14
	v_exp_f32_e32 v11, v0
	v_pk_mul_f32 v[8:9], v[12:13], v[8:9]
	v_pk_mul_f32 v[12:13], v[46:47], v[2:3] op_sel_hi:[1,0]
	v_pk_add_f32 v[10:11], v[10:11], 1.0 op_sel_hi:[1,0]
	s_nop 0
	s_nop 0
	v_rcp_f32_e32 v0, v11
	s_nop 0
	v_mul_f32_e32 v11, v14, v0
	s_nop 0
	v_rcp_f32_e32 v0, v10
	s_nop 0
	v_mul_f32_e32 v10, v15, v0
	v_pk_mul_f32 v[10:11], v[12:13], v[10:11]
	v_cvt_pk_bf16_f32 v0, v8, v9
	v_cvt_pk_bf16_f32 v3, v10, v11
	v_and_b32_e32 v8, 0xffff0000, v3
	v_lshlrev_b32_e32 v3, 16, v3
	v_or_b32_sdwa v9, v8, v0 dst_sel:DWORD dst_unused:UNUSED_PAD src0_sel:DWORD src1_sel:WORD_1
	v_or_b32_sdwa v8, v3, v0 dst_sel:DWORD dst_unused:UNUSED_PAD src0_sel:DWORD src1_sel:WORD_0
	global_store_dwordx2 v[6:7], v[8:9], off offset:176
	global_load_dwordx2 v[8:9], v[4:5], off offset:192
	v_mov_b32_e32 v12, v16
	v_mov_b32_e32 v13, v18
	s_waitcnt vmcnt(0)
	v_and_b32_e32 v15, 0xffff0000, v8
	v_lshlrev_b32_e32 v0, 16, v9
	v_lshlrev_b32_e32 v3, 16, v8
	v_and_b32_e32 v14, 0xffff0000, v9
	v_mul_f32_e32 v9, 0xbfb8aa3b, v15
	v_mul_f32_e32 v8, 0xbfb8aa3b, v3
	v_exp_f32_e32 v10, v9
	v_mul_f32_e32 v9, 0xbfb8aa3b, v0
	v_exp_f32_e32 v8, v8
	v_exp_f32_e32 v9, v9
	v_pk_mul_f32 v[12:13], v[12:13], v[2:3] op_sel_hi:[1,0]
	v_pk_add_f32 v[8:9], v[8:9], 1.0 op_sel_hi:[1,0]
	s_nop 0
	s_nop 0
	v_rcp_f32_e32 v11, v9
	s_nop 0
	v_mul_f32_e32 v9, v0, v11
	s_nop 0
	v_rcp_f32_e32 v0, v8
	s_nop 0
	v_mul_f32_e32 v8, v3, v0
	v_mul_f32_e32 v0, 0xbfb8aa3b, v14
	v_exp_f32_e32 v11, v0
	v_mov_b32_e32 v18, v17
	v_pk_mul_f32 v[8:9], v[12:13], v[8:9]
	v_pk_mul_f32 v[12:13], v[18:19], v[2:3] op_sel_hi:[1,0]
	v_pk_add_f32 v[10:11], v[10:11], 1.0 op_sel_hi:[1,0]
	s_nop 0
	s_nop 0
	v_rcp_f32_e32 v0, v11
	s_nop 0
	v_mul_f32_e32 v11, v14, v0
	s_nop 0
	v_rcp_f32_e32 v0, v10
	s_nop 0
	v_mul_f32_e32 v10, v15, v0
	v_pk_mul_f32 v[10:11], v[12:13], v[10:11]
	v_cvt_pk_bf16_f32 v0, v8, v9
	v_cvt_pk_bf16_f32 v3, v10, v11
	v_and_b32_e32 v8, 0xffff0000, v3
	v_lshlrev_b32_e32 v3, 16, v3
	v_or_b32_sdwa v9, v8, v0 dst_sel:DWORD dst_unused:UNUSED_PAD src0_sel:DWORD src1_sel:WORD_1
	v_or_b32_sdwa v8, v3, v0 dst_sel:DWORD dst_unused:UNUSED_PAD src0_sel:DWORD src1_sel:WORD_0
	global_store_dwordx2 v[6:7], v[8:9], off offset:192
	global_load_dwordx2 v[8:9], v[4:5], off offset:208
	v_mov_b32_e32 v12, v20
	v_mov_b32_e32 v13, v22
	v_mov_b32_e32 v22, v21
	s_waitcnt vmcnt(0)
	v_and_b32_e32 v15, 0xffff0000, v8
	v_lshlrev_b32_e32 v0, 16, v9
	v_lshlrev_b32_e32 v3, 16, v8
	v_and_b32_e32 v14, 0xffff0000, v9
	v_mul_f32_e32 v9, 0xbfb8aa3b, v15
	v_mul_f32_e32 v8, 0xbfb8aa3b, v3
	v_exp_f32_e32 v10, v9
	v_mul_f32_e32 v9, 0xbfb8aa3b, v0
	v_exp_f32_e32 v8, v8
	v_exp_f32_e32 v9, v9
	v_pk_mul_f32 v[12:13], v[12:13], v[2:3] op_sel_hi:[1,0]
	v_pk_add_f32 v[8:9], v[8:9], 1.0 op_sel_hi:[1,0]
	s_nop 0
	s_nop 0
	v_rcp_f32_e32 v11, v9
	s_nop 0
	v_mul_f32_e32 v9, v0, v11
	s_nop 0
	v_rcp_f32_e32 v0, v8
	s_nop 0
	v_mul_f32_e32 v8, v3, v0
	v_mul_f32_e32 v0, 0xbfb8aa3b, v14
	v_exp_f32_e32 v11, v0
	v_pk_mul_f32 v[8:9], v[12:13], v[8:9]
	v_pk_mul_f32 v[12:13], v[22:23], v[2:3] op_sel_hi:[1,0]
	v_pk_add_f32 v[10:11], v[10:11], 1.0 op_sel_hi:[1,0]
	s_nop 0
	s_nop 0
	v_rcp_f32_e32 v0, v11
	s_nop 0
	v_mul_f32_e32 v11, v14, v0
	s_nop 0
	v_rcp_f32_e32 v0, v10
	s_nop 0
	v_mul_f32_e32 v10, v15, v0
	v_pk_mul_f32 v[10:11], v[12:13], v[10:11]
	v_cvt_pk_bf16_f32 v0, v8, v9
	v_cvt_pk_bf16_f32 v3, v10, v11
	v_and_b32_e32 v8, 0xffff0000, v3
	v_lshlrev_b32_e32 v3, 16, v3
	v_or_b32_sdwa v9, v8, v0 dst_sel:DWORD dst_unused:UNUSED_PAD src0_sel:DWORD src1_sel:WORD_1
	v_or_b32_sdwa v8, v3, v0 dst_sel:DWORD dst_unused:UNUSED_PAD src0_sel:DWORD src1_sel:WORD_0
	global_store_dwordx2 v[6:7], v[8:9], off offset:208
	global_load_dwordx2 v[8:9], v[4:5], off offset:224
	v_mov_b32_e32 v12, v24
	v_mov_b32_e32 v13, v26
	v_mov_b32_e32 v26, v25
	s_waitcnt vmcnt(0)
	v_and_b32_e32 v15, 0xffff0000, v8
	v_lshlrev_b32_e32 v0, 16, v9
	v_lshlrev_b32_e32 v3, 16, v8
	v_and_b32_e32 v14, 0xffff0000, v9
	v_mul_f32_e32 v9, 0xbfb8aa3b, v15
	v_mul_f32_e32 v8, 0xbfb8aa3b, v3
	v_exp_f32_e32 v10, v9
	v_mul_f32_e32 v9, 0xbfb8aa3b, v0
	v_exp_f32_e32 v8, v8
	v_exp_f32_e32 v9, v9
	v_pk_mul_f32 v[12:13], v[12:13], v[2:3] op_sel_hi:[1,0]
	v_pk_add_f32 v[8:9], v[8:9], 1.0 op_sel_hi:[1,0]
	s_nop 0
	s_nop 0
	v_rcp_f32_e32 v11, v9
	s_nop 0
	v_mul_f32_e32 v9, v0, v11
	s_nop 0
	v_rcp_f32_e32 v0, v8
	s_nop 0
	v_mul_f32_e32 v8, v3, v0
	v_mul_f32_e32 v0, 0xbfb8aa3b, v14
	v_exp_f32_e32 v11, v0
	v_pk_mul_f32 v[8:9], v[12:13], v[8:9]
	v_pk_mul_f32 v[12:13], v[26:27], v[2:3] op_sel_hi:[1,0]
	v_pk_add_f32 v[10:11], v[10:11], 1.0 op_sel_hi:[1,0]
	s_nop 0
	s_nop 0
	v_rcp_f32_e32 v0, v11
	s_nop 0
	v_mul_f32_e32 v11, v14, v0
	s_nop 0
	v_rcp_f32_e32 v0, v10
	s_nop 0
	v_mul_f32_e32 v10, v15, v0
	v_pk_mul_f32 v[10:11], v[12:13], v[10:11]
	v_cvt_pk_bf16_f32 v0, v8, v9
	v_cvt_pk_bf16_f32 v3, v10, v11
	v_and_b32_e32 v8, 0xffff0000, v3
	v_lshlrev_b32_e32 v3, 16, v3
	v_or_b32_sdwa v9, v8, v0 dst_sel:DWORD dst_unused:UNUSED_PAD src0_sel:DWORD src1_sel:WORD_1
	v_or_b32_sdwa v8, v3, v0 dst_sel:DWORD dst_unused:UNUSED_PAD src0_sel:DWORD src1_sel:WORD_0
	global_store_dwordx2 v[6:7], v[8:9], off offset:224
	global_load_dwordx2 v[4:5], v[4:5], off offset:240
	v_mov_b32_e32 v10, v28
	v_mov_b32_e32 v11, v30
	v_mov_b32_e32 v30, v29
	s_waitcnt vmcnt(0)
	v_and_b32_e32 v13, 0xffff0000, v4
	v_lshlrev_b32_e32 v0, 16, v5
	v_lshlrev_b32_e32 v3, 16, v4
	v_and_b32_e32 v12, 0xffff0000, v5
	v_mul_f32_e32 v5, 0xbfb8aa3b, v13
	v_mul_f32_e32 v4, 0xbfb8aa3b, v3
	v_exp_f32_e32 v8, v5
	v_mul_f32_e32 v5, 0xbfb8aa3b, v0
	v_exp_f32_e32 v4, v4
	v_exp_f32_e32 v5, v5
	v_pk_mul_f32 v[10:11], v[10:11], v[2:3] op_sel_hi:[1,0]
	v_pk_add_f32 v[4:5], v[4:5], 1.0 op_sel_hi:[1,0]
	s_nop 0
	s_nop 0
	v_rcp_f32_e32 v9, v5
	s_nop 0
	v_mul_f32_e32 v5, v0, v9
	s_nop 0
	v_rcp_f32_e32 v0, v4
	s_nop 0
	v_mul_f32_e32 v4, v3, v0
	v_mul_f32_e32 v0, 0xbfb8aa3b, v12
	v_exp_f32_e32 v9, v0
	v_pk_mul_f32 v[4:5], v[10:11], v[4:5]
	v_pk_mul_f32 v[2:3], v[30:31], v[2:3] op_sel_hi:[1,0]
	v_pk_add_f32 v[8:9], v[8:9], 1.0 op_sel_hi:[1,0]
	s_nop 0
	s_nop 0
	v_rcp_f32_e32 v0, v9
	s_nop 0
	v_mul_f32_e32 v9, v12, v0
	s_nop 0
	v_rcp_f32_e32 v0, v8
	s_nop 0
	v_mul_f32_e32 v8, v13, v0
	v_pk_mul_f32 v[2:3], v[2:3], v[8:9]
	v_cvt_pk_bf16_f32 v0, v4, v5
	v_cvt_pk_bf16_f32 v2, v2, v3
	v_and_b32_e32 v3, 0xffff0000, v2
	v_lshlrev_b32_e32 v2, 16, v2
	v_or_b32_sdwa v3, v3, v0 dst_sel:DWORD dst_unused:UNUSED_PAD src0_sel:DWORD src1_sel:WORD_1
	v_or_b32_sdwa v2, v2, v0 dst_sel:DWORD dst_unused:UNUSED_PAD src0_sel:DWORD src1_sel:WORD_0
	global_store_dwordx2 v[6:7], v[2:3], off offset:240
	s_branch .LBB0_1209

.LBB0_1274:
	v_lshlrev_b32_e32 v78, 16, v60
	v_and_b32_e32 v74, 0xffff0000, v60
	v_lshlrev_b32_e32 v72, 16, v48
	v_and_b32_e32 v4, 0xffff0000, v48
	v_lshlrev_b32_e32 v60, 16, v50
	v_and_b32_e32 v48, 0xffff0000, v50
	v_lshlrev_b32_e32 v50, 16, v56
	v_lshlrev_b32_e32 v79, 16, v61
	v_and_b32_e32 v75, 0xffff0000, v61
	v_lshlrev_b32_e32 v73, 16, v49
	v_and_b32_e32 v5, 0xffff0000, v49
	v_lshlrev_b32_e32 v61, 16, v51
	v_and_b32_e32 v49, 0xffff0000, v51
	v_and_b32_e32 v51, 0xffff0000, v56
	v_lshlrev_b32_e32 v83, 16, v40
	v_and_b32_e32 v84, 0xffff0000, v40
	v_mul_f32_e32 v40, 0xbfb8aa3b, v50
	v_lshlrev_b32_e32 v56, 16, v57
	v_exp_f32_e32 v90, v40
	v_mul_f32_e32 v40, 0xbfb8aa3b, v51
	v_and_b32_e32 v57, 0xffff0000, v57
	v_exp_f32_e32 v86, v40
	v_mul_f32_e32 v40, 0xbfb8aa3b, v56
	v_lshlrev_b32_e32 v80, 16, v58
	v_exp_f32_e32 v91, v40
	v_mul_f32_e32 v40, 0xbfb8aa3b, v57
	v_and_b32_e32 v58, 0xffff0000, v58
	v_exp_f32_e32 v87, v40
	v_mul_f32_e32 v40, 0xbfb8aa3b, v80
	v_lshlrev_b32_e32 v81, 16, v59
	v_exp_f32_e32 v80, v40
	v_mul_f32_e32 v40, 0xbfb8aa3b, v58
	v_and_b32_e32 v59, 0xffff0000, v59
	v_exp_f32_e32 v50, v40
	v_mul_f32_e32 v40, 0xbfb8aa3b, v81
	v_lshlrev_b32_e32 v85, 16, v41
	v_and_b32_e32 v88, 0xffff0000, v41
	v_exp_f32_e32 v81, v40
	v_mul_f32_e32 v40, 0xbfb8aa3b, v59
	v_mul_f32_e32 v41, 0xbfb8aa3b, v84
	v_lshlrev_b32_e32 v82, 16, v46
	v_and_b32_e32 v92, 0xffff0000, v46
	v_exp_f32_e32 v51, v40
	v_mul_f32_e32 v40, 0xbfb8aa3b, v83
	v_exp_f32_e32 v46, v41
	v_mul_f32_e32 v41, 0xbfb8aa3b, v85
	v_exp_f32_e32 v40, v40
	v_exp_f32_e32 v41, v41
	v_and_b32_e32 v99, 0xffff0000, v44
	v_lshlrev_b32_e32 v97, 16, v53
	v_and_b32_e32 v101, 0xffff0000, v53
	v_lshlrev_b32_e32 v53, 16, v45
	v_and_b32_e32 v98, 0xffff0000, v45
	v_mul_f32_e32 v45, 0xbfb8aa3b, v99
	v_pk_add_f32 v[40:41], v[40:41], 1.0 op_sel_hi:[1,0]
	v_lshlrev_b32_e32 v96, 16, v52
	v_and_b32_e32 v100, 0xffff0000, v52
	v_exp_f32_e32 v52, v45
	v_lshlrev_b32_e32 v89, 16, v42
	v_lshlrev_b32_e32 v95, 16, v44
	v_mul_f32_e32 v44, 0xbfb8aa3b, v88
	v_rcp_f32_e32 v41, v41
	s_nop 0
	v_lshlrev_b32_e32 v102, 16, v47
	v_and_b32_e32 v93, 0xffff0000, v47
	v_exp_f32_e32 v47, v44
	v_mul_f32_e32 v44, 0xbfb8aa3b, v89
	v_lshlrev_b32_e32 v104, 16, v54
	v_and_b32_e32 v111, 0xffff0000, v54
	v_exp_f32_e32 v54, v44
	v_mul_f32_e32 v44, 0xbfb8aa3b, v95
	v_rcp_f32_e32 v40, v40
	s_nop 0
	v_mul_f32_e32 v45, 0xbfb8aa3b, v53
	v_exp_f32_e32 v44, v44
	v_exp_f32_e32 v45, v45
	v_pk_add_f32 v[46:47], v[46:47], 1.0 op_sel_hi:[1,0]
	v_and_b32_e32 v42, 0xffff0000, v42
	v_lshlrev_b32_e32 v94, 16, v43
	v_pk_add_f32 v[44:45], v[44:45], 1.0 op_sel_hi:[1,0]
	v_mul_f32_e32 v42, 0xbfb8aa3b, v42
	v_exp_f32_e32 v84, v42
	v_mul_f32_e32 v42, 0xbfb8aa3b, v94
	v_lshlrev_b32_e32 v105, 16, v55
	v_rcp_f32_e32 v56, v45
	s_nop 0
	v_mul_f32_e32 v45, v53, v56
	v_and_b32_e32 v112, 0xffff0000, v55
	v_exp_f32_e32 v55, v42
	v_and_b32_e32 v43, 0xffff0000, v43
	v_rcp_f32_e32 v53, v44
	s_nop 0
	v_mul_f32_e32 v44, v95, v53
	v_pk_add_f32 v[54:55], v[54:55], 1.0 op_sel_hi:[1,0]
	v_mul_f32_e32 v42, 0xbfb8aa3b, v43
	v_exp_f32_e32 v85, v42
	v_rcp_f32_e32 v47, v47
	s_nop 0
	v_pk_add_f32 v[84:85], v[84:85], 1.0 op_sel_hi:[1,0]
	v_pk_add_f32 v[90:91], v[90:91], 1.0 op_sel_hi:[1,0]
	v_pk_add_f32 v[86:87], v[86:87], 1.0 op_sel_hi:[1,0]
	v_rcp_f32_e32 v46, v46
	s_nop 0
	v_mul_f32_e32 v53, 0xbfb8aa3b, v98
	v_exp_f32_e32 v53, v53
	v_pk_add_f32 v[80:81], v[80:81], 1.0 op_sel_hi:[1,0]
	v_pk_add_f32 v[50:51], v[50:51], 1.0 op_sel_hi:[1,0]
	v_lshlrev_b32_e32 v77, 16, v63
	v_pk_add_f32 v[52:53], v[52:53], 1.0 op_sel_hi:[1,0]
	v_lshlrev_b32_e32 v76, 16, v62
	v_and_b32_e32 v63, 0xffff0000, v63
	v_and_b32_e32 v62, 0xffff0000, v62
	v_mov_b32_e32 v42, v5
	v_rcp_f32_e32 v56, v53
	s_nop 0
	v_mul_f32_e32 v53, v98, v56
	v_mov_b32_e32 v43, v73
	v_pk_mul_f32 v[42:43], v[42:43], v[42:43]
	v_mul_f32_e32 v83, 0xbfb8aa3b, v82
	v_exp_f32_e32 v94, v83
	v_mul_f32_e32 v83, 0xbfb8aa3b, v92
	v_exp_f32_e32 v88, v83
	v_rcp_f32_e32 v56, v52
	s_nop 0
	v_mul_f32_e32 v52, v99, v56
	v_rcp_f32_e32 v55, v55
	s_nop 0
	v_mov_b32_e32 v56, v48
	v_mov_b32_e32 v57, v60
	v_pk_mul_f32 v[56:57], v[56:57], v[56:57]
	v_rcp_f32_e32 v54, v54
	s_nop 0
	v_mul_f32_e32 v83, 0xbfb8aa3b, v102
	v_exp_f32_e32 v95, v83
	v_mov_b32_e32 v58, v49
	v_mov_b32_e32 v59, v61
	v_pk_mul_f32 v[58:59], v[58:59], v[58:59]
	v_pk_add_f32 v[94:95], v[94:95], 1.0 op_sel_hi:[1,0]
	s_nop 0
	s_nop 0
	v_rcp_f32_e32 v83, v95
	s_nop 0
	v_mul_f32_e32 v83, v102, v83
	s_nop 0
	v_rcp_f32_e32 v89, v94
	s_nop 0
	v_mul_f32_e32 v82, v82, v89
	s_nop 0
	v_rcp_f32_e32 v85, v85
	s_nop 0
	s_nop 0
	v_rcp_f32_e32 v84, v84
	s_nop 0
	v_mul_f32_e32 v89, 0xbfb8aa3b, v93
	v_exp_f32_e32 v89, v89
	s_nop 0
	v_pk_add_f32 v[88:89], v[88:89], 1.0 op_sel_hi:[1,0]
	s_nop 0
	s_nop 0
	v_rcp_f32_e32 v94, v89
	s_nop 0
	v_mul_f32_e32 v89, v93, v94
	s_nop 0
	v_mul_f32_e32 v98, 0xbfb8aa3b, v96
	v_rcp_f32_e32 v91, v91
	s_nop 0
	v_exp_f32_e32 v102, v98
	v_mul_f32_e32 v98, 0xbfb8aa3b, v100
	v_exp_f32_e32 v98, v98
	v_rcp_f32_e32 v90, v90
	s_nop 0
	v_mul_f32_e32 v99, 0xbfb8aa3b, v97
	v_exp_f32_e32 v103, v99
	v_rcp_f32_e32 v93, v88
	s_nop 0
	v_mul_f32_e32 v88, v92, v93
	v_pk_mul_f32 v[92:93], v[78:79], v[78:79]
	v_pk_mul_f32 v[94:95], v[74:75], v[74:75]
	v_pk_add_f32 v[102:103], v[102:103], 1.0 op_sel_hi:[1,0]
	v_add_f32_e32 v92, v92, v94
	v_add_f32_e32 v92, v93, v92
	v_add_f32_e32 v92, v95, v92
	v_rcp_f32_e32 v99, v103
	s_nop 0
	v_mul_f32_e32 v97, v97, v99
	s_nop 0
	v_rcp_f32_e32 v99, v102
	s_nop 0
	v_mul_f32_e32 v96, v96, v99
	s_nop 0
	v_rcp_f32_e32 v87, v87
	s_nop 0
	s_nop 0
	v_rcp_f32_e32 v86, v86
	s_nop 0
	v_mul_f32_e32 v99, 0xbfb8aa3b, v101
	v_exp_f32_e32 v99, v99
	s_nop 0
	v_pk_add_f32 v[98:99], v[98:99], 1.0 op_sel_hi:[1,0]
	s_nop 0
	s_nop 0
	v_rcp_f32_e32 v102, v99
	s_nop 0
	v_mul_f32_e32 v99, v101, v102
	s_nop 0
	v_mul_f32_e32 v106, 0xbfb8aa3b, v104
	v_rcp_f32_e32 v81, v81
	s_nop 0
	v_exp_f32_e32 v114, v106
	v_rcp_f32_e32 v101, v98
	s_nop 0
	v_mul_f32_e32 v98, v100, v101
	v_pk_mul_f32 v[100:101], v[76:77], v[76:77]
	v_rcp_f32_e32 v80, v80
	s_nop 0
	v_mul_f32_e32 v107, 0xbfb8aa3b, v105
	v_exp_f32_e32 v115, v107
	v_pk_mul_f32 v[102:103], v[62:63], v[62:63]
	v_add_f32_e32 v92, v100, v92
	v_add_f32_e32 v92, v102, v92
	v_pk_add_f32 v[114:115], v[114:115], 1.0 op_sel_hi:[1,0]
	v_add_f32_e32 v92, v101, v92
	v_add_f32_e32 v92, v103, v92
	v_fmac_f32_e32 v92, v72, v72
	v_fmac_f32_e32 v92, v4, v4
	v_rcp_f32_e32 v107, v115
	s_nop 0
	v_mul_f32_e32 v105, v105, v107
	v_add_f32_e32 v43, v43, v92
	v_add_f32_e32 v42, v42, v43
	v_mul_f32_e32 v106, 0xbfb8aa3b, v111
	v_rcp_f32_e32 v107, v114
	s_nop 0
	v_mul_f32_e32 v104, v104, v107
	v_add_f32_e32 v42, v57, v42
	v_exp_f32_e32 v106, v106
	v_add_f32_e32 v42, v56, v42
	v_rcp_f32_e32 v51, v51
	s_nop 0
	v_add_f32_e32 v42, v59, v42
	v_add_f32_e32 v42, v58, v42
	ds_bpermute_b32 v43, v0, v42
	v_rcp_f32_e32 v50, v50
	s_nop 0
	v_mul_f32_e32 v107, 0xbfb8aa3b, v112
	v_exp_f32_e32 v107, v107
	s_waitcnt lgkmcnt(0)
	v_add_f32_e32 v42, v42, v43
	ds_bpermute_b32 v43, v108, v42
	v_pk_add_f32 v[106:107], v[106:107], 1.0 op_sel_hi:[1,0]
	s_nop 0
	s_waitcnt lgkmcnt(0)
	v_add_f32_e32 v42, v42, v43
	ds_bpermute_b32 v43, v109, v42
	v_rcp_f32_e32 v113, v107
	s_nop 0
	v_mul_f32_e32 v107, v112, v113
	s_waitcnt lgkmcnt(0)
	v_add_f32_e32 v42, v42, v43
	ds_bpermute_b32 v43, v110, v42
	s_waitcnt lgkmcnt(0)
	v_add_f32_e32 v42, v42, v43
	v_fmamk_f32 v42, v42, 0x3b800000, v180
	v_cmp_gt_f32_e32 vcc, s91, v42
	v_mul_f32_e32 v43, 0x4b800000, v42
	v_rcp_f32_e32 v112, v106
	s_nop 0
	v_mul_f32_e32 v106, v111, v112
	v_cndmask_b32_e32 v42, v42, v43, vcc
	v_rsq_f32_e32 v42, v42
	s_nop 0
	v_mul_f32_e32 v43, 0x45800000, v42
	v_cndmask_b32_e32 v42, v42, v43, vcc
	v_pk_mul_f32 v[62:63], v[42:43], v[62:63] op_sel_hi:[0,1]
	v_pk_mul_f32 v[62:63], v[8:9], v[62:63]
	v_pk_mul_f32 v[4:5], v[42:43], v[4:5] op_sel_hi:[0,1]
	v_pk_mul_f32 v[50:51], v[50:51], v[62:63]
	v_pk_mul_f32 v[62:63], v[42:43], v[72:73] op_sel_hi:[0,1]
	v_pk_mul_f32 v[62:63], v[14:15], v[62:63]
	v_pk_mul_f32 v[4:5], v[68:69], v[4:5]
	v_pk_mul_f32 v[40:41], v[40:41], v[62:63]
	v_pk_mul_f32 v[4:5], v[46:47], v[4:5]
	v_pk_mul_f32 v[44:45], v[44:45], v[40:41]
	v_pk_mul_f32 v[40:41], v[42:43], v[60:61] op_sel_hi:[0,1]
	v_pk_mul_f32 v[40:41], v[10:11], v[40:41]
	v_pk_mul_f32 v[58:59], v[42:43], v[74:75] op_sel_hi:[0,1]
	v_pk_mul_f32 v[40:41], v[54:55], v[40:41]
	v_pk_mul_f32 v[4:5], v[52:53], v[4:5]
	v_pk_mul_f32 v[46:47], v[82:83], v[40:41]
	v_pk_mul_f32 v[40:41], v[42:43], v[48:49] op_sel_hi:[0,1]
	v_pk_mul_f32 v[40:41], v[70:71], v[40:41]
	v_pk_mul_f32 v[56:57], v[42:43], v[78:79] op_sel_hi:[0,1]
	v_pk_mul_f32 v[58:59], v[12:13], v[58:59]
	v_pk_mul_f32 v[40:41], v[84:85], v[40:41]
	v_cvt_pk_bf16_f32 v4, v4, v5
	v_pk_mul_f32 v[56:57], v[6:7], v[56:57]
	v_pk_mul_f32 v[58:59], v[86:87], v[58:59]
	v_pk_mul_f32 v[48:49], v[88:89], v[40:41]
	v_cvt_pk_bf16_f32 v44, v44, v45
	v_and_b32_e32 v5, 0xffff0000, v4
	v_pk_mul_f32 v[56:57], v[90:91], v[56:57]
	v_pk_mul_f32 v[58:59], v[98:99], v[58:59]
	v_pk_mul_f32 v[74:75], v[42:43], v[76:77] op_sel_hi:[0,1]
	v_lshlrev_b32_e32 v4, 16, v4
	v_or_b32_sdwa v45, v5, v44 dst_sel:DWORD dst_unused:UNUSED_PAD src0_sel:DWORD src1_sel:WORD_1
	v_cvt_pk_bf16_f32 v5, v48, v49
	v_pk_mul_f32 v[56:57], v[96:97], v[56:57]
	v_pk_mul_f32 v[74:75], v[2:3], v[74:75]
	v_cvt_pk_bf16_f32 v41, v58, v59
	v_or_b32_sdwa v44, v4, v44 dst_sel:DWORD dst_unused:UNUSED_PAD src0_sel:DWORD src1_sel:WORD_0
	v_cvt_pk_bf16_f32 v4, v46, v47
	v_and_b32_e32 v46, 0xffff0000, v5
	v_lshlrev_b32_e32 v5, 16, v5
	v_pk_mul_f32 v[74:75], v[80:81], v[74:75]
	v_pk_mul_f32 v[50:51], v[106:107], v[50:51]
	v_cvt_pk_bf16_f32 v40, v56, v57
	v_and_b32_e32 v42, 0xffff0000, v41
	v_lshlrev_b32_e32 v43, 16, v41
	v_or_b32_sdwa v47, v46, v4 dst_sel:DWORD dst_unused:UNUSED_PAD src0_sel:DWORD src1_sel:WORD_1
	v_or_b32_sdwa v46, v5, v4 dst_sel:DWORD dst_unused:UNUSED_PAD src0_sel:DWORD src1_sel:WORD_0
	v_lshl_add_u64 v[4:5], s[8:9], 0, v[64:65]
	s_add_u32 s8, s8, s80
	v_pk_mul_f32 v[74:75], v[104:105], v[74:75]
	v_or_b32_sdwa v41, v42, v40 dst_sel:DWORD dst_unused:UNUSED_PAD src0_sel:DWORD src1_sel:WORD_1
	v_or_b32_sdwa v40, v43, v40 dst_sel:DWORD dst_unused:UNUSED_PAD src0_sel:DWORD src1_sel:WORD_0
	v_cvt_pk_bf16_f32 v43, v50, v51
	s_addc_u32 s9, s9, s81
	v_cvt_pk_bf16_f32 v42, v74, v75
	v_and_b32_e32 v50, 0xffff0000, v43
	v_lshlrev_b32_e32 v51, 16, v43
	s_add_u32 s10, s10, s75
	v_or_b32_sdwa v43, v50, v42 dst_sel:DWORD dst_unused:UNUSED_PAD src0_sel:DWORD src1_sel:WORD_1
	v_or_b32_sdwa v42, v51, v42 dst_sel:DWORD dst_unused:UNUSED_PAD src0_sel:DWORD src1_sel:WORD_0
	s_addc_u32 s11, s11, s94
	global_store_dwordx4 v[4:5], v[40:43], off offset:-16
	global_store_dwordx4 v[4:5], v[44:47], off
	s_add_u32 s5, s5, s64
	s_waitcnt vmcnt(6)
	v_mov_b64_e32 v[62:63], v[18:19]
	v_mov_b64_e32 v[50:51], v[22:23]
	s_waitcnt vmcnt(4)
	v_mov_b64_e32 v[58:59], v[26:27]
	v_mov_b64_e32 v[42:43], v[30:31]
	s_waitcnt vmcnt(2)
	v_mov_b64_e32 v[54:55], v[34:35]
	v_mov_b64_e32 v[46:47], v[38:39]
	s_addc_u32 s14, s14, s65
	s_andn2_b64 vcc, exec, s[12:13]
	v_mov_b64_e32 v[60:61], v[16:17]
	v_mov_b64_e32 v[48:49], v[20:21]
	v_mov_b64_e32 v[56:57], v[24:25]
	v_mov_b64_e32 v[40:41], v[28:29]
	v_mov_b64_e32 v[52:53], v[32:33]
	v_mov_b64_e32 v[44:45], v[36:37]
	s_cbranch_vccz .LBB0_1277

.LBB0_1280:
	v_lshlrev_b32_e32 v78, 16, v60
	v_and_b32_e32 v74, 0xffff0000, v60
	v_lshlrev_b32_e32 v72, 16, v48
	v_and_b32_e32 v4, 0xffff0000, v48
	v_lshlrev_b32_e32 v60, 16, v50
	v_and_b32_e32 v48, 0xffff0000, v50
	v_lshlrev_b32_e32 v50, 16, v56
	v_lshlrev_b32_e32 v79, 16, v61
	v_and_b32_e32 v75, 0xffff0000, v61
	v_lshlrev_b32_e32 v73, 16, v49
	v_and_b32_e32 v5, 0xffff0000, v49
	v_lshlrev_b32_e32 v61, 16, v51
	v_and_b32_e32 v49, 0xffff0000, v51
	v_and_b32_e32 v51, 0xffff0000, v56
	v_lshlrev_b32_e32 v83, 16, v40
	v_and_b32_e32 v84, 0xffff0000, v40
	v_mul_f32_e32 v40, 0xbfb8aa3b, v50
	v_lshlrev_b32_e32 v56, 16, v57
	v_exp_f32_e32 v90, v40
	v_mul_f32_e32 v40, 0xbfb8aa3b, v51
	v_and_b32_e32 v57, 0xffff0000, v57
	v_exp_f32_e32 v86, v40
	v_mul_f32_e32 v40, 0xbfb8aa3b, v56
	v_lshlrev_b32_e32 v80, 16, v58
	v_exp_f32_e32 v91, v40
	v_mul_f32_e32 v40, 0xbfb8aa3b, v57
	v_and_b32_e32 v58, 0xffff0000, v58
	v_exp_f32_e32 v87, v40
	v_mul_f32_e32 v40, 0xbfb8aa3b, v80
	v_lshlrev_b32_e32 v81, 16, v59
	v_exp_f32_e32 v80, v40
	v_mul_f32_e32 v40, 0xbfb8aa3b, v58
	v_and_b32_e32 v59, 0xffff0000, v59
	v_exp_f32_e32 v50, v40
	v_mul_f32_e32 v40, 0xbfb8aa3b, v81
	v_lshlrev_b32_e32 v85, 16, v41
	v_and_b32_e32 v88, 0xffff0000, v41
	v_exp_f32_e32 v81, v40
	v_mul_f32_e32 v40, 0xbfb8aa3b, v59
	v_mul_f32_e32 v41, 0xbfb8aa3b, v84
	v_lshlrev_b32_e32 v82, 16, v46
	v_and_b32_e32 v92, 0xffff0000, v46
	v_exp_f32_e32 v51, v40
	v_mul_f32_e32 v40, 0xbfb8aa3b, v83
	v_exp_f32_e32 v46, v41
	v_mul_f32_e32 v41, 0xbfb8aa3b, v85
	v_exp_f32_e32 v40, v40
	v_exp_f32_e32 v41, v41
	v_and_b32_e32 v99, 0xffff0000, v44
	v_lshlrev_b32_e32 v97, 16, v53
	v_and_b32_e32 v101, 0xffff0000, v53
	v_lshlrev_b32_e32 v53, 16, v45
	v_and_b32_e32 v98, 0xffff0000, v45
	v_mul_f32_e32 v45, 0xbfb8aa3b, v99
	v_pk_add_f32 v[40:41], v[40:41], 1.0 op_sel_hi:[1,0]
	v_lshlrev_b32_e32 v96, 16, v52
	v_and_b32_e32 v100, 0xffff0000, v52
	v_exp_f32_e32 v52, v45
	v_lshlrev_b32_e32 v89, 16, v42
	v_lshlrev_b32_e32 v95, 16, v44
	v_mul_f32_e32 v44, 0xbfb8aa3b, v88
	v_rcp_f32_e32 v41, v41
	s_nop 0
	v_lshlrev_b32_e32 v102, 16, v47
	v_and_b32_e32 v93, 0xffff0000, v47
	v_exp_f32_e32 v47, v44
	v_mul_f32_e32 v44, 0xbfb8aa3b, v89
	v_lshlrev_b32_e32 v104, 16, v54
	v_and_b32_e32 v111, 0xffff0000, v54
	v_exp_f32_e32 v54, v44
	v_mul_f32_e32 v44, 0xbfb8aa3b, v95
	v_rcp_f32_e32 v40, v40
	s_nop 0
	v_mul_f32_e32 v45, 0xbfb8aa3b, v53
	v_exp_f32_e32 v44, v44
	v_exp_f32_e32 v45, v45
	v_pk_add_f32 v[46:47], v[46:47], 1.0 op_sel_hi:[1,0]
	v_and_b32_e32 v42, 0xffff0000, v42
	v_lshlrev_b32_e32 v94, 16, v43
	v_pk_add_f32 v[44:45], v[44:45], 1.0 op_sel_hi:[1,0]
	v_mul_f32_e32 v42, 0xbfb8aa3b, v42
	v_exp_f32_e32 v84, v42
	v_mul_f32_e32 v42, 0xbfb8aa3b, v94
	v_lshlrev_b32_e32 v105, 16, v55
	v_rcp_f32_e32 v56, v45
	s_nop 0
	v_mul_f32_e32 v45, v53, v56
	v_and_b32_e32 v112, 0xffff0000, v55
	v_exp_f32_e32 v55, v42
	v_and_b32_e32 v43, 0xffff0000, v43
	v_rcp_f32_e32 v53, v44
	s_nop 0
	v_mul_f32_e32 v44, v95, v53
	v_pk_add_f32 v[54:55], v[54:55], 1.0 op_sel_hi:[1,0]
	v_mul_f32_e32 v42, 0xbfb8aa3b, v43
	v_exp_f32_e32 v85, v42
	v_rcp_f32_e32 v47, v47
	s_nop 0
	v_pk_add_f32 v[84:85], v[84:85], 1.0 op_sel_hi:[1,0]
	v_pk_add_f32 v[90:91], v[90:91], 1.0 op_sel_hi:[1,0]
	v_pk_add_f32 v[86:87], v[86:87], 1.0 op_sel_hi:[1,0]
	v_rcp_f32_e32 v46, v46
	s_nop 0
	v_mul_f32_e32 v53, 0xbfb8aa3b, v98
	v_exp_f32_e32 v53, v53
	v_pk_add_f32 v[80:81], v[80:81], 1.0 op_sel_hi:[1,0]
	v_pk_add_f32 v[50:51], v[50:51], 1.0 op_sel_hi:[1,0]
	v_lshlrev_b32_e32 v77, 16, v63
	v_pk_add_f32 v[52:53], v[52:53], 1.0 op_sel_hi:[1,0]
	v_lshlrev_b32_e32 v76, 16, v62
	v_and_b32_e32 v63, 0xffff0000, v63
	v_and_b32_e32 v62, 0xffff0000, v62
	v_mov_b32_e32 v42, v5
	v_rcp_f32_e32 v56, v53
	s_nop 0
	v_mul_f32_e32 v53, v98, v56
	v_mov_b32_e32 v43, v73
	v_pk_mul_f32 v[42:43], v[42:43], v[42:43]
	v_mul_f32_e32 v83, 0xbfb8aa3b, v82
	v_exp_f32_e32 v94, v83
	v_mul_f32_e32 v83, 0xbfb8aa3b, v92
	v_exp_f32_e32 v88, v83
	v_rcp_f32_e32 v56, v52
	s_nop 0
	v_mul_f32_e32 v52, v99, v56
	v_rcp_f32_e32 v55, v55
	s_nop 0
	v_mov_b32_e32 v56, v48
	v_mov_b32_e32 v57, v60
	v_pk_mul_f32 v[56:57], v[56:57], v[56:57]
	v_rcp_f32_e32 v54, v54
	s_nop 0
	v_mul_f32_e32 v83, 0xbfb8aa3b, v102
	v_exp_f32_e32 v95, v83
	v_mov_b32_e32 v58, v49
	v_mov_b32_e32 v59, v61
	v_pk_mul_f32 v[58:59], v[58:59], v[58:59]
	v_pk_add_f32 v[94:95], v[94:95], 1.0 op_sel_hi:[1,0]
	s_nop 0
	s_nop 0
	v_rcp_f32_e32 v83, v95
	s_nop 0
	v_mul_f32_e32 v83, v102, v83
	s_nop 0
	v_rcp_f32_e32 v89, v94
	s_nop 0
	v_mul_f32_e32 v82, v82, v89
	s_nop 0
	v_rcp_f32_e32 v85, v85
	s_nop 0
	s_nop 0
	v_rcp_f32_e32 v84, v84
	s_nop 0
	v_mul_f32_e32 v89, 0xbfb8aa3b, v93
	v_exp_f32_e32 v89, v89
	s_nop 0
	v_pk_add_f32 v[88:89], v[88:89], 1.0 op_sel_hi:[1,0]
	s_nop 0
	s_nop 0
	v_rcp_f32_e32 v94, v89
	s_nop 0
	v_mul_f32_e32 v89, v93, v94
	s_nop 0
	v_mul_f32_e32 v98, 0xbfb8aa3b, v96
	v_rcp_f32_e32 v91, v91
	s_nop 0
	v_exp_f32_e32 v102, v98
	v_mul_f32_e32 v98, 0xbfb8aa3b, v100
	v_exp_f32_e32 v98, v98
	v_rcp_f32_e32 v90, v90
	s_nop 0
	v_mul_f32_e32 v99, 0xbfb8aa3b, v97
	v_exp_f32_e32 v103, v99
	v_rcp_f32_e32 v93, v88
	s_nop 0
	v_mul_f32_e32 v88, v92, v93
	v_pk_mul_f32 v[92:93], v[78:79], v[78:79]
	v_pk_mul_f32 v[94:95], v[74:75], v[74:75]
	v_pk_add_f32 v[102:103], v[102:103], 1.0 op_sel_hi:[1,0]
	v_add_f32_e32 v92, v92, v94
	v_add_f32_e32 v92, v93, v92
	v_add_f32_e32 v92, v95, v92
	v_rcp_f32_e32 v99, v103
	s_nop 0
	v_mul_f32_e32 v97, v97, v99
	s_nop 0
	v_rcp_f32_e32 v99, v102
	s_nop 0
	v_mul_f32_e32 v96, v96, v99
	s_nop 0
	v_rcp_f32_e32 v87, v87
	s_nop 0
	s_nop 0
	v_rcp_f32_e32 v86, v86
	s_nop 0
	v_mul_f32_e32 v99, 0xbfb8aa3b, v101
	v_exp_f32_e32 v99, v99
	s_nop 0
	v_pk_add_f32 v[98:99], v[98:99], 1.0 op_sel_hi:[1,0]
	s_nop 0
	s_nop 0
	v_rcp_f32_e32 v102, v99
	s_nop 0
	v_mul_f32_e32 v99, v101, v102
	s_nop 0
	v_mul_f32_e32 v106, 0xbfb8aa3b, v104
	v_rcp_f32_e32 v81, v81
	s_nop 0
	v_exp_f32_e32 v114, v106
	v_rcp_f32_e32 v101, v98
	s_nop 0
	v_mul_f32_e32 v98, v100, v101
	v_pk_mul_f32 v[100:101], v[76:77], v[76:77]
	v_rcp_f32_e32 v80, v80
	s_nop 0
	v_mul_f32_e32 v107, 0xbfb8aa3b, v105
	v_exp_f32_e32 v115, v107
	v_pk_mul_f32 v[102:103], v[62:63], v[62:63]
	v_add_f32_e32 v92, v100, v92
	v_add_f32_e32 v92, v102, v92
	v_pk_add_f32 v[114:115], v[114:115], 1.0 op_sel_hi:[1,0]
	v_add_f32_e32 v92, v101, v92
	v_add_f32_e32 v92, v103, v92
	v_fmac_f32_e32 v92, v72, v72
	v_fmac_f32_e32 v92, v4, v4
	v_rcp_f32_e32 v107, v115
	s_nop 0
	v_mul_f32_e32 v105, v105, v107
	v_add_f32_e32 v43, v43, v92
	v_add_f32_e32 v42, v42, v43
	v_mul_f32_e32 v106, 0xbfb8aa3b, v111
	v_rcp_f32_e32 v107, v114
	s_nop 0
	v_mul_f32_e32 v104, v104, v107
	v_add_f32_e32 v42, v57, v42
	v_exp_f32_e32 v106, v106
	v_add_f32_e32 v42, v56, v42
	v_rcp_f32_e32 v51, v51
	s_nop 0
	v_add_f32_e32 v42, v59, v42
	v_add_f32_e32 v42, v58, v42
	ds_bpermute_b32 v43, v0, v42
	v_rcp_f32_e32 v50, v50
	s_nop 0
	v_mul_f32_e32 v107, 0xbfb8aa3b, v112
	v_exp_f32_e32 v107, v107
	s_waitcnt lgkmcnt(0)
	v_add_f32_e32 v42, v42, v43
	ds_bpermute_b32 v43, v108, v42
	v_pk_add_f32 v[106:107], v[106:107], 1.0 op_sel_hi:[1,0]
	s_nop 0
	s_waitcnt lgkmcnt(0)
	v_add_f32_e32 v42, v42, v43
	ds_bpermute_b32 v43, v109, v42
	v_rcp_f32_e32 v113, v107
	s_nop 0
	v_mul_f32_e32 v107, v112, v113
	s_waitcnt lgkmcnt(0)
	v_add_f32_e32 v42, v42, v43
	ds_bpermute_b32 v43, v110, v42
	s_waitcnt lgkmcnt(0)
	v_add_f32_e32 v42, v42, v43
	v_fmamk_f32 v42, v42, 0x3b800000, v180
	v_cmp_gt_f32_e32 vcc, s91, v42
	v_mul_f32_e32 v43, 0x4b800000, v42
	v_rcp_f32_e32 v112, v106
	s_nop 0
	v_mul_f32_e32 v106, v111, v112
	v_cndmask_b32_e32 v42, v42, v43, vcc
	v_rsq_f32_e32 v42, v42
	s_nop 0
	v_mul_f32_e32 v43, 0x45800000, v42
	v_cndmask_b32_e32 v42, v42, v43, vcc
	v_pk_mul_f32 v[62:63], v[42:43], v[62:63] op_sel_hi:[0,1]
	v_pk_mul_f32 v[62:63], v[8:9], v[62:63]
	v_pk_mul_f32 v[4:5], v[42:43], v[4:5] op_sel_hi:[0,1]
	v_pk_mul_f32 v[50:51], v[50:51], v[62:63]
	v_pk_mul_f32 v[62:63], v[42:43], v[72:73] op_sel_hi:[0,1]
	v_pk_mul_f32 v[62:63], v[14:15], v[62:63]
	v_pk_mul_f32 v[4:5], v[68:69], v[4:5]
	v_pk_mul_f32 v[40:41], v[40:41], v[62:63]
	v_pk_mul_f32 v[4:5], v[46:47], v[4:5]
	v_pk_mul_f32 v[44:45], v[44:45], v[40:41]
	v_pk_mul_f32 v[40:41], v[42:43], v[60:61] op_sel_hi:[0,1]
	v_pk_mul_f32 v[40:41], v[10:11], v[40:41]
	v_pk_mul_f32 v[58:59], v[42:43], v[74:75] op_sel_hi:[0,1]
	v_pk_mul_f32 v[40:41], v[54:55], v[40:41]
	v_pk_mul_f32 v[4:5], v[52:53], v[4:5]
	v_pk_mul_f32 v[46:47], v[82:83], v[40:41]
	v_pk_mul_f32 v[40:41], v[42:43], v[48:49] op_sel_hi:[0,1]
	v_pk_mul_f32 v[40:41], v[70:71], v[40:41]
	v_pk_mul_f32 v[56:57], v[42:43], v[78:79] op_sel_hi:[0,1]
	v_pk_mul_f32 v[58:59], v[12:13], v[58:59]
	v_pk_mul_f32 v[40:41], v[84:85], v[40:41]
	v_cvt_pk_bf16_f32 v4, v4, v5
	v_pk_mul_f32 v[56:57], v[6:7], v[56:57]
	v_pk_mul_f32 v[58:59], v[86:87], v[58:59]
	v_pk_mul_f32 v[48:49], v[88:89], v[40:41]
	v_cvt_pk_bf16_f32 v44, v44, v45
	v_and_b32_e32 v5, 0xffff0000, v4
	v_pk_mul_f32 v[56:57], v[90:91], v[56:57]
	v_pk_mul_f32 v[58:59], v[98:99], v[58:59]
	v_pk_mul_f32 v[74:75], v[42:43], v[76:77] op_sel_hi:[0,1]
	v_lshlrev_b32_e32 v4, 16, v4
	v_or_b32_sdwa v45, v5, v44 dst_sel:DWORD dst_unused:UNUSED_PAD src0_sel:DWORD src1_sel:WORD_1
	v_cvt_pk_bf16_f32 v5, v48, v49
	v_pk_mul_f32 v[56:57], v[96:97], v[56:57]
	v_pk_mul_f32 v[74:75], v[2:3], v[74:75]
	v_cvt_pk_bf16_f32 v41, v58, v59
	v_or_b32_sdwa v44, v4, v44 dst_sel:DWORD dst_unused:UNUSED_PAD src0_sel:DWORD src1_sel:WORD_0
	v_cvt_pk_bf16_f32 v4, v46, v47
	v_and_b32_e32 v46, 0xffff0000, v5
	v_lshlrev_b32_e32 v5, 16, v5
	v_pk_mul_f32 v[74:75], v[80:81], v[74:75]
	v_pk_mul_f32 v[50:51], v[106:107], v[50:51]
	v_cvt_pk_bf16_f32 v40, v56, v57
	v_and_b32_e32 v42, 0xffff0000, v41
	v_lshlrev_b32_e32 v43, 16, v41
	v_or_b32_sdwa v47, v46, v4 dst_sel:DWORD dst_unused:UNUSED_PAD src0_sel:DWORD src1_sel:WORD_1
	v_or_b32_sdwa v46, v5, v4 dst_sel:DWORD dst_unused:UNUSED_PAD src0_sel:DWORD src1_sel:WORD_0
	v_lshl_add_u64 v[4:5], s[8:9], 0, v[64:65]
	s_add_u32 s8, s8, s80
	v_pk_mul_f32 v[74:75], v[104:105], v[74:75]
	v_or_b32_sdwa v41, v42, v40 dst_sel:DWORD dst_unused:UNUSED_PAD src0_sel:DWORD src1_sel:WORD_1
	v_or_b32_sdwa v40, v43, v40 dst_sel:DWORD dst_unused:UNUSED_PAD src0_sel:DWORD src1_sel:WORD_0
	v_cvt_pk_bf16_f32 v43, v50, v51
	s_addc_u32 s9, s9, s81
	v_cvt_pk_bf16_f32 v42, v74, v75
	v_and_b32_e32 v50, 0xffff0000, v43
	v_lshlrev_b32_e32 v51, 16, v43
	s_add_u32 s10, s10, s75
	v_or_b32_sdwa v43, v50, v42 dst_sel:DWORD dst_unused:UNUSED_PAD src0_sel:DWORD src1_sel:WORD_1
	v_or_b32_sdwa v42, v51, v42 dst_sel:DWORD dst_unused:UNUSED_PAD src0_sel:DWORD src1_sel:WORD_0
	s_addc_u32 s11, s11, s94
	global_store_dwordx4 v[4:5], v[40:43], off offset:-16
	global_store_dwordx4 v[4:5], v[44:47], off
	s_add_u32 s4, s4, s64
	s_waitcnt vmcnt(6)
	v_mov_b64_e32 v[62:63], v[18:19]
	v_mov_b64_e32 v[50:51], v[22:23]
	s_waitcnt vmcnt(4)
	v_mov_b64_e32 v[58:59], v[26:27]
	v_mov_b64_e32 v[42:43], v[30:31]
	s_waitcnt vmcnt(2)
	v_mov_b64_e32 v[54:55], v[34:35]
	v_mov_b64_e32 v[46:47], v[38:39]
	s_addc_u32 s5, s5, s65
	s_andn2_b64 vcc, exec, s[12:13]
	v_mov_b64_e32 v[60:61], v[16:17]
	v_mov_b64_e32 v[48:49], v[20:21]
	v_mov_b64_e32 v[56:57], v[24:25]
	v_mov_b64_e32 v[40:41], v[28:29]
	v_mov_b64_e32 v[52:53], v[32:33]
	v_mov_b64_e32 v[44:45], v[36:37]
	s_cbranch_vccz .LBB0_1283

.LBB0_1334:
	v_add_u32_e32 v0, 0x10000, v148
	s_waitcnt vmcnt(0)
	ds_read_b128 v[142:145], v0
	ds_read_b128 v[150:153], v0 offset:1024
	ds_read_b128 v[154:157], v0 offset:2048
	ds_read_b128 v[158:161], v0 offset:3072
	s_add_u32 s26, s24, 0xfffc0080
	s_addc_u32 s27, s25, -1
	s_cmp_eq_u32 vcc_lo, 12
	s_cselect_b32 s29, s2, s27
	s_cselect_b32 s28, s15, s26
	s_cselect_b32 s27, s13, s94
	s_cselect_b32 s26, s89, s90
	v_lshl_add_u64 v[178:179], s[24:25], 0, v[138:139]
	s_add_i32 m0, s36, 0xc000
	ds_read_b128 v[162:165], v147
	ds_read_b128 v[166:169], v147 offset:1024
	ds_read_b128 v[170:173], v147 offset:2048
	ds_read_b128 v[174:177], v147 offset:3072
	ds_read_b128 v[182:185], v147 offset:4096
	ds_read_b128 v[186:189], v147 offset:5120
	ds_read_b128 v[190:193], v147 offset:6144
	ds_read_b128 v[194:197], v147 offset:7168
	global_load_lds_dwordx4 v[178:179], off
	v_lshl_add_u64 v[178:179], s[24:25], 0, v[140:141]
	s_add_i32 m0, s36, 0xe000
	s_nop 0
	global_load_lds_dwordx4 v[178:179], off
	s_waitcnt lgkmcnt(8)
	s_barrier
	s_waitcnt lgkmcnt(0)
	s_setprio 1
	s_waitcnt lgkmcnt(0)
	v_mfma_f32_16x16x32_bf16 v[126:129], v[142:145], v[162:165], v[126:129]
	v_mfma_f32_16x16x32_bf16 v[122:125], v[154:157], v[162:165], v[122:125]
	v_mfma_f32_16x16x32_bf16 v[110:113], v[142:145], v[170:173], v[110:113]
	v_mfma_f32_16x16x32_bf16 v[106:109], v[154:157], v[170:173], v[106:109]
	v_mfma_f32_16x16x32_bf16 v[94:97], v[142:145], v[182:185], v[94:97]
	v_mfma_f32_16x16x32_bf16 v[90:93], v[154:157], v[182:185], v[90:93]
	v_mfma_f32_16x16x32_bf16 v[78:81], v[142:145], v[190:193], v[78:81]
	v_mfma_f32_16x16x32_bf16 v[74:77], v[154:157], v[190:193], v[74:77]
	v_mfma_f32_16x16x32_bf16 v[126:129], v[150:153], v[166:169], v[126:129]
	v_mfma_f32_16x16x32_bf16 v[122:125], v[158:161], v[166:169], v[122:125]
	v_mfma_f32_16x16x32_bf16 v[110:113], v[150:153], v[174:177], v[110:113]
	v_mfma_f32_16x16x32_bf16 v[106:109], v[158:161], v[174:177], v[106:109]
	v_mfma_f32_16x16x32_bf16 v[94:97], v[150:153], v[186:189], v[94:97]
	v_mfma_f32_16x16x32_bf16 v[90:93], v[158:161], v[186:189], v[90:93]
	v_mfma_f32_16x16x32_bf16 v[78:81], v[150:153], v[194:197], v[78:81]
	v_mfma_f32_16x16x32_bf16 v[74:77], v[158:161], v[194:197], v[74:77]
	s_setprio 0
	s_barrier
	s_mov_b32 m0, s21
	v_add_u32_e32 v0, 0x14000, v148
	v_lshl_add_u64 v[178:179], s[26:27], 0, v[134:135]
	s_waitcnt vmcnt(0)
	ds_read_b128 v[198:201], v0
	ds_read_b128 v[202:205], v0 offset:1024
	ds_read_b128 v[206:209], v0 offset:2048
	ds_read_b128 v[210:213], v0 offset:3072
	global_load_lds_dwordx4 v[178:179], off
	v_lshl_add_u64 v[214:215], s[26:27], 0, v[130:131]
	s_mov_b32 m0, s23
	s_nop 0
	global_load_lds_dwordx4 v[214:215], off
	s_barrier
	s_waitcnt lgkmcnt(0)
	s_setprio 1
	s_waitcnt lgkmcnt(0)
	v_mfma_f32_16x16x32_bf16 v[118:121], v[198:201], v[162:165], v[118:121]
	v_mfma_f32_16x16x32_bf16 v[114:117], v[206:209], v[162:165], v[114:117]
	v_mfma_f32_16x16x32_bf16 v[102:105], v[198:201], v[170:173], v[102:105]
	v_mfma_f32_16x16x32_bf16 v[98:101], v[206:209], v[170:173], v[98:101]
	v_mfma_f32_16x16x32_bf16 v[86:89], v[198:201], v[182:185], v[86:89]
	v_mfma_f32_16x16x32_bf16 v[82:85], v[206:209], v[182:185], v[82:85]
	v_mfma_f32_16x16x32_bf16 v[70:73], v[198:201], v[190:193], v[70:73]
	v_mfma_f32_16x16x32_bf16 v[66:69], v[206:209], v[190:193], v[66:69]
	v_mfma_f32_16x16x32_bf16 v[118:121], v[202:205], v[166:169], v[118:121]
	v_mfma_f32_16x16x32_bf16 v[114:117], v[210:213], v[166:169], v[114:117]
	v_mfma_f32_16x16x32_bf16 v[102:105], v[202:205], v[174:177], v[102:105]
	v_mfma_f32_16x16x32_bf16 v[98:101], v[210:213], v[174:177], v[98:101]
	v_mfma_f32_16x16x32_bf16 v[86:89], v[202:205], v[186:189], v[86:89]
	v_mfma_f32_16x16x32_bf16 v[82:85], v[210:213], v[186:189], v[82:85]
	v_mfma_f32_16x16x32_bf16 v[70:73], v[202:205], v[194:197], v[70:73]
	v_mfma_f32_16x16x32_bf16 v[66:69], v[210:213], v[194:197], v[66:69]
	s_setprio 0
	s_mov_b32 m0, s36
	v_lshl_add_u64 v[216:217], s[28:29], 0, v[136:137]
	s_barrier
	s_waitcnt vmcnt(0)
	ds_read_b128 v[162:165], v147 offset:16384
	ds_read_b128 v[166:169], v147 offset:17408
	ds_read_b128 v[170:173], v147 offset:18432
	ds_read_b128 v[174:177], v147 offset:19456
	ds_read_b128 v[182:185], v147 offset:20480
	ds_read_b128 v[186:189], v147 offset:21504
	ds_read_b128 v[190:193], v147 offset:22528
	ds_read_b128 v[194:197], v147 offset:23552
	global_load_lds_dwordx4 v[216:217], off
	v_lshl_add_u64 v[222:223], s[28:29], 0, v[132:133]
	s_mov_b32 m0, s37
	s_nop 0
	global_load_lds_dwordx4 v[222:223], off
	s_barrier
	s_waitcnt lgkmcnt(0)
	s_setprio 1
	s_waitcnt lgkmcnt(0)
	v_mfma_f32_16x16x32_bf16 v[62:65], v[142:145], v[162:165], v[62:65]
	v_mfma_f32_16x16x32_bf16 v[58:61], v[154:157], v[162:165], v[58:61]
	v_mfma_f32_16x16x32_bf16 v[46:49], v[142:145], v[170:173], v[46:49]
	v_mfma_f32_16x16x32_bf16 v[42:45], v[154:157], v[170:173], v[42:45]
	v_mfma_f32_16x16x32_bf16 v[30:33], v[142:145], v[182:185], v[30:33]
	v_mfma_f32_16x16x32_bf16 v[26:29], v[154:157], v[182:185], v[26:29]
	v_mfma_f32_16x16x32_bf16 v[14:17], v[142:145], v[190:193], v[14:17]
	v_mfma_f32_16x16x32_bf16 v[10:13], v[154:157], v[190:193], v[10:13]
	v_mfma_f32_16x16x32_bf16 v[62:65], v[150:153], v[166:169], v[62:65]
	v_mfma_f32_16x16x32_bf16 v[58:61], v[158:161], v[166:169], v[58:61]
	v_mfma_f32_16x16x32_bf16 v[46:49], v[150:153], v[174:177], v[46:49]
	v_mfma_f32_16x16x32_bf16 v[42:45], v[158:161], v[174:177], v[42:45]
	v_mfma_f32_16x16x32_bf16 v[30:33], v[150:153], v[186:189], v[30:33]
	v_mfma_f32_16x16x32_bf16 v[26:29], v[158:161], v[186:189], v[26:29]
	v_mfma_f32_16x16x32_bf16 v[14:17], v[150:153], v[194:197], v[14:17]
	v_mfma_f32_16x16x32_bf16 v[10:13], v[158:161], v[194:197], v[10:13]
	s_setprio 0
	s_barrier
	s_add_u32 s76, s26, 0x40000
	s_addc_u32 s77, s27, 0
	s_mov_b32 m0, s38
	v_lshl_add_u64 v[142:143], s[76:77], 0, v[134:135]
	global_load_lds_dwordx4 v[142:143], off
	v_lshl_add_u64 v[142:143], s[76:77], 0, v[130:131]
	s_mov_b32 m0, s39
	s_nop 0
	global_load_lds_dwordx4 v[142:143], off
	s_waitcnt vmcnt(6)
	s_barrier
	s_setprio 1
	v_mfma_f32_16x16x32_bf16 v[54:57], v[198:201], v[162:165], v[54:57]
	v_mfma_f32_16x16x32_bf16 v[50:53], v[206:209], v[162:165], v[50:53]
	v_mfma_f32_16x16x32_bf16 v[38:41], v[198:201], v[170:173], v[38:41]
	v_mfma_f32_16x16x32_bf16 v[34:37], v[206:209], v[170:173], v[34:37]
	v_mfma_f32_16x16x32_bf16 v[22:25], v[198:201], v[182:185], v[22:25]
	v_mfma_f32_16x16x32_bf16 v[18:21], v[206:209], v[182:185], v[18:21]
	v_mfma_f32_16x16x32_bf16 v[6:9], v[198:201], v[190:193], v[6:9]
	v_mfma_f32_16x16x32_bf16 v[2:5], v[206:209], v[190:193], v[2:5]
	v_mfma_f32_16x16x32_bf16 v[54:57], v[202:205], v[166:169], v[54:57]
	v_mfma_f32_16x16x32_bf16 v[50:53], v[210:213], v[166:169], v[50:53]
	v_mfma_f32_16x16x32_bf16 v[38:41], v[202:205], v[174:177], v[38:41]
	v_mfma_f32_16x16x32_bf16 v[34:37], v[210:213], v[174:177], v[34:37]
	v_mfma_f32_16x16x32_bf16 v[22:25], v[202:205], v[186:189], v[22:25]
	v_mfma_f32_16x16x32_bf16 v[18:21], v[210:213], v[186:189], v[18:21]
	v_mfma_f32_16x16x32_bf16 v[6:9], v[202:205], v[194:197], v[6:9]
	v_mfma_f32_16x16x32_bf16 v[2:5], v[210:213], v[194:197], v[2:5]
	s_setprio 0
	v_add_u32_e32 v0, 0x18000, v148
	s_barrier
	s_waitcnt vmcnt(0)
	ds_read_b128 v[142:145], v0
	ds_read_b128 v[150:153], v0 offset:1024
	ds_read_b128 v[154:157], v0 offset:2048
	ds_read_b128 v[158:161], v0 offset:3072
	s_add_u32 s28, s28, 0x40000
	s_addc_u32 s29, s29, 0
	s_mov_b32 m0, s60
	v_lshl_add_u64 v[198:199], s[28:29], 0, v[136:137]
	ds_read_b128 v[162:165], v147 offset:32768
	ds_read_b128 v[166:169], v147 offset:33792
	ds_read_b128 v[170:173], v147 offset:34816
	ds_read_b128 v[174:177], v147 offset:35840
	ds_read_b128 v[182:185], v147 offset:36864
	ds_read_b128 v[186:189], v147 offset:37888
	ds_read_b128 v[190:193], v147 offset:38912
	ds_read_b128 v[194:197], v147 offset:39936
	global_load_lds_dwordx4 v[198:199], off
	v_lshl_add_u64 v[198:199], s[28:29], 0, v[132:133]
	s_mov_b32 m0, s68
	s_nop 0
	global_load_lds_dwordx4 v[198:199], off
	s_waitcnt lgkmcnt(8)
	s_barrier
	s_waitcnt lgkmcnt(0)
	s_setprio 1
	s_waitcnt lgkmcnt(0)
	v_mfma_f32_16x16x32_bf16 v[126:129], v[142:145], v[162:165], v[126:129]
	v_mfma_f32_16x16x32_bf16 v[122:125], v[154:157], v[162:165], v[122:125]
	v_mfma_f32_16x16x32_bf16 v[110:113], v[142:145], v[170:173], v[110:113]
	v_mfma_f32_16x16x32_bf16 v[106:109], v[154:157], v[170:173], v[106:109]
	v_mfma_f32_16x16x32_bf16 v[94:97], v[142:145], v[182:185], v[94:97]
	v_mfma_f32_16x16x32_bf16 v[90:93], v[154:157], v[182:185], v[90:93]
	v_mfma_f32_16x16x32_bf16 v[78:81], v[142:145], v[190:193], v[78:81]
	v_mfma_f32_16x16x32_bf16 v[74:77], v[154:157], v[190:193], v[74:77]
	v_mfma_f32_16x16x32_bf16 v[126:129], v[150:153], v[166:169], v[126:129]
	v_mfma_f32_16x16x32_bf16 v[122:125], v[158:161], v[166:169], v[122:125]
	v_mfma_f32_16x16x32_bf16 v[110:113], v[150:153], v[174:177], v[110:113]
	v_mfma_f32_16x16x32_bf16 v[106:109], v[158:161], v[174:177], v[106:109]
	v_mfma_f32_16x16x32_bf16 v[94:97], v[150:153], v[186:189], v[94:97]
	v_mfma_f32_16x16x32_bf16 v[90:93], v[158:161], v[186:189], v[90:93]
	v_mfma_f32_16x16x32_bf16 v[78:81], v[150:153], v[194:197], v[78:81]
	v_mfma_f32_16x16x32_bf16 v[74:77], v[158:161], v[194:197], v[74:77]
	s_setprio 0
	s_barrier
	s_mov_b32 m0, s69
	v_add_u32_e32 v0, 0x1c000, v148
	v_lshl_add_u64 v[178:179], v[178:179], 0, s[84:85]
	s_waitcnt vmcnt(0)
	ds_read_b128 v[198:201], v0
	ds_read_b128 v[202:205], v0 offset:1024
	ds_read_b128 v[206:209], v0 offset:2048
	ds_read_b128 v[210:213], v0 offset:3072
	global_load_lds_dwordx4 v[178:179], off
	v_lshl_add_u64 v[178:179], v[214:215], 0, s[84:85]
	s_mov_b32 m0, s75
	s_nop 0
	global_load_lds_dwordx4 v[178:179], off
	s_barrier
	s_waitcnt lgkmcnt(0)
	s_setprio 1
	s_waitcnt lgkmcnt(0)
	v_mfma_f32_16x16x32_bf16 v[118:121], v[198:201], v[162:165], v[118:121]
	v_mfma_f32_16x16x32_bf16 v[114:117], v[206:209], v[162:165], v[114:117]
	v_mfma_f32_16x16x32_bf16 v[102:105], v[198:201], v[170:173], v[102:105]
	v_mfma_f32_16x16x32_bf16 v[98:101], v[206:209], v[170:173], v[98:101]
	v_mfma_f32_16x16x32_bf16 v[86:89], v[198:201], v[182:185], v[86:89]
	v_mfma_f32_16x16x32_bf16 v[82:85], v[206:209], v[182:185], v[82:85]
	v_mfma_f32_16x16x32_bf16 v[70:73], v[198:201], v[190:193], v[70:73]
	v_mfma_f32_16x16x32_bf16 v[66:69], v[206:209], v[190:193], v[66:69]
	v_mfma_f32_16x16x32_bf16 v[118:121], v[202:205], v[166:169], v[118:121]
	v_mfma_f32_16x16x32_bf16 v[114:117], v[210:213], v[166:169], v[114:117]
	v_mfma_f32_16x16x32_bf16 v[102:105], v[202:205], v[174:177], v[102:105]
	v_mfma_f32_16x16x32_bf16 v[98:101], v[210:213], v[174:177], v[98:101]
	v_mfma_f32_16x16x32_bf16 v[86:89], v[202:205], v[186:189], v[86:89]
	v_mfma_f32_16x16x32_bf16 v[82:85], v[210:213], v[186:189], v[82:85]
	v_mfma_f32_16x16x32_bf16 v[70:73], v[202:205], v[194:197], v[70:73]
	v_mfma_f32_16x16x32_bf16 v[66:69], v[210:213], v[194:197], v[66:69]
	s_setprio 0
	s_mov_b32 m0, s82
	v_lshl_add_u64 v[178:179], v[216:217], 0, s[84:85]
	s_barrier
	s_waitcnt vmcnt(0)
	ds_read_b128 v[162:165], v147 offset:49152
	ds_read_b128 v[166:169], v147 offset:50176
	ds_read_b128 v[170:173], v147 offset:51200
	ds_read_b128 v[174:177], v147 offset:52224
	ds_read_b128 v[182:185], v147 offset:53248
	ds_read_b128 v[186:189], v147 offset:54272
	ds_read_b128 v[190:193], v147 offset:55296
	ds_read_b128 v[194:197], v147 offset:56320
	global_load_lds_dwordx4 v[178:179], off
	v_lshl_add_u64 v[178:179], v[222:223], 0, s[84:85]
	s_mov_b32 m0, s92
	s_nop 0
	global_load_lds_dwordx4 v[178:179], off
	s_barrier
	s_waitcnt lgkmcnt(0)
	s_setprio 1
	s_waitcnt lgkmcnt(0)
	v_mfma_f32_16x16x32_bf16 v[62:65], v[142:145], v[162:165], v[62:65]
	v_mfma_f32_16x16x32_bf16 v[58:61], v[154:157], v[162:165], v[58:61]
	v_mfma_f32_16x16x32_bf16 v[46:49], v[142:145], v[170:173], v[46:49]
	v_mfma_f32_16x16x32_bf16 v[42:45], v[154:157], v[170:173], v[42:45]
	v_mfma_f32_16x16x32_bf16 v[30:33], v[142:145], v[182:185], v[30:33]
	v_mfma_f32_16x16x32_bf16 v[26:29], v[154:157], v[182:185], v[26:29]
	v_mfma_f32_16x16x32_bf16 v[14:17], v[142:145], v[190:193], v[14:17]
	v_mfma_f32_16x16x32_bf16 v[10:13], v[154:157], v[190:193], v[10:13]
	v_mfma_f32_16x16x32_bf16 v[62:65], v[150:153], v[166:169], v[62:65]
	v_mfma_f32_16x16x32_bf16 v[58:61], v[158:161], v[166:169], v[58:61]
	v_mfma_f32_16x16x32_bf16 v[46:49], v[150:153], v[174:177], v[46:49]
	v_mfma_f32_16x16x32_bf16 v[42:45], v[158:161], v[174:177], v[42:45]
	v_mfma_f32_16x16x32_bf16 v[30:33], v[150:153], v[186:189], v[30:33]
	v_mfma_f32_16x16x32_bf16 v[26:29], v[158:161], v[186:189], v[26:29]
	v_mfma_f32_16x16x32_bf16 v[14:17], v[150:153], v[194:197], v[14:17]
	v_mfma_f32_16x16x32_bf16 v[10:13], v[158:161], v[194:197], v[10:13]
	s_setprio 0
	s_barrier
	s_add_u32 s26, s26, 0x40080
	s_addc_u32 s27, s27, 0
	s_mov_b32 m0, s93
	v_lshl_add_u64 v[142:143], s[26:27], 0, v[134:135]
	global_load_lds_dwordx4 v[142:143], off
	v_lshl_add_u64 v[142:143], s[26:27], 0, v[130:131]
	s_mov_b32 m0, s96
	s_nop 0
	global_load_lds_dwordx4 v[142:143], off
	s_waitcnt vmcnt(6)
	s_barrier
	s_setprio 1
	v_mfma_f32_16x16x32_bf16 v[54:57], v[198:201], v[162:165], v[54:57]
	v_mfma_f32_16x16x32_bf16 v[50:53], v[206:209], v[162:165], v[50:53]
	v_mfma_f32_16x16x32_bf16 v[38:41], v[198:201], v[170:173], v[38:41]
	v_mfma_f32_16x16x32_bf16 v[34:37], v[206:209], v[170:173], v[34:37]
	v_mfma_f32_16x16x32_bf16 v[22:25], v[198:201], v[182:185], v[22:25]
	v_mfma_f32_16x16x32_bf16 v[18:21], v[206:209], v[182:185], v[18:21]
	v_mfma_f32_16x16x32_bf16 v[6:9], v[198:201], v[190:193], v[6:9]
	v_mfma_f32_16x16x32_bf16 v[2:5], v[206:209], v[190:193], v[2:5]
	v_mfma_f32_16x16x32_bf16 v[54:57], v[202:205], v[166:169], v[54:57]
	v_mfma_f32_16x16x32_bf16 v[50:53], v[210:213], v[166:169], v[50:53]
	v_mfma_f32_16x16x32_bf16 v[38:41], v[202:205], v[174:177], v[38:41]
	v_mfma_f32_16x16x32_bf16 v[34:37], v[210:213], v[174:177], v[34:37]
	v_mfma_f32_16x16x32_bf16 v[22:25], v[202:205], v[186:189], v[22:25]
	v_mfma_f32_16x16x32_bf16 v[18:21], v[210:213], v[186:189], v[18:21]
	v_mfma_f32_16x16x32_bf16 v[6:9], v[202:205], v[194:197], v[6:9]
	v_mfma_f32_16x16x32_bf16 v[2:5], v[210:213], v[194:197], v[2:5]
	s_setprio 0
	s_add_i32 vcc_lo, vcc_lo, 2
	s_add_u32 s24, s24, 0x100
	s_addc_u32 s25, s25, 0
	s_add_u32 s90, s90, 0x100
	s_addc_u32 s94, s94, 0
	s_cmp_gt_u32 vcc_lo, 13
	s_barrier
	s_cbranch_scc0 .LBB0_1334
	v_lshl_add_u32 v152, s22, 8, v146
	v_lshl_add_u32 v150, s20, 8, v149
	v_mul_lo_u32 v151, v152, s71
	v_add_u32_e32 v0, v151, v150
	v_lshl_add_u64 v[142:143], v[0:1], 1, s[8:9]
	global_load_dwordx4 v[142:145], v[142:143], off
	s_mov_b32 s20, s12
	s_mov_b32 s22, s14
	s_mov_b64 s[26:27], s[18:19]
	s_waitcnt vmcnt(0)
	v_lshlrev_b32_e32 v153, 16, v142
	v_lshlrev_b32_e32 v155, 16, v143
	v_lshlrev_b32_e32 v156, 16, v144
	v_and_b32_e32 v157, 0xffff0000, v144
	v_lshlrev_b32_e32 v158, 16, v145
	v_and_b32_e32 v159, 0xffff0000, v145
	v_mul_f32_e32 v144, 0xbfb8aa3b, v153
	v_mul_f32_e32 v145, 0xbfb8aa3b, v155
	v_exp_f32_e32 v154, v144
	v_exp_f32_e32 v155, v145
	v_mul_f32_e32 v145, 0xbfb8aa3b, v158
	v_and_b32_e32 v142, 0xffff0000, v142
	v_and_b32_e32 v143, 0xffff0000, v143
	v_pk_add_f32 v[154:155], v[154:155], 1.0 op_sel_hi:[1,0]
	v_mul_f32_e32 v142, 0xbfb8aa3b, v142
	v_mul_f32_e32 v143, 0xbfb8aa3b, v143
	v_mul_f32_e32 v144, 0xbfb8aa3b, v156
	v_exp_f32_e32 v156, v142
	v_mul_f32_e32 v142, 0xbfb8aa3b, v157
	v_exp_f32_e32 v157, v143
	v_mul_f32_e32 v143, 0xbfb8aa3b, v159
	v_rcp_f32_e32 v155, v155
	s_nop 0
	v_pk_add_f32 v[156:157], v[156:157], 1.0 op_sel_hi:[1,0]
	v_exp_f32_e32 v144, v144
	v_exp_f32_e32 v145, v145
	v_mov_b32_e32 v158, v126
	v_mov_b32_e32 v159, v128
	v_rcp_f32_e32 v154, v154
	s_nop 0
	v_pk_mul_f32 v[154:155], v[158:159], v[154:155]
	v_exp_f32_e32 v142, v142
	v_rcp_f32_e32 v157, v157
	s_nop 0
	v_exp_f32_e32 v143, v143
	v_rcp_f32_e32 v156, v156
	s_nop 0
	v_mov_b32_e32 v128, v127
	v_pk_mul_f32 v[126:127], v[128:129], v[156:157]
	v_cvt_pk_bf16_f32 v128, v154, v155
	v_cvt_pk_bf16_f32 v126, v126, v127
	v_and_b32_e32 v127, 0xffff0000, v126
	v_lshlrev_b32_e32 v126, 16, v126
	v_or_b32_sdwa v127, v127, v128 dst_sel:DWORD dst_unused:UNUSED_PAD src0_sel:DWORD src1_sel:WORD_1
	v_or_b32_sdwa v126, v126, v128 dst_sel:DWORD dst_unused:UNUSED_PAD src0_sel:DWORD src1_sel:WORD_0
	v_pk_add_f32 v[128:129], v[144:145], 1.0 op_sel_hi:[1,0]
	v_pk_add_f32 v[142:143], v[142:143], 1.0 op_sel_hi:[1,0]
	s_nop 0
	v_rcp_f32_e32 v129, v129
	s_nop 0
	s_nop 0
	v_rcp_f32_e32 v128, v128
	s_nop 0
	v_mov_b32_e32 v144, v122
	v_mov_b32_e32 v145, v124
	v_pk_mul_f32 v[128:129], v[144:145], v[128:129]
	v_rcp_f32_e32 v143, v143
	s_nop 0
	s_nop 0
	v_rcp_f32_e32 v142, v142
	s_nop 0
	v_mov_b32_e32 v124, v123
	v_pk_mul_f32 v[122:123], v[124:125], v[142:143]
	v_cvt_pk_bf16_f32 v124, v128, v129
	v_cvt_pk_bf16_f32 v122, v122, v123
	v_and_b32_e32 v123, 0xffff0000, v122
	v_lshlrev_b32_e32 v122, 16, v122
	v_or_b32_sdwa v129, v123, v124 dst_sel:DWORD dst_unused:UNUSED_PAD src0_sel:DWORD src1_sel:WORD_1
	v_or_b32_sdwa v128, v122, v124 dst_sel:DWORD dst_unused:UNUSED_PAD src0_sel:DWORD src1_sel:WORD_0
	v_mul_lo_u32 v124, v152, s61
	v_add_u32_e32 v0, v0, v124
	v_add_u32_e32 v125, 0x80, v150
	v_lshl_add_u64 v[122:123], v[0:1], 1, s[6:7]
	v_add_u32_e32 v0, v151, v125
	global_store_dwordx4 v[122:123], v[126:129], off
	v_lshl_add_u64 v[122:123], v[0:1], 1, s[8:9]
	global_load_dwordx4 v[126:129], v[122:123], off
	v_add_u32_e32 v0, v0, v124
	s_waitcnt vmcnt(0)
	v_lshlrev_b32_e32 v122, 16, v126
	v_lshlrev_b32_e32 v143, 16, v127
	v_and_b32_e32 v144, 0xffff0000, v127
	v_lshlrev_b32_e32 v127, 16, v128
	v_mul_f32_e32 v122, 0xbfb8aa3b, v122
	v_and_b32_e32 v123, 0xffff0000, v126
	v_exp_f32_e32 v126, v122
	v_mul_f32_e32 v122, 0xbfb8aa3b, v127
	v_and_b32_e32 v145, 0xffff0000, v128
	v_exp_f32_e32 v128, v122
	v_mul_f32_e32 v122, 0xbfb8aa3b, v123
	v_mul_f32_e32 v123, 0xbfb8aa3b, v143
	v_exp_f32_e32 v127, v123
	v_lshlrev_b32_e32 v153, 16, v129
	v_mul_f32_e32 v123, 0xbfb8aa3b, v153
	v_and_b32_e32 v154, 0xffff0000, v129
	v_pk_add_f32 v[126:127], v[126:127], 1.0 op_sel_hi:[1,0]
	v_exp_f32_e32 v129, v123
	v_mul_f32_e32 v123, 0xbfb8aa3b, v144
	v_exp_f32_e32 v142, v122
	v_mul_f32_e32 v122, 0xbfb8aa3b, v145
	v_exp_f32_e32 v143, v123
	v_mul_f32_e32 v123, 0xbfb8aa3b, v154
	v_exp_f32_e32 v122, v122
	v_rcp_f32_e32 v127, v127
	s_nop 0
	v_pk_add_f32 v[142:143], v[142:143], 1.0 op_sel_hi:[1,0]
	v_exp_f32_e32 v123, v123
	v_rcp_f32_e32 v126, v126
	s_nop 0
	v_mov_b32_e32 v144, v118
	v_mov_b32_e32 v145, v120
	v_pk_mul_f32 v[126:127], v[144:145], v[126:127]
	v_pk_add_f32 v[122:123], v[122:123], 1.0 op_sel_hi:[1,0]
	v_rcp_f32_e32 v143, v143
	s_nop 0
	s_nop 0
	v_rcp_f32_e32 v142, v142
	s_nop 0
	v_mov_b32_e32 v120, v119
	v_pk_mul_f32 v[118:119], v[120:121], v[142:143]
	v_cvt_pk_bf16_f32 v120, v126, v127
	v_cvt_pk_bf16_f32 v118, v118, v119
	v_and_b32_e32 v119, 0xffff0000, v118
	v_lshlrev_b32_e32 v118, 16, v118
	v_or_b32_sdwa v119, v119, v120 dst_sel:DWORD dst_unused:UNUSED_PAD src0_sel:DWORD src1_sel:WORD_1
	v_or_b32_sdwa v118, v118, v120 dst_sel:DWORD dst_unused:UNUSED_PAD src0_sel:DWORD src1_sel:WORD_0
	v_pk_add_f32 v[120:121], v[128:129], 1.0 op_sel_hi:[1,0]
	s_nop 0
	s_nop 0
	v_rcp_f32_e32 v121, v121
	s_nop 0
	s_nop 0
	v_rcp_f32_e32 v120, v120
	s_nop 0
	v_mov_b32_e32 v126, v114
	v_mov_b32_e32 v127, v116
	v_pk_mul_f32 v[120:121], v[126:127], v[120:121]
	v_rcp_f32_e32 v123, v123
	s_nop 0
	s_nop 0
	v_rcp_f32_e32 v122, v122
	s_nop 0
	v_mov_b32_e32 v116, v115
	v_pk_mul_f32 v[114:115], v[116:117], v[122:123]
	v_cvt_pk_bf16_f32 v116, v120, v121
	v_cvt_pk_bf16_f32 v114, v114, v115
	v_and_b32_e32 v115, 0xffff0000, v114
	v_lshlrev_b32_e32 v114, 16, v114
	v_add_u32_e32 v127, 0x16c00, v151
	v_or_b32_sdwa v121, v115, v116 dst_sel:DWORD dst_unused:UNUSED_PAD src0_sel:DWORD src1_sel:WORD_1
	v_or_b32_sdwa v120, v114, v116 dst_sel:DWORD dst_unused:UNUSED_PAD src0_sel:DWORD src1_sel:WORD_0
	v_lshl_add_u64 v[114:115], v[0:1], 1, s[6:7]
	v_add_u32_e32 v0, v127, v150
	global_store_dwordx4 v[114:115], v[118:121], off
	v_lshl_add_u64 v[114:115], v[0:1], 1, s[8:9]
	global_load_dwordx4 v[114:117], v[114:115], off
	v_or_b32_e32 v126, 16, v152
	s_waitcnt vmcnt(0)
	v_lshlrev_b32_e32 v121, 16, v115
	v_and_b32_e32 v122, 0xffff0000, v115
	v_lshlrev_b32_e32 v115, 16, v116
	v_and_b32_e32 v119, 0xffff0000, v114
	v_mul_f32_e32 v115, 0xbfb8aa3b, v115
	v_lshlrev_b32_e32 v118, 16, v114
	v_and_b32_e32 v120, 0xffff0000, v116
	v_exp_f32_e32 v116, v115
	v_mul_f32_e32 v115, 0xbfb8aa3b, v119
	v_mul_f32_e32 v114, 0xbfb8aa3b, v118
	v_exp_f32_e32 v118, v115
	v_mul_f32_e32 v115, 0xbfb8aa3b, v120
	v_exp_f32_e32 v120, v115
	v_mul_f32_e32 v115, 0xbfb8aa3b, v121
	v_exp_f32_e32 v114, v114
	v_exp_f32_e32 v115, v115
	v_lshlrev_b32_e32 v123, 16, v117
	v_mul_f32_e32 v119, 0xbfb8aa3b, v122
	v_and_b32_e32 v128, 0xffff0000, v117
	v_pk_add_f32 v[114:115], v[114:115], 1.0 op_sel_hi:[1,0]
	v_mul_f32_e32 v117, 0xbfb8aa3b, v123
	v_mul_f32_e32 v121, 0xbfb8aa3b, v128
	v_exp_f32_e32 v119, v119
	v_exp_f32_e32 v117, v117
	v_rcp_f32_e32 v115, v115
	s_nop 0
	v_pk_add_f32 v[118:119], v[118:119], 1.0 op_sel_hi:[1,0]
	v_exp_f32_e32 v121, v121
	v_rcp_f32_e32 v114, v114
	s_nop 0
	v_mov_b32_e32 v122, v110
	v_mov_b32_e32 v123, v112
	v_pk_mul_f32 v[114:115], v[122:123], v[114:115]
	v_rcp_f32_e32 v119, v119
	s_nop 0
	s_nop 0
	v_rcp_f32_e32 v118, v118
	s_nop 0
	v_mov_b32_e32 v112, v111
	v_pk_mul_f32 v[110:111], v[112:113], v[118:119]
	v_cvt_pk_bf16_f32 v112, v114, v115
	v_cvt_pk_bf16_f32 v110, v110, v111
	v_and_b32_e32 v111, 0xffff0000, v110
	v_lshlrev_b32_e32 v110, 16, v110
	v_or_b32_sdwa v111, v111, v112 dst_sel:DWORD dst_unused:UNUSED_PAD src0_sel:DWORD src1_sel:WORD_1
	v_or_b32_sdwa v110, v110, v112 dst_sel:DWORD dst_unused:UNUSED_PAD src0_sel:DWORD src1_sel:WORD_0
	v_pk_add_f32 v[112:113], v[116:117], 1.0 op_sel_hi:[1,0]
	s_nop 0
	s_nop 0
	v_rcp_f32_e32 v113, v113
	s_nop 0
	s_nop 0
	v_rcp_f32_e32 v112, v112
	s_nop 0
	v_mov_b32_e32 v114, v106
	v_mov_b32_e32 v115, v108
	v_pk_mul_f32 v[112:113], v[114:115], v[112:113]
	v_pk_add_f32 v[114:115], v[120:121], 1.0 op_sel_hi:[1,0]
	s_nop 0
	s_nop 0
	v_rcp_f32_e32 v115, v115
	s_nop 0
	s_nop 0
	v_rcp_f32_e32 v114, v114
	s_nop 0
	v_mov_b32_e32 v108, v107
	v_pk_mul_f32 v[106:107], v[108:109], v[114:115]
	v_mul_lo_u32 v116, v126, s61
	v_cvt_pk_bf16_f32 v106, v106, v107
	v_cvt_pk_bf16_f32 v108, v112, v113
	v_and_b32_e32 v107, 0xffff0000, v106
	v_lshlrev_b32_e32 v106, 16, v106
	v_add_u32_e32 v0, v0, v116
	v_or_b32_sdwa v113, v107, v108 dst_sel:DWORD dst_unused:UNUSED_PAD src0_sel:DWORD src1_sel:WORD_1
	v_or_b32_sdwa v112, v106, v108 dst_sel:DWORD dst_unused:UNUSED_PAD src0_sel:DWORD src1_sel:WORD_0
	v_lshl_add_u64 v[106:107], v[0:1], 1, s[6:7]
	v_add_u32_e32 v0, v127, v125
	global_store_dwordx4 v[106:107], v[110:113], off
	v_lshl_add_u64 v[106:107], v[0:1], 1, s[8:9]
	global_load_dwordx4 v[106:109], v[106:107], off
	v_add_u32_e32 v0, v0, v116
	s_waitcnt vmcnt(0)
	v_lshlrev_b32_e32 v113, 16, v107
	v_and_b32_e32 v114, 0xffff0000, v107
	v_lshlrev_b32_e32 v107, 16, v108
	v_and_b32_e32 v111, 0xffff0000, v106
	v_mul_f32_e32 v107, 0xbfb8aa3b, v107
	v_lshlrev_b32_e32 v110, 16, v106
	v_and_b32_e32 v112, 0xffff0000, v108
	v_exp_f32_e32 v108, v107
	v_mul_f32_e32 v107, 0xbfb8aa3b, v111
	v_mul_f32_e32 v106, 0xbfb8aa3b, v110
	v_exp_f32_e32 v110, v107
	v_mul_f32_e32 v107, 0xbfb8aa3b, v112
	v_exp_f32_e32 v112, v107
	v_mul_f32_e32 v107, 0xbfb8aa3b, v113
	v_exp_f32_e32 v106, v106
	v_exp_f32_e32 v107, v107
	v_lshlrev_b32_e32 v115, 16, v109
	v_mul_f32_e32 v111, 0xbfb8aa3b, v114
	v_and_b32_e32 v117, 0xffff0000, v109
	v_pk_add_f32 v[106:107], v[106:107], 1.0 op_sel_hi:[1,0]
	v_mul_f32_e32 v109, 0xbfb8aa3b, v115
	v_mul_f32_e32 v113, 0xbfb8aa3b, v117
	v_exp_f32_e32 v111, v111
	v_exp_f32_e32 v109, v109
	v_rcp_f32_e32 v107, v107
	s_nop 0
	v_pk_add_f32 v[110:111], v[110:111], 1.0 op_sel_hi:[1,0]
	v_exp_f32_e32 v113, v113
	v_rcp_f32_e32 v106, v106
	s_nop 0
	v_mov_b32_e32 v114, v102
	v_mov_b32_e32 v115, v104
	v_pk_mul_f32 v[106:107], v[114:115], v[106:107]
	v_rcp_f32_e32 v111, v111
	s_nop 0
	s_nop 0
	v_rcp_f32_e32 v110, v110
	s_nop 0
	v_mov_b32_e32 v104, v103
	v_pk_mul_f32 v[102:103], v[104:105], v[110:111]
	v_cvt_pk_bf16_f32 v104, v106, v107
	v_cvt_pk_bf16_f32 v102, v102, v103
	v_and_b32_e32 v103, 0xffff0000, v102
	v_lshlrev_b32_e32 v102, 16, v102
	v_or_b32_sdwa v103, v103, v104 dst_sel:DWORD dst_unused:UNUSED_PAD src0_sel:DWORD src1_sel:WORD_1
	v_or_b32_sdwa v102, v102, v104 dst_sel:DWORD dst_unused:UNUSED_PAD src0_sel:DWORD src1_sel:WORD_0
	v_pk_add_f32 v[104:105], v[108:109], 1.0 op_sel_hi:[1,0]
	s_nop 0
	s_nop 0
	v_rcp_f32_e32 v105, v105
	s_nop 0
	s_nop 0
	v_rcp_f32_e32 v104, v104
	s_nop 0
	v_mov_b32_e32 v106, v98
	v_mov_b32_e32 v107, v100
	v_pk_mul_f32 v[104:105], v[106:107], v[104:105]
	v_pk_add_f32 v[106:107], v[112:113], 1.0 op_sel_hi:[1,0]
	s_nop 0
	s_nop 0
	v_rcp_f32_e32 v107, v107
	s_nop 0
	s_nop 0
	v_rcp_f32_e32 v106, v106
	s_nop 0
	v_mov_b32_e32 v100, v99
	v_pk_mul_f32 v[98:99], v[100:101], v[106:107]
	v_cvt_pk_bf16_f32 v100, v104, v105
	v_cvt_pk_bf16_f32 v98, v98, v99
	v_and_b32_e32 v99, 0xffff0000, v98
	v_lshlrev_b32_e32 v98, 16, v98
	v_add_u32_e32 v109, 0x2d800, v151
	v_or_b32_sdwa v105, v99, v100 dst_sel:DWORD dst_unused:UNUSED_PAD src0_sel:DWORD src1_sel:WORD_1
	v_or_b32_sdwa v104, v98, v100 dst_sel:DWORD dst_unused:UNUSED_PAD src0_sel:DWORD src1_sel:WORD_0
	v_lshl_add_u64 v[98:99], v[0:1], 1, s[6:7]
	v_add_u32_e32 v0, v109, v150
	global_store_dwordx4 v[98:99], v[102:105], off
	v_lshl_add_u64 v[98:99], v[0:1], 1, s[8:9]
	global_load_dwordx4 v[98:101], v[98:99], off
	v_or_b32_e32 v108, 32, v152
	s_waitcnt vmcnt(0)
	v_lshlrev_b32_e32 v105, 16, v99
	v_and_b32_e32 v106, 0xffff0000, v99
	v_lshlrev_b32_e32 v99, 16, v100
	v_and_b32_e32 v103, 0xffff0000, v98
	v_mul_f32_e32 v99, 0xbfb8aa3b, v99
	v_lshlrev_b32_e32 v102, 16, v98
	v_and_b32_e32 v104, 0xffff0000, v100
	v_exp_f32_e32 v100, v99
	v_mul_f32_e32 v99, 0xbfb8aa3b, v103
	v_mul_f32_e32 v98, 0xbfb8aa3b, v102
	v_exp_f32_e32 v102, v99
	v_mul_f32_e32 v99, 0xbfb8aa3b, v104
	v_exp_f32_e32 v104, v99
	v_mul_f32_e32 v99, 0xbfb8aa3b, v105
	v_exp_f32_e32 v98, v98
	v_exp_f32_e32 v99, v99
	v_lshlrev_b32_e32 v107, 16, v101
	v_mul_f32_e32 v103, 0xbfb8aa3b, v106
	v_and_b32_e32 v110, 0xffff0000, v101
	v_pk_add_f32 v[98:99], v[98:99], 1.0 op_sel_hi:[1,0]
	v_mul_f32_e32 v101, 0xbfb8aa3b, v107
	v_mul_f32_e32 v105, 0xbfb8aa3b, v110
	v_exp_f32_e32 v103, v103
	v_exp_f32_e32 v101, v101
	v_rcp_f32_e32 v99, v99
	s_nop 0
	v_pk_add_f32 v[102:103], v[102:103], 1.0 op_sel_hi:[1,0]
	v_exp_f32_e32 v105, v105
	v_rcp_f32_e32 v98, v98
	s_nop 0
	v_mov_b32_e32 v106, v94
	v_mov_b32_e32 v107, v96
	v_pk_mul_f32 v[98:99], v[106:107], v[98:99]
	v_rcp_f32_e32 v103, v103
	s_nop 0
	s_nop 0
	v_rcp_f32_e32 v102, v102
	s_nop 0
	v_mov_b32_e32 v96, v95
	v_pk_mul_f32 v[94:95], v[96:97], v[102:103]
	v_cvt_pk_bf16_f32 v96, v98, v99
	v_cvt_pk_bf16_f32 v94, v94, v95
	v_and_b32_e32 v95, 0xffff0000, v94
	v_lshlrev_b32_e32 v94, 16, v94
	v_or_b32_sdwa v95, v95, v96 dst_sel:DWORD dst_unused:UNUSED_PAD src0_sel:DWORD src1_sel:WORD_1
	v_or_b32_sdwa v94, v94, v96 dst_sel:DWORD dst_unused:UNUSED_PAD src0_sel:DWORD src1_sel:WORD_0
	v_pk_add_f32 v[96:97], v[100:101], 1.0 op_sel_hi:[1,0]
	s_nop 0
	s_nop 0
	v_rcp_f32_e32 v97, v97
	s_nop 0
	s_nop 0
	v_rcp_f32_e32 v96, v96
	s_nop 0
	v_mov_b32_e32 v98, v90
	v_mov_b32_e32 v99, v92
	v_pk_mul_f32 v[96:97], v[98:99], v[96:97]
	v_pk_add_f32 v[98:99], v[104:105], 1.0 op_sel_hi:[1,0]
	s_nop 0
	s_nop 0
	v_rcp_f32_e32 v99, v99
	s_nop 0
	s_nop 0
	v_rcp_f32_e32 v98, v98
	s_nop 0
	v_mov_b32_e32 v92, v91
	v_pk_mul_f32 v[90:91], v[92:93], v[98:99]
	v_mul_lo_u32 v100, v108, s61
	v_cvt_pk_bf16_f32 v90, v90, v91
	v_cvt_pk_bf16_f32 v92, v96, v97
	v_and_b32_e32 v91, 0xffff0000, v90
	v_lshlrev_b32_e32 v90, 16, v90
	v_add_u32_e32 v0, v0, v100
	v_or_b32_sdwa v97, v91, v92 dst_sel:DWORD dst_unused:UNUSED_PAD src0_sel:DWORD src1_sel:WORD_1
	v_or_b32_sdwa v96, v90, v92 dst_sel:DWORD dst_unused:UNUSED_PAD src0_sel:DWORD src1_sel:WORD_0
	v_lshl_add_u64 v[90:91], v[0:1], 1, s[6:7]
	v_add_u32_e32 v0, v109, v125
	global_store_dwordx4 v[90:91], v[94:97], off
	v_lshl_add_u64 v[90:91], v[0:1], 1, s[8:9]
	global_load_dwordx4 v[90:93], v[90:91], off
	v_add_u32_e32 v0, v0, v100
	s_waitcnt vmcnt(0)
	v_lshlrev_b32_e32 v97, 16, v91
	v_and_b32_e32 v98, 0xffff0000, v91
	v_lshlrev_b32_e32 v91, 16, v92
	v_and_b32_e32 v95, 0xffff0000, v90
	v_mul_f32_e32 v91, 0xbfb8aa3b, v91
	v_lshlrev_b32_e32 v94, 16, v90
	v_and_b32_e32 v96, 0xffff0000, v92
	v_exp_f32_e32 v92, v91
	v_mul_f32_e32 v91, 0xbfb8aa3b, v95
	v_mul_f32_e32 v90, 0xbfb8aa3b, v94
	v_exp_f32_e32 v94, v91
	v_mul_f32_e32 v91, 0xbfb8aa3b, v96
	v_exp_f32_e32 v96, v91
	v_mul_f32_e32 v91, 0xbfb8aa3b, v97
	v_exp_f32_e32 v90, v90
	v_exp_f32_e32 v91, v91
	v_lshlrev_b32_e32 v99, 16, v93
	v_mul_f32_e32 v95, 0xbfb8aa3b, v98
	v_and_b32_e32 v101, 0xffff0000, v93
	v_pk_add_f32 v[90:91], v[90:91], 1.0 op_sel_hi:[1,0]
	v_mul_f32_e32 v93, 0xbfb8aa3b, v99
	v_mul_f32_e32 v97, 0xbfb8aa3b, v101
	v_exp_f32_e32 v95, v95
	v_exp_f32_e32 v93, v93
	v_rcp_f32_e32 v91, v91
	s_nop 0
	v_pk_add_f32 v[94:95], v[94:95], 1.0 op_sel_hi:[1,0]
	v_exp_f32_e32 v97, v97
	v_rcp_f32_e32 v90, v90
	s_nop 0
	v_mov_b32_e32 v98, v86
	v_mov_b32_e32 v99, v88
	v_pk_mul_f32 v[90:91], v[98:99], v[90:91]
	v_rcp_f32_e32 v95, v95
	s_nop 0
	s_nop 0
	v_rcp_f32_e32 v94, v94
	s_nop 0
	v_mov_b32_e32 v88, v87
	v_pk_mul_f32 v[86:87], v[88:89], v[94:95]
	v_cvt_pk_bf16_f32 v88, v90, v91
	v_cvt_pk_bf16_f32 v86, v86, v87
	v_and_b32_e32 v87, 0xffff0000, v86
	v_lshlrev_b32_e32 v86, 16, v86
	v_or_b32_sdwa v87, v87, v88 dst_sel:DWORD dst_unused:UNUSED_PAD src0_sel:DWORD src1_sel:WORD_1
	v_or_b32_sdwa v86, v86, v88 dst_sel:DWORD dst_unused:UNUSED_PAD src0_sel:DWORD src1_sel:WORD_0
	v_pk_add_f32 v[88:89], v[92:93], 1.0 op_sel_hi:[1,0]
	s_nop 0
	s_nop 0
	v_rcp_f32_e32 v89, v89
	s_nop 0
	s_nop 0
	v_rcp_f32_e32 v88, v88
	s_nop 0
	v_mov_b32_e32 v90, v82
	v_mov_b32_e32 v91, v84
	v_pk_mul_f32 v[88:89], v[90:91], v[88:89]
	v_pk_add_f32 v[90:91], v[96:97], 1.0 op_sel_hi:[1,0]
	s_nop 0
	s_nop 0
	v_rcp_f32_e32 v91, v91
	s_nop 0
	s_nop 0
	v_rcp_f32_e32 v90, v90
	s_nop 0
	v_mov_b32_e32 v84, v83
	v_pk_mul_f32 v[82:83], v[84:85], v[90:91]
	v_cvt_pk_bf16_f32 v84, v88, v89
	v_cvt_pk_bf16_f32 v82, v82, v83
	v_and_b32_e32 v83, 0xffff0000, v82
	v_lshlrev_b32_e32 v82, 16, v82
	v_add_u32_e32 v93, 0x44400, v151
	v_or_b32_sdwa v89, v83, v84 dst_sel:DWORD dst_unused:UNUSED_PAD src0_sel:DWORD src1_sel:WORD_1
	v_or_b32_sdwa v88, v82, v84 dst_sel:DWORD dst_unused:UNUSED_PAD src0_sel:DWORD src1_sel:WORD_0
	v_lshl_add_u64 v[82:83], v[0:1], 1, s[6:7]
	v_add_u32_e32 v0, v93, v150
	global_store_dwordx4 v[82:83], v[86:89], off
	v_lshl_add_u64 v[82:83], v[0:1], 1, s[8:9]
	global_load_dwordx4 v[82:85], v[82:83], off
	v_or_b32_e32 v92, 48, v152
	s_waitcnt vmcnt(0)
	v_lshlrev_b32_e32 v89, 16, v83
	v_and_b32_e32 v90, 0xffff0000, v83
	v_lshlrev_b32_e32 v83, 16, v84
	v_and_b32_e32 v87, 0xffff0000, v82
	v_mul_f32_e32 v83, 0xbfb8aa3b, v83
	v_lshlrev_b32_e32 v86, 16, v82
	v_and_b32_e32 v88, 0xffff0000, v84
	v_exp_f32_e32 v84, v83
	v_mul_f32_e32 v83, 0xbfb8aa3b, v87
	v_mul_f32_e32 v82, 0xbfb8aa3b, v86
	v_exp_f32_e32 v86, v83
	v_mul_f32_e32 v83, 0xbfb8aa3b, v88
	v_exp_f32_e32 v88, v83
	v_mul_f32_e32 v83, 0xbfb8aa3b, v89
	v_exp_f32_e32 v82, v82
	v_exp_f32_e32 v83, v83
	v_lshlrev_b32_e32 v91, 16, v85
	v_mul_f32_e32 v87, 0xbfb8aa3b, v90
	v_and_b32_e32 v94, 0xffff0000, v85
	v_pk_add_f32 v[82:83], v[82:83], 1.0 op_sel_hi:[1,0]
	v_mul_f32_e32 v85, 0xbfb8aa3b, v91
	v_mul_f32_e32 v89, 0xbfb8aa3b, v94
	v_exp_f32_e32 v87, v87
	v_exp_f32_e32 v85, v85
	v_rcp_f32_e32 v83, v83
	s_nop 0
	v_pk_add_f32 v[86:87], v[86:87], 1.0 op_sel_hi:[1,0]
	v_exp_f32_e32 v89, v89
	v_rcp_f32_e32 v82, v82
	s_nop 0
	v_mov_b32_e32 v90, v78
	v_mov_b32_e32 v91, v80
	v_pk_mul_f32 v[82:83], v[90:91], v[82:83]
	v_rcp_f32_e32 v87, v87
	s_nop 0
	s_nop 0
	v_rcp_f32_e32 v86, v86
	s_nop 0
	v_mov_b32_e32 v80, v79
	v_pk_mul_f32 v[78:79], v[80:81], v[86:87]
	v_cvt_pk_bf16_f32 v80, v82, v83
	v_cvt_pk_bf16_f32 v78, v78, v79
	v_and_b32_e32 v79, 0xffff0000, v78
	v_lshlrev_b32_e32 v78, 16, v78
	v_or_b32_sdwa v79, v79, v80 dst_sel:DWORD dst_unused:UNUSED_PAD src0_sel:DWORD src1_sel:WORD_1
	v_or_b32_sdwa v78, v78, v80 dst_sel:DWORD dst_unused:UNUSED_PAD src0_sel:DWORD src1_sel:WORD_0
	v_pk_add_f32 v[80:81], v[84:85], 1.0 op_sel_hi:[1,0]
	s_nop 0
	s_nop 0
	v_rcp_f32_e32 v81, v81
	s_nop 0
	s_nop 0
	v_rcp_f32_e32 v80, v80
	s_nop 0
	v_mov_b32_e32 v82, v74
	v_mov_b32_e32 v83, v76
	v_pk_mul_f32 v[80:81], v[82:83], v[80:81]
	v_pk_add_f32 v[82:83], v[88:89], 1.0 op_sel_hi:[1,0]
	s_nop 0
	s_nop 0
	v_rcp_f32_e32 v83, v83
	s_nop 0
	s_nop 0
	v_rcp_f32_e32 v82, v82
	s_nop 0
	v_mov_b32_e32 v76, v75
	v_pk_mul_f32 v[74:75], v[76:77], v[82:83]
	v_mul_lo_u32 v84, v92, s61
	v_cvt_pk_bf16_f32 v74, v74, v75
	v_cvt_pk_bf16_f32 v76, v80, v81
	v_and_b32_e32 v75, 0xffff0000, v74
	v_lshlrev_b32_e32 v74, 16, v74
	v_add_u32_e32 v0, v0, v84
	v_or_b32_sdwa v81, v75, v76 dst_sel:DWORD dst_unused:UNUSED_PAD src0_sel:DWORD src1_sel:WORD_1
	v_or_b32_sdwa v80, v74, v76 dst_sel:DWORD dst_unused:UNUSED_PAD src0_sel:DWORD src1_sel:WORD_0
	v_lshl_add_u64 v[74:75], v[0:1], 1, s[6:7]
	v_add_u32_e32 v0, v93, v125
	global_store_dwordx4 v[74:75], v[78:81], off
	v_lshl_add_u64 v[74:75], v[0:1], 1, s[8:9]
	global_load_dwordx4 v[74:77], v[74:75], off
	v_add_u32_e32 v0, v0, v84
	s_waitcnt vmcnt(0)
	v_lshlrev_b32_e32 v81, 16, v75
	v_and_b32_e32 v82, 0xffff0000, v75
	v_lshlrev_b32_e32 v75, 16, v76
	v_and_b32_e32 v79, 0xffff0000, v74
	v_mul_f32_e32 v75, 0xbfb8aa3b, v75
	v_lshlrev_b32_e32 v78, 16, v74
	v_and_b32_e32 v80, 0xffff0000, v76
	v_exp_f32_e32 v76, v75
	v_mul_f32_e32 v75, 0xbfb8aa3b, v79
	v_mul_f32_e32 v74, 0xbfb8aa3b, v78
	v_exp_f32_e32 v78, v75
	v_mul_f32_e32 v75, 0xbfb8aa3b, v80
	v_exp_f32_e32 v80, v75
	v_mul_f32_e32 v75, 0xbfb8aa3b, v81
	v_exp_f32_e32 v74, v74
	v_exp_f32_e32 v75, v75
	v_lshlrev_b32_e32 v83, 16, v77
	v_mul_f32_e32 v79, 0xbfb8aa3b, v82
	v_and_b32_e32 v85, 0xffff0000, v77
	v_pk_add_f32 v[74:75], v[74:75], 1.0 op_sel_hi:[1,0]
	v_mul_f32_e32 v77, 0xbfb8aa3b, v83
	v_mul_f32_e32 v81, 0xbfb8aa3b, v85
	v_exp_f32_e32 v79, v79
	v_exp_f32_e32 v77, v77
	v_rcp_f32_e32 v75, v75
	s_nop 0
	v_pk_add_f32 v[78:79], v[78:79], 1.0 op_sel_hi:[1,0]
	v_exp_f32_e32 v81, v81
	v_rcp_f32_e32 v74, v74
	s_nop 0
	v_mov_b32_e32 v82, v70
	v_mov_b32_e32 v83, v72
	v_pk_mul_f32 v[74:75], v[82:83], v[74:75]
	v_rcp_f32_e32 v79, v79
	s_nop 0
	s_nop 0
	v_rcp_f32_e32 v78, v78
	s_nop 0
	v_mov_b32_e32 v72, v71
	v_pk_mul_f32 v[70:71], v[72:73], v[78:79]
	v_cvt_pk_bf16_f32 v72, v74, v75
	v_cvt_pk_bf16_f32 v70, v70, v71
	v_and_b32_e32 v71, 0xffff0000, v70
	v_lshlrev_b32_e32 v70, 16, v70
	v_or_b32_sdwa v71, v71, v72 dst_sel:DWORD dst_unused:UNUSED_PAD src0_sel:DWORD src1_sel:WORD_1
	v_or_b32_sdwa v70, v70, v72 dst_sel:DWORD dst_unused:UNUSED_PAD src0_sel:DWORD src1_sel:WORD_0
	v_pk_add_f32 v[72:73], v[76:77], 1.0 op_sel_hi:[1,0]
	s_nop 0
	s_nop 0
	v_rcp_f32_e32 v73, v73
	s_nop 0
	s_nop 0
	v_rcp_f32_e32 v72, v72
	s_nop 0
	v_mov_b32_e32 v74, v66
	v_mov_b32_e32 v75, v68
	v_pk_mul_f32 v[72:73], v[74:75], v[72:73]
	v_pk_add_f32 v[74:75], v[80:81], 1.0 op_sel_hi:[1,0]
	s_nop 0
	s_nop 0
	v_rcp_f32_e32 v75, v75
	s_nop 0
	s_nop 0
	v_rcp_f32_e32 v74, v74
	s_nop 0
	v_mov_b32_e32 v68, v67
	v_pk_mul_f32 v[66:67], v[68:69], v[74:75]
	v_cvt_pk_bf16_f32 v68, v72, v73
	v_cvt_pk_bf16_f32 v66, v66, v67
	v_and_b32_e32 v67, 0xffff0000, v66
	v_lshlrev_b32_e32 v66, 16, v66
	v_add_u32_e32 v76, 0xb6000, v151
	v_or_b32_sdwa v73, v67, v68 dst_sel:DWORD dst_unused:UNUSED_PAD src0_sel:DWORD src1_sel:WORD_1
	v_or_b32_sdwa v72, v66, v68 dst_sel:DWORD dst_unused:UNUSED_PAD src0_sel:DWORD src1_sel:WORD_0
	v_lshl_add_u64 v[66:67], v[0:1], 1, s[6:7]
	v_add_u32_e32 v0, v76, v150
	global_store_dwordx4 v[66:67], v[70:73], off
	v_lshl_add_u64 v[66:67], v[0:1], 1, s[8:9]
	global_load_dwordx4 v[66:69], v[66:67], off
	s_waitcnt vmcnt(0)
	v_lshlrev_b32_e32 v73, 16, v67
	v_and_b32_e32 v74, 0xffff0000, v67
	v_lshlrev_b32_e32 v67, 16, v68
	v_and_b32_e32 v71, 0xffff0000, v66
	v_mul_f32_e32 v67, 0xbfb8aa3b, v67
	v_lshlrev_b32_e32 v70, 16, v66
	v_and_b32_e32 v72, 0xffff0000, v68
	v_exp_f32_e32 v68, v67
	v_mul_f32_e32 v67, 0xbfb8aa3b, v71
	v_mul_f32_e32 v66, 0xbfb8aa3b, v70
	v_exp_f32_e32 v70, v67
	v_mul_f32_e32 v67, 0xbfb8aa3b, v72
	v_exp_f32_e32 v72, v67
	v_mul_f32_e32 v67, 0xbfb8aa3b, v73
	v_exp_f32_e32 v66, v66
	v_exp_f32_e32 v67, v67
	v_lshlrev_b32_e32 v75, 16, v69
	v_mul_f32_e32 v71, 0xbfb8aa3b, v74
	v_and_b32_e32 v77, 0xffff0000, v69
	v_pk_add_f32 v[66:67], v[66:67], 1.0 op_sel_hi:[1,0]
	v_mul_f32_e32 v69, 0xbfb8aa3b, v75
	v_mul_f32_e32 v73, 0xbfb8aa3b, v77
	v_exp_f32_e32 v71, v71
	v_exp_f32_e32 v69, v69
	v_rcp_f32_e32 v67, v67
	s_nop 0
	v_pk_add_f32 v[70:71], v[70:71], 1.0 op_sel_hi:[1,0]
	v_exp_f32_e32 v73, v73
	v_rcp_f32_e32 v66, v66
	s_nop 0
	v_mov_b32_e32 v74, v62
	v_mov_b32_e32 v75, v64
	v_pk_mul_f32 v[66:67], v[74:75], v[66:67]
	v_rcp_f32_e32 v71, v71
	s_nop 0
	s_nop 0
	v_rcp_f32_e32 v70, v70
	s_nop 0
	v_mov_b32_e32 v64, v63
	v_pk_mul_f32 v[62:63], v[64:65], v[70:71]
	v_cvt_pk_bf16_f32 v64, v66, v67
	v_cvt_pk_bf16_f32 v62, v62, v63
	v_and_b32_e32 v63, 0xffff0000, v62
	v_lshlrev_b32_e32 v62, 16, v62
	v_or_b32_sdwa v63, v63, v64 dst_sel:DWORD dst_unused:UNUSED_PAD src0_sel:DWORD src1_sel:WORD_1
	v_or_b32_sdwa v62, v62, v64 dst_sel:DWORD dst_unused:UNUSED_PAD src0_sel:DWORD src1_sel:WORD_0
	v_pk_add_f32 v[64:65], v[68:69], 1.0 op_sel_hi:[1,0]
	s_nop 0
	s_nop 0
	v_rcp_f32_e32 v65, v65
	s_nop 0
	s_nop 0
	v_rcp_f32_e32 v64, v64
	s_nop 0
	v_mov_b32_e32 v66, v58
	v_mov_b32_e32 v67, v60
	v_pk_mul_f32 v[64:65], v[66:67], v[64:65]
	v_pk_add_f32 v[66:67], v[72:73], 1.0 op_sel_hi:[1,0]
	s_nop 0
	s_nop 0
	v_rcp_f32_e32 v67, v67
	s_nop 0
	s_nop 0
	v_rcp_f32_e32 v66, v66
	s_nop 0
	v_mov_b32_e32 v60, v59
	v_pk_mul_f32 v[58:59], v[60:61], v[66:67]
	v_add_u32_e32 v68, 0xfff6a000, v124
	v_cvt_pk_bf16_f32 v58, v58, v59
	v_cvt_pk_bf16_f32 v60, v64, v65
	v_and_b32_e32 v59, 0xffff0000, v58
	v_lshlrev_b32_e32 v58, 16, v58
	v_add_u32_e32 v0, v0, v68
	v_or_b32_sdwa v65, v59, v60 dst_sel:DWORD dst_unused:UNUSED_PAD src0_sel:DWORD src1_sel:WORD_1
	v_or_b32_sdwa v64, v58, v60 dst_sel:DWORD dst_unused:UNUSED_PAD src0_sel:DWORD src1_sel:WORD_0
	v_lshl_add_u64 v[58:59], v[0:1], 1, s[6:7]
	v_add_u32_e32 v0, v76, v125
	global_store_dwordx4 v[58:59], v[62:65], off
	v_lshl_add_u64 v[58:59], v[0:1], 1, s[8:9]
	global_load_dwordx4 v[58:61], v[58:59], off
	v_add_u32_e32 v0, v0, v68
	s_waitcnt vmcnt(0)
	v_lshlrev_b32_e32 v65, 16, v59
	v_and_b32_e32 v66, 0xffff0000, v59
	v_lshlrev_b32_e32 v59, 16, v60
	v_and_b32_e32 v63, 0xffff0000, v58
	v_mul_f32_e32 v59, 0xbfb8aa3b, v59
	v_lshlrev_b32_e32 v62, 16, v58
	v_and_b32_e32 v64, 0xffff0000, v60
	v_exp_f32_e32 v60, v59
	v_mul_f32_e32 v59, 0xbfb8aa3b, v63
	v_mul_f32_e32 v58, 0xbfb8aa3b, v62
	v_exp_f32_e32 v62, v59
	v_mul_f32_e32 v59, 0xbfb8aa3b, v64
	v_exp_f32_e32 v64, v59
	v_mul_f32_e32 v59, 0xbfb8aa3b, v65
	v_exp_f32_e32 v58, v58
	v_exp_f32_e32 v59, v59
	v_lshlrev_b32_e32 v67, 16, v61
	v_mul_f32_e32 v63, 0xbfb8aa3b, v66
	v_and_b32_e32 v69, 0xffff0000, v61
	v_pk_add_f32 v[58:59], v[58:59], 1.0 op_sel_hi:[1,0]
	v_mul_f32_e32 v61, 0xbfb8aa3b, v67
	v_mul_f32_e32 v65, 0xbfb8aa3b, v69
	v_exp_f32_e32 v63, v63
	v_exp_f32_e32 v61, v61
	v_rcp_f32_e32 v59, v59
	s_nop 0
	v_pk_add_f32 v[62:63], v[62:63], 1.0 op_sel_hi:[1,0]
	v_exp_f32_e32 v65, v65
	v_rcp_f32_e32 v58, v58
	s_nop 0
	v_mov_b32_e32 v66, v54
	v_mov_b32_e32 v67, v56
	v_pk_mul_f32 v[58:59], v[66:67], v[58:59]
	v_rcp_f32_e32 v63, v63
	s_nop 0
	s_nop 0
	v_rcp_f32_e32 v62, v62
	s_nop 0
	v_mov_b32_e32 v56, v55
	v_pk_mul_f32 v[54:55], v[56:57], v[62:63]
	v_cvt_pk_bf16_f32 v56, v58, v59
	v_cvt_pk_bf16_f32 v54, v54, v55
	v_and_b32_e32 v55, 0xffff0000, v54
	v_lshlrev_b32_e32 v54, 16, v54
	v_or_b32_sdwa v55, v55, v56 dst_sel:DWORD dst_unused:UNUSED_PAD src0_sel:DWORD src1_sel:WORD_1
	v_or_b32_sdwa v54, v54, v56 dst_sel:DWORD dst_unused:UNUSED_PAD src0_sel:DWORD src1_sel:WORD_0
	v_pk_add_f32 v[56:57], v[60:61], 1.0 op_sel_hi:[1,0]
	s_nop 0
	s_nop 0
	v_rcp_f32_e32 v57, v57
	s_nop 0
	s_nop 0
	v_rcp_f32_e32 v56, v56
	s_nop 0
	v_mov_b32_e32 v58, v50
	v_mov_b32_e32 v59, v52
	v_pk_mul_f32 v[56:57], v[58:59], v[56:57]
	v_pk_add_f32 v[58:59], v[64:65], 1.0 op_sel_hi:[1,0]
	s_nop 0
	s_nop 0
	v_rcp_f32_e32 v59, v59
	s_nop 0
	s_nop 0
	v_rcp_f32_e32 v58, v58
	s_nop 0
	v_mov_b32_e32 v52, v51
	v_pk_mul_f32 v[50:51], v[52:53], v[58:59]
	v_cvt_pk_bf16_f32 v52, v56, v57
	v_cvt_pk_bf16_f32 v50, v50, v51
	v_and_b32_e32 v51, 0xffff0000, v50
	v_lshlrev_b32_e32 v50, 16, v50
	v_add_u32_e32 v60, 0xccc00, v151
	v_or_b32_sdwa v57, v51, v52 dst_sel:DWORD dst_unused:UNUSED_PAD src0_sel:DWORD src1_sel:WORD_1
	v_or_b32_sdwa v56, v50, v52 dst_sel:DWORD dst_unused:UNUSED_PAD src0_sel:DWORD src1_sel:WORD_0
	v_lshl_add_u64 v[50:51], v[0:1], 1, s[6:7]
	v_add_u32_e32 v0, v60, v150
	global_store_dwordx4 v[50:51], v[54:57], off
	v_lshl_add_u64 v[50:51], v[0:1], 1, s[8:9]
	global_load_dwordx4 v[50:53], v[50:51], off
	s_waitcnt vmcnt(0)
	v_lshlrev_b32_e32 v57, 16, v51
	v_and_b32_e32 v58, 0xffff0000, v51
	v_lshlrev_b32_e32 v51, 16, v52
	v_and_b32_e32 v55, 0xffff0000, v50
	v_mul_f32_e32 v51, 0xbfb8aa3b, v51
	v_lshlrev_b32_e32 v54, 16, v50
	v_and_b32_e32 v56, 0xffff0000, v52
	v_exp_f32_e32 v52, v51
	v_mul_f32_e32 v51, 0xbfb8aa3b, v55
	v_mul_f32_e32 v50, 0xbfb8aa3b, v54
	v_exp_f32_e32 v54, v51
	v_mul_f32_e32 v51, 0xbfb8aa3b, v56
	v_exp_f32_e32 v56, v51
	v_mul_f32_e32 v51, 0xbfb8aa3b, v57
	v_exp_f32_e32 v50, v50
	v_exp_f32_e32 v51, v51
	v_lshlrev_b32_e32 v59, 16, v53
	v_mul_f32_e32 v55, 0xbfb8aa3b, v58
	v_and_b32_e32 v61, 0xffff0000, v53
	v_pk_add_f32 v[50:51], v[50:51], 1.0 op_sel_hi:[1,0]
	v_mul_f32_e32 v53, 0xbfb8aa3b, v59
	v_mul_f32_e32 v57, 0xbfb8aa3b, v61
	v_exp_f32_e32 v55, v55
	v_exp_f32_e32 v53, v53
	v_rcp_f32_e32 v51, v51
	s_nop 0
	v_pk_add_f32 v[54:55], v[54:55], 1.0 op_sel_hi:[1,0]
	v_exp_f32_e32 v57, v57
	v_rcp_f32_e32 v50, v50
	s_nop 0
	v_mov_b32_e32 v58, v46
	v_mov_b32_e32 v59, v48
	v_pk_mul_f32 v[50:51], v[58:59], v[50:51]
	v_rcp_f32_e32 v55, v55
	s_nop 0
	s_nop 0
	v_rcp_f32_e32 v54, v54
	s_nop 0
	v_mov_b32_e32 v48, v47
	v_pk_mul_f32 v[46:47], v[48:49], v[54:55]
	v_cvt_pk_bf16_f32 v48, v50, v51
	v_cvt_pk_bf16_f32 v46, v46, v47
	v_and_b32_e32 v47, 0xffff0000, v46
	v_lshlrev_b32_e32 v46, 16, v46
	v_or_b32_sdwa v47, v47, v48 dst_sel:DWORD dst_unused:UNUSED_PAD src0_sel:DWORD src1_sel:WORD_1
	v_or_b32_sdwa v46, v46, v48 dst_sel:DWORD dst_unused:UNUSED_PAD src0_sel:DWORD src1_sel:WORD_0
	v_pk_add_f32 v[48:49], v[52:53], 1.0 op_sel_hi:[1,0]
	s_nop 0
	s_nop 0
	v_rcp_f32_e32 v49, v49
	s_nop 0
	s_nop 0
	v_rcp_f32_e32 v48, v48
	s_nop 0
	v_mov_b32_e32 v50, v42
	v_mov_b32_e32 v51, v44
	v_pk_mul_f32 v[48:49], v[50:51], v[48:49]
	v_pk_add_f32 v[50:51], v[56:57], 1.0 op_sel_hi:[1,0]
	s_nop 0
	s_nop 0
	v_rcp_f32_e32 v51, v51
	s_nop 0
	s_nop 0
	v_rcp_f32_e32 v50, v50
	s_nop 0
	v_mov_b32_e32 v44, v43
	v_pk_mul_f32 v[42:43], v[44:45], v[50:51]
	v_add_u32_e32 v52, 0xfff57400, v124
	v_cvt_pk_bf16_f32 v42, v42, v43
	v_cvt_pk_bf16_f32 v44, v48, v49
	v_and_b32_e32 v43, 0xffff0000, v42
	v_lshlrev_b32_e32 v42, 16, v42
	v_add_u32_e32 v0, v0, v52
	v_or_b32_sdwa v49, v43, v44 dst_sel:DWORD dst_unused:UNUSED_PAD src0_sel:DWORD src1_sel:WORD_1
	v_or_b32_sdwa v48, v42, v44 dst_sel:DWORD dst_unused:UNUSED_PAD src0_sel:DWORD src1_sel:WORD_0
	v_lshl_add_u64 v[42:43], v[0:1], 1, s[6:7]
	v_add_u32_e32 v0, v60, v125
	global_store_dwordx4 v[42:43], v[46:49], off
	v_lshl_add_u64 v[42:43], v[0:1], 1, s[8:9]
	global_load_dwordx4 v[42:45], v[42:43], off
	v_add_u32_e32 v0, v0, v52
	s_waitcnt vmcnt(0)
	v_lshlrev_b32_e32 v49, 16, v43
	v_and_b32_e32 v50, 0xffff0000, v43
	v_lshlrev_b32_e32 v43, 16, v44
	v_and_b32_e32 v47, 0xffff0000, v42
	v_mul_f32_e32 v43, 0xbfb8aa3b, v43
	v_lshlrev_b32_e32 v46, 16, v42
	v_and_b32_e32 v48, 0xffff0000, v44
	v_exp_f32_e32 v44, v43
	v_mul_f32_e32 v43, 0xbfb8aa3b, v47
	v_mul_f32_e32 v42, 0xbfb8aa3b, v46
	v_exp_f32_e32 v46, v43
	v_mul_f32_e32 v43, 0xbfb8aa3b, v48
	v_exp_f32_e32 v48, v43
	v_mul_f32_e32 v43, 0xbfb8aa3b, v49
	v_exp_f32_e32 v42, v42
	v_exp_f32_e32 v43, v43
	v_lshlrev_b32_e32 v51, 16, v45
	v_mul_f32_e32 v47, 0xbfb8aa3b, v50
	v_and_b32_e32 v53, 0xffff0000, v45
	v_pk_add_f32 v[42:43], v[42:43], 1.0 op_sel_hi:[1,0]
	v_mul_f32_e32 v45, 0xbfb8aa3b, v51
	v_mul_f32_e32 v49, 0xbfb8aa3b, v53
	v_exp_f32_e32 v47, v47
	v_exp_f32_e32 v45, v45
	v_rcp_f32_e32 v43, v43
	s_nop 0
	v_pk_add_f32 v[46:47], v[46:47], 1.0 op_sel_hi:[1,0]
	v_exp_f32_e32 v49, v49
	v_rcp_f32_e32 v42, v42
	s_nop 0
	v_mov_b32_e32 v50, v38
	v_mov_b32_e32 v51, v40
	v_pk_mul_f32 v[42:43], v[50:51], v[42:43]
	v_rcp_f32_e32 v47, v47
	s_nop 0
	s_nop 0
	v_rcp_f32_e32 v46, v46
	s_nop 0
	v_mov_b32_e32 v40, v39
	v_pk_mul_f32 v[38:39], v[40:41], v[46:47]
	v_cvt_pk_bf16_f32 v40, v42, v43
	v_cvt_pk_bf16_f32 v38, v38, v39
	v_and_b32_e32 v39, 0xffff0000, v38
	v_lshlrev_b32_e32 v38, 16, v38
	v_or_b32_sdwa v39, v39, v40 dst_sel:DWORD dst_unused:UNUSED_PAD src0_sel:DWORD src1_sel:WORD_1
	v_or_b32_sdwa v38, v38, v40 dst_sel:DWORD dst_unused:UNUSED_PAD src0_sel:DWORD src1_sel:WORD_0
	v_pk_add_f32 v[40:41], v[44:45], 1.0 op_sel_hi:[1,0]
	s_nop 0
	s_nop 0
	v_rcp_f32_e32 v41, v41
	s_nop 0
	s_nop 0
	v_rcp_f32_e32 v40, v40
	s_nop 0
	v_mov_b32_e32 v42, v34
	v_mov_b32_e32 v43, v36
	v_pk_mul_f32 v[40:41], v[42:43], v[40:41]
	v_pk_add_f32 v[42:43], v[48:49], 1.0 op_sel_hi:[1,0]
	s_nop 0
	s_nop 0
	v_rcp_f32_e32 v43, v43
	s_nop 0
	s_nop 0
	v_rcp_f32_e32 v42, v42
	s_nop 0
	v_mov_b32_e32 v36, v35
	v_pk_mul_f32 v[34:35], v[36:37], v[42:43]
	v_cvt_pk_bf16_f32 v36, v40, v41
	v_cvt_pk_bf16_f32 v34, v34, v35
	v_and_b32_e32 v35, 0xffff0000, v34
	v_lshlrev_b32_e32 v34, 16, v34
	v_add_u32_e32 v44, 0xe3800, v151
	v_or_b32_sdwa v41, v35, v36 dst_sel:DWORD dst_unused:UNUSED_PAD src0_sel:DWORD src1_sel:WORD_1
	v_or_b32_sdwa v40, v34, v36 dst_sel:DWORD dst_unused:UNUSED_PAD src0_sel:DWORD src1_sel:WORD_0
	v_lshl_add_u64 v[34:35], v[0:1], 1, s[6:7]
	v_add_u32_e32 v0, v44, v150
	global_store_dwordx4 v[34:35], v[38:41], off
	v_lshl_add_u64 v[34:35], v[0:1], 1, s[8:9]
	global_load_dwordx4 v[34:37], v[34:35], off
	s_waitcnt vmcnt(0)
	v_lshlrev_b32_e32 v41, 16, v35
	v_and_b32_e32 v42, 0xffff0000, v35
	v_lshlrev_b32_e32 v35, 16, v36
	v_and_b32_e32 v39, 0xffff0000, v34
	v_mul_f32_e32 v35, 0xbfb8aa3b, v35
	v_lshlrev_b32_e32 v38, 16, v34
	v_and_b32_e32 v40, 0xffff0000, v36
	v_exp_f32_e32 v36, v35
	v_mul_f32_e32 v35, 0xbfb8aa3b, v39
	v_mul_f32_e32 v34, 0xbfb8aa3b, v38
	v_exp_f32_e32 v38, v35
	v_mul_f32_e32 v35, 0xbfb8aa3b, v40
	v_exp_f32_e32 v40, v35
	v_mul_f32_e32 v35, 0xbfb8aa3b, v41
	v_exp_f32_e32 v34, v34
	v_exp_f32_e32 v35, v35
	v_lshlrev_b32_e32 v43, 16, v37
	v_mul_f32_e32 v39, 0xbfb8aa3b, v42
	v_and_b32_e32 v45, 0xffff0000, v37
	v_pk_add_f32 v[34:35], v[34:35], 1.0 op_sel_hi:[1,0]
	v_mul_f32_e32 v37, 0xbfb8aa3b, v43
	v_mul_f32_e32 v41, 0xbfb8aa3b, v45
	v_exp_f32_e32 v39, v39
	v_exp_f32_e32 v37, v37
	v_rcp_f32_e32 v35, v35
	s_nop 0
	v_pk_add_f32 v[38:39], v[38:39], 1.0 op_sel_hi:[1,0]
	v_exp_f32_e32 v41, v41
	v_rcp_f32_e32 v34, v34
	s_nop 0
	v_mov_b32_e32 v42, v30
	v_mov_b32_e32 v43, v32
	v_pk_mul_f32 v[34:35], v[42:43], v[34:35]
	v_rcp_f32_e32 v39, v39
	s_nop 0
	s_nop 0
	v_rcp_f32_e32 v38, v38
	s_nop 0
	v_mov_b32_e32 v32, v31
	v_pk_mul_f32 v[30:31], v[32:33], v[38:39]
	v_cvt_pk_bf16_f32 v32, v34, v35
	v_cvt_pk_bf16_f32 v30, v30, v31
	v_and_b32_e32 v31, 0xffff0000, v30
	v_lshlrev_b32_e32 v30, 16, v30
	v_or_b32_sdwa v31, v31, v32 dst_sel:DWORD dst_unused:UNUSED_PAD src0_sel:DWORD src1_sel:WORD_1
	v_or_b32_sdwa v30, v30, v32 dst_sel:DWORD dst_unused:UNUSED_PAD src0_sel:DWORD src1_sel:WORD_0
	v_pk_add_f32 v[32:33], v[36:37], 1.0 op_sel_hi:[1,0]
	s_nop 0
	s_nop 0
	v_rcp_f32_e32 v33, v33
	s_nop 0
	s_nop 0
	v_rcp_f32_e32 v32, v32
	s_nop 0
	v_mov_b32_e32 v34, v26
	v_mov_b32_e32 v35, v28
	v_pk_mul_f32 v[32:33], v[34:35], v[32:33]
	v_pk_add_f32 v[34:35], v[40:41], 1.0 op_sel_hi:[1,0]
	s_nop 0
	s_nop 0
	v_rcp_f32_e32 v35, v35
	s_nop 0
	s_nop 0
	v_rcp_f32_e32 v34, v34
	s_nop 0
	v_mov_b32_e32 v28, v27
	v_pk_mul_f32 v[26:27], v[28:29], v[34:35]
	v_add_u32_e32 v36, 0xfff44800, v124
	v_cvt_pk_bf16_f32 v26, v26, v27
	v_cvt_pk_bf16_f32 v28, v32, v33
	v_and_b32_e32 v27, 0xffff0000, v26
	v_lshlrev_b32_e32 v26, 16, v26
	v_add_u32_e32 v0, v0, v36
	v_or_b32_sdwa v33, v27, v28 dst_sel:DWORD dst_unused:UNUSED_PAD src0_sel:DWORD src1_sel:WORD_1
	v_or_b32_sdwa v32, v26, v28 dst_sel:DWORD dst_unused:UNUSED_PAD src0_sel:DWORD src1_sel:WORD_0
	v_lshl_add_u64 v[26:27], v[0:1], 1, s[6:7]
	v_add_u32_e32 v0, v44, v125
	global_store_dwordx4 v[26:27], v[30:33], off
	v_lshl_add_u64 v[26:27], v[0:1], 1, s[8:9]
	global_load_dwordx4 v[26:29], v[26:27], off
	v_add_u32_e32 v0, v0, v36
	s_waitcnt vmcnt(0)
	v_lshlrev_b32_e32 v33, 16, v27
	v_and_b32_e32 v34, 0xffff0000, v27
	v_lshlrev_b32_e32 v27, 16, v28
	v_and_b32_e32 v31, 0xffff0000, v26
	v_mul_f32_e32 v27, 0xbfb8aa3b, v27
	v_lshlrev_b32_e32 v30, 16, v26
	v_and_b32_e32 v32, 0xffff0000, v28
	v_exp_f32_e32 v28, v27
	v_mul_f32_e32 v27, 0xbfb8aa3b, v31
	v_mul_f32_e32 v26, 0xbfb8aa3b, v30
	v_exp_f32_e32 v30, v27
	v_mul_f32_e32 v27, 0xbfb8aa3b, v32
	v_exp_f32_e32 v32, v27
	v_mul_f32_e32 v27, 0xbfb8aa3b, v33
	v_exp_f32_e32 v26, v26
	v_exp_f32_e32 v27, v27
	v_lshlrev_b32_e32 v35, 16, v29
	v_mul_f32_e32 v31, 0xbfb8aa3b, v34
	v_and_b32_e32 v37, 0xffff0000, v29
	v_pk_add_f32 v[26:27], v[26:27], 1.0 op_sel_hi:[1,0]
	v_mul_f32_e32 v29, 0xbfb8aa3b, v35
	v_mul_f32_e32 v33, 0xbfb8aa3b, v37
	v_exp_f32_e32 v31, v31
	v_exp_f32_e32 v29, v29
	v_rcp_f32_e32 v27, v27
	s_nop 0
	v_pk_add_f32 v[30:31], v[30:31], 1.0 op_sel_hi:[1,0]
	v_exp_f32_e32 v33, v33
	v_rcp_f32_e32 v26, v26
	s_nop 0
	v_mov_b32_e32 v34, v22
	v_mov_b32_e32 v35, v24
	v_pk_mul_f32 v[26:27], v[34:35], v[26:27]
	v_rcp_f32_e32 v31, v31
	s_nop 0
	s_nop 0
	v_rcp_f32_e32 v30, v30
	s_nop 0
	v_mov_b32_e32 v24, v23
	v_pk_mul_f32 v[22:23], v[24:25], v[30:31]
	v_cvt_pk_bf16_f32 v24, v26, v27
	v_cvt_pk_bf16_f32 v22, v22, v23
	v_and_b32_e32 v23, 0xffff0000, v22
	v_lshlrev_b32_e32 v22, 16, v22
	v_or_b32_sdwa v23, v23, v24 dst_sel:DWORD dst_unused:UNUSED_PAD src0_sel:DWORD src1_sel:WORD_1
	v_or_b32_sdwa v22, v22, v24 dst_sel:DWORD dst_unused:UNUSED_PAD src0_sel:DWORD src1_sel:WORD_0
	v_pk_add_f32 v[24:25], v[28:29], 1.0 op_sel_hi:[1,0]
	s_nop 0
	s_nop 0
	v_rcp_f32_e32 v25, v25
	s_nop 0
	s_nop 0
	v_rcp_f32_e32 v24, v24
	s_nop 0
	v_mov_b32_e32 v26, v18
	v_mov_b32_e32 v27, v20
	v_pk_mul_f32 v[24:25], v[26:27], v[24:25]
	v_pk_add_f32 v[26:27], v[32:33], 1.0 op_sel_hi:[1,0]
	s_nop 0
	s_nop 0
	v_rcp_f32_e32 v27, v27
	s_nop 0
	s_nop 0
	v_rcp_f32_e32 v26, v26
	s_nop 0
	v_mov_b32_e32 v20, v19
	v_pk_mul_f32 v[18:19], v[20:21], v[26:27]
	v_cvt_pk_bf16_f32 v20, v24, v25
	v_cvt_pk_bf16_f32 v18, v18, v19
	v_and_b32_e32 v19, 0xffff0000, v18
	v_lshlrev_b32_e32 v18, 16, v18
	v_add_u32_e32 v28, 0xfa400, v151
	v_or_b32_sdwa v25, v19, v20 dst_sel:DWORD dst_unused:UNUSED_PAD src0_sel:DWORD src1_sel:WORD_1
	v_or_b32_sdwa v24, v18, v20 dst_sel:DWORD dst_unused:UNUSED_PAD src0_sel:DWORD src1_sel:WORD_0
	v_lshl_add_u64 v[18:19], v[0:1], 1, s[6:7]
	v_add_u32_e32 v0, v28, v150
	global_store_dwordx4 v[18:19], v[22:25], off
	v_lshl_add_u64 v[18:19], v[0:1], 1, s[8:9]
	global_load_dwordx4 v[18:21], v[18:19], off
	s_waitcnt vmcnt(0)
	v_lshlrev_b32_e32 v25, 16, v19
	v_and_b32_e32 v26, 0xffff0000, v19
	v_lshlrev_b32_e32 v19, 16, v20
	v_and_b32_e32 v23, 0xffff0000, v18
	v_mul_f32_e32 v19, 0xbfb8aa3b, v19
	v_lshlrev_b32_e32 v22, 16, v18
	v_and_b32_e32 v24, 0xffff0000, v20
	v_exp_f32_e32 v20, v19
	v_mul_f32_e32 v19, 0xbfb8aa3b, v23
	v_mul_f32_e32 v18, 0xbfb8aa3b, v22
	v_exp_f32_e32 v22, v19
	v_mul_f32_e32 v19, 0xbfb8aa3b, v24
	v_exp_f32_e32 v24, v19
	v_mul_f32_e32 v19, 0xbfb8aa3b, v25
	v_exp_f32_e32 v18, v18
	v_exp_f32_e32 v19, v19
	v_lshlrev_b32_e32 v27, 16, v21
	v_mul_f32_e32 v23, 0xbfb8aa3b, v26
	v_and_b32_e32 v29, 0xffff0000, v21
	v_pk_add_f32 v[18:19], v[18:19], 1.0 op_sel_hi:[1,0]
	v_mul_f32_e32 v21, 0xbfb8aa3b, v27
	v_mul_f32_e32 v25, 0xbfb8aa3b, v29
	v_exp_f32_e32 v23, v23
	v_exp_f32_e32 v21, v21
	v_rcp_f32_e32 v19, v19
	s_nop 0
	v_pk_add_f32 v[22:23], v[22:23], 1.0 op_sel_hi:[1,0]
	v_exp_f32_e32 v25, v25
	v_rcp_f32_e32 v18, v18
	s_nop 0
	v_mov_b32_e32 v26, v14
	v_mov_b32_e32 v27, v16
	v_pk_mul_f32 v[18:19], v[26:27], v[18:19]
	v_rcp_f32_e32 v23, v23
	s_nop 0
	s_nop 0
	v_rcp_f32_e32 v22, v22
	s_nop 0
	v_mov_b32_e32 v16, v15
	v_pk_mul_f32 v[14:15], v[16:17], v[22:23]
	v_cvt_pk_bf16_f32 v16, v18, v19
	v_cvt_pk_bf16_f32 v14, v14, v15
	v_and_b32_e32 v15, 0xffff0000, v14
	v_lshlrev_b32_e32 v14, 16, v14
	v_or_b32_sdwa v15, v15, v16 dst_sel:DWORD dst_unused:UNUSED_PAD src0_sel:DWORD src1_sel:WORD_1
	v_or_b32_sdwa v14, v14, v16 dst_sel:DWORD dst_unused:UNUSED_PAD src0_sel:DWORD src1_sel:WORD_0
	v_pk_add_f32 v[16:17], v[20:21], 1.0 op_sel_hi:[1,0]
	s_nop 0
	s_nop 0
	v_rcp_f32_e32 v17, v17
	s_nop 0
	s_nop 0
	v_rcp_f32_e32 v16, v16
	s_nop 0
	v_mov_b32_e32 v18, v10
	v_mov_b32_e32 v19, v12
	v_pk_mul_f32 v[16:17], v[18:19], v[16:17]
	v_pk_add_f32 v[18:19], v[24:25], 1.0 op_sel_hi:[1,0]
	s_nop 0
	s_nop 0
	v_rcp_f32_e32 v19, v19
	s_nop 0
	s_nop 0
	v_rcp_f32_e32 v18, v18
	s_nop 0
	v_mov_b32_e32 v12, v11
	v_pk_mul_f32 v[10:11], v[12:13], v[18:19]
	v_add_u32_e32 v20, 0xfff31c00, v124
	v_cvt_pk_bf16_f32 v10, v10, v11
	v_cvt_pk_bf16_f32 v12, v16, v17
	v_and_b32_e32 v11, 0xffff0000, v10
	v_lshlrev_b32_e32 v10, 16, v10
	v_add_u32_e32 v0, v0, v20
	v_or_b32_sdwa v17, v11, v12 dst_sel:DWORD dst_unused:UNUSED_PAD src0_sel:DWORD src1_sel:WORD_1
	v_or_b32_sdwa v16, v10, v12 dst_sel:DWORD dst_unused:UNUSED_PAD src0_sel:DWORD src1_sel:WORD_0
	v_lshl_add_u64 v[10:11], v[0:1], 1, s[6:7]
	v_add_u32_e32 v0, v28, v125
	global_store_dwordx4 v[10:11], v[14:17], off
	v_lshl_add_u64 v[10:11], v[0:1], 1, s[8:9]
	global_load_dwordx4 v[10:13], v[10:11], off
	v_add_u32_e32 v0, v0, v20
	s_waitcnt vmcnt(0)
	v_lshlrev_b32_e32 v17, 16, v11
	v_and_b32_e32 v18, 0xffff0000, v11
	v_lshlrev_b32_e32 v11, 16, v12
	v_and_b32_e32 v15, 0xffff0000, v10
	v_mul_f32_e32 v11, 0xbfb8aa3b, v11
	v_lshlrev_b32_e32 v14, 16, v10
	v_and_b32_e32 v16, 0xffff0000, v12
	v_exp_f32_e32 v12, v11
	v_mul_f32_e32 v11, 0xbfb8aa3b, v15
	v_mul_f32_e32 v10, 0xbfb8aa3b, v14
	v_exp_f32_e32 v14, v11
	v_mul_f32_e32 v11, 0xbfb8aa3b, v16
	v_exp_f32_e32 v16, v11
	v_mul_f32_e32 v11, 0xbfb8aa3b, v17
	v_exp_f32_e32 v10, v10
	v_exp_f32_e32 v11, v11
	v_lshlrev_b32_e32 v19, 16, v13
	v_mul_f32_e32 v15, 0xbfb8aa3b, v18
	v_and_b32_e32 v21, 0xffff0000, v13
	v_pk_add_f32 v[10:11], v[10:11], 1.0 op_sel_hi:[1,0]
	v_mul_f32_e32 v13, 0xbfb8aa3b, v19
	v_mul_f32_e32 v17, 0xbfb8aa3b, v21
	v_exp_f32_e32 v15, v15
	v_exp_f32_e32 v13, v13
	v_rcp_f32_e32 v11, v11
	s_nop 0
	v_pk_add_f32 v[14:15], v[14:15], 1.0 op_sel_hi:[1,0]
	v_exp_f32_e32 v17, v17
	v_rcp_f32_e32 v10, v10
	s_nop 0
	v_mov_b32_e32 v18, v6
	v_mov_b32_e32 v19, v8
	v_pk_mul_f32 v[10:11], v[18:19], v[10:11]
	v_rcp_f32_e32 v15, v15
	s_nop 0
	s_nop 0
	v_rcp_f32_e32 v14, v14
	s_nop 0
	v_mov_b32_e32 v8, v7
	v_pk_mul_f32 v[6:7], v[8:9], v[14:15]
	v_cvt_pk_bf16_f32 v8, v10, v11
	v_cvt_pk_bf16_f32 v6, v6, v7
	v_and_b32_e32 v7, 0xffff0000, v6
	v_lshlrev_b32_e32 v6, 16, v6
	v_or_b32_sdwa v7, v7, v8 dst_sel:DWORD dst_unused:UNUSED_PAD src0_sel:DWORD src1_sel:WORD_1
	v_or_b32_sdwa v6, v6, v8 dst_sel:DWORD dst_unused:UNUSED_PAD src0_sel:DWORD src1_sel:WORD_0
	v_pk_add_f32 v[8:9], v[12:13], 1.0 op_sel_hi:[1,0]
	s_nop 0
	s_nop 0
	v_rcp_f32_e32 v9, v9
	s_nop 0
	s_nop 0
	v_rcp_f32_e32 v8, v8
	s_nop 0
	v_mov_b32_e32 v10, v2
	v_mov_b32_e32 v11, v4
	v_pk_mul_f32 v[8:9], v[10:11], v[8:9]
	v_pk_add_f32 v[10:11], v[16:17], 1.0 op_sel_hi:[1,0]
	s_nop 0
	s_nop 0
	v_rcp_f32_e32 v11, v11
	s_nop 0
	s_mov_b64 s[24:25], s[16:17]
	v_rcp_f32_e32 v10, v10
	s_nop 0
	v_mov_b32_e32 v4, v3
	v_pk_mul_f32 v[2:3], v[4:5], v[10:11]
	v_cvt_pk_bf16_f32 v4, v8, v9
	v_cvt_pk_bf16_f32 v2, v2, v3
	v_and_b32_e32 v3, 0xffff0000, v2
	v_lshlrev_b32_e32 v2, 16, v2
	v_or_b32_sdwa v9, v3, v4 dst_sel:DWORD dst_unused:UNUSED_PAD src0_sel:DWORD src1_sel:WORD_1
	v_or_b32_sdwa v8, v2, v4 dst_sel:DWORD dst_unused:UNUSED_PAD src0_sel:DWORD src1_sel:WORD_0
	v_lshl_add_u64 v[2:3], v[0:1], 1, s[6:7]
	s_and_b64 vcc, exec, s[10:11]
	global_store_dwordx4 v[2:3], v[6:9], off
	s_cbranch_vccz .LBB0_1331
	s_waitcnt vmcnt(0)
	v_readlane_b32 s76, v255, 8
	s_mov_b32 s92, 0x3b2aaaab
	s_cmp_gt_u32 s5, 3
	v_readlane_b32 s77, v255, 9
	s_mul_i32 s60, s33, 0x1800
	s_mul_hi_i32 s62, s64, 0x300
	s_mul_i32 s75, s33, 0x16c00
	s_mov_b32 s93, 0x3c800000
	s_mov_b32 s82, s70
	s_cbranch_scc1 .LBB0_1338
	s_barrier

.LBB0_1347:
	v_add_u32_e32 v0, 0x10000, v148
	s_waitcnt vmcnt(0)
	ds_read_b128 v[142:145], v0
	ds_read_b128 v[150:153], v0 offset:1024
	ds_read_b128 v[154:157], v0 offset:2048
	ds_read_b128 v[158:161], v0 offset:3072
	s_add_u32 s26, s24, 0xfffc0080
	s_addc_u32 s27, s25, -1
	s_cmp_eq_u32 s97, 12
	s_cselect_b32 s29, s2, s27
	s_cselect_b32 s28, s15, s26
	s_cselect_b32 s27, s13, s94
	s_cselect_b32 s26, s89, s90
	v_lshl_add_u64 v[178:179], s[24:25], 0, v[138:139]
	s_add_i32 m0, s35, 0xc000
	ds_read_b128 v[162:165], v147
	ds_read_b128 v[166:169], v147 offset:1024
	ds_read_b128 v[170:173], v147 offset:2048
	ds_read_b128 v[174:177], v147 offset:3072
	ds_read_b128 v[182:185], v147 offset:4096
	ds_read_b128 v[186:189], v147 offset:5120
	ds_read_b128 v[190:193], v147 offset:6144
	ds_read_b128 v[194:197], v147 offset:7168
	global_load_lds_dwordx4 v[178:179], off
	v_lshl_add_u64 v[178:179], s[24:25], 0, v[140:141]
	s_add_i32 m0, s35, 0xe000
	s_nop 0
	global_load_lds_dwordx4 v[178:179], off
	s_waitcnt lgkmcnt(8)
	s_barrier
	s_waitcnt lgkmcnt(0)
	s_setprio 1
	s_waitcnt lgkmcnt(0)
	v_mfma_f32_16x16x32_bf16 v[126:129], v[142:145], v[162:165], v[126:129]
	v_mfma_f32_16x16x32_bf16 v[122:125], v[154:157], v[162:165], v[122:125]
	v_mfma_f32_16x16x32_bf16 v[110:113], v[142:145], v[170:173], v[110:113]
	v_mfma_f32_16x16x32_bf16 v[106:109], v[154:157], v[170:173], v[106:109]
	v_mfma_f32_16x16x32_bf16 v[94:97], v[142:145], v[182:185], v[94:97]
	v_mfma_f32_16x16x32_bf16 v[90:93], v[154:157], v[182:185], v[90:93]
	v_mfma_f32_16x16x32_bf16 v[78:81], v[142:145], v[190:193], v[78:81]
	v_mfma_f32_16x16x32_bf16 v[74:77], v[154:157], v[190:193], v[74:77]
	v_mfma_f32_16x16x32_bf16 v[126:129], v[150:153], v[166:169], v[126:129]
	v_mfma_f32_16x16x32_bf16 v[122:125], v[158:161], v[166:169], v[122:125]
	v_mfma_f32_16x16x32_bf16 v[110:113], v[150:153], v[174:177], v[110:113]
	v_mfma_f32_16x16x32_bf16 v[106:109], v[158:161], v[174:177], v[106:109]
	v_mfma_f32_16x16x32_bf16 v[94:97], v[150:153], v[186:189], v[94:97]
	v_mfma_f32_16x16x32_bf16 v[90:93], v[158:161], v[186:189], v[90:93]
	v_mfma_f32_16x16x32_bf16 v[78:81], v[150:153], v[194:197], v[78:81]
	v_mfma_f32_16x16x32_bf16 v[74:77], v[158:161], v[194:197], v[74:77]
	s_setprio 0
	s_barrier
	s_mov_b32 m0, s21
	v_add_u32_e32 v0, 0x14000, v148
	v_lshl_add_u64 v[178:179], s[26:27], 0, v[134:135]
	s_waitcnt vmcnt(0)
	ds_read_b128 v[198:201], v0
	ds_read_b128 v[202:205], v0 offset:1024
	ds_read_b128 v[206:209], v0 offset:2048
	ds_read_b128 v[210:213], v0 offset:3072
	global_load_lds_dwordx4 v[178:179], off
	v_lshl_add_u64 v[214:215], s[26:27], 0, v[130:131]
	s_mov_b32 m0, s23
	s_nop 0
	global_load_lds_dwordx4 v[214:215], off
	s_barrier
	s_waitcnt lgkmcnt(0)
	s_setprio 1
	s_waitcnt lgkmcnt(0)
	v_mfma_f32_16x16x32_bf16 v[118:121], v[198:201], v[162:165], v[118:121]
	v_mfma_f32_16x16x32_bf16 v[114:117], v[206:209], v[162:165], v[114:117]
	v_mfma_f32_16x16x32_bf16 v[102:105], v[198:201], v[170:173], v[102:105]
	v_mfma_f32_16x16x32_bf16 v[98:101], v[206:209], v[170:173], v[98:101]
	v_mfma_f32_16x16x32_bf16 v[86:89], v[198:201], v[182:185], v[86:89]
	v_mfma_f32_16x16x32_bf16 v[82:85], v[206:209], v[182:185], v[82:85]
	v_mfma_f32_16x16x32_bf16 v[70:73], v[198:201], v[190:193], v[70:73]
	v_mfma_f32_16x16x32_bf16 v[66:69], v[206:209], v[190:193], v[66:69]
	v_mfma_f32_16x16x32_bf16 v[118:121], v[202:205], v[166:169], v[118:121]
	v_mfma_f32_16x16x32_bf16 v[114:117], v[210:213], v[166:169], v[114:117]
	v_mfma_f32_16x16x32_bf16 v[102:105], v[202:205], v[174:177], v[102:105]
	v_mfma_f32_16x16x32_bf16 v[98:101], v[210:213], v[174:177], v[98:101]
	v_mfma_f32_16x16x32_bf16 v[86:89], v[202:205], v[186:189], v[86:89]
	v_mfma_f32_16x16x32_bf16 v[82:85], v[210:213], v[186:189], v[82:85]
	v_mfma_f32_16x16x32_bf16 v[70:73], v[202:205], v[194:197], v[70:73]
	v_mfma_f32_16x16x32_bf16 v[66:69], v[210:213], v[194:197], v[66:69]
	s_setprio 0
	s_mov_b32 m0, s35
	v_lshl_add_u64 v[216:217], s[28:29], 0, v[136:137]
	s_barrier
	s_waitcnt vmcnt(0)
	ds_read_b128 v[162:165], v147 offset:16384
	ds_read_b128 v[166:169], v147 offset:17408
	ds_read_b128 v[170:173], v147 offset:18432
	ds_read_b128 v[174:177], v147 offset:19456
	ds_read_b128 v[182:185], v147 offset:20480
	ds_read_b128 v[186:189], v147 offset:21504
	ds_read_b128 v[190:193], v147 offset:22528
	ds_read_b128 v[194:197], v147 offset:23552
	global_load_lds_dwordx4 v[216:217], off
	v_lshl_add_u64 v[222:223], s[28:29], 0, v[132:133]
	s_mov_b32 m0, s36
	s_nop 0
	global_load_lds_dwordx4 v[222:223], off
	s_barrier
	s_waitcnt lgkmcnt(0)
	s_setprio 1
	s_waitcnt lgkmcnt(0)
	v_mfma_f32_16x16x32_bf16 v[62:65], v[142:145], v[162:165], v[62:65]
	v_mfma_f32_16x16x32_bf16 v[58:61], v[154:157], v[162:165], v[58:61]
	v_mfma_f32_16x16x32_bf16 v[46:49], v[142:145], v[170:173], v[46:49]
	v_mfma_f32_16x16x32_bf16 v[42:45], v[154:157], v[170:173], v[42:45]
	v_mfma_f32_16x16x32_bf16 v[30:33], v[142:145], v[182:185], v[30:33]
	v_mfma_f32_16x16x32_bf16 v[26:29], v[154:157], v[182:185], v[26:29]
	v_mfma_f32_16x16x32_bf16 v[14:17], v[142:145], v[190:193], v[14:17]
	v_mfma_f32_16x16x32_bf16 v[10:13], v[154:157], v[190:193], v[10:13]
	v_mfma_f32_16x16x32_bf16 v[62:65], v[150:153], v[166:169], v[62:65]
	v_mfma_f32_16x16x32_bf16 v[58:61], v[158:161], v[166:169], v[58:61]
	v_mfma_f32_16x16x32_bf16 v[46:49], v[150:153], v[174:177], v[46:49]
	v_mfma_f32_16x16x32_bf16 v[42:45], v[158:161], v[174:177], v[42:45]
	v_mfma_f32_16x16x32_bf16 v[30:33], v[150:153], v[186:189], v[30:33]
	v_mfma_f32_16x16x32_bf16 v[26:29], v[158:161], v[186:189], v[26:29]
	v_mfma_f32_16x16x32_bf16 v[14:17], v[150:153], v[194:197], v[14:17]
	v_mfma_f32_16x16x32_bf16 v[10:13], v[158:161], v[194:197], v[10:13]
	s_setprio 0
	s_barrier
	s_add_u32 s76, s26, 0x40000
	s_addc_u32 s77, s27, 0
	s_mov_b32 m0, s37
	v_lshl_add_u64 v[142:143], s[76:77], 0, v[134:135]
	global_load_lds_dwordx4 v[142:143], off
	v_lshl_add_u64 v[142:143], s[76:77], 0, v[130:131]
	s_mov_b32 m0, s38
	s_nop 0
	global_load_lds_dwordx4 v[142:143], off
	s_waitcnt vmcnt(6)
	s_barrier
	s_setprio 1
	v_mfma_f32_16x16x32_bf16 v[54:57], v[198:201], v[162:165], v[54:57]
	v_mfma_f32_16x16x32_bf16 v[50:53], v[206:209], v[162:165], v[50:53]
	v_mfma_f32_16x16x32_bf16 v[38:41], v[198:201], v[170:173], v[38:41]
	v_mfma_f32_16x16x32_bf16 v[34:37], v[206:209], v[170:173], v[34:37]
	v_mfma_f32_16x16x32_bf16 v[22:25], v[198:201], v[182:185], v[22:25]
	v_mfma_f32_16x16x32_bf16 v[18:21], v[206:209], v[182:185], v[18:21]
	v_mfma_f32_16x16x32_bf16 v[6:9], v[198:201], v[190:193], v[6:9]
	v_mfma_f32_16x16x32_bf16 v[2:5], v[206:209], v[190:193], v[2:5]
	v_mfma_f32_16x16x32_bf16 v[54:57], v[202:205], v[166:169], v[54:57]
	v_mfma_f32_16x16x32_bf16 v[50:53], v[210:213], v[166:169], v[50:53]
	v_mfma_f32_16x16x32_bf16 v[38:41], v[202:205], v[174:177], v[38:41]
	v_mfma_f32_16x16x32_bf16 v[34:37], v[210:213], v[174:177], v[34:37]
	v_mfma_f32_16x16x32_bf16 v[22:25], v[202:205], v[186:189], v[22:25]
	v_mfma_f32_16x16x32_bf16 v[18:21], v[210:213], v[186:189], v[18:21]
	v_mfma_f32_16x16x32_bf16 v[6:9], v[202:205], v[194:197], v[6:9]
	v_mfma_f32_16x16x32_bf16 v[2:5], v[210:213], v[194:197], v[2:5]
	s_setprio 0
	v_add_u32_e32 v0, 0x18000, v148
	s_barrier
	s_waitcnt vmcnt(0)
	ds_read_b128 v[142:145], v0
	ds_read_b128 v[150:153], v0 offset:1024
	ds_read_b128 v[154:157], v0 offset:2048
	ds_read_b128 v[158:161], v0 offset:3072
	s_add_u32 s28, s28, 0x40000
	s_addc_u32 s29, s29, 0
	s_mov_b32 m0, s39
	v_lshl_add_u64 v[198:199], s[28:29], 0, v[136:137]
	ds_read_b128 v[162:165], v147 offset:32768
	ds_read_b128 v[166:169], v147 offset:33792
	ds_read_b128 v[170:173], v147 offset:34816
	ds_read_b128 v[174:177], v147 offset:35840
	ds_read_b128 v[182:185], v147 offset:36864
	ds_read_b128 v[186:189], v147 offset:37888
	ds_read_b128 v[190:193], v147 offset:38912
	ds_read_b128 v[194:197], v147 offset:39936
	global_load_lds_dwordx4 v[198:199], off
	v_lshl_add_u64 v[198:199], s[28:29], 0, v[132:133]
	s_mov_b32 m0, s60
	s_nop 0
	global_load_lds_dwordx4 v[198:199], off
	s_waitcnt lgkmcnt(8)
	s_barrier
	s_waitcnt lgkmcnt(0)
	s_setprio 1
	s_waitcnt lgkmcnt(0)
	v_mfma_f32_16x16x32_bf16 v[126:129], v[142:145], v[162:165], v[126:129]
	v_mfma_f32_16x16x32_bf16 v[122:125], v[154:157], v[162:165], v[122:125]
	v_mfma_f32_16x16x32_bf16 v[110:113], v[142:145], v[170:173], v[110:113]
	v_mfma_f32_16x16x32_bf16 v[106:109], v[154:157], v[170:173], v[106:109]
	v_mfma_f32_16x16x32_bf16 v[94:97], v[142:145], v[182:185], v[94:97]
	v_mfma_f32_16x16x32_bf16 v[90:93], v[154:157], v[182:185], v[90:93]
	v_mfma_f32_16x16x32_bf16 v[78:81], v[142:145], v[190:193], v[78:81]
	v_mfma_f32_16x16x32_bf16 v[74:77], v[154:157], v[190:193], v[74:77]
	v_mfma_f32_16x16x32_bf16 v[126:129], v[150:153], v[166:169], v[126:129]
	v_mfma_f32_16x16x32_bf16 v[122:125], v[158:161], v[166:169], v[122:125]
	v_mfma_f32_16x16x32_bf16 v[110:113], v[150:153], v[174:177], v[110:113]
	v_mfma_f32_16x16x32_bf16 v[106:109], v[158:161], v[174:177], v[106:109]
	v_mfma_f32_16x16x32_bf16 v[94:97], v[150:153], v[186:189], v[94:97]
	v_mfma_f32_16x16x32_bf16 v[90:93], v[158:161], v[186:189], v[90:93]
	v_mfma_f32_16x16x32_bf16 v[78:81], v[150:153], v[194:197], v[78:81]
	v_mfma_f32_16x16x32_bf16 v[74:77], v[158:161], v[194:197], v[74:77]
	s_setprio 0
	s_barrier
	s_mov_b32 m0, s68
	v_add_u32_e32 v0, 0x1c000, v148
	v_lshl_add_u64 v[178:179], v[178:179], 0, s[84:85]
	s_waitcnt vmcnt(0)
	ds_read_b128 v[198:201], v0
	ds_read_b128 v[202:205], v0 offset:1024
	ds_read_b128 v[206:209], v0 offset:2048
	ds_read_b128 v[210:213], v0 offset:3072
	global_load_lds_dwordx4 v[178:179], off
	v_lshl_add_u64 v[178:179], v[214:215], 0, s[84:85]
	s_mov_b32 m0, s69
	s_nop 0
	global_load_lds_dwordx4 v[178:179], off
	s_barrier
	s_waitcnt lgkmcnt(0)
	s_setprio 1
	s_waitcnt lgkmcnt(0)
	v_mfma_f32_16x16x32_bf16 v[118:121], v[198:201], v[162:165], v[118:121]
	v_mfma_f32_16x16x32_bf16 v[114:117], v[206:209], v[162:165], v[114:117]
	v_mfma_f32_16x16x32_bf16 v[102:105], v[198:201], v[170:173], v[102:105]
	v_mfma_f32_16x16x32_bf16 v[98:101], v[206:209], v[170:173], v[98:101]
	v_mfma_f32_16x16x32_bf16 v[86:89], v[198:201], v[182:185], v[86:89]
	v_mfma_f32_16x16x32_bf16 v[82:85], v[206:209], v[182:185], v[82:85]
	v_mfma_f32_16x16x32_bf16 v[70:73], v[198:201], v[190:193], v[70:73]
	v_mfma_f32_16x16x32_bf16 v[66:69], v[206:209], v[190:193], v[66:69]
	v_mfma_f32_16x16x32_bf16 v[118:121], v[202:205], v[166:169], v[118:121]
	v_mfma_f32_16x16x32_bf16 v[114:117], v[210:213], v[166:169], v[114:117]
	v_mfma_f32_16x16x32_bf16 v[102:105], v[202:205], v[174:177], v[102:105]
	v_mfma_f32_16x16x32_bf16 v[98:101], v[210:213], v[174:177], v[98:101]
	v_mfma_f32_16x16x32_bf16 v[86:89], v[202:205], v[186:189], v[86:89]
	v_mfma_f32_16x16x32_bf16 v[82:85], v[210:213], v[186:189], v[82:85]
	v_mfma_f32_16x16x32_bf16 v[70:73], v[202:205], v[194:197], v[70:73]
	v_mfma_f32_16x16x32_bf16 v[66:69], v[210:213], v[194:197], v[66:69]
	s_setprio 0
	s_mov_b32 m0, s75
	v_lshl_add_u64 v[178:179], v[216:217], 0, s[84:85]
	s_barrier
	s_waitcnt vmcnt(0)
	ds_read_b128 v[162:165], v147 offset:49152
	ds_read_b128 v[166:169], v147 offset:50176
	ds_read_b128 v[170:173], v147 offset:51200
	ds_read_b128 v[174:177], v147 offset:52224
	ds_read_b128 v[182:185], v147 offset:53248
	ds_read_b128 v[186:189], v147 offset:54272
	ds_read_b128 v[190:193], v147 offset:55296
	ds_read_b128 v[194:197], v147 offset:56320
	global_load_lds_dwordx4 v[178:179], off
	v_lshl_add_u64 v[178:179], v[222:223], 0, s[84:85]
	s_mov_b32 m0, s82
	s_nop 0
	global_load_lds_dwordx4 v[178:179], off
	s_barrier
	s_waitcnt lgkmcnt(0)
	s_setprio 1
	s_waitcnt lgkmcnt(0)
	v_mfma_f32_16x16x32_bf16 v[62:65], v[142:145], v[162:165], v[62:65]
	v_mfma_f32_16x16x32_bf16 v[58:61], v[154:157], v[162:165], v[58:61]
	v_mfma_f32_16x16x32_bf16 v[46:49], v[142:145], v[170:173], v[46:49]
	v_mfma_f32_16x16x32_bf16 v[42:45], v[154:157], v[170:173], v[42:45]
	v_mfma_f32_16x16x32_bf16 v[30:33], v[142:145], v[182:185], v[30:33]
	v_mfma_f32_16x16x32_bf16 v[26:29], v[154:157], v[182:185], v[26:29]
	v_mfma_f32_16x16x32_bf16 v[14:17], v[142:145], v[190:193], v[14:17]
	v_mfma_f32_16x16x32_bf16 v[10:13], v[154:157], v[190:193], v[10:13]
	v_mfma_f32_16x16x32_bf16 v[62:65], v[150:153], v[166:169], v[62:65]
	v_mfma_f32_16x16x32_bf16 v[58:61], v[158:161], v[166:169], v[58:61]
	v_mfma_f32_16x16x32_bf16 v[46:49], v[150:153], v[174:177], v[46:49]
	v_mfma_f32_16x16x32_bf16 v[42:45], v[158:161], v[174:177], v[42:45]
	v_mfma_f32_16x16x32_bf16 v[30:33], v[150:153], v[186:189], v[30:33]
	v_mfma_f32_16x16x32_bf16 v[26:29], v[158:161], v[186:189], v[26:29]
	v_mfma_f32_16x16x32_bf16 v[14:17], v[150:153], v[194:197], v[14:17]
	v_mfma_f32_16x16x32_bf16 v[10:13], v[158:161], v[194:197], v[10:13]
	s_setprio 0
	s_barrier
	s_add_u32 s26, s26, 0x40080
	s_addc_u32 s27, s27, 0
	s_mov_b32 m0, s92
	v_lshl_add_u64 v[142:143], s[26:27], 0, v[134:135]
	global_load_lds_dwordx4 v[142:143], off
	v_lshl_add_u64 v[142:143], s[26:27], 0, v[130:131]
	s_mov_b32 m0, s93
	s_nop 0
	global_load_lds_dwordx4 v[142:143], off
	s_waitcnt vmcnt(6)
	s_barrier
	s_setprio 1
	v_mfma_f32_16x16x32_bf16 v[54:57], v[198:201], v[162:165], v[54:57]
	v_mfma_f32_16x16x32_bf16 v[50:53], v[206:209], v[162:165], v[50:53]
	v_mfma_f32_16x16x32_bf16 v[38:41], v[198:201], v[170:173], v[38:41]
	v_mfma_f32_16x16x32_bf16 v[34:37], v[206:209], v[170:173], v[34:37]
	v_mfma_f32_16x16x32_bf16 v[22:25], v[198:201], v[182:185], v[22:25]
	v_mfma_f32_16x16x32_bf16 v[18:21], v[206:209], v[182:185], v[18:21]
	v_mfma_f32_16x16x32_bf16 v[6:9], v[198:201], v[190:193], v[6:9]
	v_mfma_f32_16x16x32_bf16 v[2:5], v[206:209], v[190:193], v[2:5]
	v_mfma_f32_16x16x32_bf16 v[54:57], v[202:205], v[166:169], v[54:57]
	v_mfma_f32_16x16x32_bf16 v[50:53], v[210:213], v[166:169], v[50:53]
	v_mfma_f32_16x16x32_bf16 v[38:41], v[202:205], v[174:177], v[38:41]
	v_mfma_f32_16x16x32_bf16 v[34:37], v[210:213], v[174:177], v[34:37]
	v_mfma_f32_16x16x32_bf16 v[22:25], v[202:205], v[186:189], v[22:25]
	v_mfma_f32_16x16x32_bf16 v[18:21], v[210:213], v[186:189], v[18:21]
	v_mfma_f32_16x16x32_bf16 v[6:9], v[202:205], v[194:197], v[6:9]
	v_mfma_f32_16x16x32_bf16 v[2:5], v[210:213], v[194:197], v[2:5]
	s_setprio 0
	s_add_i32 s97, s97, 2
	s_add_u32 s24, s24, 0x100
	s_addc_u32 s25, s25, 0
	s_add_u32 s90, s90, 0x100
	s_addc_u32 s94, s94, 0
	s_cmp_gt_u32 s97, 13
	s_barrier
	s_cbranch_scc0 .LBB0_1347
	v_lshl_add_u32 v152, s22, 8, v146
	v_lshl_add_u32 v150, s20, 8, v149
	v_mul_lo_u32 v151, v152, s71
	v_add_u32_e32 v0, v151, v150
	v_lshl_add_u64 v[142:143], v[0:1], 1, s[8:9]
	global_load_dwordx4 v[142:145], v[142:143], off
	s_mov_b32 s20, s12
	s_mov_b32 s22, s14
	s_mov_b64 s[26:27], s[18:19]
	s_waitcnt vmcnt(0)
	v_lshlrev_b32_e32 v153, 16, v142
	v_lshlrev_b32_e32 v155, 16, v143
	v_lshlrev_b32_e32 v156, 16, v144
	v_and_b32_e32 v157, 0xffff0000, v144
	v_lshlrev_b32_e32 v158, 16, v145
	v_and_b32_e32 v159, 0xffff0000, v145
	v_mul_f32_e32 v144, 0xbfb8aa3b, v153
	v_mul_f32_e32 v145, 0xbfb8aa3b, v155
	v_exp_f32_e32 v154, v144
	v_exp_f32_e32 v155, v145
	v_mul_f32_e32 v145, 0xbfb8aa3b, v158
	v_and_b32_e32 v142, 0xffff0000, v142
	v_and_b32_e32 v143, 0xffff0000, v143
	v_pk_add_f32 v[154:155], v[154:155], 1.0 op_sel_hi:[1,0]
	v_mul_f32_e32 v142, 0xbfb8aa3b, v142
	v_mul_f32_e32 v143, 0xbfb8aa3b, v143
	v_mul_f32_e32 v144, 0xbfb8aa3b, v156
	v_exp_f32_e32 v156, v142
	v_mul_f32_e32 v142, 0xbfb8aa3b, v157
	v_exp_f32_e32 v157, v143
	v_mul_f32_e32 v143, 0xbfb8aa3b, v159
	v_rcp_f32_e32 v155, v155
	s_nop 0
	v_pk_add_f32 v[156:157], v[156:157], 1.0 op_sel_hi:[1,0]
	v_exp_f32_e32 v144, v144
	v_exp_f32_e32 v145, v145
	v_mov_b32_e32 v158, v126
	v_mov_b32_e32 v159, v128
	v_rcp_f32_e32 v154, v154
	s_nop 0
	v_pk_mul_f32 v[154:155], v[158:159], v[154:155]
	v_exp_f32_e32 v142, v142
	v_rcp_f32_e32 v157, v157
	s_nop 0
	v_exp_f32_e32 v143, v143
	v_rcp_f32_e32 v156, v156
	s_nop 0
	v_mov_b32_e32 v128, v127
	v_pk_mul_f32 v[126:127], v[128:129], v[156:157]
	v_cvt_pk_bf16_f32 v128, v154, v155
	v_cvt_pk_bf16_f32 v126, v126, v127
	v_and_b32_e32 v127, 0xffff0000, v126
	v_lshlrev_b32_e32 v126, 16, v126
	v_or_b32_sdwa v127, v127, v128 dst_sel:DWORD dst_unused:UNUSED_PAD src0_sel:DWORD src1_sel:WORD_1
	v_or_b32_sdwa v126, v126, v128 dst_sel:DWORD dst_unused:UNUSED_PAD src0_sel:DWORD src1_sel:WORD_0
	v_pk_add_f32 v[128:129], v[144:145], 1.0 op_sel_hi:[1,0]
	v_pk_add_f32 v[142:143], v[142:143], 1.0 op_sel_hi:[1,0]
	s_nop 0
	v_rcp_f32_e32 v129, v129
	s_nop 0
	s_nop 0
	v_rcp_f32_e32 v128, v128
	s_nop 0
	v_mov_b32_e32 v144, v122
	v_mov_b32_e32 v145, v124
	v_pk_mul_f32 v[128:129], v[144:145], v[128:129]
	v_rcp_f32_e32 v143, v143
	s_nop 0
	s_nop 0
	v_rcp_f32_e32 v142, v142
	s_nop 0
	v_mov_b32_e32 v124, v123
	v_pk_mul_f32 v[122:123], v[124:125], v[142:143]
	v_cvt_pk_bf16_f32 v124, v128, v129
	v_cvt_pk_bf16_f32 v122, v122, v123
	v_and_b32_e32 v123, 0xffff0000, v122
	v_lshlrev_b32_e32 v122, 16, v122
	v_or_b32_sdwa v129, v123, v124 dst_sel:DWORD dst_unused:UNUSED_PAD src0_sel:DWORD src1_sel:WORD_1
	v_or_b32_sdwa v128, v122, v124 dst_sel:DWORD dst_unused:UNUSED_PAD src0_sel:DWORD src1_sel:WORD_0
	v_mul_lo_u32 v124, v152, s61
	v_add_u32_e32 v0, v0, v124
	v_add_u32_e32 v125, 0x80, v150
	v_lshl_add_u64 v[122:123], v[0:1], 1, s[6:7]
	v_add_u32_e32 v0, v151, v125
	global_store_dwordx4 v[122:123], v[126:129], off
	v_lshl_add_u64 v[122:123], v[0:1], 1, s[8:9]
	global_load_dwordx4 v[126:129], v[122:123], off
	v_add_u32_e32 v0, v0, v124
	s_waitcnt vmcnt(0)
	v_lshlrev_b32_e32 v122, 16, v126
	v_lshlrev_b32_e32 v143, 16, v127
	v_and_b32_e32 v144, 0xffff0000, v127
	v_lshlrev_b32_e32 v127, 16, v128
	v_mul_f32_e32 v122, 0xbfb8aa3b, v122
	v_and_b32_e32 v123, 0xffff0000, v126
	v_exp_f32_e32 v126, v122
	v_mul_f32_e32 v122, 0xbfb8aa3b, v127
	v_and_b32_e32 v145, 0xffff0000, v128
	v_exp_f32_e32 v128, v122
	v_mul_f32_e32 v122, 0xbfb8aa3b, v123
	v_mul_f32_e32 v123, 0xbfb8aa3b, v143
	v_exp_f32_e32 v127, v123
	v_lshlrev_b32_e32 v153, 16, v129
	v_mul_f32_e32 v123, 0xbfb8aa3b, v153
	v_and_b32_e32 v154, 0xffff0000, v129
	v_pk_add_f32 v[126:127], v[126:127], 1.0 op_sel_hi:[1,0]
	v_exp_f32_e32 v129, v123
	v_mul_f32_e32 v123, 0xbfb8aa3b, v144
	v_exp_f32_e32 v142, v122
	v_mul_f32_e32 v122, 0xbfb8aa3b, v145
	v_exp_f32_e32 v143, v123
	v_mul_f32_e32 v123, 0xbfb8aa3b, v154
	v_exp_f32_e32 v122, v122
	v_rcp_f32_e32 v127, v127
	s_nop 0
	v_pk_add_f32 v[142:143], v[142:143], 1.0 op_sel_hi:[1,0]
	v_exp_f32_e32 v123, v123
	v_rcp_f32_e32 v126, v126
	s_nop 0
	v_mov_b32_e32 v144, v118
	v_mov_b32_e32 v145, v120
	v_pk_mul_f32 v[126:127], v[144:145], v[126:127]
	v_pk_add_f32 v[122:123], v[122:123], 1.0 op_sel_hi:[1,0]
	v_rcp_f32_e32 v143, v143
	s_nop 0
	s_nop 0
	v_rcp_f32_e32 v142, v142
	s_nop 0
	v_mov_b32_e32 v120, v119
	v_pk_mul_f32 v[118:119], v[120:121], v[142:143]
	v_cvt_pk_bf16_f32 v120, v126, v127
	v_cvt_pk_bf16_f32 v118, v118, v119
	v_and_b32_e32 v119, 0xffff0000, v118
	v_lshlrev_b32_e32 v118, 16, v118
	v_or_b32_sdwa v119, v119, v120 dst_sel:DWORD dst_unused:UNUSED_PAD src0_sel:DWORD src1_sel:WORD_1
	v_or_b32_sdwa v118, v118, v120 dst_sel:DWORD dst_unused:UNUSED_PAD src0_sel:DWORD src1_sel:WORD_0
	v_pk_add_f32 v[120:121], v[128:129], 1.0 op_sel_hi:[1,0]
	s_nop 0
	s_nop 0
	v_rcp_f32_e32 v121, v121
	s_nop 0
	s_nop 0
	v_rcp_f32_e32 v120, v120
	s_nop 0
	v_mov_b32_e32 v126, v114
	v_mov_b32_e32 v127, v116
	v_pk_mul_f32 v[120:121], v[126:127], v[120:121]
	v_rcp_f32_e32 v123, v123
	s_nop 0
	s_nop 0
	v_rcp_f32_e32 v122, v122
	s_nop 0
	v_mov_b32_e32 v116, v115
	v_pk_mul_f32 v[114:115], v[116:117], v[122:123]
	v_cvt_pk_bf16_f32 v116, v120, v121
	v_cvt_pk_bf16_f32 v114, v114, v115
	v_and_b32_e32 v115, 0xffff0000, v114
	v_lshlrev_b32_e32 v114, 16, v114
	v_add_u32_e32 v127, 0x16c00, v151
	v_or_b32_sdwa v121, v115, v116 dst_sel:DWORD dst_unused:UNUSED_PAD src0_sel:DWORD src1_sel:WORD_1
	v_or_b32_sdwa v120, v114, v116 dst_sel:DWORD dst_unused:UNUSED_PAD src0_sel:DWORD src1_sel:WORD_0
	v_lshl_add_u64 v[114:115], v[0:1], 1, s[6:7]
	v_add_u32_e32 v0, v127, v150
	global_store_dwordx4 v[114:115], v[118:121], off
	v_lshl_add_u64 v[114:115], v[0:1], 1, s[8:9]
	global_load_dwordx4 v[114:117], v[114:115], off
	v_or_b32_e32 v126, 16, v152
	s_waitcnt vmcnt(0)
	v_lshlrev_b32_e32 v121, 16, v115
	v_and_b32_e32 v122, 0xffff0000, v115
	v_lshlrev_b32_e32 v115, 16, v116
	v_and_b32_e32 v119, 0xffff0000, v114
	v_mul_f32_e32 v115, 0xbfb8aa3b, v115
	v_lshlrev_b32_e32 v118, 16, v114
	v_and_b32_e32 v120, 0xffff0000, v116
	v_exp_f32_e32 v116, v115
	v_mul_f32_e32 v115, 0xbfb8aa3b, v119
	v_mul_f32_e32 v114, 0xbfb8aa3b, v118
	v_exp_f32_e32 v118, v115
	v_mul_f32_e32 v115, 0xbfb8aa3b, v120
	v_exp_f32_e32 v120, v115
	v_mul_f32_e32 v115, 0xbfb8aa3b, v121
	v_exp_f32_e32 v114, v114
	v_exp_f32_e32 v115, v115
	v_lshlrev_b32_e32 v123, 16, v117
	v_mul_f32_e32 v119, 0xbfb8aa3b, v122
	v_and_b32_e32 v128, 0xffff0000, v117
	v_pk_add_f32 v[114:115], v[114:115], 1.0 op_sel_hi:[1,0]
	v_mul_f32_e32 v117, 0xbfb8aa3b, v123
	v_mul_f32_e32 v121, 0xbfb8aa3b, v128
	v_exp_f32_e32 v119, v119
	v_exp_f32_e32 v117, v117
	v_rcp_f32_e32 v115, v115
	s_nop 0
	v_pk_add_f32 v[118:119], v[118:119], 1.0 op_sel_hi:[1,0]
	v_exp_f32_e32 v121, v121
	v_rcp_f32_e32 v114, v114
	s_nop 0
	v_mov_b32_e32 v122, v110
	v_mov_b32_e32 v123, v112
	v_pk_mul_f32 v[114:115], v[122:123], v[114:115]
	v_rcp_f32_e32 v119, v119
	s_nop 0
	s_nop 0
	v_rcp_f32_e32 v118, v118
	s_nop 0
	v_mov_b32_e32 v112, v111
	v_pk_mul_f32 v[110:111], v[112:113], v[118:119]
	v_cvt_pk_bf16_f32 v112, v114, v115
	v_cvt_pk_bf16_f32 v110, v110, v111
	v_and_b32_e32 v111, 0xffff0000, v110
	v_lshlrev_b32_e32 v110, 16, v110
	v_or_b32_sdwa v111, v111, v112 dst_sel:DWORD dst_unused:UNUSED_PAD src0_sel:DWORD src1_sel:WORD_1
	v_or_b32_sdwa v110, v110, v112 dst_sel:DWORD dst_unused:UNUSED_PAD src0_sel:DWORD src1_sel:WORD_0
	v_pk_add_f32 v[112:113], v[116:117], 1.0 op_sel_hi:[1,0]
	s_nop 0
	s_nop 0
	v_rcp_f32_e32 v113, v113
	s_nop 0
	s_nop 0
	v_rcp_f32_e32 v112, v112
	s_nop 0
	v_mov_b32_e32 v114, v106
	v_mov_b32_e32 v115, v108
	v_pk_mul_f32 v[112:113], v[114:115], v[112:113]
	v_pk_add_f32 v[114:115], v[120:121], 1.0 op_sel_hi:[1,0]
	s_nop 0
	s_nop 0
	v_rcp_f32_e32 v115, v115
	s_nop 0
	s_nop 0
	v_rcp_f32_e32 v114, v114
	s_nop 0
	v_mov_b32_e32 v108, v107
	v_pk_mul_f32 v[106:107], v[108:109], v[114:115]
	v_mul_lo_u32 v116, v126, s61
	v_cvt_pk_bf16_f32 v106, v106, v107
	v_cvt_pk_bf16_f32 v108, v112, v113
	v_and_b32_e32 v107, 0xffff0000, v106
	v_lshlrev_b32_e32 v106, 16, v106
	v_add_u32_e32 v0, v0, v116
	v_or_b32_sdwa v113, v107, v108 dst_sel:DWORD dst_unused:UNUSED_PAD src0_sel:DWORD src1_sel:WORD_1
	v_or_b32_sdwa v112, v106, v108 dst_sel:DWORD dst_unused:UNUSED_PAD src0_sel:DWORD src1_sel:WORD_0
	v_lshl_add_u64 v[106:107], v[0:1], 1, s[6:7]
	v_add_u32_e32 v0, v127, v125
	global_store_dwordx4 v[106:107], v[110:113], off
	v_lshl_add_u64 v[106:107], v[0:1], 1, s[8:9]
	global_load_dwordx4 v[106:109], v[106:107], off
	v_add_u32_e32 v0, v0, v116
	s_waitcnt vmcnt(0)
	v_lshlrev_b32_e32 v113, 16, v107
	v_and_b32_e32 v114, 0xffff0000, v107
	v_lshlrev_b32_e32 v107, 16, v108
	v_and_b32_e32 v111, 0xffff0000, v106
	v_mul_f32_e32 v107, 0xbfb8aa3b, v107
	v_lshlrev_b32_e32 v110, 16, v106
	v_and_b32_e32 v112, 0xffff0000, v108
	v_exp_f32_e32 v108, v107
	v_mul_f32_e32 v107, 0xbfb8aa3b, v111
	v_mul_f32_e32 v106, 0xbfb8aa3b, v110
	v_exp_f32_e32 v110, v107
	v_mul_f32_e32 v107, 0xbfb8aa3b, v112
	v_exp_f32_e32 v112, v107
	v_mul_f32_e32 v107, 0xbfb8aa3b, v113
	v_exp_f32_e32 v106, v106
	v_exp_f32_e32 v107, v107
	v_lshlrev_b32_e32 v115, 16, v109
	v_mul_f32_e32 v111, 0xbfb8aa3b, v114
	v_and_b32_e32 v117, 0xffff0000, v109
	v_pk_add_f32 v[106:107], v[106:107], 1.0 op_sel_hi:[1,0]
	v_mul_f32_e32 v109, 0xbfb8aa3b, v115
	v_mul_f32_e32 v113, 0xbfb8aa3b, v117
	v_exp_f32_e32 v111, v111
	v_exp_f32_e32 v109, v109
	v_rcp_f32_e32 v107, v107
	s_nop 0
	v_pk_add_f32 v[110:111], v[110:111], 1.0 op_sel_hi:[1,0]
	v_exp_f32_e32 v113, v113
	v_rcp_f32_e32 v106, v106
	s_nop 0
	v_mov_b32_e32 v114, v102
	v_mov_b32_e32 v115, v104
	v_pk_mul_f32 v[106:107], v[114:115], v[106:107]
	v_rcp_f32_e32 v111, v111
	s_nop 0
	s_nop 0
	v_rcp_f32_e32 v110, v110
	s_nop 0
	v_mov_b32_e32 v104, v103
	v_pk_mul_f32 v[102:103], v[104:105], v[110:111]
	v_cvt_pk_bf16_f32 v104, v106, v107
	v_cvt_pk_bf16_f32 v102, v102, v103
	v_and_b32_e32 v103, 0xffff0000, v102
	v_lshlrev_b32_e32 v102, 16, v102
	v_or_b32_sdwa v103, v103, v104 dst_sel:DWORD dst_unused:UNUSED_PAD src0_sel:DWORD src1_sel:WORD_1
	v_or_b32_sdwa v102, v102, v104 dst_sel:DWORD dst_unused:UNUSED_PAD src0_sel:DWORD src1_sel:WORD_0
	v_pk_add_f32 v[104:105], v[108:109], 1.0 op_sel_hi:[1,0]
	s_nop 0
	s_nop 0
	v_rcp_f32_e32 v105, v105
	s_nop 0
	s_nop 0
	v_rcp_f32_e32 v104, v104
	s_nop 0
	v_mov_b32_e32 v106, v98
	v_mov_b32_e32 v107, v100
	v_pk_mul_f32 v[104:105], v[106:107], v[104:105]
	v_pk_add_f32 v[106:107], v[112:113], 1.0 op_sel_hi:[1,0]
	s_nop 0
	s_nop 0
	v_rcp_f32_e32 v107, v107
	s_nop 0
	s_nop 0
	v_rcp_f32_e32 v106, v106
	s_nop 0
	v_mov_b32_e32 v100, v99
	v_pk_mul_f32 v[98:99], v[100:101], v[106:107]
	v_cvt_pk_bf16_f32 v100, v104, v105
	v_cvt_pk_bf16_f32 v98, v98, v99
	v_and_b32_e32 v99, 0xffff0000, v98
	v_lshlrev_b32_e32 v98, 16, v98
	v_add_u32_e32 v109, 0x2d800, v151
	v_or_b32_sdwa v105, v99, v100 dst_sel:DWORD dst_unused:UNUSED_PAD src0_sel:DWORD src1_sel:WORD_1
	v_or_b32_sdwa v104, v98, v100 dst_sel:DWORD dst_unused:UNUSED_PAD src0_sel:DWORD src1_sel:WORD_0
	v_lshl_add_u64 v[98:99], v[0:1], 1, s[6:7]
	v_add_u32_e32 v0, v109, v150
	global_store_dwordx4 v[98:99], v[102:105], off
	v_lshl_add_u64 v[98:99], v[0:1], 1, s[8:9]
	global_load_dwordx4 v[98:101], v[98:99], off
	v_or_b32_e32 v108, 32, v152
	s_waitcnt vmcnt(0)
	v_lshlrev_b32_e32 v105, 16, v99
	v_and_b32_e32 v106, 0xffff0000, v99
	v_lshlrev_b32_e32 v99, 16, v100
	v_and_b32_e32 v103, 0xffff0000, v98
	v_mul_f32_e32 v99, 0xbfb8aa3b, v99
	v_lshlrev_b32_e32 v102, 16, v98
	v_and_b32_e32 v104, 0xffff0000, v100
	v_exp_f32_e32 v100, v99
	v_mul_f32_e32 v99, 0xbfb8aa3b, v103
	v_mul_f32_e32 v98, 0xbfb8aa3b, v102
	v_exp_f32_e32 v102, v99
	v_mul_f32_e32 v99, 0xbfb8aa3b, v104
	v_exp_f32_e32 v104, v99
	v_mul_f32_e32 v99, 0xbfb8aa3b, v105
	v_exp_f32_e32 v98, v98
	v_exp_f32_e32 v99, v99
	v_lshlrev_b32_e32 v107, 16, v101
	v_mul_f32_e32 v103, 0xbfb8aa3b, v106
	v_and_b32_e32 v110, 0xffff0000, v101
	v_pk_add_f32 v[98:99], v[98:99], 1.0 op_sel_hi:[1,0]
	v_mul_f32_e32 v101, 0xbfb8aa3b, v107
	v_mul_f32_e32 v105, 0xbfb8aa3b, v110
	v_exp_f32_e32 v103, v103
	v_exp_f32_e32 v101, v101
	v_rcp_f32_e32 v99, v99
	s_nop 0
	v_pk_add_f32 v[102:103], v[102:103], 1.0 op_sel_hi:[1,0]
	v_exp_f32_e32 v105, v105
	v_rcp_f32_e32 v98, v98
	s_nop 0
	v_mov_b32_e32 v106, v94
	v_mov_b32_e32 v107, v96
	v_pk_mul_f32 v[98:99], v[106:107], v[98:99]
	v_rcp_f32_e32 v103, v103
	s_nop 0
	s_nop 0
	v_rcp_f32_e32 v102, v102
	s_nop 0
	v_mov_b32_e32 v96, v95
	v_pk_mul_f32 v[94:95], v[96:97], v[102:103]
	v_cvt_pk_bf16_f32 v96, v98, v99
	v_cvt_pk_bf16_f32 v94, v94, v95
	v_and_b32_e32 v95, 0xffff0000, v94
	v_lshlrev_b32_e32 v94, 16, v94
	v_or_b32_sdwa v95, v95, v96 dst_sel:DWORD dst_unused:UNUSED_PAD src0_sel:DWORD src1_sel:WORD_1
	v_or_b32_sdwa v94, v94, v96 dst_sel:DWORD dst_unused:UNUSED_PAD src0_sel:DWORD src1_sel:WORD_0
	v_pk_add_f32 v[96:97], v[100:101], 1.0 op_sel_hi:[1,0]
	s_nop 0
	s_nop 0
	v_rcp_f32_e32 v97, v97
	s_nop 0
	s_nop 0
	v_rcp_f32_e32 v96, v96
	s_nop 0
	v_mov_b32_e32 v98, v90
	v_mov_b32_e32 v99, v92
	v_pk_mul_f32 v[96:97], v[98:99], v[96:97]
	v_pk_add_f32 v[98:99], v[104:105], 1.0 op_sel_hi:[1,0]
	s_nop 0
	s_nop 0
	v_rcp_f32_e32 v99, v99
	s_nop 0
	s_nop 0
	v_rcp_f32_e32 v98, v98
	s_nop 0
	v_mov_b32_e32 v92, v91
	v_pk_mul_f32 v[90:91], v[92:93], v[98:99]
	v_mul_lo_u32 v100, v108, s61
	v_cvt_pk_bf16_f32 v90, v90, v91
	v_cvt_pk_bf16_f32 v92, v96, v97
	v_and_b32_e32 v91, 0xffff0000, v90
	v_lshlrev_b32_e32 v90, 16, v90
	v_add_u32_e32 v0, v0, v100
	v_or_b32_sdwa v97, v91, v92 dst_sel:DWORD dst_unused:UNUSED_PAD src0_sel:DWORD src1_sel:WORD_1
	v_or_b32_sdwa v96, v90, v92 dst_sel:DWORD dst_unused:UNUSED_PAD src0_sel:DWORD src1_sel:WORD_0
	v_lshl_add_u64 v[90:91], v[0:1], 1, s[6:7]
	v_add_u32_e32 v0, v109, v125
	global_store_dwordx4 v[90:91], v[94:97], off
	v_lshl_add_u64 v[90:91], v[0:1], 1, s[8:9]
	global_load_dwordx4 v[90:93], v[90:91], off
	v_add_u32_e32 v0, v0, v100
	s_waitcnt vmcnt(0)
	v_lshlrev_b32_e32 v97, 16, v91
	v_and_b32_e32 v98, 0xffff0000, v91
	v_lshlrev_b32_e32 v91, 16, v92
	v_and_b32_e32 v95, 0xffff0000, v90
	v_mul_f32_e32 v91, 0xbfb8aa3b, v91
	v_lshlrev_b32_e32 v94, 16, v90
	v_and_b32_e32 v96, 0xffff0000, v92
	v_exp_f32_e32 v92, v91
	v_mul_f32_e32 v91, 0xbfb8aa3b, v95
	v_mul_f32_e32 v90, 0xbfb8aa3b, v94
	v_exp_f32_e32 v94, v91
	v_mul_f32_e32 v91, 0xbfb8aa3b, v96
	v_exp_f32_e32 v96, v91
	v_mul_f32_e32 v91, 0xbfb8aa3b, v97
	v_exp_f32_e32 v90, v90
	v_exp_f32_e32 v91, v91
	v_lshlrev_b32_e32 v99, 16, v93
	v_mul_f32_e32 v95, 0xbfb8aa3b, v98
	v_and_b32_e32 v101, 0xffff0000, v93
	v_pk_add_f32 v[90:91], v[90:91], 1.0 op_sel_hi:[1,0]
	v_mul_f32_e32 v93, 0xbfb8aa3b, v99
	v_mul_f32_e32 v97, 0xbfb8aa3b, v101
	v_exp_f32_e32 v95, v95
	v_exp_f32_e32 v93, v93
	v_rcp_f32_e32 v91, v91
	s_nop 0
	v_pk_add_f32 v[94:95], v[94:95], 1.0 op_sel_hi:[1,0]
	v_exp_f32_e32 v97, v97
	v_rcp_f32_e32 v90, v90
	s_nop 0
	v_mov_b32_e32 v98, v86
	v_mov_b32_e32 v99, v88
	v_pk_mul_f32 v[90:91], v[98:99], v[90:91]
	v_rcp_f32_e32 v95, v95
	s_nop 0
	s_nop 0
	v_rcp_f32_e32 v94, v94
	s_nop 0
	v_mov_b32_e32 v88, v87
	v_pk_mul_f32 v[86:87], v[88:89], v[94:95]
	v_cvt_pk_bf16_f32 v88, v90, v91
	v_cvt_pk_bf16_f32 v86, v86, v87
	v_and_b32_e32 v87, 0xffff0000, v86
	v_lshlrev_b32_e32 v86, 16, v86
	v_or_b32_sdwa v87, v87, v88 dst_sel:DWORD dst_unused:UNUSED_PAD src0_sel:DWORD src1_sel:WORD_1
	v_or_b32_sdwa v86, v86, v88 dst_sel:DWORD dst_unused:UNUSED_PAD src0_sel:DWORD src1_sel:WORD_0
	v_pk_add_f32 v[88:89], v[92:93], 1.0 op_sel_hi:[1,0]
	s_nop 0
	s_nop 0
	v_rcp_f32_e32 v89, v89
	s_nop 0
	s_nop 0
	v_rcp_f32_e32 v88, v88
	s_nop 0
	v_mov_b32_e32 v90, v82
	v_mov_b32_e32 v91, v84
	v_pk_mul_f32 v[88:89], v[90:91], v[88:89]
	v_pk_add_f32 v[90:91], v[96:97], 1.0 op_sel_hi:[1,0]
	s_nop 0
	s_nop 0
	v_rcp_f32_e32 v91, v91
	s_nop 0
	s_nop 0
	v_rcp_f32_e32 v90, v90
	s_nop 0
	v_mov_b32_e32 v84, v83
	v_pk_mul_f32 v[82:83], v[84:85], v[90:91]
	v_cvt_pk_bf16_f32 v84, v88, v89
	v_cvt_pk_bf16_f32 v82, v82, v83
	v_and_b32_e32 v83, 0xffff0000, v82
	v_lshlrev_b32_e32 v82, 16, v82
	v_add_u32_e32 v93, 0x44400, v151
	v_or_b32_sdwa v89, v83, v84 dst_sel:DWORD dst_unused:UNUSED_PAD src0_sel:DWORD src1_sel:WORD_1
	v_or_b32_sdwa v88, v82, v84 dst_sel:DWORD dst_unused:UNUSED_PAD src0_sel:DWORD src1_sel:WORD_0
	v_lshl_add_u64 v[82:83], v[0:1], 1, s[6:7]
	v_add_u32_e32 v0, v93, v150
	global_store_dwordx4 v[82:83], v[86:89], off
	v_lshl_add_u64 v[82:83], v[0:1], 1, s[8:9]
	global_load_dwordx4 v[82:85], v[82:83], off
	v_or_b32_e32 v92, 48, v152
	s_waitcnt vmcnt(0)
	v_lshlrev_b32_e32 v89, 16, v83
	v_and_b32_e32 v90, 0xffff0000, v83
	v_lshlrev_b32_e32 v83, 16, v84
	v_and_b32_e32 v87, 0xffff0000, v82
	v_mul_f32_e32 v83, 0xbfb8aa3b, v83
	v_lshlrev_b32_e32 v86, 16, v82
	v_and_b32_e32 v88, 0xffff0000, v84
	v_exp_f32_e32 v84, v83
	v_mul_f32_e32 v83, 0xbfb8aa3b, v87
	v_mul_f32_e32 v82, 0xbfb8aa3b, v86
	v_exp_f32_e32 v86, v83
	v_mul_f32_e32 v83, 0xbfb8aa3b, v88
	v_exp_f32_e32 v88, v83
	v_mul_f32_e32 v83, 0xbfb8aa3b, v89
	v_exp_f32_e32 v82, v82
	v_exp_f32_e32 v83, v83
	v_lshlrev_b32_e32 v91, 16, v85
	v_mul_f32_e32 v87, 0xbfb8aa3b, v90
	v_and_b32_e32 v94, 0xffff0000, v85
	v_pk_add_f32 v[82:83], v[82:83], 1.0 op_sel_hi:[1,0]
	v_mul_f32_e32 v85, 0xbfb8aa3b, v91
	v_mul_f32_e32 v89, 0xbfb8aa3b, v94
	v_exp_f32_e32 v87, v87
	v_exp_f32_e32 v85, v85
	v_rcp_f32_e32 v83, v83
	s_nop 0
	v_pk_add_f32 v[86:87], v[86:87], 1.0 op_sel_hi:[1,0]
	v_exp_f32_e32 v89, v89
	v_rcp_f32_e32 v82, v82
	s_nop 0
	v_mov_b32_e32 v90, v78
	v_mov_b32_e32 v91, v80
	v_pk_mul_f32 v[82:83], v[90:91], v[82:83]
	v_rcp_f32_e32 v87, v87
	s_nop 0
	s_nop 0
	v_rcp_f32_e32 v86, v86
	s_nop 0
	v_mov_b32_e32 v80, v79
	v_pk_mul_f32 v[78:79], v[80:81], v[86:87]
	v_cvt_pk_bf16_f32 v80, v82, v83
	v_cvt_pk_bf16_f32 v78, v78, v79
	v_and_b32_e32 v79, 0xffff0000, v78
	v_lshlrev_b32_e32 v78, 16, v78
	v_or_b32_sdwa v79, v79, v80 dst_sel:DWORD dst_unused:UNUSED_PAD src0_sel:DWORD src1_sel:WORD_1
	v_or_b32_sdwa v78, v78, v80 dst_sel:DWORD dst_unused:UNUSED_PAD src0_sel:DWORD src1_sel:WORD_0
	v_pk_add_f32 v[80:81], v[84:85], 1.0 op_sel_hi:[1,0]
	s_nop 0
	s_nop 0
	v_rcp_f32_e32 v81, v81
	s_nop 0
	s_nop 0
	v_rcp_f32_e32 v80, v80
	s_nop 0
	v_mov_b32_e32 v82, v74
	v_mov_b32_e32 v83, v76
	v_pk_mul_f32 v[80:81], v[82:83], v[80:81]
	v_pk_add_f32 v[82:83], v[88:89], 1.0 op_sel_hi:[1,0]
	s_nop 0
	s_nop 0
	v_rcp_f32_e32 v83, v83
	s_nop 0
	s_nop 0
	v_rcp_f32_e32 v82, v82
	s_nop 0
	v_mov_b32_e32 v76, v75
	v_pk_mul_f32 v[74:75], v[76:77], v[82:83]
	v_mul_lo_u32 v84, v92, s61
	v_cvt_pk_bf16_f32 v74, v74, v75
	v_cvt_pk_bf16_f32 v76, v80, v81
	v_and_b32_e32 v75, 0xffff0000, v74
	v_lshlrev_b32_e32 v74, 16, v74
	v_add_u32_e32 v0, v0, v84
	v_or_b32_sdwa v81, v75, v76 dst_sel:DWORD dst_unused:UNUSED_PAD src0_sel:DWORD src1_sel:WORD_1
	v_or_b32_sdwa v80, v74, v76 dst_sel:DWORD dst_unused:UNUSED_PAD src0_sel:DWORD src1_sel:WORD_0
	v_lshl_add_u64 v[74:75], v[0:1], 1, s[6:7]
	v_add_u32_e32 v0, v93, v125
	global_store_dwordx4 v[74:75], v[78:81], off
	v_lshl_add_u64 v[74:75], v[0:1], 1, s[8:9]
	global_load_dwordx4 v[74:77], v[74:75], off
	v_add_u32_e32 v0, v0, v84
	s_waitcnt vmcnt(0)
	v_lshlrev_b32_e32 v81, 16, v75
	v_and_b32_e32 v82, 0xffff0000, v75
	v_lshlrev_b32_e32 v75, 16, v76
	v_and_b32_e32 v79, 0xffff0000, v74
	v_mul_f32_e32 v75, 0xbfb8aa3b, v75
	v_lshlrev_b32_e32 v78, 16, v74
	v_and_b32_e32 v80, 0xffff0000, v76
	v_exp_f32_e32 v76, v75
	v_mul_f32_e32 v75, 0xbfb8aa3b, v79
	v_mul_f32_e32 v74, 0xbfb8aa3b, v78
	v_exp_f32_e32 v78, v75
	v_mul_f32_e32 v75, 0xbfb8aa3b, v80
	v_exp_f32_e32 v80, v75
	v_mul_f32_e32 v75, 0xbfb8aa3b, v81
	v_exp_f32_e32 v74, v74
	v_exp_f32_e32 v75, v75
	v_lshlrev_b32_e32 v83, 16, v77
	v_mul_f32_e32 v79, 0xbfb8aa3b, v82
	v_and_b32_e32 v85, 0xffff0000, v77
	v_pk_add_f32 v[74:75], v[74:75], 1.0 op_sel_hi:[1,0]
	v_mul_f32_e32 v77, 0xbfb8aa3b, v83
	v_mul_f32_e32 v81, 0xbfb8aa3b, v85
	v_exp_f32_e32 v79, v79
	v_exp_f32_e32 v77, v77
	v_rcp_f32_e32 v75, v75
	s_nop 0
	v_pk_add_f32 v[78:79], v[78:79], 1.0 op_sel_hi:[1,0]
	v_exp_f32_e32 v81, v81
	v_rcp_f32_e32 v74, v74
	s_nop 0
	v_mov_b32_e32 v82, v70
	v_mov_b32_e32 v83, v72
	v_pk_mul_f32 v[74:75], v[82:83], v[74:75]
	v_rcp_f32_e32 v79, v79
	s_nop 0
	s_nop 0
	v_rcp_f32_e32 v78, v78
	s_nop 0
	v_mov_b32_e32 v72, v71
	v_pk_mul_f32 v[70:71], v[72:73], v[78:79]
	v_cvt_pk_bf16_f32 v72, v74, v75
	v_cvt_pk_bf16_f32 v70, v70, v71
	v_and_b32_e32 v71, 0xffff0000, v70
	v_lshlrev_b32_e32 v70, 16, v70
	v_or_b32_sdwa v71, v71, v72 dst_sel:DWORD dst_unused:UNUSED_PAD src0_sel:DWORD src1_sel:WORD_1
	v_or_b32_sdwa v70, v70, v72 dst_sel:DWORD dst_unused:UNUSED_PAD src0_sel:DWORD src1_sel:WORD_0
	v_pk_add_f32 v[72:73], v[76:77], 1.0 op_sel_hi:[1,0]
	s_nop 0
	s_nop 0
	v_rcp_f32_e32 v73, v73
	s_nop 0
	s_nop 0
	v_rcp_f32_e32 v72, v72
	s_nop 0
	v_mov_b32_e32 v74, v66
	v_mov_b32_e32 v75, v68
	v_pk_mul_f32 v[72:73], v[74:75], v[72:73]
	v_pk_add_f32 v[74:75], v[80:81], 1.0 op_sel_hi:[1,0]
	s_nop 0
	s_nop 0
	v_rcp_f32_e32 v75, v75
	s_nop 0
	s_nop 0
	v_rcp_f32_e32 v74, v74
	s_nop 0
	v_mov_b32_e32 v68, v67
	v_pk_mul_f32 v[66:67], v[68:69], v[74:75]
	v_cvt_pk_bf16_f32 v68, v72, v73
	v_cvt_pk_bf16_f32 v66, v66, v67
	v_and_b32_e32 v67, 0xffff0000, v66
	v_lshlrev_b32_e32 v66, 16, v66
	v_add_u32_e32 v76, 0xb6000, v151
	v_or_b32_sdwa v73, v67, v68 dst_sel:DWORD dst_unused:UNUSED_PAD src0_sel:DWORD src1_sel:WORD_1
	v_or_b32_sdwa v72, v66, v68 dst_sel:DWORD dst_unused:UNUSED_PAD src0_sel:DWORD src1_sel:WORD_0
	v_lshl_add_u64 v[66:67], v[0:1], 1, s[6:7]
	v_add_u32_e32 v0, v76, v150
	global_store_dwordx4 v[66:67], v[70:73], off
	v_lshl_add_u64 v[66:67], v[0:1], 1, s[8:9]
	global_load_dwordx4 v[66:69], v[66:67], off
	s_waitcnt vmcnt(0)
	v_lshlrev_b32_e32 v73, 16, v67
	v_and_b32_e32 v74, 0xffff0000, v67
	v_lshlrev_b32_e32 v67, 16, v68
	v_and_b32_e32 v71, 0xffff0000, v66
	v_mul_f32_e32 v67, 0xbfb8aa3b, v67
	v_lshlrev_b32_e32 v70, 16, v66
	v_and_b32_e32 v72, 0xffff0000, v68
	v_exp_f32_e32 v68, v67
	v_mul_f32_e32 v67, 0xbfb8aa3b, v71
	v_mul_f32_e32 v66, 0xbfb8aa3b, v70
	v_exp_f32_e32 v70, v67
	v_mul_f32_e32 v67, 0xbfb8aa3b, v72
	v_exp_f32_e32 v72, v67
	v_mul_f32_e32 v67, 0xbfb8aa3b, v73
	v_exp_f32_e32 v66, v66
	v_exp_f32_e32 v67, v67
	v_lshlrev_b32_e32 v75, 16, v69
	v_mul_f32_e32 v71, 0xbfb8aa3b, v74
	v_and_b32_e32 v77, 0xffff0000, v69
	v_pk_add_f32 v[66:67], v[66:67], 1.0 op_sel_hi:[1,0]
	v_mul_f32_e32 v69, 0xbfb8aa3b, v75
	v_mul_f32_e32 v73, 0xbfb8aa3b, v77
	v_exp_f32_e32 v71, v71
	v_exp_f32_e32 v69, v69
	v_rcp_f32_e32 v67, v67
	s_nop 0
	v_pk_add_f32 v[70:71], v[70:71], 1.0 op_sel_hi:[1,0]
	v_exp_f32_e32 v73, v73
	v_rcp_f32_e32 v66, v66
	s_nop 0
	v_mov_b32_e32 v74, v62
	v_mov_b32_e32 v75, v64
	v_pk_mul_f32 v[66:67], v[74:75], v[66:67]
	v_rcp_f32_e32 v71, v71
	s_nop 0
	s_nop 0
	v_rcp_f32_e32 v70, v70
	s_nop 0
	v_mov_b32_e32 v64, v63
	v_pk_mul_f32 v[62:63], v[64:65], v[70:71]
	v_cvt_pk_bf16_f32 v64, v66, v67
	v_cvt_pk_bf16_f32 v62, v62, v63
	v_and_b32_e32 v63, 0xffff0000, v62
	v_lshlrev_b32_e32 v62, 16, v62
	v_or_b32_sdwa v63, v63, v64 dst_sel:DWORD dst_unused:UNUSED_PAD src0_sel:DWORD src1_sel:WORD_1
	v_or_b32_sdwa v62, v62, v64 dst_sel:DWORD dst_unused:UNUSED_PAD src0_sel:DWORD src1_sel:WORD_0
	v_pk_add_f32 v[64:65], v[68:69], 1.0 op_sel_hi:[1,0]
	s_nop 0
	s_nop 0
	v_rcp_f32_e32 v65, v65
	s_nop 0
	s_nop 0
	v_rcp_f32_e32 v64, v64
	s_nop 0
	v_mov_b32_e32 v66, v58
	v_mov_b32_e32 v67, v60
	v_pk_mul_f32 v[64:65], v[66:67], v[64:65]
	v_pk_add_f32 v[66:67], v[72:73], 1.0 op_sel_hi:[1,0]
	s_nop 0
	s_nop 0
	v_rcp_f32_e32 v67, v67
	s_nop 0
	s_nop 0
	v_rcp_f32_e32 v66, v66
	s_nop 0
	v_mov_b32_e32 v60, v59
	v_pk_mul_f32 v[58:59], v[60:61], v[66:67]
	v_add_u32_e32 v68, 0xfff6a000, v124
	v_cvt_pk_bf16_f32 v58, v58, v59
	v_cvt_pk_bf16_f32 v60, v64, v65
	v_and_b32_e32 v59, 0xffff0000, v58
	v_lshlrev_b32_e32 v58, 16, v58
	v_add_u32_e32 v0, v0, v68
	v_or_b32_sdwa v65, v59, v60 dst_sel:DWORD dst_unused:UNUSED_PAD src0_sel:DWORD src1_sel:WORD_1
	v_or_b32_sdwa v64, v58, v60 dst_sel:DWORD dst_unused:UNUSED_PAD src0_sel:DWORD src1_sel:WORD_0
	v_lshl_add_u64 v[58:59], v[0:1], 1, s[6:7]
	v_add_u32_e32 v0, v76, v125
	global_store_dwordx4 v[58:59], v[62:65], off
	v_lshl_add_u64 v[58:59], v[0:1], 1, s[8:9]
	global_load_dwordx4 v[58:61], v[58:59], off
	v_add_u32_e32 v0, v0, v68
	s_waitcnt vmcnt(0)
	v_lshlrev_b32_e32 v65, 16, v59
	v_and_b32_e32 v66, 0xffff0000, v59
	v_lshlrev_b32_e32 v59, 16, v60
	v_and_b32_e32 v63, 0xffff0000, v58
	v_mul_f32_e32 v59, 0xbfb8aa3b, v59
	v_lshlrev_b32_e32 v62, 16, v58
	v_and_b32_e32 v64, 0xffff0000, v60
	v_exp_f32_e32 v60, v59
	v_mul_f32_e32 v59, 0xbfb8aa3b, v63
	v_mul_f32_e32 v58, 0xbfb8aa3b, v62
	v_exp_f32_e32 v62, v59
	v_mul_f32_e32 v59, 0xbfb8aa3b, v64
	v_exp_f32_e32 v64, v59
	v_mul_f32_e32 v59, 0xbfb8aa3b, v65
	v_exp_f32_e32 v58, v58
	v_exp_f32_e32 v59, v59
	v_lshlrev_b32_e32 v67, 16, v61
	v_mul_f32_e32 v63, 0xbfb8aa3b, v66
	v_and_b32_e32 v69, 0xffff0000, v61
	v_pk_add_f32 v[58:59], v[58:59], 1.0 op_sel_hi:[1,0]
	v_mul_f32_e32 v61, 0xbfb8aa3b, v67
	v_mul_f32_e32 v65, 0xbfb8aa3b, v69
	v_exp_f32_e32 v63, v63
	v_exp_f32_e32 v61, v61
	v_rcp_f32_e32 v59, v59
	s_nop 0
	v_pk_add_f32 v[62:63], v[62:63], 1.0 op_sel_hi:[1,0]
	v_exp_f32_e32 v65, v65
	v_rcp_f32_e32 v58, v58
	s_nop 0
	v_mov_b32_e32 v66, v54
	v_mov_b32_e32 v67, v56
	v_pk_mul_f32 v[58:59], v[66:67], v[58:59]
	v_rcp_f32_e32 v63, v63
	s_nop 0
	s_nop 0
	v_rcp_f32_e32 v62, v62
	s_nop 0
	v_mov_b32_e32 v56, v55
	v_pk_mul_f32 v[54:55], v[56:57], v[62:63]
	v_cvt_pk_bf16_f32 v56, v58, v59
	v_cvt_pk_bf16_f32 v54, v54, v55
	v_and_b32_e32 v55, 0xffff0000, v54
	v_lshlrev_b32_e32 v54, 16, v54
	v_or_b32_sdwa v55, v55, v56 dst_sel:DWORD dst_unused:UNUSED_PAD src0_sel:DWORD src1_sel:WORD_1
	v_or_b32_sdwa v54, v54, v56 dst_sel:DWORD dst_unused:UNUSED_PAD src0_sel:DWORD src1_sel:WORD_0
	v_pk_add_f32 v[56:57], v[60:61], 1.0 op_sel_hi:[1,0]
	s_nop 0
	s_nop 0
	v_rcp_f32_e32 v57, v57
	s_nop 0
	s_nop 0
	v_rcp_f32_e32 v56, v56
	s_nop 0
	v_mov_b32_e32 v58, v50
	v_mov_b32_e32 v59, v52
	v_pk_mul_f32 v[56:57], v[58:59], v[56:57]
	v_pk_add_f32 v[58:59], v[64:65], 1.0 op_sel_hi:[1,0]
	s_nop 0
	s_nop 0
	v_rcp_f32_e32 v59, v59
	s_nop 0
	s_nop 0
	v_rcp_f32_e32 v58, v58
	s_nop 0
	v_mov_b32_e32 v52, v51
	v_pk_mul_f32 v[50:51], v[52:53], v[58:59]
	v_cvt_pk_bf16_f32 v52, v56, v57
	v_cvt_pk_bf16_f32 v50, v50, v51
	v_and_b32_e32 v51, 0xffff0000, v50
	v_lshlrev_b32_e32 v50, 16, v50
	v_add_u32_e32 v60, 0xccc00, v151
	v_or_b32_sdwa v57, v51, v52 dst_sel:DWORD dst_unused:UNUSED_PAD src0_sel:DWORD src1_sel:WORD_1
	v_or_b32_sdwa v56, v50, v52 dst_sel:DWORD dst_unused:UNUSED_PAD src0_sel:DWORD src1_sel:WORD_0
	v_lshl_add_u64 v[50:51], v[0:1], 1, s[6:7]
	v_add_u32_e32 v0, v60, v150
	global_store_dwordx4 v[50:51], v[54:57], off
	v_lshl_add_u64 v[50:51], v[0:1], 1, s[8:9]
	global_load_dwordx4 v[50:53], v[50:51], off
	s_waitcnt vmcnt(0)
	v_lshlrev_b32_e32 v57, 16, v51
	v_and_b32_e32 v58, 0xffff0000, v51
	v_lshlrev_b32_e32 v51, 16, v52
	v_and_b32_e32 v55, 0xffff0000, v50
	v_mul_f32_e32 v51, 0xbfb8aa3b, v51
	v_lshlrev_b32_e32 v54, 16, v50
	v_and_b32_e32 v56, 0xffff0000, v52
	v_exp_f32_e32 v52, v51
	v_mul_f32_e32 v51, 0xbfb8aa3b, v55
	v_mul_f32_e32 v50, 0xbfb8aa3b, v54
	v_exp_f32_e32 v54, v51
	v_mul_f32_e32 v51, 0xbfb8aa3b, v56
	v_exp_f32_e32 v56, v51
	v_mul_f32_e32 v51, 0xbfb8aa3b, v57
	v_exp_f32_e32 v50, v50
	v_exp_f32_e32 v51, v51
	v_lshlrev_b32_e32 v59, 16, v53
	v_mul_f32_e32 v55, 0xbfb8aa3b, v58
	v_and_b32_e32 v61, 0xffff0000, v53
	v_pk_add_f32 v[50:51], v[50:51], 1.0 op_sel_hi:[1,0]
	v_mul_f32_e32 v53, 0xbfb8aa3b, v59
	v_mul_f32_e32 v57, 0xbfb8aa3b, v61
	v_exp_f32_e32 v55, v55
	v_exp_f32_e32 v53, v53
	v_rcp_f32_e32 v51, v51
	s_nop 0
	v_pk_add_f32 v[54:55], v[54:55], 1.0 op_sel_hi:[1,0]
	v_exp_f32_e32 v57, v57
	v_rcp_f32_e32 v50, v50
	s_nop 0
	v_mov_b32_e32 v58, v46
	v_mov_b32_e32 v59, v48
	v_pk_mul_f32 v[50:51], v[58:59], v[50:51]
	v_rcp_f32_e32 v55, v55
	s_nop 0
	s_nop 0
	v_rcp_f32_e32 v54, v54
	s_nop 0
	v_mov_b32_e32 v48, v47
	v_pk_mul_f32 v[46:47], v[48:49], v[54:55]
	v_cvt_pk_bf16_f32 v48, v50, v51
	v_cvt_pk_bf16_f32 v46, v46, v47
	v_and_b32_e32 v47, 0xffff0000, v46
	v_lshlrev_b32_e32 v46, 16, v46
	v_or_b32_sdwa v47, v47, v48 dst_sel:DWORD dst_unused:UNUSED_PAD src0_sel:DWORD src1_sel:WORD_1
	v_or_b32_sdwa v46, v46, v48 dst_sel:DWORD dst_unused:UNUSED_PAD src0_sel:DWORD src1_sel:WORD_0
	v_pk_add_f32 v[48:49], v[52:53], 1.0 op_sel_hi:[1,0]
	s_nop 0
	s_nop 0
	v_rcp_f32_e32 v49, v49
	s_nop 0
	s_nop 0
	v_rcp_f32_e32 v48, v48
	s_nop 0
	v_mov_b32_e32 v50, v42
	v_mov_b32_e32 v51, v44
	v_pk_mul_f32 v[48:49], v[50:51], v[48:49]
	v_pk_add_f32 v[50:51], v[56:57], 1.0 op_sel_hi:[1,0]
	s_nop 0
	s_nop 0
	v_rcp_f32_e32 v51, v51
	s_nop 0
	s_nop 0
	v_rcp_f32_e32 v50, v50
	s_nop 0
	v_mov_b32_e32 v44, v43
	v_pk_mul_f32 v[42:43], v[44:45], v[50:51]
	v_add_u32_e32 v52, 0xfff57400, v124
	v_cvt_pk_bf16_f32 v42, v42, v43
	v_cvt_pk_bf16_f32 v44, v48, v49
	v_and_b32_e32 v43, 0xffff0000, v42
	v_lshlrev_b32_e32 v42, 16, v42
	v_add_u32_e32 v0, v0, v52
	v_or_b32_sdwa v49, v43, v44 dst_sel:DWORD dst_unused:UNUSED_PAD src0_sel:DWORD src1_sel:WORD_1
	v_or_b32_sdwa v48, v42, v44 dst_sel:DWORD dst_unused:UNUSED_PAD src0_sel:DWORD src1_sel:WORD_0
	v_lshl_add_u64 v[42:43], v[0:1], 1, s[6:7]
	v_add_u32_e32 v0, v60, v125
	global_store_dwordx4 v[42:43], v[46:49], off
	v_lshl_add_u64 v[42:43], v[0:1], 1, s[8:9]
	global_load_dwordx4 v[42:45], v[42:43], off
	v_add_u32_e32 v0, v0, v52
	s_waitcnt vmcnt(0)
	v_lshlrev_b32_e32 v49, 16, v43
	v_and_b32_e32 v50, 0xffff0000, v43
	v_lshlrev_b32_e32 v43, 16, v44
	v_and_b32_e32 v47, 0xffff0000, v42
	v_mul_f32_e32 v43, 0xbfb8aa3b, v43
	v_lshlrev_b32_e32 v46, 16, v42
	v_and_b32_e32 v48, 0xffff0000, v44
	v_exp_f32_e32 v44, v43
	v_mul_f32_e32 v43, 0xbfb8aa3b, v47
	v_mul_f32_e32 v42, 0xbfb8aa3b, v46
	v_exp_f32_e32 v46, v43
	v_mul_f32_e32 v43, 0xbfb8aa3b, v48
	v_exp_f32_e32 v48, v43
	v_mul_f32_e32 v43, 0xbfb8aa3b, v49
	v_exp_f32_e32 v42, v42
	v_exp_f32_e32 v43, v43
	v_lshlrev_b32_e32 v51, 16, v45
	v_mul_f32_e32 v47, 0xbfb8aa3b, v50
	v_and_b32_e32 v53, 0xffff0000, v45
	v_pk_add_f32 v[42:43], v[42:43], 1.0 op_sel_hi:[1,0]
	v_mul_f32_e32 v45, 0xbfb8aa3b, v51
	v_mul_f32_e32 v49, 0xbfb8aa3b, v53
	v_exp_f32_e32 v47, v47
	v_exp_f32_e32 v45, v45
	v_rcp_f32_e32 v43, v43
	s_nop 0
	v_pk_add_f32 v[46:47], v[46:47], 1.0 op_sel_hi:[1,0]
	v_exp_f32_e32 v49, v49
	v_rcp_f32_e32 v42, v42
	s_nop 0
	v_mov_b32_e32 v50, v38
	v_mov_b32_e32 v51, v40
	v_pk_mul_f32 v[42:43], v[50:51], v[42:43]
	v_rcp_f32_e32 v47, v47
	s_nop 0
	s_nop 0
	v_rcp_f32_e32 v46, v46
	s_nop 0
	v_mov_b32_e32 v40, v39
	v_pk_mul_f32 v[38:39], v[40:41], v[46:47]
	v_cvt_pk_bf16_f32 v40, v42, v43
	v_cvt_pk_bf16_f32 v38, v38, v39
	v_and_b32_e32 v39, 0xffff0000, v38
	v_lshlrev_b32_e32 v38, 16, v38
	v_or_b32_sdwa v39, v39, v40 dst_sel:DWORD dst_unused:UNUSED_PAD src0_sel:DWORD src1_sel:WORD_1
	v_or_b32_sdwa v38, v38, v40 dst_sel:DWORD dst_unused:UNUSED_PAD src0_sel:DWORD src1_sel:WORD_0
	v_pk_add_f32 v[40:41], v[44:45], 1.0 op_sel_hi:[1,0]
	s_nop 0
	s_nop 0
	v_rcp_f32_e32 v41, v41
	s_nop 0
	s_nop 0
	v_rcp_f32_e32 v40, v40
	s_nop 0
	v_mov_b32_e32 v42, v34
	v_mov_b32_e32 v43, v36
	v_pk_mul_f32 v[40:41], v[42:43], v[40:41]
	v_pk_add_f32 v[42:43], v[48:49], 1.0 op_sel_hi:[1,0]
	s_nop 0
	s_nop 0
	v_rcp_f32_e32 v43, v43
	s_nop 0
	s_nop 0
	v_rcp_f32_e32 v42, v42
	s_nop 0
	v_mov_b32_e32 v36, v35
	v_pk_mul_f32 v[34:35], v[36:37], v[42:43]
	v_cvt_pk_bf16_f32 v36, v40, v41
	v_cvt_pk_bf16_f32 v34, v34, v35
	v_and_b32_e32 v35, 0xffff0000, v34
	v_lshlrev_b32_e32 v34, 16, v34
	v_add_u32_e32 v44, 0xe3800, v151
	v_or_b32_sdwa v41, v35, v36 dst_sel:DWORD dst_unused:UNUSED_PAD src0_sel:DWORD src1_sel:WORD_1
	v_or_b32_sdwa v40, v34, v36 dst_sel:DWORD dst_unused:UNUSED_PAD src0_sel:DWORD src1_sel:WORD_0
	v_lshl_add_u64 v[34:35], v[0:1], 1, s[6:7]
	v_add_u32_e32 v0, v44, v150
	global_store_dwordx4 v[34:35], v[38:41], off
	v_lshl_add_u64 v[34:35], v[0:1], 1, s[8:9]
	global_load_dwordx4 v[34:37], v[34:35], off
	s_waitcnt vmcnt(0)
	v_lshlrev_b32_e32 v41, 16, v35
	v_and_b32_e32 v42, 0xffff0000, v35
	v_lshlrev_b32_e32 v35, 16, v36
	v_and_b32_e32 v39, 0xffff0000, v34
	v_mul_f32_e32 v35, 0xbfb8aa3b, v35
	v_lshlrev_b32_e32 v38, 16, v34
	v_and_b32_e32 v40, 0xffff0000, v36
	v_exp_f32_e32 v36, v35
	v_mul_f32_e32 v35, 0xbfb8aa3b, v39
	v_mul_f32_e32 v34, 0xbfb8aa3b, v38
	v_exp_f32_e32 v38, v35
	v_mul_f32_e32 v35, 0xbfb8aa3b, v40
	v_exp_f32_e32 v40, v35
	v_mul_f32_e32 v35, 0xbfb8aa3b, v41
	v_exp_f32_e32 v34, v34
	v_exp_f32_e32 v35, v35
	v_lshlrev_b32_e32 v43, 16, v37
	v_mul_f32_e32 v39, 0xbfb8aa3b, v42
	v_and_b32_e32 v45, 0xffff0000, v37
	v_pk_add_f32 v[34:35], v[34:35], 1.0 op_sel_hi:[1,0]
	v_mul_f32_e32 v37, 0xbfb8aa3b, v43
	v_mul_f32_e32 v41, 0xbfb8aa3b, v45
	v_exp_f32_e32 v39, v39
	v_exp_f32_e32 v37, v37
	v_rcp_f32_e32 v35, v35
	s_nop 0
	v_pk_add_f32 v[38:39], v[38:39], 1.0 op_sel_hi:[1,0]
	v_exp_f32_e32 v41, v41
	v_rcp_f32_e32 v34, v34
	s_nop 0
	v_mov_b32_e32 v42, v30
	v_mov_b32_e32 v43, v32
	v_pk_mul_f32 v[34:35], v[42:43], v[34:35]
	v_rcp_f32_e32 v39, v39
	s_nop 0
	s_nop 0
	v_rcp_f32_e32 v38, v38
	s_nop 0
	v_mov_b32_e32 v32, v31
	v_pk_mul_f32 v[30:31], v[32:33], v[38:39]
	v_cvt_pk_bf16_f32 v32, v34, v35
	v_cvt_pk_bf16_f32 v30, v30, v31
	v_and_b32_e32 v31, 0xffff0000, v30
	v_lshlrev_b32_e32 v30, 16, v30
	v_or_b32_sdwa v31, v31, v32 dst_sel:DWORD dst_unused:UNUSED_PAD src0_sel:DWORD src1_sel:WORD_1
	v_or_b32_sdwa v30, v30, v32 dst_sel:DWORD dst_unused:UNUSED_PAD src0_sel:DWORD src1_sel:WORD_0
	v_pk_add_f32 v[32:33], v[36:37], 1.0 op_sel_hi:[1,0]
	s_nop 0
	s_nop 0
	v_rcp_f32_e32 v33, v33
	s_nop 0
	s_nop 0
	v_rcp_f32_e32 v32, v32
	s_nop 0
	v_mov_b32_e32 v34, v26
	v_mov_b32_e32 v35, v28
	v_pk_mul_f32 v[32:33], v[34:35], v[32:33]
	v_pk_add_f32 v[34:35], v[40:41], 1.0 op_sel_hi:[1,0]
	s_nop 0
	s_nop 0
	v_rcp_f32_e32 v35, v35
	s_nop 0
	s_nop 0
	v_rcp_f32_e32 v34, v34
	s_nop 0
	v_mov_b32_e32 v28, v27
	v_pk_mul_f32 v[26:27], v[28:29], v[34:35]
	v_add_u32_e32 v36, 0xfff44800, v124
	v_cvt_pk_bf16_f32 v26, v26, v27
	v_cvt_pk_bf16_f32 v28, v32, v33
	v_and_b32_e32 v27, 0xffff0000, v26
	v_lshlrev_b32_e32 v26, 16, v26
	v_add_u32_e32 v0, v0, v36
	v_or_b32_sdwa v33, v27, v28 dst_sel:DWORD dst_unused:UNUSED_PAD src0_sel:DWORD src1_sel:WORD_1
	v_or_b32_sdwa v32, v26, v28 dst_sel:DWORD dst_unused:UNUSED_PAD src0_sel:DWORD src1_sel:WORD_0
	v_lshl_add_u64 v[26:27], v[0:1], 1, s[6:7]
	v_add_u32_e32 v0, v44, v125
	global_store_dwordx4 v[26:27], v[30:33], off
	v_lshl_add_u64 v[26:27], v[0:1], 1, s[8:9]
	global_load_dwordx4 v[26:29], v[26:27], off
	v_add_u32_e32 v0, v0, v36
	s_waitcnt vmcnt(0)
	v_lshlrev_b32_e32 v33, 16, v27
	v_and_b32_e32 v34, 0xffff0000, v27
	v_lshlrev_b32_e32 v27, 16, v28
	v_and_b32_e32 v31, 0xffff0000, v26
	v_mul_f32_e32 v27, 0xbfb8aa3b, v27
	v_lshlrev_b32_e32 v30, 16, v26
	v_and_b32_e32 v32, 0xffff0000, v28
	v_exp_f32_e32 v28, v27
	v_mul_f32_e32 v27, 0xbfb8aa3b, v31
	v_mul_f32_e32 v26, 0xbfb8aa3b, v30
	v_exp_f32_e32 v30, v27
	v_mul_f32_e32 v27, 0xbfb8aa3b, v32
	v_exp_f32_e32 v32, v27
	v_mul_f32_e32 v27, 0xbfb8aa3b, v33
	v_exp_f32_e32 v26, v26
	v_exp_f32_e32 v27, v27
	v_lshlrev_b32_e32 v35, 16, v29
	v_mul_f32_e32 v31, 0xbfb8aa3b, v34
	v_and_b32_e32 v37, 0xffff0000, v29
	v_pk_add_f32 v[26:27], v[26:27], 1.0 op_sel_hi:[1,0]
	v_mul_f32_e32 v29, 0xbfb8aa3b, v35
	v_mul_f32_e32 v33, 0xbfb8aa3b, v37
	v_exp_f32_e32 v31, v31
	v_exp_f32_e32 v29, v29
	v_rcp_f32_e32 v27, v27
	s_nop 0
	v_pk_add_f32 v[30:31], v[30:31], 1.0 op_sel_hi:[1,0]
	v_exp_f32_e32 v33, v33
	v_rcp_f32_e32 v26, v26
	s_nop 0
	v_mov_b32_e32 v34, v22
	v_mov_b32_e32 v35, v24
	v_pk_mul_f32 v[26:27], v[34:35], v[26:27]
	v_rcp_f32_e32 v31, v31
	s_nop 0
	s_nop 0
	v_rcp_f32_e32 v30, v30
	s_nop 0
	v_mov_b32_e32 v24, v23
	v_pk_mul_f32 v[22:23], v[24:25], v[30:31]
	v_cvt_pk_bf16_f32 v24, v26, v27
	v_cvt_pk_bf16_f32 v22, v22, v23
	v_and_b32_e32 v23, 0xffff0000, v22
	v_lshlrev_b32_e32 v22, 16, v22
	v_or_b32_sdwa v23, v23, v24 dst_sel:DWORD dst_unused:UNUSED_PAD src0_sel:DWORD src1_sel:WORD_1
	v_or_b32_sdwa v22, v22, v24 dst_sel:DWORD dst_unused:UNUSED_PAD src0_sel:DWORD src1_sel:WORD_0
	v_pk_add_f32 v[24:25], v[28:29], 1.0 op_sel_hi:[1,0]
	s_nop 0
	s_nop 0
	v_rcp_f32_e32 v25, v25
	s_nop 0
	s_nop 0
	v_rcp_f32_e32 v24, v24
	s_nop 0
	v_mov_b32_e32 v26, v18
	v_mov_b32_e32 v27, v20
	v_pk_mul_f32 v[24:25], v[26:27], v[24:25]
	v_pk_add_f32 v[26:27], v[32:33], 1.0 op_sel_hi:[1,0]
	s_nop 0
	s_nop 0
	v_rcp_f32_e32 v27, v27
	s_nop 0
	s_nop 0
	v_rcp_f32_e32 v26, v26
	s_nop 0
	v_mov_b32_e32 v20, v19
	v_pk_mul_f32 v[18:19], v[20:21], v[26:27]
	v_cvt_pk_bf16_f32 v20, v24, v25
	v_cvt_pk_bf16_f32 v18, v18, v19
	v_and_b32_e32 v19, 0xffff0000, v18
	v_lshlrev_b32_e32 v18, 16, v18
	v_add_u32_e32 v28, 0xfa400, v151
	v_or_b32_sdwa v25, v19, v20 dst_sel:DWORD dst_unused:UNUSED_PAD src0_sel:DWORD src1_sel:WORD_1
	v_or_b32_sdwa v24, v18, v20 dst_sel:DWORD dst_unused:UNUSED_PAD src0_sel:DWORD src1_sel:WORD_0
	v_lshl_add_u64 v[18:19], v[0:1], 1, s[6:7]
	v_add_u32_e32 v0, v28, v150
	global_store_dwordx4 v[18:19], v[22:25], off
	v_lshl_add_u64 v[18:19], v[0:1], 1, s[8:9]
	global_load_dwordx4 v[18:21], v[18:19], off
	s_waitcnt vmcnt(0)
	v_lshlrev_b32_e32 v25, 16, v19
	v_and_b32_e32 v26, 0xffff0000, v19
	v_lshlrev_b32_e32 v19, 16, v20
	v_and_b32_e32 v23, 0xffff0000, v18
	v_mul_f32_e32 v19, 0xbfb8aa3b, v19
	v_lshlrev_b32_e32 v22, 16, v18
	v_and_b32_e32 v24, 0xffff0000, v20
	v_exp_f32_e32 v20, v19
	v_mul_f32_e32 v19, 0xbfb8aa3b, v23
	v_mul_f32_e32 v18, 0xbfb8aa3b, v22
	v_exp_f32_e32 v22, v19
	v_mul_f32_e32 v19, 0xbfb8aa3b, v24
	v_exp_f32_e32 v24, v19
	v_mul_f32_e32 v19, 0xbfb8aa3b, v25
	v_exp_f32_e32 v18, v18
	v_exp_f32_e32 v19, v19
	v_lshlrev_b32_e32 v27, 16, v21
	v_mul_f32_e32 v23, 0xbfb8aa3b, v26
	v_and_b32_e32 v29, 0xffff0000, v21
	v_pk_add_f32 v[18:19], v[18:19], 1.0 op_sel_hi:[1,0]
	v_mul_f32_e32 v21, 0xbfb8aa3b, v27
	v_mul_f32_e32 v25, 0xbfb8aa3b, v29
	v_exp_f32_e32 v23, v23
	v_exp_f32_e32 v21, v21
	v_rcp_f32_e32 v19, v19
	s_nop 0
	v_pk_add_f32 v[22:23], v[22:23], 1.0 op_sel_hi:[1,0]
	v_exp_f32_e32 v25, v25
	v_rcp_f32_e32 v18, v18
	s_nop 0
	v_mov_b32_e32 v26, v14
	v_mov_b32_e32 v27, v16
	v_pk_mul_f32 v[18:19], v[26:27], v[18:19]
	v_rcp_f32_e32 v23, v23
	s_nop 0
	s_nop 0
	v_rcp_f32_e32 v22, v22
	s_nop 0
	v_mov_b32_e32 v16, v15
	v_pk_mul_f32 v[14:15], v[16:17], v[22:23]
	v_cvt_pk_bf16_f32 v16, v18, v19
	v_cvt_pk_bf16_f32 v14, v14, v15
	v_and_b32_e32 v15, 0xffff0000, v14
	v_lshlrev_b32_e32 v14, 16, v14
	v_or_b32_sdwa v15, v15, v16 dst_sel:DWORD dst_unused:UNUSED_PAD src0_sel:DWORD src1_sel:WORD_1
	v_or_b32_sdwa v14, v14, v16 dst_sel:DWORD dst_unused:UNUSED_PAD src0_sel:DWORD src1_sel:WORD_0
	v_pk_add_f32 v[16:17], v[20:21], 1.0 op_sel_hi:[1,0]
	s_nop 0
	s_nop 0
	v_rcp_f32_e32 v17, v17
	s_nop 0
	s_nop 0
	v_rcp_f32_e32 v16, v16
	s_nop 0
	v_mov_b32_e32 v18, v10
	v_mov_b32_e32 v19, v12
	v_pk_mul_f32 v[16:17], v[18:19], v[16:17]
	v_pk_add_f32 v[18:19], v[24:25], 1.0 op_sel_hi:[1,0]
	s_nop 0
	s_nop 0
	v_rcp_f32_e32 v19, v19
	s_nop 0
	s_nop 0
	v_rcp_f32_e32 v18, v18
	s_nop 0
	v_mov_b32_e32 v12, v11
	v_pk_mul_f32 v[10:11], v[12:13], v[18:19]
	v_add_u32_e32 v20, 0xfff31c00, v124
	v_cvt_pk_bf16_f32 v10, v10, v11
	v_cvt_pk_bf16_f32 v12, v16, v17
	v_and_b32_e32 v11, 0xffff0000, v10
	v_lshlrev_b32_e32 v10, 16, v10
	v_add_u32_e32 v0, v0, v20
	v_or_b32_sdwa v17, v11, v12 dst_sel:DWORD dst_unused:UNUSED_PAD src0_sel:DWORD src1_sel:WORD_1
	v_or_b32_sdwa v16, v10, v12 dst_sel:DWORD dst_unused:UNUSED_PAD src0_sel:DWORD src1_sel:WORD_0
	v_lshl_add_u64 v[10:11], v[0:1], 1, s[6:7]
	v_add_u32_e32 v0, v28, v125
	global_store_dwordx4 v[10:11], v[14:17], off
	v_lshl_add_u64 v[10:11], v[0:1], 1, s[8:9]
	global_load_dwordx4 v[10:13], v[10:11], off
	v_add_u32_e32 v0, v0, v20
	s_waitcnt vmcnt(0)
	v_lshlrev_b32_e32 v17, 16, v11
	v_and_b32_e32 v18, 0xffff0000, v11
	v_lshlrev_b32_e32 v11, 16, v12
	v_and_b32_e32 v15, 0xffff0000, v10
	v_mul_f32_e32 v11, 0xbfb8aa3b, v11
	v_lshlrev_b32_e32 v14, 16, v10
	v_and_b32_e32 v16, 0xffff0000, v12
	v_exp_f32_e32 v12, v11
	v_mul_f32_e32 v11, 0xbfb8aa3b, v15
	v_mul_f32_e32 v10, 0xbfb8aa3b, v14
	v_exp_f32_e32 v14, v11
	v_mul_f32_e32 v11, 0xbfb8aa3b, v16
	v_exp_f32_e32 v16, v11
	v_mul_f32_e32 v11, 0xbfb8aa3b, v17
	v_exp_f32_e32 v10, v10
	v_exp_f32_e32 v11, v11
	v_lshlrev_b32_e32 v19, 16, v13
	v_mul_f32_e32 v15, 0xbfb8aa3b, v18
	v_and_b32_e32 v21, 0xffff0000, v13
	v_pk_add_f32 v[10:11], v[10:11], 1.0 op_sel_hi:[1,0]
	v_mul_f32_e32 v13, 0xbfb8aa3b, v19
	v_mul_f32_e32 v17, 0xbfb8aa3b, v21
	v_exp_f32_e32 v15, v15
	v_exp_f32_e32 v13, v13
	v_rcp_f32_e32 v11, v11
	s_nop 0
	v_pk_add_f32 v[14:15], v[14:15], 1.0 op_sel_hi:[1,0]
	v_exp_f32_e32 v17, v17
	v_rcp_f32_e32 v10, v10
	s_nop 0
	v_mov_b32_e32 v18, v6
	v_mov_b32_e32 v19, v8
	v_pk_mul_f32 v[10:11], v[18:19], v[10:11]
	v_rcp_f32_e32 v15, v15
	s_nop 0
	s_nop 0
	v_rcp_f32_e32 v14, v14
	s_nop 0
	v_mov_b32_e32 v8, v7
	v_pk_mul_f32 v[6:7], v[8:9], v[14:15]
	v_cvt_pk_bf16_f32 v8, v10, v11
	v_cvt_pk_bf16_f32 v6, v6, v7
	v_and_b32_e32 v7, 0xffff0000, v6
	v_lshlrev_b32_e32 v6, 16, v6
	v_or_b32_sdwa v7, v7, v8 dst_sel:DWORD dst_unused:UNUSED_PAD src0_sel:DWORD src1_sel:WORD_1
	v_or_b32_sdwa v6, v6, v8 dst_sel:DWORD dst_unused:UNUSED_PAD src0_sel:DWORD src1_sel:WORD_0
	v_pk_add_f32 v[8:9], v[12:13], 1.0 op_sel_hi:[1,0]
	s_nop 0
	s_nop 0
	v_rcp_f32_e32 v9, v9
	s_nop 0
	s_nop 0
	v_rcp_f32_e32 v8, v8
	s_nop 0
	v_mov_b32_e32 v10, v2
	v_mov_b32_e32 v11, v4
	v_pk_mul_f32 v[8:9], v[10:11], v[8:9]
	v_pk_add_f32 v[10:11], v[16:17], 1.0 op_sel_hi:[1,0]
	s_nop 0
	s_nop 0
	v_rcp_f32_e32 v11, v11
	s_nop 0
	s_mov_b64 s[24:25], s[16:17]
	v_rcp_f32_e32 v10, v10
	s_nop 0
	v_mov_b32_e32 v4, v3
	v_pk_mul_f32 v[2:3], v[4:5], v[10:11]
	v_cvt_pk_bf16_f32 v4, v8, v9
	v_cvt_pk_bf16_f32 v2, v2, v3
	v_and_b32_e32 v3, 0xffff0000, v2
	v_lshlrev_b32_e32 v2, 16, v2
	v_or_b32_sdwa v9, v3, v4 dst_sel:DWORD dst_unused:UNUSED_PAD src0_sel:DWORD src1_sel:WORD_1
	v_or_b32_sdwa v8, v2, v4 dst_sel:DWORD dst_unused:UNUSED_PAD src0_sel:DWORD src1_sel:WORD_0
	v_lshl_add_u64 v[2:3], v[0:1], 1, s[6:7]
	s_and_b64 vcc, exec, s[10:11]
	global_store_dwordx4 v[2:3], v[6:9], off
	s_cbranch_vccz .LBB0_1344
	s_waitcnt vmcnt(0)
	v_readlane_b32 s76, v255, 8
	s_mov_b32 s92, 0x3b2aaaab
	s_cmp_gt_u32 s4, 3
	v_readlane_b32 s77, v255, 9
	s_mul_i32 s60, s33, 0x1800
	s_mul_hi_i32 s62, s64, 0x300
	s_mul_i32 s75, s33, 0x16c00
	s_mov_b32 s93, 0x3c800000
	s_mov_b32 s82, s70
	s_cbranch_scc1 .LBB0_1351
	s_barrier

.LBB0_1359:
	v_add_u32_e32 v0, 0x10000, v154
	s_waitcnt vmcnt(0)
	ds_read_b128 v[130:133], v0
	ds_read_b128 v[146:149], v0 offset:1024
	ds_read_b128 v[156:159], v0 offset:2048
	ds_read_b128 v[160:163], v0 offset:3072
	s_add_u32 s28, s26, 0xfffc0080
	s_addc_u32 s29, s27, -1
	s_cmp_eq_u32 vcc_lo, 12
	s_cselect_b32 s31, s2, s29
	s_cselect_b32 s30, s17, s28
	s_cselect_b32 s29, s15, s94
	s_cselect_b32 s28, s89, s90
	v_lshl_add_u64 v[150:151], s[26:27], 0, v[142:143]
	s_add_i32 m0, s39, 0xc000
	ds_read_b128 v[164:167], v153
	ds_read_b128 v[168:171], v153 offset:1024
	ds_read_b128 v[172:175], v153 offset:2048
	ds_read_b128 v[176:179], v153 offset:3072
	ds_read_b128 v[182:185], v153 offset:4096
	ds_read_b128 v[186:189], v153 offset:5120
	ds_read_b128 v[190:193], v153 offset:6144
	ds_read_b128 v[194:197], v153 offset:7168
	global_load_lds_dwordx4 v[150:151], off
	v_lshl_add_u64 v[150:151], s[26:27], 0, v[144:145]
	s_add_i32 m0, s39, 0xe000
	s_nop 0
	global_load_lds_dwordx4 v[150:151], off
	s_waitcnt lgkmcnt(8)
	s_barrier
	s_waitcnt lgkmcnt(0)
	s_setprio 1
	s_waitcnt lgkmcnt(0)
	v_mfma_f32_16x16x32_bf16 v[126:129], v[130:133], v[164:167], v[126:129]
	v_mfma_f32_16x16x32_bf16 v[122:125], v[156:159], v[164:167], v[122:125]
	v_mfma_f32_16x16x32_bf16 v[110:113], v[130:133], v[172:175], v[110:113]
	v_mfma_f32_16x16x32_bf16 v[106:109], v[156:159], v[172:175], v[106:109]
	v_mfma_f32_16x16x32_bf16 v[94:97], v[130:133], v[182:185], v[94:97]
	v_mfma_f32_16x16x32_bf16 v[90:93], v[156:159], v[182:185], v[90:93]
	v_mfma_f32_16x16x32_bf16 v[78:81], v[130:133], v[190:193], v[78:81]
	v_mfma_f32_16x16x32_bf16 v[74:77], v[156:159], v[190:193], v[74:77]
	v_mfma_f32_16x16x32_bf16 v[126:129], v[146:149], v[168:171], v[126:129]
	v_mfma_f32_16x16x32_bf16 v[122:125], v[160:163], v[168:171], v[122:125]
	v_mfma_f32_16x16x32_bf16 v[110:113], v[146:149], v[176:179], v[110:113]
	v_mfma_f32_16x16x32_bf16 v[106:109], v[160:163], v[176:179], v[106:109]
	v_mfma_f32_16x16x32_bf16 v[94:97], v[146:149], v[186:189], v[94:97]
	v_mfma_f32_16x16x32_bf16 v[90:93], v[160:163], v[186:189], v[90:93]
	v_mfma_f32_16x16x32_bf16 v[78:81], v[146:149], v[194:197], v[78:81]
	v_mfma_f32_16x16x32_bf16 v[74:77], v[160:163], v[194:197], v[74:77]
	s_setprio 0
	s_barrier
	s_mov_b32 m0, s23
	v_add_u32_e32 v0, 0x14000, v154
	v_lshl_add_u64 v[150:151], s[28:29], 0, v[138:139]
	s_waitcnt vmcnt(0)
	ds_read_b128 v[198:201], v0
	ds_read_b128 v[202:205], v0 offset:1024
	ds_read_b128 v[206:209], v0 offset:2048
	ds_read_b128 v[210:213], v0 offset:3072
	global_load_lds_dwordx4 v[150:151], off
	v_lshl_add_u64 v[214:215], s[28:29], 0, v[134:135]
	s_mov_b32 m0, s25
	s_nop 0
	global_load_lds_dwordx4 v[214:215], off
	s_barrier
	s_waitcnt lgkmcnt(0)
	s_setprio 1
	s_waitcnt lgkmcnt(0)
	v_mfma_f32_16x16x32_bf16 v[118:121], v[198:201], v[164:167], v[118:121]
	v_mfma_f32_16x16x32_bf16 v[114:117], v[206:209], v[164:167], v[114:117]
	v_mfma_f32_16x16x32_bf16 v[102:105], v[198:201], v[172:175], v[102:105]
	v_mfma_f32_16x16x32_bf16 v[98:101], v[206:209], v[172:175], v[98:101]
	v_mfma_f32_16x16x32_bf16 v[86:89], v[198:201], v[182:185], v[86:89]
	v_mfma_f32_16x16x32_bf16 v[82:85], v[206:209], v[182:185], v[82:85]
	v_mfma_f32_16x16x32_bf16 v[70:73], v[198:201], v[190:193], v[70:73]
	v_mfma_f32_16x16x32_bf16 v[66:69], v[206:209], v[190:193], v[66:69]
	v_mfma_f32_16x16x32_bf16 v[118:121], v[202:205], v[168:171], v[118:121]
	v_mfma_f32_16x16x32_bf16 v[114:117], v[210:213], v[168:171], v[114:117]
	v_mfma_f32_16x16x32_bf16 v[102:105], v[202:205], v[176:179], v[102:105]
	v_mfma_f32_16x16x32_bf16 v[98:101], v[210:213], v[176:179], v[98:101]
	v_mfma_f32_16x16x32_bf16 v[86:89], v[202:205], v[186:189], v[86:89]
	v_mfma_f32_16x16x32_bf16 v[82:85], v[210:213], v[186:189], v[82:85]
	v_mfma_f32_16x16x32_bf16 v[70:73], v[202:205], v[194:197], v[70:73]
	v_mfma_f32_16x16x32_bf16 v[66:69], v[210:213], v[194:197], v[66:69]
	s_setprio 0
	s_mov_b32 m0, s39
	v_lshl_add_u64 v[216:217], s[30:31], 0, v[140:141]
	s_barrier
	s_waitcnt vmcnt(0)
	ds_read_b128 v[164:167], v153 offset:16384
	ds_read_b128 v[168:171], v153 offset:17408
	ds_read_b128 v[172:175], v153 offset:18432
	ds_read_b128 v[176:179], v153 offset:19456
	ds_read_b128 v[182:185], v153 offset:20480
	ds_read_b128 v[186:189], v153 offset:21504
	ds_read_b128 v[190:193], v153 offset:22528
	ds_read_b128 v[194:197], v153 offset:23552
	global_load_lds_dwordx4 v[216:217], off
	v_lshl_add_u64 v[222:223], s[30:31], 0, v[136:137]
	s_mov_b32 m0, s82
	s_nop 0
	global_load_lds_dwordx4 v[222:223], off
	s_barrier
	s_waitcnt lgkmcnt(0)
	s_setprio 1
	s_waitcnt lgkmcnt(0)
	v_mfma_f32_16x16x32_bf16 v[62:65], v[130:133], v[164:167], v[62:65]
	v_mfma_f32_16x16x32_bf16 v[58:61], v[156:159], v[164:167], v[58:61]
	v_mfma_f32_16x16x32_bf16 v[46:49], v[130:133], v[172:175], v[46:49]
	v_mfma_f32_16x16x32_bf16 v[42:45], v[156:159], v[172:175], v[42:45]
	v_mfma_f32_16x16x32_bf16 v[30:33], v[130:133], v[182:185], v[30:33]
	v_mfma_f32_16x16x32_bf16 v[26:29], v[156:159], v[182:185], v[26:29]
	v_mfma_f32_16x16x32_bf16 v[14:17], v[130:133], v[190:193], v[14:17]
	v_mfma_f32_16x16x32_bf16 v[10:13], v[156:159], v[190:193], v[10:13]
	v_mfma_f32_16x16x32_bf16 v[62:65], v[146:149], v[168:171], v[62:65]
	v_mfma_f32_16x16x32_bf16 v[58:61], v[160:163], v[168:171], v[58:61]
	v_mfma_f32_16x16x32_bf16 v[46:49], v[146:149], v[176:179], v[46:49]
	v_mfma_f32_16x16x32_bf16 v[42:45], v[160:163], v[176:179], v[42:45]
	v_mfma_f32_16x16x32_bf16 v[30:33], v[146:149], v[186:189], v[30:33]
	v_mfma_f32_16x16x32_bf16 v[26:29], v[160:163], v[186:189], v[26:29]
	v_mfma_f32_16x16x32_bf16 v[14:17], v[146:149], v[194:197], v[14:17]
	v_mfma_f32_16x16x32_bf16 v[10:13], v[160:163], v[194:197], v[10:13]
	s_setprio 0
	s_barrier
	s_add_u32 s76, s28, 0x40000
	s_addc_u32 s77, s29, 0
	s_mov_b32 m0, s96
	v_lshl_add_u64 v[130:131], s[76:77], 0, v[138:139]
	global_load_lds_dwordx4 v[130:131], off
	v_lshl_add_u64 v[130:131], s[76:77], 0, v[134:135]
	s_mov_b32 m0, s97
	s_nop 0
	global_load_lds_dwordx4 v[130:131], off
	s_waitcnt vmcnt(6)
	s_barrier
	s_setprio 1
	v_mfma_f32_16x16x32_bf16 v[54:57], v[198:201], v[164:167], v[54:57]
	v_mfma_f32_16x16x32_bf16 v[50:53], v[206:209], v[164:167], v[50:53]
	v_mfma_f32_16x16x32_bf16 v[38:41], v[198:201], v[172:175], v[38:41]
	v_mfma_f32_16x16x32_bf16 v[34:37], v[206:209], v[172:175], v[34:37]
	v_mfma_f32_16x16x32_bf16 v[22:25], v[198:201], v[182:185], v[22:25]
	v_mfma_f32_16x16x32_bf16 v[18:21], v[206:209], v[182:185], v[18:21]
	v_mfma_f32_16x16x32_bf16 v[6:9], v[198:201], v[190:193], v[6:9]
	v_mfma_f32_16x16x32_bf16 v[2:5], v[206:209], v[190:193], v[2:5]
	v_mfma_f32_16x16x32_bf16 v[54:57], v[202:205], v[168:171], v[54:57]
	v_mfma_f32_16x16x32_bf16 v[50:53], v[210:213], v[168:171], v[50:53]
	v_mfma_f32_16x16x32_bf16 v[38:41], v[202:205], v[176:179], v[38:41]
	v_mfma_f32_16x16x32_bf16 v[34:37], v[210:213], v[176:179], v[34:37]
	v_mfma_f32_16x16x32_bf16 v[22:25], v[202:205], v[186:189], v[22:25]
	v_mfma_f32_16x16x32_bf16 v[18:21], v[210:213], v[186:189], v[18:21]
	v_mfma_f32_16x16x32_bf16 v[6:9], v[202:205], v[194:197], v[6:9]
	v_mfma_f32_16x16x32_bf16 v[2:5], v[210:213], v[194:197], v[2:5]
	s_setprio 0
	v_add_u32_e32 v0, 0x18000, v154
	s_barrier
	s_waitcnt vmcnt(0)
	ds_read_b128 v[130:133], v0
	ds_read_b128 v[146:149], v0 offset:1024
	ds_read_b128 v[156:159], v0 offset:2048
	ds_read_b128 v[160:163], v0 offset:3072
	s_add_u32 s30, s30, 0x40000
	s_addc_u32 s31, s31, 0
	s_mov_b32 m0, s68
	v_lshl_add_u64 v[198:199], s[30:31], 0, v[140:141]
	ds_read_b128 v[164:167], v153 offset:32768
	ds_read_b128 v[168:171], v153 offset:33792
	ds_read_b128 v[172:175], v153 offset:34816
	ds_read_b128 v[176:179], v153 offset:35840
	ds_read_b128 v[182:185], v153 offset:36864
	ds_read_b128 v[186:189], v153 offset:37888
	ds_read_b128 v[190:193], v153 offset:38912
	ds_read_b128 v[194:197], v153 offset:39936
	global_load_lds_dwordx4 v[198:199], off
	v_lshl_add_u64 v[198:199], s[30:31], 0, v[136:137]
	s_mov_b32 m0, s69
	s_nop 0
	global_load_lds_dwordx4 v[198:199], off
	s_waitcnt lgkmcnt(8)
	s_barrier
	s_waitcnt lgkmcnt(0)
	s_setprio 1
	s_waitcnt lgkmcnt(0)
	v_mfma_f32_16x16x32_bf16 v[126:129], v[130:133], v[164:167], v[126:129]
	v_mfma_f32_16x16x32_bf16 v[122:125], v[156:159], v[164:167], v[122:125]
	v_mfma_f32_16x16x32_bf16 v[110:113], v[130:133], v[172:175], v[110:113]
	v_mfma_f32_16x16x32_bf16 v[106:109], v[156:159], v[172:175], v[106:109]
	v_mfma_f32_16x16x32_bf16 v[94:97], v[130:133], v[182:185], v[94:97]
	v_mfma_f32_16x16x32_bf16 v[90:93], v[156:159], v[182:185], v[90:93]
	v_mfma_f32_16x16x32_bf16 v[78:81], v[130:133], v[190:193], v[78:81]
	v_mfma_f32_16x16x32_bf16 v[74:77], v[156:159], v[190:193], v[74:77]
	v_mfma_f32_16x16x32_bf16 v[126:129], v[146:149], v[168:171], v[126:129]
	v_mfma_f32_16x16x32_bf16 v[122:125], v[160:163], v[168:171], v[122:125]
	v_mfma_f32_16x16x32_bf16 v[110:113], v[146:149], v[176:179], v[110:113]
	v_mfma_f32_16x16x32_bf16 v[106:109], v[160:163], v[176:179], v[106:109]
	v_mfma_f32_16x16x32_bf16 v[94:97], v[146:149], v[186:189], v[94:97]
	v_mfma_f32_16x16x32_bf16 v[90:93], v[160:163], v[186:189], v[90:93]
	v_mfma_f32_16x16x32_bf16 v[78:81], v[146:149], v[194:197], v[78:81]
	v_mfma_f32_16x16x32_bf16 v[74:77], v[160:163], v[194:197], v[74:77]
	s_setprio 0
	s_barrier
	s_mov_b32 m0, s4
	v_add_u32_e32 v0, 0x1c000, v154
	v_lshl_add_u64 v[150:151], v[150:151], 0, s[84:85]
	s_waitcnt vmcnt(0)
	ds_read_b128 v[198:201], v0
	ds_read_b128 v[202:205], v0 offset:1024
	ds_read_b128 v[206:209], v0 offset:2048
	ds_read_b128 v[210:213], v0 offset:3072
	global_load_lds_dwordx4 v[150:151], off
	v_lshl_add_u64 v[150:151], v[214:215], 0, s[84:85]
	s_mov_b32 m0, s5
	s_nop 0
	global_load_lds_dwordx4 v[150:151], off
	s_barrier
	s_waitcnt lgkmcnt(0)
	s_setprio 1
	s_waitcnt lgkmcnt(0)
	v_mfma_f32_16x16x32_bf16 v[118:121], v[198:201], v[164:167], v[118:121]
	v_mfma_f32_16x16x32_bf16 v[114:117], v[206:209], v[164:167], v[114:117]
	v_mfma_f32_16x16x32_bf16 v[102:105], v[198:201], v[172:175], v[102:105]
	v_mfma_f32_16x16x32_bf16 v[98:101], v[206:209], v[172:175], v[98:101]
	v_mfma_f32_16x16x32_bf16 v[86:89], v[198:201], v[182:185], v[86:89]
	v_mfma_f32_16x16x32_bf16 v[82:85], v[206:209], v[182:185], v[82:85]
	v_mfma_f32_16x16x32_bf16 v[70:73], v[198:201], v[190:193], v[70:73]
	v_mfma_f32_16x16x32_bf16 v[66:69], v[206:209], v[190:193], v[66:69]
	v_mfma_f32_16x16x32_bf16 v[118:121], v[202:205], v[168:171], v[118:121]
	v_mfma_f32_16x16x32_bf16 v[114:117], v[210:213], v[168:171], v[114:117]
	v_mfma_f32_16x16x32_bf16 v[102:105], v[202:205], v[176:179], v[102:105]
	v_mfma_f32_16x16x32_bf16 v[98:101], v[210:213], v[176:179], v[98:101]
	v_mfma_f32_16x16x32_bf16 v[86:89], v[202:205], v[186:189], v[86:89]
	v_mfma_f32_16x16x32_bf16 v[82:85], v[210:213], v[186:189], v[82:85]
	v_mfma_f32_16x16x32_bf16 v[70:73], v[202:205], v[194:197], v[70:73]
	v_mfma_f32_16x16x32_bf16 v[66:69], v[210:213], v[194:197], v[66:69]
	s_setprio 0
	s_mov_b32 m0, s60
	v_lshl_add_u64 v[150:151], v[216:217], 0, s[84:85]
	s_barrier
	s_waitcnt vmcnt(0)
	ds_read_b128 v[164:167], v153 offset:49152
	ds_read_b128 v[168:171], v153 offset:50176
	ds_read_b128 v[172:175], v153 offset:51200
	ds_read_b128 v[176:179], v153 offset:52224
	ds_read_b128 v[182:185], v153 offset:53248
	ds_read_b128 v[186:189], v153 offset:54272
	ds_read_b128 v[190:193], v153 offset:55296
	ds_read_b128 v[194:197], v153 offset:56320
	global_load_lds_dwordx4 v[150:151], off
	v_lshl_add_u64 v[150:151], v[222:223], 0, s[84:85]
	s_mov_b32 m0, s92
	s_nop 0
	global_load_lds_dwordx4 v[150:151], off
	s_barrier
	s_waitcnt lgkmcnt(0)
	s_setprio 1
	s_waitcnt lgkmcnt(0)
	v_mfma_f32_16x16x32_bf16 v[62:65], v[130:133], v[164:167], v[62:65]
	v_mfma_f32_16x16x32_bf16 v[58:61], v[156:159], v[164:167], v[58:61]
	v_mfma_f32_16x16x32_bf16 v[46:49], v[130:133], v[172:175], v[46:49]
	v_mfma_f32_16x16x32_bf16 v[42:45], v[156:159], v[172:175], v[42:45]
	v_mfma_f32_16x16x32_bf16 v[30:33], v[130:133], v[182:185], v[30:33]
	v_mfma_f32_16x16x32_bf16 v[26:29], v[156:159], v[182:185], v[26:29]
	v_mfma_f32_16x16x32_bf16 v[14:17], v[130:133], v[190:193], v[14:17]
	v_mfma_f32_16x16x32_bf16 v[10:13], v[156:159], v[190:193], v[10:13]
	v_mfma_f32_16x16x32_bf16 v[62:65], v[146:149], v[168:171], v[62:65]
	v_mfma_f32_16x16x32_bf16 v[58:61], v[160:163], v[168:171], v[58:61]
	v_mfma_f32_16x16x32_bf16 v[46:49], v[146:149], v[176:179], v[46:49]
	v_mfma_f32_16x16x32_bf16 v[42:45], v[160:163], v[176:179], v[42:45]
	v_mfma_f32_16x16x32_bf16 v[30:33], v[146:149], v[186:189], v[30:33]
	v_mfma_f32_16x16x32_bf16 v[26:29], v[160:163], v[186:189], v[26:29]
	v_mfma_f32_16x16x32_bf16 v[14:17], v[146:149], v[194:197], v[14:17]
	v_mfma_f32_16x16x32_bf16 v[10:13], v[160:163], v[194:197], v[10:13]
	s_setprio 0
	s_barrier
	s_add_u32 s28, s28, 0x40080
	s_addc_u32 s29, s29, 0
	s_mov_b32 m0, s93
	v_lshl_add_u64 v[130:131], s[28:29], 0, v[138:139]
	global_load_lds_dwordx4 v[130:131], off
	v_lshl_add_u64 v[130:131], s[28:29], 0, v[134:135]
	s_mov_b32 m0, s3
	s_nop 0
	global_load_lds_dwordx4 v[130:131], off
	s_waitcnt vmcnt(6)
	s_barrier
	s_setprio 1
	v_mfma_f32_16x16x32_bf16 v[54:57], v[198:201], v[164:167], v[54:57]
	v_mfma_f32_16x16x32_bf16 v[50:53], v[206:209], v[164:167], v[50:53]
	v_mfma_f32_16x16x32_bf16 v[38:41], v[198:201], v[172:175], v[38:41]
	v_mfma_f32_16x16x32_bf16 v[34:37], v[206:209], v[172:175], v[34:37]
	v_mfma_f32_16x16x32_bf16 v[22:25], v[198:201], v[182:185], v[22:25]
	v_mfma_f32_16x16x32_bf16 v[18:21], v[206:209], v[182:185], v[18:21]
	v_mfma_f32_16x16x32_bf16 v[6:9], v[198:201], v[190:193], v[6:9]
	v_mfma_f32_16x16x32_bf16 v[2:5], v[206:209], v[190:193], v[2:5]
	v_mfma_f32_16x16x32_bf16 v[54:57], v[202:205], v[168:171], v[54:57]
	v_mfma_f32_16x16x32_bf16 v[50:53], v[210:213], v[168:171], v[50:53]
	v_mfma_f32_16x16x32_bf16 v[38:41], v[202:205], v[176:179], v[38:41]
	v_mfma_f32_16x16x32_bf16 v[34:37], v[210:213], v[176:179], v[34:37]
	v_mfma_f32_16x16x32_bf16 v[22:25], v[202:205], v[186:189], v[22:25]
	v_mfma_f32_16x16x32_bf16 v[18:21], v[210:213], v[186:189], v[18:21]
	v_mfma_f32_16x16x32_bf16 v[6:9], v[202:205], v[194:197], v[6:9]
	v_mfma_f32_16x16x32_bf16 v[2:5], v[210:213], v[194:197], v[2:5]
	s_setprio 0
	s_add_i32 vcc_lo, vcc_lo, 2
	s_add_u32 s26, s26, 0x100
	s_addc_u32 s27, s27, 0
	s_add_u32 s90, s90, 0x100
	s_addc_u32 s94, s94, 0
	s_cmp_gt_u32 vcc_lo, 13
	s_barrier
	s_cbranch_scc0 .LBB0_1359
	v_lshl_add_u32 v159, s24, 8, v152
	v_lshl_add_u32 v156, s22, 8, v155
	v_mul_lo_u32 v157, v159, s71
	v_add_u32_e32 v0, v157, v156
	v_lshl_add_u64 v[130:131], v[0:1], 1, s[6:7]
	global_load_dwordx4 v[130:133], v[130:131], off
	v_mul_lo_u32 v158, v159, s61
	v_add_u32_e32 v0, v0, v158
	v_lshl_add_u64 v[146:147], v[0:1], 1, s[10:11]
	s_mov_b32 s22, s14
	s_mov_b32 s24, s16
	s_mov_b64 s[28:29], s[20:21]
	s_waitcnt vmcnt(0)
	v_lshlrev_b32_e32 v148, 16, v130
	v_and_b32_e32 v149, 0xffff0000, v130
	v_lshlrev_b32_e32 v151, 16, v131
	v_and_b32_e32 v163, 0xffff0000, v131
	v_lshlrev_b32_e32 v150, 16, v132
	v_and_b32_e32 v161, 0xffff0000, v132
	v_lshlrev_b32_e32 v164, 16, v133
	v_and_b32_e32 v165, 0xffff0000, v133
	global_load_dwordx4 v[130:133], v[146:147], off
	v_mul_f32_e32 v0, 0xbfb8aa3b, v148
	v_exp_f32_e32 v160, v0
	v_mul_f32_e32 v0, 0xbfb8aa3b, v150
	v_exp_f32_e32 v150, v0
	v_mul_f32_e32 v0, 0xbfb8aa3b, v149
	v_exp_f32_e32 v162, v0
	v_mul_f32_e32 v0, 0xbfb8aa3b, v161
	v_exp_f32_e32 v148, v0
	v_mul_f32_e32 v0, 0xbfb8aa3b, v151
	v_exp_f32_e32 v161, v0
	v_mul_f32_e32 v0, 0xbfb8aa3b, v164
	v_exp_f32_e32 v151, v0
	v_mul_f32_e32 v0, 0xbfb8aa3b, v163
	v_exp_f32_e32 v163, v0
	v_mul_f32_e32 v0, 0xbfb8aa3b, v165
	v_pk_add_f32 v[160:161], v[160:161], 1.0 op_sel_hi:[1,0]
	v_exp_f32_e32 v149, v0
	v_pk_add_f32 v[162:163], v[162:163], 1.0 op_sel_hi:[1,0]
	v_rcp_f32_e32 v161, v161
	s_nop 0
	s_waitcnt vmcnt(0)
	v_lshlrev_b32_e32 v165, 16, v131
	v_rcp_f32_e32 v160, v160
	s_nop 0
	v_mov_b32_e32 v166, v126
	v_mov_b32_e32 v167, v128
	v_lshlrev_b32_e32 v164, 16, v130
	v_pk_fma_f32 v[160:161], v[166:167], v[160:161], v[164:165]
	v_rcp_f32_e32 v163, v163
	s_nop 0
	v_and_b32_e32 v131, 0xffff0000, v131
	v_and_b32_e32 v130, 0xffff0000, v130
	v_rcp_f32_e32 v162, v162
	s_nop 0
	v_mov_b32_e32 v128, v127
	v_pk_fma_f32 v[126:127], v[128:129], v[162:163], v[130:131]
	v_cvt_pk_bf16_f32 v0, v160, v161
	v_cvt_pk_bf16_f32 v126, v126, v127
	v_and_b32_e32 v127, 0xffff0000, v126
	v_lshlrev_b32_e32 v126, 16, v126
	v_lshlrev_b32_e32 v131, 16, v133
	v_lshlrev_b32_e32 v130, 16, v132
	v_and_b32_e32 v129, 0xffff0000, v133
	v_and_b32_e32 v128, 0xffff0000, v132
	v_pk_add_f32 v[132:133], v[150:151], 1.0 op_sel_hi:[1,0]
	v_or_b32_sdwa v127, v127, v0 dst_sel:DWORD dst_unused:UNUSED_PAD src0_sel:DWORD src1_sel:WORD_1
	v_or_b32_sdwa v126, v126, v0 dst_sel:DWORD dst_unused:UNUSED_PAD src0_sel:DWORD src1_sel:WORD_0
	s_nop 0
	v_rcp_f32_e32 v133, v133
	s_nop 0
	s_nop 0
	v_rcp_f32_e32 v132, v132
	s_nop 0
	v_mov_b32_e32 v150, v122
	v_mov_b32_e32 v151, v124
	v_pk_fma_f32 v[130:131], v[150:151], v[132:133], v[130:131]
	v_pk_add_f32 v[132:133], v[148:149], 1.0 op_sel_hi:[1,0]
	s_nop 0
	s_nop 0
	v_rcp_f32_e32 v133, v133
	s_nop 0
	s_nop 0
	v_rcp_f32_e32 v132, v132
	s_nop 0
	v_mov_b32_e32 v124, v123
	v_pk_fma_f32 v[122:123], v[124:125], v[132:133], v[128:129]
	v_cvt_pk_bf16_f32 v0, v130, v131
	v_cvt_pk_bf16_f32 v122, v122, v123
	v_and_b32_e32 v123, 0xffff0000, v122
	v_lshlrev_b32_e32 v122, 16, v122
	v_or_b32_sdwa v129, v123, v0 dst_sel:DWORD dst_unused:UNUSED_PAD src0_sel:DWORD src1_sel:WORD_1
	v_or_b32_sdwa v128, v122, v0 dst_sel:DWORD dst_unused:UNUSED_PAD src0_sel:DWORD src1_sel:WORD_0
	global_store_dwordx4 v[146:147], v[126:129], off
	s_nop 1
	v_add_u32_e32 v126, 0x80, v156
	v_add_u32_e32 v0, v157, v126
	v_lshl_add_u64 v[122:123], v[0:1], 1, s[6:7]
	global_load_dwordx4 v[122:125], v[122:123], off
	v_add_u32_e32 v0, v0, v158
	s_waitcnt vmcnt(0)
	v_lshlrev_b32_e32 v127, 16, v122
	v_and_b32_e32 v133, 0xffff0000, v122
	v_lshlrev_b32_e32 v147, 16, v123
	v_and_b32_e32 v149, 0xffff0000, v123
	v_lshl_add_u64 v[122:123], v[0:1], 1, s[10:11]
	global_load_dwordx4 v[128:131], v[122:123], off
	v_lshlrev_b32_e32 v146, 16, v124
	v_mul_f32_e32 v0, 0xbfb8aa3b, v127
	v_exp_f32_e32 v132, v0
	v_mul_f32_e32 v0, 0xbfb8aa3b, v146
	v_and_b32_e32 v124, 0xffff0000, v124
	v_exp_f32_e32 v146, v0
	v_mul_f32_e32 v0, 0xbfb8aa3b, v133
	v_exp_f32_e32 v148, v0
	v_mul_f32_e32 v0, 0xbfb8aa3b, v124
	v_exp_f32_e32 v124, v0
	v_mul_f32_e32 v0, 0xbfb8aa3b, v147
	v_exp_f32_e32 v133, v0
	v_lshlrev_b32_e32 v150, 16, v125
	v_mul_f32_e32 v0, 0xbfb8aa3b, v150
	v_and_b32_e32 v125, 0xffff0000, v125
	v_exp_f32_e32 v147, v0
	v_mul_f32_e32 v0, 0xbfb8aa3b, v149
	v_exp_f32_e32 v149, v0
	v_mul_f32_e32 v0, 0xbfb8aa3b, v125
	v_pk_add_f32 v[132:133], v[132:133], 1.0 op_sel_hi:[1,0]
	v_exp_f32_e32 v125, v0
	v_pk_add_f32 v[148:149], v[148:149], 1.0 op_sel_hi:[1,0]
	v_pk_add_f32 v[124:125], v[124:125], 1.0 op_sel_hi:[1,0]
	v_rcp_f32_e32 v133, v133
	s_nop 0
	s_waitcnt vmcnt(0)
	v_lshlrev_b32_e32 v151, 16, v129
	v_rcp_f32_e32 v132, v132
	s_nop 0
	v_mov_b32_e32 v160, v118
	v_mov_b32_e32 v161, v120
	v_lshlrev_b32_e32 v150, 16, v128
	v_pk_fma_f32 v[132:133], v[160:161], v[132:133], v[150:151]
	v_rcp_f32_e32 v149, v149
	s_nop 0
	v_and_b32_e32 v129, 0xffff0000, v129
	v_and_b32_e32 v128, 0xffff0000, v128
	v_rcp_f32_e32 v148, v148
	s_nop 0
	v_mov_b32_e32 v120, v119
	v_pk_fma_f32 v[118:119], v[120:121], v[148:149], v[128:129]
	v_cvt_pk_bf16_f32 v0, v132, v133
	v_cvt_pk_bf16_f32 v118, v118, v119
	v_and_b32_e32 v119, 0xffff0000, v118
	v_lshlrev_b32_e32 v118, 16, v118
	v_lshlrev_b32_e32 v121, 16, v131
	v_lshlrev_b32_e32 v120, 16, v130
	v_and_b32_e32 v129, 0xffff0000, v131
	v_and_b32_e32 v128, 0xffff0000, v130
	v_pk_add_f32 v[130:131], v[146:147], 1.0 op_sel_hi:[1,0]
	v_or_b32_sdwa v119, v119, v0 dst_sel:DWORD dst_unused:UNUSED_PAD src0_sel:DWORD src1_sel:WORD_1
	v_or_b32_sdwa v118, v118, v0 dst_sel:DWORD dst_unused:UNUSED_PAD src0_sel:DWORD src1_sel:WORD_0
	s_nop 0
	v_rcp_f32_e32 v131, v131
	s_nop 0
	s_nop 0
	v_rcp_f32_e32 v130, v130
	s_nop 0
	v_mov_b32_e32 v132, v114
	v_mov_b32_e32 v133, v116
	v_pk_fma_f32 v[120:121], v[132:133], v[130:131], v[120:121]
	v_rcp_f32_e32 v125, v125
	s_nop 0
	s_nop 0
	v_rcp_f32_e32 v124, v124
	s_nop 0
	v_mov_b32_e32 v116, v115
	v_pk_fma_f32 v[114:115], v[116:117], v[124:125], v[128:129]
	v_cvt_pk_bf16_f32 v0, v120, v121
	v_cvt_pk_bf16_f32 v114, v114, v115
	v_and_b32_e32 v115, 0xffff0000, v114
	v_lshlrev_b32_e32 v114, 16, v114
	v_add_u32_e32 v127, 0x16c00, v157
	v_or_b32_sdwa v121, v115, v0 dst_sel:DWORD dst_unused:UNUSED_PAD src0_sel:DWORD src1_sel:WORD_1
	v_or_b32_sdwa v120, v114, v0 dst_sel:DWORD dst_unused:UNUSED_PAD src0_sel:DWORD src1_sel:WORD_0
	v_add_u32_e32 v0, v127, v156
	global_store_dwordx4 v[122:123], v[118:121], off
	v_lshl_add_u64 v[114:115], v[0:1], 1, s[6:7]
	global_load_dwordx4 v[114:117], v[114:115], off
	v_or_b32_e32 v118, 16, v159
	v_mul_lo_u32 v146, v118, s61
	v_add_u32_e32 v0, v0, v146
	s_waitcnt vmcnt(0)
	v_lshlrev_b32_e32 v122, 16, v114
	v_and_b32_e32 v123, 0xffff0000, v114
	v_lshlrev_b32_e32 v125, 16, v115
	v_and_b32_e32 v129, 0xffff0000, v115
	v_lshl_add_u64 v[114:115], v[0:1], 1, s[10:11]
	global_load_dwordx4 v[118:121], v[114:115], off
	v_lshlrev_b32_e32 v124, 16, v116
	v_mul_f32_e32 v0, 0xbfb8aa3b, v122
	v_exp_f32_e32 v122, v0
	v_mul_f32_e32 v0, 0xbfb8aa3b, v124
	v_and_b32_e32 v116, 0xffff0000, v116
	v_exp_f32_e32 v124, v0
	v_mul_f32_e32 v0, 0xbfb8aa3b, v123
	v_exp_f32_e32 v128, v0
	v_mul_f32_e32 v0, 0xbfb8aa3b, v116
	v_exp_f32_e32 v116, v0
	v_mul_f32_e32 v0, 0xbfb8aa3b, v125
	v_exp_f32_e32 v123, v0
	v_lshlrev_b32_e32 v130, 16, v117
	v_mul_f32_e32 v0, 0xbfb8aa3b, v130
	v_and_b32_e32 v117, 0xffff0000, v117
	v_exp_f32_e32 v125, v0
	v_mul_f32_e32 v0, 0xbfb8aa3b, v129
	v_exp_f32_e32 v129, v0
	v_mul_f32_e32 v0, 0xbfb8aa3b, v117
	v_pk_add_f32 v[122:123], v[122:123], 1.0 op_sel_hi:[1,0]
	v_exp_f32_e32 v117, v0
	v_pk_add_f32 v[128:129], v[128:129], 1.0 op_sel_hi:[1,0]
	v_pk_add_f32 v[116:117], v[116:117], 1.0 op_sel_hi:[1,0]
	v_rcp_f32_e32 v123, v123
	s_nop 0
	s_waitcnt vmcnt(0)
	v_lshlrev_b32_e32 v131, 16, v119
	v_rcp_f32_e32 v122, v122
	s_nop 0
	v_mov_b32_e32 v132, v110
	v_mov_b32_e32 v133, v112
	v_lshlrev_b32_e32 v130, 16, v118
	v_pk_fma_f32 v[122:123], v[132:133], v[122:123], v[130:131]
	v_rcp_f32_e32 v129, v129
	s_nop 0
	v_and_b32_e32 v119, 0xffff0000, v119
	v_and_b32_e32 v118, 0xffff0000, v118
	v_rcp_f32_e32 v128, v128
	s_nop 0
	v_mov_b32_e32 v112, v111
	v_pk_fma_f32 v[110:111], v[112:113], v[128:129], v[118:119]
	v_cvt_pk_bf16_f32 v0, v122, v123
	v_cvt_pk_bf16_f32 v110, v110, v111
	v_and_b32_e32 v111, 0xffff0000, v110
	v_lshlrev_b32_e32 v110, 16, v110
	v_lshlrev_b32_e32 v113, 16, v121
	v_lshlrev_b32_e32 v112, 16, v120
	v_and_b32_e32 v119, 0xffff0000, v121
	v_and_b32_e32 v118, 0xffff0000, v120
	v_pk_add_f32 v[120:121], v[124:125], 1.0 op_sel_hi:[1,0]
	v_or_b32_sdwa v111, v111, v0 dst_sel:DWORD dst_unused:UNUSED_PAD src0_sel:DWORD src1_sel:WORD_1
	v_or_b32_sdwa v110, v110, v0 dst_sel:DWORD dst_unused:UNUSED_PAD src0_sel:DWORD src1_sel:WORD_0
	s_nop 0
	v_rcp_f32_e32 v121, v121
	s_nop 0
	s_nop 0
	v_rcp_f32_e32 v120, v120
	s_nop 0
	v_mov_b32_e32 v122, v106
	v_mov_b32_e32 v123, v108
	v_pk_fma_f32 v[112:113], v[122:123], v[120:121], v[112:113]
	v_rcp_f32_e32 v117, v117
	s_nop 0
	s_nop 0
	v_rcp_f32_e32 v116, v116
	s_nop 0
	v_mov_b32_e32 v108, v107
	v_pk_fma_f32 v[106:107], v[108:109], v[116:117], v[118:119]
	v_cvt_pk_bf16_f32 v0, v112, v113
	v_cvt_pk_bf16_f32 v106, v106, v107
	v_and_b32_e32 v107, 0xffff0000, v106
	v_lshlrev_b32_e32 v106, 16, v106
	v_or_b32_sdwa v113, v107, v0 dst_sel:DWORD dst_unused:UNUSED_PAD src0_sel:DWORD src1_sel:WORD_1
	v_or_b32_sdwa v112, v106, v0 dst_sel:DWORD dst_unused:UNUSED_PAD src0_sel:DWORD src1_sel:WORD_0
	v_add_u32_e32 v0, v127, v126
	global_store_dwordx4 v[114:115], v[110:113], off
	v_lshl_add_u64 v[106:107], v[0:1], 1, s[6:7]
	global_load_dwordx4 v[106:109], v[106:107], off
	v_add_u32_e32 v0, v0, v146
	s_waitcnt vmcnt(0)
	v_lshlrev_b32_e32 v114, 16, v106
	v_and_b32_e32 v115, 0xffff0000, v106
	v_lshlrev_b32_e32 v117, 16, v107
	v_and_b32_e32 v119, 0xffff0000, v107
	v_lshl_add_u64 v[106:107], v[0:1], 1, s[10:11]
	global_load_dwordx4 v[110:113], v[106:107], off
	v_lshlrev_b32_e32 v116, 16, v108
	v_mul_f32_e32 v0, 0xbfb8aa3b, v114
	v_exp_f32_e32 v114, v0
	v_mul_f32_e32 v0, 0xbfb8aa3b, v116
	v_and_b32_e32 v108, 0xffff0000, v108
	v_exp_f32_e32 v116, v0
	v_mul_f32_e32 v0, 0xbfb8aa3b, v115
	v_exp_f32_e32 v118, v0
	v_mul_f32_e32 v0, 0xbfb8aa3b, v108
	v_exp_f32_e32 v108, v0
	v_mul_f32_e32 v0, 0xbfb8aa3b, v117
	v_exp_f32_e32 v115, v0
	v_lshlrev_b32_e32 v120, 16, v109
	v_mul_f32_e32 v0, 0xbfb8aa3b, v120
	v_and_b32_e32 v109, 0xffff0000, v109
	v_exp_f32_e32 v117, v0
	v_mul_f32_e32 v0, 0xbfb8aa3b, v119
	v_exp_f32_e32 v119, v0
	v_mul_f32_e32 v0, 0xbfb8aa3b, v109
	v_pk_add_f32 v[114:115], v[114:115], 1.0 op_sel_hi:[1,0]
	v_exp_f32_e32 v109, v0
	v_pk_add_f32 v[118:119], v[118:119], 1.0 op_sel_hi:[1,0]
	v_pk_add_f32 v[108:109], v[108:109], 1.0 op_sel_hi:[1,0]
	v_rcp_f32_e32 v115, v115
	s_nop 0
	s_waitcnt vmcnt(0)
	v_lshlrev_b32_e32 v121, 16, v111
	v_rcp_f32_e32 v114, v114
	s_nop 0
	v_mov_b32_e32 v122, v102
	v_mov_b32_e32 v123, v104
	v_lshlrev_b32_e32 v120, 16, v110
	v_pk_fma_f32 v[114:115], v[122:123], v[114:115], v[120:121]
	v_rcp_f32_e32 v119, v119
	s_nop 0
	v_and_b32_e32 v111, 0xffff0000, v111
	v_and_b32_e32 v110, 0xffff0000, v110
	v_rcp_f32_e32 v118, v118
	s_nop 0
	v_mov_b32_e32 v104, v103
	v_pk_fma_f32 v[102:103], v[104:105], v[118:119], v[110:111]
	v_cvt_pk_bf16_f32 v0, v114, v115
	v_cvt_pk_bf16_f32 v102, v102, v103
	v_and_b32_e32 v103, 0xffff0000, v102
	v_lshlrev_b32_e32 v102, 16, v102
	v_lshlrev_b32_e32 v105, 16, v113
	v_lshlrev_b32_e32 v104, 16, v112
	v_and_b32_e32 v111, 0xffff0000, v113
	v_and_b32_e32 v110, 0xffff0000, v112
	v_pk_add_f32 v[112:113], v[116:117], 1.0 op_sel_hi:[1,0]
	v_or_b32_sdwa v103, v103, v0 dst_sel:DWORD dst_unused:UNUSED_PAD src0_sel:DWORD src1_sel:WORD_1
	v_or_b32_sdwa v102, v102, v0 dst_sel:DWORD dst_unused:UNUSED_PAD src0_sel:DWORD src1_sel:WORD_0
	s_nop 0
	v_rcp_f32_e32 v113, v113
	s_nop 0
	s_nop 0
	v_rcp_f32_e32 v112, v112
	s_nop 0
	v_mov_b32_e32 v114, v98
	v_mov_b32_e32 v115, v100
	v_pk_fma_f32 v[104:105], v[114:115], v[112:113], v[104:105]
	v_add_u32_e32 v116, 0x2d800, v157
	v_rcp_f32_e32 v109, v109
	s_nop 0
	s_nop 0
	v_rcp_f32_e32 v108, v108
	s_nop 0
	v_mov_b32_e32 v100, v99
	v_pk_fma_f32 v[98:99], v[100:101], v[108:109], v[110:111]
	v_cvt_pk_bf16_f32 v0, v104, v105
	v_cvt_pk_bf16_f32 v98, v98, v99
	v_and_b32_e32 v99, 0xffff0000, v98
	v_lshlrev_b32_e32 v98, 16, v98
	v_or_b32_sdwa v105, v99, v0 dst_sel:DWORD dst_unused:UNUSED_PAD src0_sel:DWORD src1_sel:WORD_1
	v_or_b32_sdwa v104, v98, v0 dst_sel:DWORD dst_unused:UNUSED_PAD src0_sel:DWORD src1_sel:WORD_0
	v_add_u32_e32 v0, v116, v156
	global_store_dwordx4 v[106:107], v[102:105], off
	v_lshl_add_u64 v[98:99], v[0:1], 1, s[6:7]
	global_load_dwordx4 v[98:101], v[98:99], off
	v_or_b32_e32 v102, 32, v159
	v_mul_lo_u32 v117, v102, s61
	v_add_u32_e32 v0, v0, v117
	s_waitcnt vmcnt(0)
	v_lshlrev_b32_e32 v106, 16, v98
	v_and_b32_e32 v107, 0xffff0000, v98
	v_lshlrev_b32_e32 v109, 16, v99
	v_and_b32_e32 v111, 0xffff0000, v99
	v_lshl_add_u64 v[98:99], v[0:1], 1, s[10:11]
	global_load_dwordx4 v[102:105], v[98:99], off
	v_lshlrev_b32_e32 v108, 16, v100
	v_mul_f32_e32 v0, 0xbfb8aa3b, v106
	v_exp_f32_e32 v106, v0
	v_mul_f32_e32 v0, 0xbfb8aa3b, v108
	v_and_b32_e32 v100, 0xffff0000, v100
	v_exp_f32_e32 v108, v0
	v_mul_f32_e32 v0, 0xbfb8aa3b, v107
	v_exp_f32_e32 v110, v0
	v_mul_f32_e32 v0, 0xbfb8aa3b, v100
	v_exp_f32_e32 v100, v0
	v_mul_f32_e32 v0, 0xbfb8aa3b, v109
	v_exp_f32_e32 v107, v0
	v_lshlrev_b32_e32 v112, 16, v101
	v_mul_f32_e32 v0, 0xbfb8aa3b, v112
	v_and_b32_e32 v101, 0xffff0000, v101
	v_exp_f32_e32 v109, v0
	v_mul_f32_e32 v0, 0xbfb8aa3b, v111
	v_exp_f32_e32 v111, v0
	v_mul_f32_e32 v0, 0xbfb8aa3b, v101
	v_pk_add_f32 v[106:107], v[106:107], 1.0 op_sel_hi:[1,0]
	v_exp_f32_e32 v101, v0
	v_pk_add_f32 v[110:111], v[110:111], 1.0 op_sel_hi:[1,0]
	v_pk_add_f32 v[100:101], v[100:101], 1.0 op_sel_hi:[1,0]
	v_rcp_f32_e32 v107, v107
	s_nop 0
	s_waitcnt vmcnt(0)
	v_lshlrev_b32_e32 v113, 16, v103
	v_rcp_f32_e32 v106, v106
	s_nop 0
	v_mov_b32_e32 v114, v94
	v_mov_b32_e32 v115, v96
	v_lshlrev_b32_e32 v112, 16, v102
	v_pk_fma_f32 v[106:107], v[114:115], v[106:107], v[112:113]
	v_rcp_f32_e32 v111, v111
	s_nop 0
	v_and_b32_e32 v103, 0xffff0000, v103
	v_and_b32_e32 v102, 0xffff0000, v102
	v_rcp_f32_e32 v110, v110
	s_nop 0
	v_mov_b32_e32 v96, v95
	v_pk_fma_f32 v[94:95], v[96:97], v[110:111], v[102:103]
	v_cvt_pk_bf16_f32 v0, v106, v107
	v_cvt_pk_bf16_f32 v94, v94, v95
	v_and_b32_e32 v95, 0xffff0000, v94
	v_lshlrev_b32_e32 v94, 16, v94
	v_lshlrev_b32_e32 v97, 16, v105
	v_lshlrev_b32_e32 v96, 16, v104
	v_and_b32_e32 v103, 0xffff0000, v105
	v_and_b32_e32 v102, 0xffff0000, v104
	v_pk_add_f32 v[104:105], v[108:109], 1.0 op_sel_hi:[1,0]
	v_or_b32_sdwa v95, v95, v0 dst_sel:DWORD dst_unused:UNUSED_PAD src0_sel:DWORD src1_sel:WORD_1
	v_or_b32_sdwa v94, v94, v0 dst_sel:DWORD dst_unused:UNUSED_PAD src0_sel:DWORD src1_sel:WORD_0
	s_nop 0
	v_rcp_f32_e32 v105, v105
	s_nop 0
	s_nop 0
	v_rcp_f32_e32 v104, v104
	s_nop 0
	v_mov_b32_e32 v106, v90
	v_mov_b32_e32 v107, v92
	v_pk_fma_f32 v[96:97], v[106:107], v[104:105], v[96:97]
	v_rcp_f32_e32 v101, v101
	s_nop 0
	s_nop 0
	v_rcp_f32_e32 v100, v100
	s_nop 0
	v_mov_b32_e32 v92, v91
	v_pk_fma_f32 v[90:91], v[92:93], v[100:101], v[102:103]
	v_cvt_pk_bf16_f32 v0, v96, v97
	v_cvt_pk_bf16_f32 v90, v90, v91
	v_and_b32_e32 v91, 0xffff0000, v90
	v_lshlrev_b32_e32 v90, 16, v90
	v_or_b32_sdwa v97, v91, v0 dst_sel:DWORD dst_unused:UNUSED_PAD src0_sel:DWORD src1_sel:WORD_1
	v_or_b32_sdwa v96, v90, v0 dst_sel:DWORD dst_unused:UNUSED_PAD src0_sel:DWORD src1_sel:WORD_0
	v_add_u32_e32 v0, v116, v126
	global_store_dwordx4 v[98:99], v[94:97], off
	v_lshl_add_u64 v[90:91], v[0:1], 1, s[6:7]
	global_load_dwordx4 v[90:93], v[90:91], off
	v_add_u32_e32 v0, v0, v117
	s_waitcnt vmcnt(0)
	v_lshlrev_b32_e32 v98, 16, v90
	v_and_b32_e32 v99, 0xffff0000, v90
	v_lshlrev_b32_e32 v101, 16, v91
	v_and_b32_e32 v103, 0xffff0000, v91
	v_lshl_add_u64 v[90:91], v[0:1], 1, s[10:11]
	global_load_dwordx4 v[94:97], v[90:91], off
	v_lshlrev_b32_e32 v100, 16, v92
	v_mul_f32_e32 v0, 0xbfb8aa3b, v98
	v_exp_f32_e32 v98, v0
	v_mul_f32_e32 v0, 0xbfb8aa3b, v100
	v_and_b32_e32 v92, 0xffff0000, v92
	v_exp_f32_e32 v100, v0
	v_mul_f32_e32 v0, 0xbfb8aa3b, v99
	v_exp_f32_e32 v102, v0
	v_mul_f32_e32 v0, 0xbfb8aa3b, v92
	v_exp_f32_e32 v92, v0
	v_mul_f32_e32 v0, 0xbfb8aa3b, v101
	v_exp_f32_e32 v99, v0
	v_lshlrev_b32_e32 v104, 16, v93
	v_mul_f32_e32 v0, 0xbfb8aa3b, v104
	v_and_b32_e32 v93, 0xffff0000, v93
	v_exp_f32_e32 v101, v0
	v_mul_f32_e32 v0, 0xbfb8aa3b, v103
	v_exp_f32_e32 v103, v0
	v_mul_f32_e32 v0, 0xbfb8aa3b, v93
	v_pk_add_f32 v[98:99], v[98:99], 1.0 op_sel_hi:[1,0]
	v_exp_f32_e32 v93, v0
	v_pk_add_f32 v[102:103], v[102:103], 1.0 op_sel_hi:[1,0]
	v_pk_add_f32 v[92:93], v[92:93], 1.0 op_sel_hi:[1,0]
	v_rcp_f32_e32 v99, v99
	s_nop 0
	s_waitcnt vmcnt(0)
	v_lshlrev_b32_e32 v105, 16, v95
	v_rcp_f32_e32 v98, v98
	s_nop 0
	v_mov_b32_e32 v106, v86
	v_mov_b32_e32 v107, v88
	v_lshlrev_b32_e32 v104, 16, v94
	v_pk_fma_f32 v[98:99], v[106:107], v[98:99], v[104:105]
	v_rcp_f32_e32 v103, v103
	s_nop 0
	v_and_b32_e32 v95, 0xffff0000, v95
	v_and_b32_e32 v94, 0xffff0000, v94
	v_rcp_f32_e32 v102, v102
	s_nop 0
	v_mov_b32_e32 v88, v87
	v_pk_fma_f32 v[86:87], v[88:89], v[102:103], v[94:95]
	v_cvt_pk_bf16_f32 v0, v98, v99
	v_cvt_pk_bf16_f32 v86, v86, v87
	v_and_b32_e32 v87, 0xffff0000, v86
	v_lshlrev_b32_e32 v86, 16, v86
	v_lshlrev_b32_e32 v89, 16, v97
	v_lshlrev_b32_e32 v88, 16, v96
	v_and_b32_e32 v95, 0xffff0000, v97
	v_and_b32_e32 v94, 0xffff0000, v96
	v_pk_add_f32 v[96:97], v[100:101], 1.0 op_sel_hi:[1,0]
	v_or_b32_sdwa v87, v87, v0 dst_sel:DWORD dst_unused:UNUSED_PAD src0_sel:DWORD src1_sel:WORD_1
	v_or_b32_sdwa v86, v86, v0 dst_sel:DWORD dst_unused:UNUSED_PAD src0_sel:DWORD src1_sel:WORD_0
	s_nop 0
	v_rcp_f32_e32 v97, v97
	s_nop 0
	s_nop 0
	v_rcp_f32_e32 v96, v96
	s_nop 0
	v_mov_b32_e32 v98, v82
	v_mov_b32_e32 v99, v84
	v_pk_fma_f32 v[88:89], v[98:99], v[96:97], v[88:89]
	v_add_u32_e32 v100, 0x44400, v157
	v_rcp_f32_e32 v93, v93
	s_nop 0
	s_nop 0
	v_rcp_f32_e32 v92, v92
	s_nop 0
	v_mov_b32_e32 v84, v83
	v_pk_fma_f32 v[82:83], v[84:85], v[92:93], v[94:95]
	v_cvt_pk_bf16_f32 v0, v88, v89
	v_cvt_pk_bf16_f32 v82, v82, v83
	v_and_b32_e32 v83, 0xffff0000, v82
	v_lshlrev_b32_e32 v82, 16, v82
	v_or_b32_sdwa v89, v83, v0 dst_sel:DWORD dst_unused:UNUSED_PAD src0_sel:DWORD src1_sel:WORD_1
	v_or_b32_sdwa v88, v82, v0 dst_sel:DWORD dst_unused:UNUSED_PAD src0_sel:DWORD src1_sel:WORD_0
	v_add_u32_e32 v0, v100, v156
	global_store_dwordx4 v[90:91], v[86:89], off
	v_lshl_add_u64 v[82:83], v[0:1], 1, s[6:7]
	global_load_dwordx4 v[82:85], v[82:83], off
	v_or_b32_e32 v86, 48, v159
	v_mul_lo_u32 v101, v86, s61
	v_add_u32_e32 v0, v0, v101
	s_waitcnt vmcnt(0)
	v_lshlrev_b32_e32 v90, 16, v82
	v_and_b32_e32 v91, 0xffff0000, v82
	v_lshlrev_b32_e32 v93, 16, v83
	v_and_b32_e32 v95, 0xffff0000, v83
	v_lshl_add_u64 v[82:83], v[0:1], 1, s[10:11]
	global_load_dwordx4 v[86:89], v[82:83], off
	v_lshlrev_b32_e32 v92, 16, v84
	v_mul_f32_e32 v0, 0xbfb8aa3b, v90
	v_exp_f32_e32 v90, v0
	v_mul_f32_e32 v0, 0xbfb8aa3b, v92
	v_and_b32_e32 v84, 0xffff0000, v84
	v_exp_f32_e32 v92, v0
	v_mul_f32_e32 v0, 0xbfb8aa3b, v91
	v_exp_f32_e32 v94, v0
	v_mul_f32_e32 v0, 0xbfb8aa3b, v84
	v_exp_f32_e32 v84, v0
	v_mul_f32_e32 v0, 0xbfb8aa3b, v93
	v_exp_f32_e32 v91, v0
	v_lshlrev_b32_e32 v96, 16, v85
	v_mul_f32_e32 v0, 0xbfb8aa3b, v96
	v_and_b32_e32 v85, 0xffff0000, v85
	v_exp_f32_e32 v93, v0
	v_mul_f32_e32 v0, 0xbfb8aa3b, v95
	v_exp_f32_e32 v95, v0
	v_mul_f32_e32 v0, 0xbfb8aa3b, v85
	v_pk_add_f32 v[90:91], v[90:91], 1.0 op_sel_hi:[1,0]
	v_exp_f32_e32 v85, v0
	v_pk_add_f32 v[94:95], v[94:95], 1.0 op_sel_hi:[1,0]
	v_pk_add_f32 v[84:85], v[84:85], 1.0 op_sel_hi:[1,0]
	v_rcp_f32_e32 v91, v91
	s_nop 0
	s_waitcnt vmcnt(0)
	v_lshlrev_b32_e32 v97, 16, v87
	v_rcp_f32_e32 v90, v90
	s_nop 0
	v_mov_b32_e32 v98, v78
	v_mov_b32_e32 v99, v80
	v_lshlrev_b32_e32 v96, 16, v86
	v_pk_fma_f32 v[90:91], v[98:99], v[90:91], v[96:97]
	v_rcp_f32_e32 v95, v95
	s_nop 0
	v_and_b32_e32 v87, 0xffff0000, v87
	v_and_b32_e32 v86, 0xffff0000, v86
	v_rcp_f32_e32 v94, v94
	s_nop 0
	v_mov_b32_e32 v80, v79
	v_pk_fma_f32 v[78:79], v[80:81], v[94:95], v[86:87]
	v_cvt_pk_bf16_f32 v0, v90, v91
	v_cvt_pk_bf16_f32 v78, v78, v79
	v_and_b32_e32 v79, 0xffff0000, v78
	v_lshlrev_b32_e32 v78, 16, v78
	v_lshlrev_b32_e32 v81, 16, v89
	v_lshlrev_b32_e32 v80, 16, v88
	v_and_b32_e32 v87, 0xffff0000, v89
	v_and_b32_e32 v86, 0xffff0000, v88
	v_pk_add_f32 v[88:89], v[92:93], 1.0 op_sel_hi:[1,0]
	v_or_b32_sdwa v79, v79, v0 dst_sel:DWORD dst_unused:UNUSED_PAD src0_sel:DWORD src1_sel:WORD_1
	v_or_b32_sdwa v78, v78, v0 dst_sel:DWORD dst_unused:UNUSED_PAD src0_sel:DWORD src1_sel:WORD_0
	s_nop 0
	v_rcp_f32_e32 v89, v89
	s_nop 0
	s_nop 0
	v_rcp_f32_e32 v88, v88
	s_nop 0
	v_mov_b32_e32 v90, v74
	v_mov_b32_e32 v91, v76
	v_pk_fma_f32 v[80:81], v[90:91], v[88:89], v[80:81]
	v_rcp_f32_e32 v85, v85
	s_nop 0
	s_nop 0
	v_rcp_f32_e32 v84, v84
	s_nop 0
	v_mov_b32_e32 v76, v75
	v_pk_fma_f32 v[74:75], v[76:77], v[84:85], v[86:87]
	v_cvt_pk_bf16_f32 v0, v80, v81
	v_cvt_pk_bf16_f32 v74, v74, v75
	v_and_b32_e32 v75, 0xffff0000, v74
	v_lshlrev_b32_e32 v74, 16, v74
	v_or_b32_sdwa v81, v75, v0 dst_sel:DWORD dst_unused:UNUSED_PAD src0_sel:DWORD src1_sel:WORD_1
	v_or_b32_sdwa v80, v74, v0 dst_sel:DWORD dst_unused:UNUSED_PAD src0_sel:DWORD src1_sel:WORD_0
	v_add_u32_e32 v0, v100, v126
	global_store_dwordx4 v[82:83], v[78:81], off
	v_lshl_add_u64 v[74:75], v[0:1], 1, s[6:7]
	global_load_dwordx4 v[74:77], v[74:75], off
	v_add_u32_e32 v0, v0, v101
	s_waitcnt vmcnt(0)
	v_lshlrev_b32_e32 v82, 16, v74
	v_and_b32_e32 v83, 0xffff0000, v74
	v_lshlrev_b32_e32 v85, 16, v75
	v_and_b32_e32 v87, 0xffff0000, v75
	v_lshl_add_u64 v[74:75], v[0:1], 1, s[10:11]
	global_load_dwordx4 v[78:81], v[74:75], off
	v_lshlrev_b32_e32 v84, 16, v76
	v_mul_f32_e32 v0, 0xbfb8aa3b, v82
	v_exp_f32_e32 v82, v0
	v_mul_f32_e32 v0, 0xbfb8aa3b, v84
	v_and_b32_e32 v76, 0xffff0000, v76
	v_exp_f32_e32 v84, v0
	v_mul_f32_e32 v0, 0xbfb8aa3b, v83
	v_exp_f32_e32 v86, v0
	v_mul_f32_e32 v0, 0xbfb8aa3b, v76
	v_exp_f32_e32 v76, v0
	v_mul_f32_e32 v0, 0xbfb8aa3b, v85
	v_exp_f32_e32 v83, v0
	v_lshlrev_b32_e32 v88, 16, v77
	v_mul_f32_e32 v0, 0xbfb8aa3b, v88
	v_and_b32_e32 v77, 0xffff0000, v77
	v_exp_f32_e32 v85, v0
	v_mul_f32_e32 v0, 0xbfb8aa3b, v87
	v_exp_f32_e32 v87, v0
	v_mul_f32_e32 v0, 0xbfb8aa3b, v77
	v_pk_add_f32 v[82:83], v[82:83], 1.0 op_sel_hi:[1,0]
	v_exp_f32_e32 v77, v0
	v_pk_add_f32 v[86:87], v[86:87], 1.0 op_sel_hi:[1,0]
	v_pk_add_f32 v[76:77], v[76:77], 1.0 op_sel_hi:[1,0]
	v_rcp_f32_e32 v83, v83
	s_nop 0
	s_waitcnt vmcnt(0)
	v_lshlrev_b32_e32 v89, 16, v79
	v_rcp_f32_e32 v82, v82
	s_nop 0
	v_mov_b32_e32 v90, v70
	v_mov_b32_e32 v91, v72
	v_lshlrev_b32_e32 v88, 16, v78
	v_pk_fma_f32 v[82:83], v[90:91], v[82:83], v[88:89]
	v_rcp_f32_e32 v87, v87
	s_nop 0
	v_and_b32_e32 v79, 0xffff0000, v79
	v_and_b32_e32 v78, 0xffff0000, v78
	v_rcp_f32_e32 v86, v86
	s_nop 0
	v_mov_b32_e32 v72, v71
	v_pk_fma_f32 v[70:71], v[72:73], v[86:87], v[78:79]
	v_cvt_pk_bf16_f32 v0, v82, v83
	v_cvt_pk_bf16_f32 v70, v70, v71
	v_and_b32_e32 v71, 0xffff0000, v70
	v_lshlrev_b32_e32 v70, 16, v70
	v_lshlrev_b32_e32 v73, 16, v81
	v_lshlrev_b32_e32 v72, 16, v80
	v_and_b32_e32 v79, 0xffff0000, v81
	v_and_b32_e32 v78, 0xffff0000, v80
	v_pk_add_f32 v[80:81], v[84:85], 1.0 op_sel_hi:[1,0]
	v_or_b32_sdwa v71, v71, v0 dst_sel:DWORD dst_unused:UNUSED_PAD src0_sel:DWORD src1_sel:WORD_1
	v_or_b32_sdwa v70, v70, v0 dst_sel:DWORD dst_unused:UNUSED_PAD src0_sel:DWORD src1_sel:WORD_0
	s_nop 0
	v_rcp_f32_e32 v81, v81
	s_nop 0
	s_nop 0
	v_rcp_f32_e32 v80, v80
	s_nop 0
	v_mov_b32_e32 v82, v66
	v_mov_b32_e32 v83, v68
	v_pk_fma_f32 v[72:73], v[82:83], v[80:81], v[72:73]
	v_add_u32_e32 v84, 0xb6000, v157
	v_rcp_f32_e32 v77, v77
	s_nop 0
	v_add_u32_e32 v85, 0xfff6a000, v158
	v_rcp_f32_e32 v76, v76
	s_nop 0
	v_mov_b32_e32 v68, v67
	v_pk_fma_f32 v[66:67], v[68:69], v[76:77], v[78:79]
	v_cvt_pk_bf16_f32 v0, v72, v73
	v_cvt_pk_bf16_f32 v66, v66, v67
	v_and_b32_e32 v67, 0xffff0000, v66
	v_lshlrev_b32_e32 v66, 16, v66
	v_or_b32_sdwa v73, v67, v0 dst_sel:DWORD dst_unused:UNUSED_PAD src0_sel:DWORD src1_sel:WORD_1
	v_or_b32_sdwa v72, v66, v0 dst_sel:DWORD dst_unused:UNUSED_PAD src0_sel:DWORD src1_sel:WORD_0
	v_add_u32_e32 v0, v84, v156
	global_store_dwordx4 v[74:75], v[70:73], off
	v_lshl_add_u64 v[66:67], v[0:1], 1, s[6:7]
	global_load_dwordx4 v[66:69], v[66:67], off
	v_add_u32_e32 v0, v0, v85
	s_waitcnt vmcnt(0)
	v_lshlrev_b32_e32 v74, 16, v66
	v_and_b32_e32 v75, 0xffff0000, v66
	v_lshlrev_b32_e32 v77, 16, v67
	v_and_b32_e32 v79, 0xffff0000, v67
	v_lshl_add_u64 v[66:67], v[0:1], 1, s[10:11]
	global_load_dwordx4 v[70:73], v[66:67], off
	v_lshlrev_b32_e32 v76, 16, v68
	v_mul_f32_e32 v0, 0xbfb8aa3b, v74
	v_exp_f32_e32 v74, v0
	v_mul_f32_e32 v0, 0xbfb8aa3b, v76
	v_and_b32_e32 v68, 0xffff0000, v68
	v_exp_f32_e32 v76, v0
	v_mul_f32_e32 v0, 0xbfb8aa3b, v75
	v_exp_f32_e32 v78, v0
	v_mul_f32_e32 v0, 0xbfb8aa3b, v68
	v_exp_f32_e32 v68, v0
	v_mul_f32_e32 v0, 0xbfb8aa3b, v77
	v_exp_f32_e32 v75, v0
	v_lshlrev_b32_e32 v80, 16, v69
	v_mul_f32_e32 v0, 0xbfb8aa3b, v80
	v_and_b32_e32 v69, 0xffff0000, v69
	v_exp_f32_e32 v77, v0
	v_mul_f32_e32 v0, 0xbfb8aa3b, v79
	v_exp_f32_e32 v79, v0
	v_mul_f32_e32 v0, 0xbfb8aa3b, v69
	v_pk_add_f32 v[74:75], v[74:75], 1.0 op_sel_hi:[1,0]
	v_exp_f32_e32 v69, v0
	v_pk_add_f32 v[78:79], v[78:79], 1.0 op_sel_hi:[1,0]
	v_pk_add_f32 v[68:69], v[68:69], 1.0 op_sel_hi:[1,0]
	v_rcp_f32_e32 v75, v75
	s_nop 0
	s_waitcnt vmcnt(0)
	v_lshlrev_b32_e32 v81, 16, v71
	v_rcp_f32_e32 v74, v74
	s_nop 0
	v_mov_b32_e32 v82, v62
	v_mov_b32_e32 v83, v64
	v_lshlrev_b32_e32 v80, 16, v70
	v_pk_fma_f32 v[74:75], v[82:83], v[74:75], v[80:81]
	v_rcp_f32_e32 v79, v79
	s_nop 0
	v_and_b32_e32 v71, 0xffff0000, v71
	v_and_b32_e32 v70, 0xffff0000, v70
	v_rcp_f32_e32 v78, v78
	s_nop 0
	v_mov_b32_e32 v64, v63
	v_pk_fma_f32 v[62:63], v[64:65], v[78:79], v[70:71]
	v_cvt_pk_bf16_f32 v0, v74, v75
	v_cvt_pk_bf16_f32 v62, v62, v63
	v_and_b32_e32 v63, 0xffff0000, v62
	v_lshlrev_b32_e32 v62, 16, v62
	v_lshlrev_b32_e32 v65, 16, v73
	v_lshlrev_b32_e32 v64, 16, v72
	v_and_b32_e32 v71, 0xffff0000, v73
	v_and_b32_e32 v70, 0xffff0000, v72
	v_pk_add_f32 v[72:73], v[76:77], 1.0 op_sel_hi:[1,0]
	v_or_b32_sdwa v63, v63, v0 dst_sel:DWORD dst_unused:UNUSED_PAD src0_sel:DWORD src1_sel:WORD_1
	v_or_b32_sdwa v62, v62, v0 dst_sel:DWORD dst_unused:UNUSED_PAD src0_sel:DWORD src1_sel:WORD_0
	s_nop 0
	v_rcp_f32_e32 v73, v73
	s_nop 0
	s_nop 0
	v_rcp_f32_e32 v72, v72
	s_nop 0
	v_mov_b32_e32 v74, v58
	v_mov_b32_e32 v75, v60
	v_pk_fma_f32 v[64:65], v[74:75], v[72:73], v[64:65]
	v_rcp_f32_e32 v69, v69
	s_nop 0
	s_nop 0
	v_rcp_f32_e32 v68, v68
	s_nop 0
	v_mov_b32_e32 v60, v59
	v_pk_fma_f32 v[58:59], v[60:61], v[68:69], v[70:71]
	v_cvt_pk_bf16_f32 v0, v64, v65
	v_cvt_pk_bf16_f32 v58, v58, v59
	v_and_b32_e32 v59, 0xffff0000, v58
	v_lshlrev_b32_e32 v58, 16, v58
	v_or_b32_sdwa v65, v59, v0 dst_sel:DWORD dst_unused:UNUSED_PAD src0_sel:DWORD src1_sel:WORD_1
	v_or_b32_sdwa v64, v58, v0 dst_sel:DWORD dst_unused:UNUSED_PAD src0_sel:DWORD src1_sel:WORD_0
	v_add_u32_e32 v0, v84, v126
	global_store_dwordx4 v[66:67], v[62:65], off
	v_lshl_add_u64 v[58:59], v[0:1], 1, s[6:7]
	global_load_dwordx4 v[58:61], v[58:59], off
	v_add_u32_e32 v0, v0, v85
	s_waitcnt vmcnt(0)
	v_lshlrev_b32_e32 v66, 16, v58
	v_and_b32_e32 v67, 0xffff0000, v58
	v_lshlrev_b32_e32 v69, 16, v59
	v_and_b32_e32 v71, 0xffff0000, v59
	v_lshl_add_u64 v[58:59], v[0:1], 1, s[10:11]
	global_load_dwordx4 v[62:65], v[58:59], off
	v_lshlrev_b32_e32 v68, 16, v60
	v_mul_f32_e32 v0, 0xbfb8aa3b, v66
	v_exp_f32_e32 v66, v0
	v_mul_f32_e32 v0, 0xbfb8aa3b, v68
	v_and_b32_e32 v60, 0xffff0000, v60
	v_exp_f32_e32 v68, v0
	v_mul_f32_e32 v0, 0xbfb8aa3b, v67
	v_exp_f32_e32 v70, v0
	v_mul_f32_e32 v0, 0xbfb8aa3b, v60
	v_exp_f32_e32 v60, v0
	v_mul_f32_e32 v0, 0xbfb8aa3b, v69
	v_exp_f32_e32 v67, v0
	v_lshlrev_b32_e32 v72, 16, v61
	v_mul_f32_e32 v0, 0xbfb8aa3b, v72
	v_and_b32_e32 v61, 0xffff0000, v61
	v_exp_f32_e32 v69, v0
	v_mul_f32_e32 v0, 0xbfb8aa3b, v71
	v_exp_f32_e32 v71, v0
	v_mul_f32_e32 v0, 0xbfb8aa3b, v61
	v_pk_add_f32 v[66:67], v[66:67], 1.0 op_sel_hi:[1,0]
	v_exp_f32_e32 v61, v0
	v_pk_add_f32 v[70:71], v[70:71], 1.0 op_sel_hi:[1,0]
	v_pk_add_f32 v[60:61], v[60:61], 1.0 op_sel_hi:[1,0]
	v_rcp_f32_e32 v67, v67
	s_nop 0
	s_waitcnt vmcnt(0)
	v_lshlrev_b32_e32 v73, 16, v63
	v_rcp_f32_e32 v66, v66
	s_nop 0
	v_mov_b32_e32 v74, v54
	v_mov_b32_e32 v75, v56
	v_lshlrev_b32_e32 v72, 16, v62
	v_pk_fma_f32 v[66:67], v[74:75], v[66:67], v[72:73]
	v_rcp_f32_e32 v71, v71
	s_nop 0
	v_and_b32_e32 v63, 0xffff0000, v63
	v_and_b32_e32 v62, 0xffff0000, v62
	v_rcp_f32_e32 v70, v70
	s_nop 0
	v_mov_b32_e32 v56, v55
	v_pk_fma_f32 v[54:55], v[56:57], v[70:71], v[62:63]
	v_cvt_pk_bf16_f32 v0, v66, v67
	v_cvt_pk_bf16_f32 v54, v54, v55
	v_and_b32_e32 v55, 0xffff0000, v54
	v_lshlrev_b32_e32 v54, 16, v54
	v_lshlrev_b32_e32 v57, 16, v65
	v_lshlrev_b32_e32 v56, 16, v64
	v_and_b32_e32 v63, 0xffff0000, v65
	v_and_b32_e32 v62, 0xffff0000, v64
	v_pk_add_f32 v[64:65], v[68:69], 1.0 op_sel_hi:[1,0]
	v_or_b32_sdwa v55, v55, v0 dst_sel:DWORD dst_unused:UNUSED_PAD src0_sel:DWORD src1_sel:WORD_1
	v_or_b32_sdwa v54, v54, v0 dst_sel:DWORD dst_unused:UNUSED_PAD src0_sel:DWORD src1_sel:WORD_0
	s_nop 0
	v_rcp_f32_e32 v65, v65
	s_nop 0
	s_nop 0
	v_rcp_f32_e32 v64, v64
	s_nop 0
	v_mov_b32_e32 v66, v50
	v_mov_b32_e32 v67, v52
	v_pk_fma_f32 v[56:57], v[66:67], v[64:65], v[56:57]
	v_add_u32_e32 v68, 0xccc00, v157
	v_rcp_f32_e32 v61, v61
	s_nop 0
	v_add_u32_e32 v69, 0xfff57400, v158
	v_rcp_f32_e32 v60, v60
	s_nop 0
	v_mov_b32_e32 v52, v51
	v_pk_fma_f32 v[50:51], v[52:53], v[60:61], v[62:63]
	v_cvt_pk_bf16_f32 v0, v56, v57
	v_cvt_pk_bf16_f32 v50, v50, v51
	v_and_b32_e32 v51, 0xffff0000, v50
	v_lshlrev_b32_e32 v50, 16, v50
	v_or_b32_sdwa v57, v51, v0 dst_sel:DWORD dst_unused:UNUSED_PAD src0_sel:DWORD src1_sel:WORD_1
	v_or_b32_sdwa v56, v50, v0 dst_sel:DWORD dst_unused:UNUSED_PAD src0_sel:DWORD src1_sel:WORD_0
	v_add_u32_e32 v0, v68, v156
	global_store_dwordx4 v[58:59], v[54:57], off
	v_lshl_add_u64 v[50:51], v[0:1], 1, s[6:7]
	global_load_dwordx4 v[50:53], v[50:51], off
	v_add_u32_e32 v0, v0, v69
	s_waitcnt vmcnt(0)
	v_lshlrev_b32_e32 v58, 16, v50
	v_and_b32_e32 v59, 0xffff0000, v50
	v_lshlrev_b32_e32 v61, 16, v51
	v_and_b32_e32 v63, 0xffff0000, v51
	v_lshl_add_u64 v[50:51], v[0:1], 1, s[10:11]
	global_load_dwordx4 v[54:57], v[50:51], off
	v_lshlrev_b32_e32 v60, 16, v52
	v_mul_f32_e32 v0, 0xbfb8aa3b, v58
	v_exp_f32_e32 v58, v0
	v_mul_f32_e32 v0, 0xbfb8aa3b, v60
	v_and_b32_e32 v52, 0xffff0000, v52
	v_exp_f32_e32 v60, v0
	v_mul_f32_e32 v0, 0xbfb8aa3b, v59
	v_exp_f32_e32 v62, v0
	v_mul_f32_e32 v0, 0xbfb8aa3b, v52
	v_exp_f32_e32 v52, v0
	v_mul_f32_e32 v0, 0xbfb8aa3b, v61
	v_exp_f32_e32 v59, v0
	v_lshlrev_b32_e32 v64, 16, v53
	v_mul_f32_e32 v0, 0xbfb8aa3b, v64
	v_and_b32_e32 v53, 0xffff0000, v53
	v_exp_f32_e32 v61, v0
	v_mul_f32_e32 v0, 0xbfb8aa3b, v63
	v_exp_f32_e32 v63, v0
	v_mul_f32_e32 v0, 0xbfb8aa3b, v53
	v_pk_add_f32 v[58:59], v[58:59], 1.0 op_sel_hi:[1,0]
	v_exp_f32_e32 v53, v0
	v_pk_add_f32 v[62:63], v[62:63], 1.0 op_sel_hi:[1,0]
	v_pk_add_f32 v[52:53], v[52:53], 1.0 op_sel_hi:[1,0]
	v_rcp_f32_e32 v59, v59
	s_nop 0
	s_waitcnt vmcnt(0)
	v_lshlrev_b32_e32 v65, 16, v55
	v_rcp_f32_e32 v58, v58
	s_nop 0
	v_mov_b32_e32 v66, v46
	v_mov_b32_e32 v67, v48
	v_lshlrev_b32_e32 v64, 16, v54
	v_pk_fma_f32 v[58:59], v[66:67], v[58:59], v[64:65]
	v_rcp_f32_e32 v63, v63
	s_nop 0
	v_and_b32_e32 v55, 0xffff0000, v55
	v_and_b32_e32 v54, 0xffff0000, v54
	v_rcp_f32_e32 v62, v62
	s_nop 0
	v_mov_b32_e32 v48, v47
	v_pk_fma_f32 v[46:47], v[48:49], v[62:63], v[54:55]
	v_cvt_pk_bf16_f32 v0, v58, v59
	v_cvt_pk_bf16_f32 v46, v46, v47
	v_and_b32_e32 v47, 0xffff0000, v46
	v_lshlrev_b32_e32 v46, 16, v46
	v_lshlrev_b32_e32 v49, 16, v57
	v_lshlrev_b32_e32 v48, 16, v56
	v_and_b32_e32 v55, 0xffff0000, v57
	v_and_b32_e32 v54, 0xffff0000, v56
	v_pk_add_f32 v[56:57], v[60:61], 1.0 op_sel_hi:[1,0]
	v_or_b32_sdwa v47, v47, v0 dst_sel:DWORD dst_unused:UNUSED_PAD src0_sel:DWORD src1_sel:WORD_1
	v_or_b32_sdwa v46, v46, v0 dst_sel:DWORD dst_unused:UNUSED_PAD src0_sel:DWORD src1_sel:WORD_0
	s_nop 0
	v_rcp_f32_e32 v57, v57
	s_nop 0
	s_nop 0
	v_rcp_f32_e32 v56, v56
	s_nop 0
	v_mov_b32_e32 v58, v42
	v_mov_b32_e32 v59, v44
	v_pk_fma_f32 v[48:49], v[58:59], v[56:57], v[48:49]
	v_rcp_f32_e32 v53, v53
	s_nop 0
	s_nop 0
	v_rcp_f32_e32 v52, v52
	s_nop 0
	v_mov_b32_e32 v44, v43
	v_pk_fma_f32 v[42:43], v[44:45], v[52:53], v[54:55]
	v_cvt_pk_bf16_f32 v0, v48, v49
	v_cvt_pk_bf16_f32 v42, v42, v43
	v_and_b32_e32 v43, 0xffff0000, v42
	v_lshlrev_b32_e32 v42, 16, v42
	v_or_b32_sdwa v49, v43, v0 dst_sel:DWORD dst_unused:UNUSED_PAD src0_sel:DWORD src1_sel:WORD_1
	v_or_b32_sdwa v48, v42, v0 dst_sel:DWORD dst_unused:UNUSED_PAD src0_sel:DWORD src1_sel:WORD_0
	v_add_u32_e32 v0, v68, v126
	global_store_dwordx4 v[50:51], v[46:49], off
	v_lshl_add_u64 v[42:43], v[0:1], 1, s[6:7]
	global_load_dwordx4 v[42:45], v[42:43], off
	v_add_u32_e32 v0, v0, v69
	s_waitcnt vmcnt(0)
	v_lshlrev_b32_e32 v50, 16, v42
	v_and_b32_e32 v51, 0xffff0000, v42
	v_lshlrev_b32_e32 v53, 16, v43
	v_and_b32_e32 v55, 0xffff0000, v43
	v_lshl_add_u64 v[42:43], v[0:1], 1, s[10:11]
	global_load_dwordx4 v[46:49], v[42:43], off
	v_lshlrev_b32_e32 v52, 16, v44
	v_mul_f32_e32 v0, 0xbfb8aa3b, v50
	v_exp_f32_e32 v50, v0
	v_mul_f32_e32 v0, 0xbfb8aa3b, v52
	v_and_b32_e32 v44, 0xffff0000, v44
	v_exp_f32_e32 v52, v0
	v_mul_f32_e32 v0, 0xbfb8aa3b, v51
	v_exp_f32_e32 v54, v0
	v_mul_f32_e32 v0, 0xbfb8aa3b, v44
	v_exp_f32_e32 v44, v0
	v_mul_f32_e32 v0, 0xbfb8aa3b, v53
	v_exp_f32_e32 v51, v0
	v_lshlrev_b32_e32 v56, 16, v45
	v_mul_f32_e32 v0, 0xbfb8aa3b, v56
	v_and_b32_e32 v45, 0xffff0000, v45
	v_exp_f32_e32 v53, v0
	v_mul_f32_e32 v0, 0xbfb8aa3b, v55
	v_exp_f32_e32 v55, v0
	v_mul_f32_e32 v0, 0xbfb8aa3b, v45
	v_pk_add_f32 v[50:51], v[50:51], 1.0 op_sel_hi:[1,0]
	v_exp_f32_e32 v45, v0
	v_pk_add_f32 v[54:55], v[54:55], 1.0 op_sel_hi:[1,0]
	v_pk_add_f32 v[44:45], v[44:45], 1.0 op_sel_hi:[1,0]
	v_rcp_f32_e32 v51, v51
	s_nop 0
	s_waitcnt vmcnt(0)
	v_lshlrev_b32_e32 v57, 16, v47
	v_rcp_f32_e32 v50, v50
	s_nop 0
	v_mov_b32_e32 v58, v38
	v_mov_b32_e32 v59, v40
	v_lshlrev_b32_e32 v56, 16, v46
	v_pk_fma_f32 v[50:51], v[58:59], v[50:51], v[56:57]
	v_rcp_f32_e32 v55, v55
	s_nop 0
	v_and_b32_e32 v47, 0xffff0000, v47
	v_and_b32_e32 v46, 0xffff0000, v46
	v_rcp_f32_e32 v54, v54
	s_nop 0
	v_mov_b32_e32 v40, v39
	v_pk_fma_f32 v[38:39], v[40:41], v[54:55], v[46:47]
	v_cvt_pk_bf16_f32 v0, v50, v51
	v_cvt_pk_bf16_f32 v38, v38, v39
	v_and_b32_e32 v39, 0xffff0000, v38
	v_lshlrev_b32_e32 v38, 16, v38
	v_lshlrev_b32_e32 v41, 16, v49
	v_lshlrev_b32_e32 v40, 16, v48
	v_and_b32_e32 v47, 0xffff0000, v49
	v_and_b32_e32 v46, 0xffff0000, v48
	v_pk_add_f32 v[48:49], v[52:53], 1.0 op_sel_hi:[1,0]
	v_or_b32_sdwa v39, v39, v0 dst_sel:DWORD dst_unused:UNUSED_PAD src0_sel:DWORD src1_sel:WORD_1
	v_or_b32_sdwa v38, v38, v0 dst_sel:DWORD dst_unused:UNUSED_PAD src0_sel:DWORD src1_sel:WORD_0
	s_nop 0
	v_rcp_f32_e32 v49, v49
	s_nop 0
	s_nop 0
	v_rcp_f32_e32 v48, v48
	s_nop 0
	v_mov_b32_e32 v50, v34
	v_mov_b32_e32 v51, v36
	v_pk_fma_f32 v[40:41], v[50:51], v[48:49], v[40:41]
	v_add_u32_e32 v52, 0xe3800, v157
	v_rcp_f32_e32 v45, v45
	s_nop 0
	v_add_u32_e32 v53, 0xfff44800, v158
	v_rcp_f32_e32 v44, v44
	s_nop 0
	v_mov_b32_e32 v36, v35
	v_pk_fma_f32 v[34:35], v[36:37], v[44:45], v[46:47]
	v_cvt_pk_bf16_f32 v0, v40, v41
	v_cvt_pk_bf16_f32 v34, v34, v35
	v_and_b32_e32 v35, 0xffff0000, v34
	v_lshlrev_b32_e32 v34, 16, v34
	v_or_b32_sdwa v41, v35, v0 dst_sel:DWORD dst_unused:UNUSED_PAD src0_sel:DWORD src1_sel:WORD_1
	v_or_b32_sdwa v40, v34, v0 dst_sel:DWORD dst_unused:UNUSED_PAD src0_sel:DWORD src1_sel:WORD_0
	v_add_u32_e32 v0, v52, v156
	global_store_dwordx4 v[42:43], v[38:41], off
	v_lshl_add_u64 v[34:35], v[0:1], 1, s[6:7]
	global_load_dwordx4 v[34:37], v[34:35], off
	v_add_u32_e32 v0, v0, v53
	s_waitcnt vmcnt(0)
	v_lshlrev_b32_e32 v42, 16, v34
	v_and_b32_e32 v43, 0xffff0000, v34
	v_lshlrev_b32_e32 v45, 16, v35
	v_and_b32_e32 v47, 0xffff0000, v35
	v_lshl_add_u64 v[34:35], v[0:1], 1, s[10:11]
	global_load_dwordx4 v[38:41], v[34:35], off
	v_lshlrev_b32_e32 v44, 16, v36
	v_mul_f32_e32 v0, 0xbfb8aa3b, v42
	v_exp_f32_e32 v42, v0
	v_mul_f32_e32 v0, 0xbfb8aa3b, v44
	v_and_b32_e32 v36, 0xffff0000, v36
	v_exp_f32_e32 v44, v0
	v_mul_f32_e32 v0, 0xbfb8aa3b, v43
	v_exp_f32_e32 v46, v0
	v_mul_f32_e32 v0, 0xbfb8aa3b, v36
	v_exp_f32_e32 v36, v0
	v_mul_f32_e32 v0, 0xbfb8aa3b, v45
	v_exp_f32_e32 v43, v0
	v_lshlrev_b32_e32 v48, 16, v37
	v_mul_f32_e32 v0, 0xbfb8aa3b, v48
	v_and_b32_e32 v37, 0xffff0000, v37
	v_exp_f32_e32 v45, v0
	v_mul_f32_e32 v0, 0xbfb8aa3b, v47
	v_exp_f32_e32 v47, v0
	v_mul_f32_e32 v0, 0xbfb8aa3b, v37
	v_pk_add_f32 v[42:43], v[42:43], 1.0 op_sel_hi:[1,0]
	v_exp_f32_e32 v37, v0
	v_pk_add_f32 v[46:47], v[46:47], 1.0 op_sel_hi:[1,0]
	v_pk_add_f32 v[36:37], v[36:37], 1.0 op_sel_hi:[1,0]
	v_rcp_f32_e32 v43, v43
	s_nop 0
	s_waitcnt vmcnt(0)
	v_lshlrev_b32_e32 v49, 16, v39
	v_rcp_f32_e32 v42, v42
	s_nop 0
	v_mov_b32_e32 v50, v30
	v_mov_b32_e32 v51, v32
	v_lshlrev_b32_e32 v48, 16, v38
	v_pk_fma_f32 v[42:43], v[50:51], v[42:43], v[48:49]
	v_rcp_f32_e32 v47, v47
	s_nop 0
	v_and_b32_e32 v39, 0xffff0000, v39
	v_and_b32_e32 v38, 0xffff0000, v38
	v_rcp_f32_e32 v46, v46
	s_nop 0
	v_mov_b32_e32 v32, v31
	v_pk_fma_f32 v[30:31], v[32:33], v[46:47], v[38:39]
	v_cvt_pk_bf16_f32 v0, v42, v43
	v_cvt_pk_bf16_f32 v30, v30, v31
	v_and_b32_e32 v31, 0xffff0000, v30
	v_lshlrev_b32_e32 v30, 16, v30
	v_lshlrev_b32_e32 v33, 16, v41
	v_lshlrev_b32_e32 v32, 16, v40
	v_and_b32_e32 v39, 0xffff0000, v41
	v_and_b32_e32 v38, 0xffff0000, v40
	v_pk_add_f32 v[40:41], v[44:45], 1.0 op_sel_hi:[1,0]
	v_or_b32_sdwa v31, v31, v0 dst_sel:DWORD dst_unused:UNUSED_PAD src0_sel:DWORD src1_sel:WORD_1
	v_or_b32_sdwa v30, v30, v0 dst_sel:DWORD dst_unused:UNUSED_PAD src0_sel:DWORD src1_sel:WORD_0
	s_nop 0
	v_rcp_f32_e32 v41, v41
	s_nop 0
	s_nop 0
	v_rcp_f32_e32 v40, v40
	s_nop 0
	v_mov_b32_e32 v42, v26
	v_mov_b32_e32 v43, v28
	v_pk_fma_f32 v[32:33], v[42:43], v[40:41], v[32:33]
	v_rcp_f32_e32 v37, v37
	s_nop 0
	s_nop 0
	v_rcp_f32_e32 v36, v36
	s_nop 0
	v_mov_b32_e32 v28, v27
	v_pk_fma_f32 v[26:27], v[28:29], v[36:37], v[38:39]
	v_cvt_pk_bf16_f32 v0, v32, v33
	v_cvt_pk_bf16_f32 v26, v26, v27
	v_and_b32_e32 v27, 0xffff0000, v26
	v_lshlrev_b32_e32 v26, 16, v26
	v_or_b32_sdwa v33, v27, v0 dst_sel:DWORD dst_unused:UNUSED_PAD src0_sel:DWORD src1_sel:WORD_1
	v_or_b32_sdwa v32, v26, v0 dst_sel:DWORD dst_unused:UNUSED_PAD src0_sel:DWORD src1_sel:WORD_0
	v_add_u32_e32 v0, v52, v126
	global_store_dwordx4 v[34:35], v[30:33], off
	v_lshl_add_u64 v[26:27], v[0:1], 1, s[6:7]
	global_load_dwordx4 v[26:29], v[26:27], off
	v_add_u32_e32 v0, v0, v53
	s_waitcnt vmcnt(0)
	v_lshlrev_b32_e32 v34, 16, v26
	v_and_b32_e32 v35, 0xffff0000, v26
	v_lshlrev_b32_e32 v37, 16, v27
	v_and_b32_e32 v39, 0xffff0000, v27
	v_lshl_add_u64 v[26:27], v[0:1], 1, s[10:11]
	global_load_dwordx4 v[30:33], v[26:27], off
	v_lshlrev_b32_e32 v36, 16, v28
	v_mul_f32_e32 v0, 0xbfb8aa3b, v34
	v_exp_f32_e32 v34, v0
	v_mul_f32_e32 v0, 0xbfb8aa3b, v36
	v_and_b32_e32 v28, 0xffff0000, v28
	v_exp_f32_e32 v36, v0
	v_mul_f32_e32 v0, 0xbfb8aa3b, v35
	v_exp_f32_e32 v38, v0
	v_mul_f32_e32 v0, 0xbfb8aa3b, v28
	v_exp_f32_e32 v28, v0
	v_mul_f32_e32 v0, 0xbfb8aa3b, v37
	v_exp_f32_e32 v35, v0
	v_lshlrev_b32_e32 v40, 16, v29
	v_mul_f32_e32 v0, 0xbfb8aa3b, v40
	v_and_b32_e32 v29, 0xffff0000, v29
	v_exp_f32_e32 v37, v0
	v_mul_f32_e32 v0, 0xbfb8aa3b, v39
	v_exp_f32_e32 v39, v0
	v_mul_f32_e32 v0, 0xbfb8aa3b, v29
	v_pk_add_f32 v[34:35], v[34:35], 1.0 op_sel_hi:[1,0]
	v_exp_f32_e32 v29, v0
	v_pk_add_f32 v[38:39], v[38:39], 1.0 op_sel_hi:[1,0]
	v_pk_add_f32 v[28:29], v[28:29], 1.0 op_sel_hi:[1,0]
	v_rcp_f32_e32 v35, v35
	s_nop 0
	s_waitcnt vmcnt(0)
	v_lshlrev_b32_e32 v41, 16, v31
	v_rcp_f32_e32 v34, v34
	s_nop 0
	v_mov_b32_e32 v42, v22
	v_mov_b32_e32 v43, v24
	v_lshlrev_b32_e32 v40, 16, v30
	v_pk_fma_f32 v[34:35], v[42:43], v[34:35], v[40:41]
	v_rcp_f32_e32 v39, v39
	s_nop 0
	v_and_b32_e32 v31, 0xffff0000, v31
	v_and_b32_e32 v30, 0xffff0000, v30
	v_rcp_f32_e32 v38, v38
	s_nop 0
	v_mov_b32_e32 v24, v23
	v_pk_fma_f32 v[22:23], v[24:25], v[38:39], v[30:31]
	v_cvt_pk_bf16_f32 v0, v34, v35
	v_cvt_pk_bf16_f32 v22, v22, v23
	v_and_b32_e32 v23, 0xffff0000, v22
	v_lshlrev_b32_e32 v22, 16, v22
	v_lshlrev_b32_e32 v25, 16, v33
	v_lshlrev_b32_e32 v24, 16, v32
	v_and_b32_e32 v31, 0xffff0000, v33
	v_and_b32_e32 v30, 0xffff0000, v32
	v_pk_add_f32 v[32:33], v[36:37], 1.0 op_sel_hi:[1,0]
	v_or_b32_sdwa v23, v23, v0 dst_sel:DWORD dst_unused:UNUSED_PAD src0_sel:DWORD src1_sel:WORD_1
	v_or_b32_sdwa v22, v22, v0 dst_sel:DWORD dst_unused:UNUSED_PAD src0_sel:DWORD src1_sel:WORD_0
	s_nop 0
	v_rcp_f32_e32 v33, v33
	s_nop 0
	s_nop 0
	v_rcp_f32_e32 v32, v32
	s_nop 0
	v_mov_b32_e32 v34, v18
	v_mov_b32_e32 v35, v20
	v_pk_fma_f32 v[24:25], v[34:35], v[32:33], v[24:25]
	v_add_u32_e32 v36, 0xfa400, v157
	v_rcp_f32_e32 v29, v29
	s_nop 0
	v_add_u32_e32 v37, 0xfff31c00, v158
	v_rcp_f32_e32 v28, v28
	s_nop 0
	v_mov_b32_e32 v20, v19
	v_pk_fma_f32 v[18:19], v[20:21], v[28:29], v[30:31]
	v_cvt_pk_bf16_f32 v0, v24, v25
	v_cvt_pk_bf16_f32 v18, v18, v19
	v_and_b32_e32 v19, 0xffff0000, v18
	v_lshlrev_b32_e32 v18, 16, v18
	v_or_b32_sdwa v25, v19, v0 dst_sel:DWORD dst_unused:UNUSED_PAD src0_sel:DWORD src1_sel:WORD_1
	v_or_b32_sdwa v24, v18, v0 dst_sel:DWORD dst_unused:UNUSED_PAD src0_sel:DWORD src1_sel:WORD_0
	v_add_u32_e32 v0, v36, v156
	global_store_dwordx4 v[26:27], v[22:25], off
	v_lshl_add_u64 v[18:19], v[0:1], 1, s[6:7]
	global_load_dwordx4 v[18:21], v[18:19], off
	v_add_u32_e32 v0, v0, v37
	s_waitcnt vmcnt(0)
	v_lshlrev_b32_e32 v26, 16, v18
	v_and_b32_e32 v27, 0xffff0000, v18
	v_lshlrev_b32_e32 v29, 16, v19
	v_and_b32_e32 v31, 0xffff0000, v19
	v_lshl_add_u64 v[18:19], v[0:1], 1, s[10:11]
	global_load_dwordx4 v[22:25], v[18:19], off
	v_lshlrev_b32_e32 v28, 16, v20
	v_mul_f32_e32 v0, 0xbfb8aa3b, v26
	v_exp_f32_e32 v26, v0
	v_mul_f32_e32 v0, 0xbfb8aa3b, v28
	v_and_b32_e32 v20, 0xffff0000, v20
	v_exp_f32_e32 v28, v0
	v_mul_f32_e32 v0, 0xbfb8aa3b, v27
	v_exp_f32_e32 v30, v0
	v_mul_f32_e32 v0, 0xbfb8aa3b, v20
	v_exp_f32_e32 v20, v0
	v_mul_f32_e32 v0, 0xbfb8aa3b, v29
	v_exp_f32_e32 v27, v0
	v_lshlrev_b32_e32 v32, 16, v21
	v_mul_f32_e32 v0, 0xbfb8aa3b, v32
	v_and_b32_e32 v21, 0xffff0000, v21
	v_exp_f32_e32 v29, v0
	v_mul_f32_e32 v0, 0xbfb8aa3b, v31
	v_exp_f32_e32 v31, v0
	v_mul_f32_e32 v0, 0xbfb8aa3b, v21
	v_pk_add_f32 v[26:27], v[26:27], 1.0 op_sel_hi:[1,0]
	v_exp_f32_e32 v21, v0
	v_pk_add_f32 v[30:31], v[30:31], 1.0 op_sel_hi:[1,0]
	v_pk_add_f32 v[20:21], v[20:21], 1.0 op_sel_hi:[1,0]
	v_rcp_f32_e32 v27, v27
	s_nop 0
	s_waitcnt vmcnt(0)
	v_lshlrev_b32_e32 v33, 16, v23
	v_rcp_f32_e32 v26, v26
	s_nop 0
	v_mov_b32_e32 v34, v14
	v_mov_b32_e32 v35, v16
	v_lshlrev_b32_e32 v32, 16, v22
	v_pk_fma_f32 v[26:27], v[34:35], v[26:27], v[32:33]
	v_rcp_f32_e32 v31, v31
	s_nop 0
	v_and_b32_e32 v23, 0xffff0000, v23
	v_and_b32_e32 v22, 0xffff0000, v22
	v_rcp_f32_e32 v30, v30
	s_nop 0
	v_mov_b32_e32 v16, v15
	v_pk_fma_f32 v[14:15], v[16:17], v[30:31], v[22:23]
	v_cvt_pk_bf16_f32 v0, v26, v27
	v_cvt_pk_bf16_f32 v14, v14, v15
	v_and_b32_e32 v15, 0xffff0000, v14
	v_lshlrev_b32_e32 v14, 16, v14
	v_lshlrev_b32_e32 v17, 16, v25
	v_lshlrev_b32_e32 v16, 16, v24
	v_and_b32_e32 v23, 0xffff0000, v25
	v_and_b32_e32 v22, 0xffff0000, v24
	v_pk_add_f32 v[24:25], v[28:29], 1.0 op_sel_hi:[1,0]
	v_or_b32_sdwa v15, v15, v0 dst_sel:DWORD dst_unused:UNUSED_PAD src0_sel:DWORD src1_sel:WORD_1
	v_or_b32_sdwa v14, v14, v0 dst_sel:DWORD dst_unused:UNUSED_PAD src0_sel:DWORD src1_sel:WORD_0
	s_nop 0
	v_rcp_f32_e32 v25, v25
	s_nop 0
	s_nop 0
	v_rcp_f32_e32 v24, v24
	s_nop 0
	v_mov_b32_e32 v26, v10
	v_mov_b32_e32 v27, v12
	v_pk_fma_f32 v[16:17], v[26:27], v[24:25], v[16:17]
	v_rcp_f32_e32 v21, v21
	s_nop 0
	s_nop 0
	v_rcp_f32_e32 v20, v20
	s_nop 0
	v_mov_b32_e32 v12, v11
	v_pk_fma_f32 v[10:11], v[12:13], v[20:21], v[22:23]
	v_cvt_pk_bf16_f32 v0, v16, v17
	v_cvt_pk_bf16_f32 v10, v10, v11
	v_and_b32_e32 v11, 0xffff0000, v10
	v_lshlrev_b32_e32 v10, 16, v10
	v_or_b32_sdwa v17, v11, v0 dst_sel:DWORD dst_unused:UNUSED_PAD src0_sel:DWORD src1_sel:WORD_1
	v_or_b32_sdwa v16, v10, v0 dst_sel:DWORD dst_unused:UNUSED_PAD src0_sel:DWORD src1_sel:WORD_0
	v_add_u32_e32 v0, v36, v126
	global_store_dwordx4 v[18:19], v[14:17], off
	v_lshl_add_u64 v[10:11], v[0:1], 1, s[6:7]
	global_load_dwordx4 v[10:13], v[10:11], off
	v_add_u32_e32 v0, v0, v37
	s_waitcnt vmcnt(0)
	v_lshlrev_b32_e32 v18, 16, v10
	v_and_b32_e32 v19, 0xffff0000, v10
	v_lshlrev_b32_e32 v21, 16, v11
	v_and_b32_e32 v23, 0xffff0000, v11
	v_lshl_add_u64 v[10:11], v[0:1], 1, s[10:11]
	global_load_dwordx4 v[14:17], v[10:11], off
	v_lshlrev_b32_e32 v20, 16, v12
	v_mul_f32_e32 v0, 0xbfb8aa3b, v18
	v_exp_f32_e32 v18, v0
	v_mul_f32_e32 v0, 0xbfb8aa3b, v20
	v_and_b32_e32 v12, 0xffff0000, v12
	v_exp_f32_e32 v20, v0
	v_mul_f32_e32 v0, 0xbfb8aa3b, v19
	v_exp_f32_e32 v22, v0
	v_mul_f32_e32 v0, 0xbfb8aa3b, v12
	v_exp_f32_e32 v12, v0
	v_mul_f32_e32 v0, 0xbfb8aa3b, v21
	v_exp_f32_e32 v19, v0
	v_lshlrev_b32_e32 v24, 16, v13
	v_mul_f32_e32 v0, 0xbfb8aa3b, v24
	v_and_b32_e32 v13, 0xffff0000, v13
	v_exp_f32_e32 v21, v0
	v_mul_f32_e32 v0, 0xbfb8aa3b, v23
	v_exp_f32_e32 v23, v0
	v_mul_f32_e32 v0, 0xbfb8aa3b, v13
	v_pk_add_f32 v[18:19], v[18:19], 1.0 op_sel_hi:[1,0]
	v_exp_f32_e32 v13, v0
	v_pk_add_f32 v[22:23], v[22:23], 1.0 op_sel_hi:[1,0]
	v_pk_add_f32 v[12:13], v[12:13], 1.0 op_sel_hi:[1,0]
	v_rcp_f32_e32 v19, v19
	s_nop 0
	s_waitcnt vmcnt(0)
	v_lshlrev_b32_e32 v25, 16, v15
	v_rcp_f32_e32 v18, v18
	s_nop 0
	v_mov_b32_e32 v26, v6
	v_mov_b32_e32 v27, v8
	v_lshlrev_b32_e32 v24, 16, v14
	v_pk_fma_f32 v[18:19], v[26:27], v[18:19], v[24:25]
	v_rcp_f32_e32 v23, v23
	s_nop 0
	v_and_b32_e32 v15, 0xffff0000, v15
	v_and_b32_e32 v14, 0xffff0000, v14
	v_rcp_f32_e32 v22, v22
	s_nop 0
	v_mov_b32_e32 v8, v7
	v_pk_fma_f32 v[6:7], v[8:9], v[22:23], v[14:15]
	v_cvt_pk_bf16_f32 v0, v18, v19
	v_cvt_pk_bf16_f32 v6, v6, v7
	v_and_b32_e32 v7, 0xffff0000, v6
	v_lshlrev_b32_e32 v6, 16, v6
	v_lshlrev_b32_e32 v9, 16, v17
	v_lshlrev_b32_e32 v8, 16, v16
	v_and_b32_e32 v15, 0xffff0000, v17
	v_and_b32_e32 v14, 0xffff0000, v16
	v_pk_add_f32 v[16:17], v[20:21], 1.0 op_sel_hi:[1,0]
	v_or_b32_sdwa v7, v7, v0 dst_sel:DWORD dst_unused:UNUSED_PAD src0_sel:DWORD src1_sel:WORD_1
	v_or_b32_sdwa v6, v6, v0 dst_sel:DWORD dst_unused:UNUSED_PAD src0_sel:DWORD src1_sel:WORD_0
	s_nop 0
	v_rcp_f32_e32 v17, v17
	s_nop 0
	s_nop 0
	v_rcp_f32_e32 v16, v16
	s_nop 0
	v_mov_b32_e32 v18, v2
	v_mov_b32_e32 v19, v4
	v_pk_fma_f32 v[8:9], v[18:19], v[16:17], v[8:9]
	v_rcp_f32_e32 v13, v13
	s_nop 0
	s_mov_b64 s[26:27], s[18:19]
	v_rcp_f32_e32 v12, v12
	s_nop 0
	v_mov_b32_e32 v4, v3
	v_pk_fma_f32 v[2:3], v[4:5], v[12:13], v[14:15]
	v_cvt_pk_bf16_f32 v0, v8, v9
	v_cvt_pk_bf16_f32 v2, v2, v3
	v_and_b32_e32 v3, 0xffff0000, v2
	v_lshlrev_b32_e32 v2, 16, v2
	v_or_b32_sdwa v9, v3, v0 dst_sel:DWORD dst_unused:UNUSED_PAD src0_sel:DWORD src1_sel:WORD_1
	v_or_b32_sdwa v8, v2, v0 dst_sel:DWORD dst_unused:UNUSED_PAD src0_sel:DWORD src1_sel:WORD_0
	s_and_b64 vcc, exec, s[12:13]
	global_store_dwordx4 v[10:11], v[6:9], off
	s_cbranch_vccz .LBB0_1356
	s_waitcnt vmcnt(0)
	v_readlane_b32 s76, v255, 8
	s_mov_b32 s92, 0x3b2aaaab
	s_cmp_gt_u32 s36, 3
	v_readlane_b32 s77, v255, 9
	s_mul_i32 s60, s33, 0x1800
	s_mul_hi_i32 s62, s64, 0x300
	s_mul_i32 s75, s33, 0x16c00
	s_mov_b32 s93, 0x3c800000
	s_cbranch_scc1 .LBB0_1363
	s_barrier

.LBB0_1372:
	v_add_u32_e32 v0, 0x10000, v154
	s_waitcnt vmcnt(0)
	ds_read_b128 v[130:133], v0
	ds_read_b128 v[146:149], v0 offset:1024
	ds_read_b128 v[156:159], v0 offset:2048
	ds_read_b128 v[160:163], v0 offset:3072
	s_add_u32 s28, s26, 0xfffc0080
	s_addc_u32 s29, s27, -1
	s_cmp_eq_u32 s97, 12
	s_cselect_b32 s31, s2, s29
	s_cselect_b32 s30, s17, s28
	s_cselect_b32 s29, s15, s94
	s_cselect_b32 s28, s89, s90
	v_lshl_add_u64 v[150:151], s[26:27], 0, v[142:143]
	s_add_i32 m0, s38, 0xc000
	ds_read_b128 v[164:167], v153
	ds_read_b128 v[168:171], v153 offset:1024
	ds_read_b128 v[172:175], v153 offset:2048
	ds_read_b128 v[176:179], v153 offset:3072
	ds_read_b128 v[182:185], v153 offset:4096
	ds_read_b128 v[186:189], v153 offset:5120
	ds_read_b128 v[190:193], v153 offset:6144
	ds_read_b128 v[194:197], v153 offset:7168
	global_load_lds_dwordx4 v[150:151], off
	v_lshl_add_u64 v[150:151], s[26:27], 0, v[144:145]
	s_add_i32 m0, s38, 0xe000
	s_nop 0
	global_load_lds_dwordx4 v[150:151], off
	s_waitcnt lgkmcnt(8)
	s_barrier
	s_waitcnt lgkmcnt(0)
	s_setprio 1
	s_waitcnt lgkmcnt(0)
	v_mfma_f32_16x16x32_bf16 v[126:129], v[130:133], v[164:167], v[126:129]
	v_mfma_f32_16x16x32_bf16 v[122:125], v[156:159], v[164:167], v[122:125]
	v_mfma_f32_16x16x32_bf16 v[110:113], v[130:133], v[172:175], v[110:113]
	v_mfma_f32_16x16x32_bf16 v[106:109], v[156:159], v[172:175], v[106:109]
	v_mfma_f32_16x16x32_bf16 v[94:97], v[130:133], v[182:185], v[94:97]
	v_mfma_f32_16x16x32_bf16 v[90:93], v[156:159], v[182:185], v[90:93]
	v_mfma_f32_16x16x32_bf16 v[78:81], v[130:133], v[190:193], v[78:81]
	v_mfma_f32_16x16x32_bf16 v[74:77], v[156:159], v[190:193], v[74:77]
	v_mfma_f32_16x16x32_bf16 v[126:129], v[146:149], v[168:171], v[126:129]
	v_mfma_f32_16x16x32_bf16 v[122:125], v[160:163], v[168:171], v[122:125]
	v_mfma_f32_16x16x32_bf16 v[110:113], v[146:149], v[176:179], v[110:113]
	v_mfma_f32_16x16x32_bf16 v[106:109], v[160:163], v[176:179], v[106:109]
	v_mfma_f32_16x16x32_bf16 v[94:97], v[146:149], v[186:189], v[94:97]
	v_mfma_f32_16x16x32_bf16 v[90:93], v[160:163], v[186:189], v[90:93]
	v_mfma_f32_16x16x32_bf16 v[78:81], v[146:149], v[194:197], v[78:81]
	v_mfma_f32_16x16x32_bf16 v[74:77], v[160:163], v[194:197], v[74:77]
	s_setprio 0
	s_barrier
	s_mov_b32 m0, s23
	v_add_u32_e32 v0, 0x14000, v154
	v_lshl_add_u64 v[150:151], s[28:29], 0, v[138:139]
	s_waitcnt vmcnt(0)
	ds_read_b128 v[198:201], v0
	ds_read_b128 v[202:205], v0 offset:1024
	ds_read_b128 v[206:209], v0 offset:2048
	ds_read_b128 v[210:213], v0 offset:3072
	global_load_lds_dwordx4 v[150:151], off
	v_lshl_add_u64 v[214:215], s[28:29], 0, v[134:135]
	s_mov_b32 m0, s25
	s_nop 0
	global_load_lds_dwordx4 v[214:215], off
	s_barrier
	s_waitcnt lgkmcnt(0)
	s_setprio 1
	s_waitcnt lgkmcnt(0)
	v_mfma_f32_16x16x32_bf16 v[118:121], v[198:201], v[164:167], v[118:121]
	v_mfma_f32_16x16x32_bf16 v[114:117], v[206:209], v[164:167], v[114:117]
	v_mfma_f32_16x16x32_bf16 v[102:105], v[198:201], v[172:175], v[102:105]
	v_mfma_f32_16x16x32_bf16 v[98:101], v[206:209], v[172:175], v[98:101]
	v_mfma_f32_16x16x32_bf16 v[86:89], v[198:201], v[182:185], v[86:89]
	v_mfma_f32_16x16x32_bf16 v[82:85], v[206:209], v[182:185], v[82:85]
	v_mfma_f32_16x16x32_bf16 v[70:73], v[198:201], v[190:193], v[70:73]
	v_mfma_f32_16x16x32_bf16 v[66:69], v[206:209], v[190:193], v[66:69]
	v_mfma_f32_16x16x32_bf16 v[118:121], v[202:205], v[168:171], v[118:121]
	v_mfma_f32_16x16x32_bf16 v[114:117], v[210:213], v[168:171], v[114:117]
	v_mfma_f32_16x16x32_bf16 v[102:105], v[202:205], v[176:179], v[102:105]
	v_mfma_f32_16x16x32_bf16 v[98:101], v[210:213], v[176:179], v[98:101]
	v_mfma_f32_16x16x32_bf16 v[86:89], v[202:205], v[186:189], v[86:89]
	v_mfma_f32_16x16x32_bf16 v[82:85], v[210:213], v[186:189], v[82:85]
	v_mfma_f32_16x16x32_bf16 v[70:73], v[202:205], v[194:197], v[70:73]
	v_mfma_f32_16x16x32_bf16 v[66:69], v[210:213], v[194:197], v[66:69]
	s_setprio 0
	s_mov_b32 m0, s38
	v_lshl_add_u64 v[216:217], s[30:31], 0, v[140:141]
	s_barrier
	s_waitcnt vmcnt(0)
	ds_read_b128 v[164:167], v153 offset:16384
	ds_read_b128 v[168:171], v153 offset:17408
	ds_read_b128 v[172:175], v153 offset:18432
	ds_read_b128 v[176:179], v153 offset:19456
	ds_read_b128 v[182:185], v153 offset:20480
	ds_read_b128 v[186:189], v153 offset:21504
	ds_read_b128 v[190:193], v153 offset:22528
	ds_read_b128 v[194:197], v153 offset:23552
	global_load_lds_dwordx4 v[216:217], off
	v_lshl_add_u64 v[222:223], s[30:31], 0, v[136:137]
	s_mov_b32 m0, s39
	s_nop 0
	global_load_lds_dwordx4 v[222:223], off
	s_barrier
	s_waitcnt lgkmcnt(0)
	s_setprio 1
	s_waitcnt lgkmcnt(0)
	v_mfma_f32_16x16x32_bf16 v[62:65], v[130:133], v[164:167], v[62:65]
	v_mfma_f32_16x16x32_bf16 v[58:61], v[156:159], v[164:167], v[58:61]
	v_mfma_f32_16x16x32_bf16 v[46:49], v[130:133], v[172:175], v[46:49]
	v_mfma_f32_16x16x32_bf16 v[42:45], v[156:159], v[172:175], v[42:45]
	v_mfma_f32_16x16x32_bf16 v[30:33], v[130:133], v[182:185], v[30:33]
	v_mfma_f32_16x16x32_bf16 v[26:29], v[156:159], v[182:185], v[26:29]
	v_mfma_f32_16x16x32_bf16 v[14:17], v[130:133], v[190:193], v[14:17]
	v_mfma_f32_16x16x32_bf16 v[10:13], v[156:159], v[190:193], v[10:13]
	v_mfma_f32_16x16x32_bf16 v[62:65], v[146:149], v[168:171], v[62:65]
	v_mfma_f32_16x16x32_bf16 v[58:61], v[160:163], v[168:171], v[58:61]
	v_mfma_f32_16x16x32_bf16 v[46:49], v[146:149], v[176:179], v[46:49]
	v_mfma_f32_16x16x32_bf16 v[42:45], v[160:163], v[176:179], v[42:45]
	v_mfma_f32_16x16x32_bf16 v[30:33], v[146:149], v[186:189], v[30:33]
	v_mfma_f32_16x16x32_bf16 v[26:29], v[160:163], v[186:189], v[26:29]
	v_mfma_f32_16x16x32_bf16 v[14:17], v[146:149], v[194:197], v[14:17]
	v_mfma_f32_16x16x32_bf16 v[10:13], v[160:163], v[194:197], v[10:13]
	s_setprio 0
	s_barrier
	s_add_u32 s76, s28, 0x40000
	s_addc_u32 s77, s29, 0
	s_mov_b32 m0, s68
	v_lshl_add_u64 v[130:131], s[76:77], 0, v[138:139]
	global_load_lds_dwordx4 v[130:131], off
	v_lshl_add_u64 v[130:131], s[76:77], 0, v[134:135]
	s_mov_b32 m0, s69
	s_nop 0
	global_load_lds_dwordx4 v[130:131], off
	s_waitcnt vmcnt(6)
	s_barrier
	s_setprio 1
	v_mfma_f32_16x16x32_bf16 v[54:57], v[198:201], v[164:167], v[54:57]
	v_mfma_f32_16x16x32_bf16 v[50:53], v[206:209], v[164:167], v[50:53]
	v_mfma_f32_16x16x32_bf16 v[38:41], v[198:201], v[172:175], v[38:41]
	v_mfma_f32_16x16x32_bf16 v[34:37], v[206:209], v[172:175], v[34:37]
	v_mfma_f32_16x16x32_bf16 v[22:25], v[198:201], v[182:185], v[22:25]
	v_mfma_f32_16x16x32_bf16 v[18:21], v[206:209], v[182:185], v[18:21]
	v_mfma_f32_16x16x32_bf16 v[6:9], v[198:201], v[190:193], v[6:9]
	v_mfma_f32_16x16x32_bf16 v[2:5], v[206:209], v[190:193], v[2:5]
	v_mfma_f32_16x16x32_bf16 v[54:57], v[202:205], v[168:171], v[54:57]
	v_mfma_f32_16x16x32_bf16 v[50:53], v[210:213], v[168:171], v[50:53]
	v_mfma_f32_16x16x32_bf16 v[38:41], v[202:205], v[176:179], v[38:41]
	v_mfma_f32_16x16x32_bf16 v[34:37], v[210:213], v[176:179], v[34:37]
	v_mfma_f32_16x16x32_bf16 v[22:25], v[202:205], v[186:189], v[22:25]
	v_mfma_f32_16x16x32_bf16 v[18:21], v[210:213], v[186:189], v[18:21]
	v_mfma_f32_16x16x32_bf16 v[6:9], v[202:205], v[194:197], v[6:9]
	v_mfma_f32_16x16x32_bf16 v[2:5], v[210:213], v[194:197], v[2:5]
	s_setprio 0
	v_add_u32_e32 v0, 0x18000, v154
	s_barrier
	s_waitcnt vmcnt(0)
	ds_read_b128 v[130:133], v0
	ds_read_b128 v[146:149], v0 offset:1024
	ds_read_b128 v[156:159], v0 offset:2048
	ds_read_b128 v[160:163], v0 offset:3072
	s_add_u32 s30, s30, 0x40000
	s_addc_u32 s31, s31, 0
	s_mov_b32 m0, s82
	v_lshl_add_u64 v[198:199], s[30:31], 0, v[140:141]
	ds_read_b128 v[164:167], v153 offset:32768
	ds_read_b128 v[168:171], v153 offset:33792
	ds_read_b128 v[172:175], v153 offset:34816
	ds_read_b128 v[176:179], v153 offset:35840
	ds_read_b128 v[182:185], v153 offset:36864
	ds_read_b128 v[186:189], v153 offset:37888
	ds_read_b128 v[190:193], v153 offset:38912
	ds_read_b128 v[194:197], v153 offset:39936
	global_load_lds_dwordx4 v[198:199], off
	v_lshl_add_u64 v[198:199], s[30:31], 0, v[136:137]
	s_mov_b32 m0, s96
	s_nop 0
	global_load_lds_dwordx4 v[198:199], off
	s_waitcnt lgkmcnt(8)
	s_barrier
	s_waitcnt lgkmcnt(0)
	s_setprio 1
	s_waitcnt lgkmcnt(0)
	v_mfma_f32_16x16x32_bf16 v[126:129], v[130:133], v[164:167], v[126:129]
	v_mfma_f32_16x16x32_bf16 v[122:125], v[156:159], v[164:167], v[122:125]
	v_mfma_f32_16x16x32_bf16 v[110:113], v[130:133], v[172:175], v[110:113]
	v_mfma_f32_16x16x32_bf16 v[106:109], v[156:159], v[172:175], v[106:109]
	v_mfma_f32_16x16x32_bf16 v[94:97], v[130:133], v[182:185], v[94:97]
	v_mfma_f32_16x16x32_bf16 v[90:93], v[156:159], v[182:185], v[90:93]
	v_mfma_f32_16x16x32_bf16 v[78:81], v[130:133], v[190:193], v[78:81]
	v_mfma_f32_16x16x32_bf16 v[74:77], v[156:159], v[190:193], v[74:77]
	v_mfma_f32_16x16x32_bf16 v[126:129], v[146:149], v[168:171], v[126:129]
	v_mfma_f32_16x16x32_bf16 v[122:125], v[160:163], v[168:171], v[122:125]
	v_mfma_f32_16x16x32_bf16 v[110:113], v[146:149], v[176:179], v[110:113]
	v_mfma_f32_16x16x32_bf16 v[106:109], v[160:163], v[176:179], v[106:109]
	v_mfma_f32_16x16x32_bf16 v[94:97], v[146:149], v[186:189], v[94:97]
	v_mfma_f32_16x16x32_bf16 v[90:93], v[160:163], v[186:189], v[90:93]
	v_mfma_f32_16x16x32_bf16 v[78:81], v[146:149], v[194:197], v[78:81]
	v_mfma_f32_16x16x32_bf16 v[74:77], v[160:163], v[194:197], v[74:77]
	s_setprio 0
	s_barrier
	s_mov_b32 m0, s4
	v_add_u32_e32 v0, 0x1c000, v154
	v_lshl_add_u64 v[150:151], v[150:151], 0, s[84:85]
	s_waitcnt vmcnt(0)
	ds_read_b128 v[198:201], v0
	ds_read_b128 v[202:205], v0 offset:1024
	ds_read_b128 v[206:209], v0 offset:2048
	ds_read_b128 v[210:213], v0 offset:3072
	global_load_lds_dwordx4 v[150:151], off
	v_lshl_add_u64 v[150:151], v[214:215], 0, s[84:85]
	s_mov_b32 m0, s5
	s_nop 0
	global_load_lds_dwordx4 v[150:151], off
	s_barrier
	s_waitcnt lgkmcnt(0)
	s_setprio 1
	s_waitcnt lgkmcnt(0)
	v_mfma_f32_16x16x32_bf16 v[118:121], v[198:201], v[164:167], v[118:121]
	v_mfma_f32_16x16x32_bf16 v[114:117], v[206:209], v[164:167], v[114:117]
	v_mfma_f32_16x16x32_bf16 v[102:105], v[198:201], v[172:175], v[102:105]
	v_mfma_f32_16x16x32_bf16 v[98:101], v[206:209], v[172:175], v[98:101]
	v_mfma_f32_16x16x32_bf16 v[86:89], v[198:201], v[182:185], v[86:89]
	v_mfma_f32_16x16x32_bf16 v[82:85], v[206:209], v[182:185], v[82:85]
	v_mfma_f32_16x16x32_bf16 v[70:73], v[198:201], v[190:193], v[70:73]
	v_mfma_f32_16x16x32_bf16 v[66:69], v[206:209], v[190:193], v[66:69]
	v_mfma_f32_16x16x32_bf16 v[118:121], v[202:205], v[168:171], v[118:121]
	v_mfma_f32_16x16x32_bf16 v[114:117], v[210:213], v[168:171], v[114:117]
	v_mfma_f32_16x16x32_bf16 v[102:105], v[202:205], v[176:179], v[102:105]
	v_mfma_f32_16x16x32_bf16 v[98:101], v[210:213], v[176:179], v[98:101]
	v_mfma_f32_16x16x32_bf16 v[86:89], v[202:205], v[186:189], v[86:89]
	v_mfma_f32_16x16x32_bf16 v[82:85], v[210:213], v[186:189], v[82:85]
	v_mfma_f32_16x16x32_bf16 v[70:73], v[202:205], v[194:197], v[70:73]
	v_mfma_f32_16x16x32_bf16 v[66:69], v[210:213], v[194:197], v[66:69]
	s_setprio 0
	s_mov_b32 m0, s60
	v_lshl_add_u64 v[150:151], v[216:217], 0, s[84:85]
	s_barrier
	s_waitcnt vmcnt(0)
	ds_read_b128 v[164:167], v153 offset:49152
	ds_read_b128 v[168:171], v153 offset:50176
	ds_read_b128 v[172:175], v153 offset:51200
	ds_read_b128 v[176:179], v153 offset:52224
	ds_read_b128 v[182:185], v153 offset:53248
	ds_read_b128 v[186:189], v153 offset:54272
	ds_read_b128 v[190:193], v153 offset:55296
	ds_read_b128 v[194:197], v153 offset:56320
	global_load_lds_dwordx4 v[150:151], off
	v_lshl_add_u64 v[150:151], v[222:223], 0, s[84:85]
	s_mov_b32 m0, s92
	s_nop 0
	global_load_lds_dwordx4 v[150:151], off
	s_barrier
	s_waitcnt lgkmcnt(0)
	s_setprio 1
	s_waitcnt lgkmcnt(0)
	v_mfma_f32_16x16x32_bf16 v[62:65], v[130:133], v[164:167], v[62:65]
	v_mfma_f32_16x16x32_bf16 v[58:61], v[156:159], v[164:167], v[58:61]
	v_mfma_f32_16x16x32_bf16 v[46:49], v[130:133], v[172:175], v[46:49]
	v_mfma_f32_16x16x32_bf16 v[42:45], v[156:159], v[172:175], v[42:45]
	v_mfma_f32_16x16x32_bf16 v[30:33], v[130:133], v[182:185], v[30:33]
	v_mfma_f32_16x16x32_bf16 v[26:29], v[156:159], v[182:185], v[26:29]
	v_mfma_f32_16x16x32_bf16 v[14:17], v[130:133], v[190:193], v[14:17]
	v_mfma_f32_16x16x32_bf16 v[10:13], v[156:159], v[190:193], v[10:13]
	v_mfma_f32_16x16x32_bf16 v[62:65], v[146:149], v[168:171], v[62:65]
	v_mfma_f32_16x16x32_bf16 v[58:61], v[160:163], v[168:171], v[58:61]
	v_mfma_f32_16x16x32_bf16 v[46:49], v[146:149], v[176:179], v[46:49]
	v_mfma_f32_16x16x32_bf16 v[42:45], v[160:163], v[176:179], v[42:45]
	v_mfma_f32_16x16x32_bf16 v[30:33], v[146:149], v[186:189], v[30:33]
	v_mfma_f32_16x16x32_bf16 v[26:29], v[160:163], v[186:189], v[26:29]
	v_mfma_f32_16x16x32_bf16 v[14:17], v[146:149], v[194:197], v[14:17]
	v_mfma_f32_16x16x32_bf16 v[10:13], v[160:163], v[194:197], v[10:13]
	s_setprio 0
	s_barrier
	s_add_u32 s28, s28, 0x40080
	s_addc_u32 s29, s29, 0
	s_mov_b32 m0, s93
	v_lshl_add_u64 v[130:131], s[28:29], 0, v[138:139]
	global_load_lds_dwordx4 v[130:131], off
	v_lshl_add_u64 v[130:131], s[28:29], 0, v[134:135]
	s_mov_b32 m0, s3
	s_nop 0
	global_load_lds_dwordx4 v[130:131], off
	s_waitcnt vmcnt(6)
	s_barrier
	s_setprio 1
	v_mfma_f32_16x16x32_bf16 v[54:57], v[198:201], v[164:167], v[54:57]
	v_mfma_f32_16x16x32_bf16 v[50:53], v[206:209], v[164:167], v[50:53]
	v_mfma_f32_16x16x32_bf16 v[38:41], v[198:201], v[172:175], v[38:41]
	v_mfma_f32_16x16x32_bf16 v[34:37], v[206:209], v[172:175], v[34:37]
	v_mfma_f32_16x16x32_bf16 v[22:25], v[198:201], v[182:185], v[22:25]
	v_mfma_f32_16x16x32_bf16 v[18:21], v[206:209], v[182:185], v[18:21]
	v_mfma_f32_16x16x32_bf16 v[6:9], v[198:201], v[190:193], v[6:9]
	v_mfma_f32_16x16x32_bf16 v[2:5], v[206:209], v[190:193], v[2:5]
	v_mfma_f32_16x16x32_bf16 v[54:57], v[202:205], v[168:171], v[54:57]
	v_mfma_f32_16x16x32_bf16 v[50:53], v[210:213], v[168:171], v[50:53]
	v_mfma_f32_16x16x32_bf16 v[38:41], v[202:205], v[176:179], v[38:41]
	v_mfma_f32_16x16x32_bf16 v[34:37], v[210:213], v[176:179], v[34:37]
	v_mfma_f32_16x16x32_bf16 v[22:25], v[202:205], v[186:189], v[22:25]
	v_mfma_f32_16x16x32_bf16 v[18:21], v[210:213], v[186:189], v[18:21]
	v_mfma_f32_16x16x32_bf16 v[6:9], v[202:205], v[194:197], v[6:9]
	v_mfma_f32_16x16x32_bf16 v[2:5], v[210:213], v[194:197], v[2:5]
	s_setprio 0
	s_add_i32 s97, s97, 2
	s_add_u32 s26, s26, 0x100
	s_addc_u32 s27, s27, 0
	s_add_u32 s90, s90, 0x100
	s_addc_u32 s94, s94, 0
	s_cmp_gt_u32 s97, 13
	s_barrier
	s_cbranch_scc0 .LBB0_1372
	v_lshl_add_u32 v159, s24, 8, v152
	v_lshl_add_u32 v156, s22, 8, v155
	v_mul_lo_u32 v157, v159, s71
	v_add_u32_e32 v0, v157, v156
	v_lshl_add_u64 v[130:131], v[0:1], 1, s[6:7]
	global_load_dwordx4 v[130:133], v[130:131], off
	v_mul_lo_u32 v158, v159, s61
	v_add_u32_e32 v0, v0, v158
	v_lshl_add_u64 v[146:147], v[0:1], 1, s[10:11]
	s_mov_b32 s22, s14
	s_mov_b32 s24, s16
	s_mov_b64 s[28:29], s[20:21]
	s_waitcnt vmcnt(0)
	v_lshlrev_b32_e32 v148, 16, v130
	v_and_b32_e32 v149, 0xffff0000, v130
	v_lshlrev_b32_e32 v151, 16, v131
	v_and_b32_e32 v163, 0xffff0000, v131
	v_lshlrev_b32_e32 v150, 16, v132
	v_and_b32_e32 v161, 0xffff0000, v132
	v_lshlrev_b32_e32 v164, 16, v133
	v_and_b32_e32 v165, 0xffff0000, v133
	global_load_dwordx4 v[130:133], v[146:147], off
	v_mul_f32_e32 v0, 0xbfb8aa3b, v148
	v_exp_f32_e32 v160, v0
	v_mul_f32_e32 v0, 0xbfb8aa3b, v150
	v_exp_f32_e32 v150, v0
	v_mul_f32_e32 v0, 0xbfb8aa3b, v149
	v_exp_f32_e32 v162, v0
	v_mul_f32_e32 v0, 0xbfb8aa3b, v161
	v_exp_f32_e32 v148, v0
	v_mul_f32_e32 v0, 0xbfb8aa3b, v151
	v_exp_f32_e32 v161, v0
	v_mul_f32_e32 v0, 0xbfb8aa3b, v164
	v_exp_f32_e32 v151, v0
	v_mul_f32_e32 v0, 0xbfb8aa3b, v163
	v_exp_f32_e32 v163, v0
	v_mul_f32_e32 v0, 0xbfb8aa3b, v165
	v_pk_add_f32 v[160:161], v[160:161], 1.0 op_sel_hi:[1,0]
	v_exp_f32_e32 v149, v0
	v_pk_add_f32 v[162:163], v[162:163], 1.0 op_sel_hi:[1,0]
	v_rcp_f32_e32 v161, v161
	s_nop 0
	s_waitcnt vmcnt(0)
	v_lshlrev_b32_e32 v165, 16, v131
	v_rcp_f32_e32 v160, v160
	s_nop 0
	v_mov_b32_e32 v166, v126
	v_mov_b32_e32 v167, v128
	v_lshlrev_b32_e32 v164, 16, v130
	v_pk_fma_f32 v[160:161], v[166:167], v[160:161], v[164:165]
	v_rcp_f32_e32 v163, v163
	s_nop 0
	v_and_b32_e32 v131, 0xffff0000, v131
	v_and_b32_e32 v130, 0xffff0000, v130
	v_rcp_f32_e32 v162, v162
	s_nop 0
	v_mov_b32_e32 v128, v127
	v_pk_fma_f32 v[126:127], v[128:129], v[162:163], v[130:131]
	v_cvt_pk_bf16_f32 v0, v160, v161
	v_cvt_pk_bf16_f32 v126, v126, v127
	v_and_b32_e32 v127, 0xffff0000, v126
	v_lshlrev_b32_e32 v126, 16, v126
	v_lshlrev_b32_e32 v131, 16, v133
	v_lshlrev_b32_e32 v130, 16, v132
	v_and_b32_e32 v129, 0xffff0000, v133
	v_and_b32_e32 v128, 0xffff0000, v132
	v_pk_add_f32 v[132:133], v[150:151], 1.0 op_sel_hi:[1,0]
	v_or_b32_sdwa v127, v127, v0 dst_sel:DWORD dst_unused:UNUSED_PAD src0_sel:DWORD src1_sel:WORD_1
	v_or_b32_sdwa v126, v126, v0 dst_sel:DWORD dst_unused:UNUSED_PAD src0_sel:DWORD src1_sel:WORD_0
	s_nop 0
	v_rcp_f32_e32 v133, v133
	s_nop 0
	s_nop 0
	v_rcp_f32_e32 v132, v132
	s_nop 0
	v_mov_b32_e32 v150, v122
	v_mov_b32_e32 v151, v124
	v_pk_fma_f32 v[130:131], v[150:151], v[132:133], v[130:131]
	v_pk_add_f32 v[132:133], v[148:149], 1.0 op_sel_hi:[1,0]
	s_nop 0
	s_nop 0
	v_rcp_f32_e32 v133, v133
	s_nop 0
	s_nop 0
	v_rcp_f32_e32 v132, v132
	s_nop 0
	v_mov_b32_e32 v124, v123
	v_pk_fma_f32 v[122:123], v[124:125], v[132:133], v[128:129]
	v_cvt_pk_bf16_f32 v0, v130, v131
	v_cvt_pk_bf16_f32 v122, v122, v123
	v_and_b32_e32 v123, 0xffff0000, v122
	v_lshlrev_b32_e32 v122, 16, v122
	v_or_b32_sdwa v129, v123, v0 dst_sel:DWORD dst_unused:UNUSED_PAD src0_sel:DWORD src1_sel:WORD_1
	v_or_b32_sdwa v128, v122, v0 dst_sel:DWORD dst_unused:UNUSED_PAD src0_sel:DWORD src1_sel:WORD_0
	global_store_dwordx4 v[146:147], v[126:129], off
	s_nop 1
	v_add_u32_e32 v126, 0x80, v156
	v_add_u32_e32 v0, v157, v126
	v_lshl_add_u64 v[122:123], v[0:1], 1, s[6:7]
	global_load_dwordx4 v[122:125], v[122:123], off
	v_add_u32_e32 v0, v0, v158
	s_waitcnt vmcnt(0)
	v_lshlrev_b32_e32 v127, 16, v122
	v_and_b32_e32 v133, 0xffff0000, v122
	v_lshlrev_b32_e32 v147, 16, v123
	v_and_b32_e32 v149, 0xffff0000, v123
	v_lshl_add_u64 v[122:123], v[0:1], 1, s[10:11]
	global_load_dwordx4 v[128:131], v[122:123], off
	v_lshlrev_b32_e32 v146, 16, v124
	v_mul_f32_e32 v0, 0xbfb8aa3b, v127
	v_exp_f32_e32 v132, v0
	v_mul_f32_e32 v0, 0xbfb8aa3b, v146
	v_and_b32_e32 v124, 0xffff0000, v124
	v_exp_f32_e32 v146, v0
	v_mul_f32_e32 v0, 0xbfb8aa3b, v133
	v_exp_f32_e32 v148, v0
	v_mul_f32_e32 v0, 0xbfb8aa3b, v124
	v_exp_f32_e32 v124, v0
	v_mul_f32_e32 v0, 0xbfb8aa3b, v147
	v_exp_f32_e32 v133, v0
	v_lshlrev_b32_e32 v150, 16, v125
	v_mul_f32_e32 v0, 0xbfb8aa3b, v150
	v_and_b32_e32 v125, 0xffff0000, v125
	v_exp_f32_e32 v147, v0
	v_mul_f32_e32 v0, 0xbfb8aa3b, v149
	v_exp_f32_e32 v149, v0
	v_mul_f32_e32 v0, 0xbfb8aa3b, v125
	v_pk_add_f32 v[132:133], v[132:133], 1.0 op_sel_hi:[1,0]
	v_exp_f32_e32 v125, v0
	v_pk_add_f32 v[148:149], v[148:149], 1.0 op_sel_hi:[1,0]
	v_pk_add_f32 v[124:125], v[124:125], 1.0 op_sel_hi:[1,0]
	v_rcp_f32_e32 v133, v133
	s_nop 0
	s_waitcnt vmcnt(0)
	v_lshlrev_b32_e32 v151, 16, v129
	v_rcp_f32_e32 v132, v132
	s_nop 0
	v_mov_b32_e32 v160, v118
	v_mov_b32_e32 v161, v120
	v_lshlrev_b32_e32 v150, 16, v128
	v_pk_fma_f32 v[132:133], v[160:161], v[132:133], v[150:151]
	v_rcp_f32_e32 v149, v149
	s_nop 0
	v_and_b32_e32 v129, 0xffff0000, v129
	v_and_b32_e32 v128, 0xffff0000, v128
	v_rcp_f32_e32 v148, v148
	s_nop 0
	v_mov_b32_e32 v120, v119
	v_pk_fma_f32 v[118:119], v[120:121], v[148:149], v[128:129]
	v_cvt_pk_bf16_f32 v0, v132, v133
	v_cvt_pk_bf16_f32 v118, v118, v119
	v_and_b32_e32 v119, 0xffff0000, v118
	v_lshlrev_b32_e32 v118, 16, v118
	v_lshlrev_b32_e32 v121, 16, v131
	v_lshlrev_b32_e32 v120, 16, v130
	v_and_b32_e32 v129, 0xffff0000, v131
	v_and_b32_e32 v128, 0xffff0000, v130
	v_pk_add_f32 v[130:131], v[146:147], 1.0 op_sel_hi:[1,0]
	v_or_b32_sdwa v119, v119, v0 dst_sel:DWORD dst_unused:UNUSED_PAD src0_sel:DWORD src1_sel:WORD_1
	v_or_b32_sdwa v118, v118, v0 dst_sel:DWORD dst_unused:UNUSED_PAD src0_sel:DWORD src1_sel:WORD_0
	s_nop 0
	v_rcp_f32_e32 v131, v131
	s_nop 0
	s_nop 0
	v_rcp_f32_e32 v130, v130
	s_nop 0
	v_mov_b32_e32 v132, v114
	v_mov_b32_e32 v133, v116
	v_pk_fma_f32 v[120:121], v[132:133], v[130:131], v[120:121]
	v_rcp_f32_e32 v125, v125
	s_nop 0
	s_nop 0
	v_rcp_f32_e32 v124, v124
	s_nop 0
	v_mov_b32_e32 v116, v115
	v_pk_fma_f32 v[114:115], v[116:117], v[124:125], v[128:129]
	v_cvt_pk_bf16_f32 v0, v120, v121
	v_cvt_pk_bf16_f32 v114, v114, v115
	v_and_b32_e32 v115, 0xffff0000, v114
	v_lshlrev_b32_e32 v114, 16, v114
	v_add_u32_e32 v127, 0x16c00, v157
	v_or_b32_sdwa v121, v115, v0 dst_sel:DWORD dst_unused:UNUSED_PAD src0_sel:DWORD src1_sel:WORD_1
	v_or_b32_sdwa v120, v114, v0 dst_sel:DWORD dst_unused:UNUSED_PAD src0_sel:DWORD src1_sel:WORD_0
	v_add_u32_e32 v0, v127, v156
	global_store_dwordx4 v[122:123], v[118:121], off
	v_lshl_add_u64 v[114:115], v[0:1], 1, s[6:7]
	global_load_dwordx4 v[114:117], v[114:115], off
	v_or_b32_e32 v118, 16, v159
	v_mul_lo_u32 v146, v118, s61
	v_add_u32_e32 v0, v0, v146
	s_waitcnt vmcnt(0)
	v_lshlrev_b32_e32 v122, 16, v114
	v_and_b32_e32 v123, 0xffff0000, v114
	v_lshlrev_b32_e32 v125, 16, v115
	v_and_b32_e32 v129, 0xffff0000, v115
	v_lshl_add_u64 v[114:115], v[0:1], 1, s[10:11]
	global_load_dwordx4 v[118:121], v[114:115], off
	v_lshlrev_b32_e32 v124, 16, v116
	v_mul_f32_e32 v0, 0xbfb8aa3b, v122
	v_exp_f32_e32 v122, v0
	v_mul_f32_e32 v0, 0xbfb8aa3b, v124
	v_and_b32_e32 v116, 0xffff0000, v116
	v_exp_f32_e32 v124, v0
	v_mul_f32_e32 v0, 0xbfb8aa3b, v123
	v_exp_f32_e32 v128, v0
	v_mul_f32_e32 v0, 0xbfb8aa3b, v116
	v_exp_f32_e32 v116, v0
	v_mul_f32_e32 v0, 0xbfb8aa3b, v125
	v_exp_f32_e32 v123, v0
	v_lshlrev_b32_e32 v130, 16, v117
	v_mul_f32_e32 v0, 0xbfb8aa3b, v130
	v_and_b32_e32 v117, 0xffff0000, v117
	v_exp_f32_e32 v125, v0
	v_mul_f32_e32 v0, 0xbfb8aa3b, v129
	v_exp_f32_e32 v129, v0
	v_mul_f32_e32 v0, 0xbfb8aa3b, v117
	v_pk_add_f32 v[122:123], v[122:123], 1.0 op_sel_hi:[1,0]
	v_exp_f32_e32 v117, v0
	v_pk_add_f32 v[128:129], v[128:129], 1.0 op_sel_hi:[1,0]
	v_pk_add_f32 v[116:117], v[116:117], 1.0 op_sel_hi:[1,0]
	v_rcp_f32_e32 v123, v123
	s_nop 0
	s_waitcnt vmcnt(0)
	v_lshlrev_b32_e32 v131, 16, v119
	v_rcp_f32_e32 v122, v122
	s_nop 0
	v_mov_b32_e32 v132, v110
	v_mov_b32_e32 v133, v112
	v_lshlrev_b32_e32 v130, 16, v118
	v_pk_fma_f32 v[122:123], v[132:133], v[122:123], v[130:131]
	v_rcp_f32_e32 v129, v129
	s_nop 0
	v_and_b32_e32 v119, 0xffff0000, v119
	v_and_b32_e32 v118, 0xffff0000, v118
	v_rcp_f32_e32 v128, v128
	s_nop 0
	v_mov_b32_e32 v112, v111
	v_pk_fma_f32 v[110:111], v[112:113], v[128:129], v[118:119]
	v_cvt_pk_bf16_f32 v0, v122, v123
	v_cvt_pk_bf16_f32 v110, v110, v111
	v_and_b32_e32 v111, 0xffff0000, v110
	v_lshlrev_b32_e32 v110, 16, v110
	v_lshlrev_b32_e32 v113, 16, v121
	v_lshlrev_b32_e32 v112, 16, v120
	v_and_b32_e32 v119, 0xffff0000, v121
	v_and_b32_e32 v118, 0xffff0000, v120
	v_pk_add_f32 v[120:121], v[124:125], 1.0 op_sel_hi:[1,0]
	v_or_b32_sdwa v111, v111, v0 dst_sel:DWORD dst_unused:UNUSED_PAD src0_sel:DWORD src1_sel:WORD_1
	v_or_b32_sdwa v110, v110, v0 dst_sel:DWORD dst_unused:UNUSED_PAD src0_sel:DWORD src1_sel:WORD_0
	s_nop 0
	v_rcp_f32_e32 v121, v121
	s_nop 0
	s_nop 0
	v_rcp_f32_e32 v120, v120
	s_nop 0
	v_mov_b32_e32 v122, v106
	v_mov_b32_e32 v123, v108
	v_pk_fma_f32 v[112:113], v[122:123], v[120:121], v[112:113]
	v_rcp_f32_e32 v117, v117
	s_nop 0
	s_nop 0
	v_rcp_f32_e32 v116, v116
	s_nop 0
	v_mov_b32_e32 v108, v107
	v_pk_fma_f32 v[106:107], v[108:109], v[116:117], v[118:119]
	v_cvt_pk_bf16_f32 v0, v112, v113
	v_cvt_pk_bf16_f32 v106, v106, v107
	v_and_b32_e32 v107, 0xffff0000, v106
	v_lshlrev_b32_e32 v106, 16, v106
	v_or_b32_sdwa v113, v107, v0 dst_sel:DWORD dst_unused:UNUSED_PAD src0_sel:DWORD src1_sel:WORD_1
	v_or_b32_sdwa v112, v106, v0 dst_sel:DWORD dst_unused:UNUSED_PAD src0_sel:DWORD src1_sel:WORD_0
	v_add_u32_e32 v0, v127, v126
	global_store_dwordx4 v[114:115], v[110:113], off
	v_lshl_add_u64 v[106:107], v[0:1], 1, s[6:7]
	global_load_dwordx4 v[106:109], v[106:107], off
	v_add_u32_e32 v0, v0, v146
	s_waitcnt vmcnt(0)
	v_lshlrev_b32_e32 v114, 16, v106
	v_and_b32_e32 v115, 0xffff0000, v106
	v_lshlrev_b32_e32 v117, 16, v107
	v_and_b32_e32 v119, 0xffff0000, v107
	v_lshl_add_u64 v[106:107], v[0:1], 1, s[10:11]
	global_load_dwordx4 v[110:113], v[106:107], off
	v_lshlrev_b32_e32 v116, 16, v108
	v_mul_f32_e32 v0, 0xbfb8aa3b, v114
	v_exp_f32_e32 v114, v0
	v_mul_f32_e32 v0, 0xbfb8aa3b, v116
	v_and_b32_e32 v108, 0xffff0000, v108
	v_exp_f32_e32 v116, v0
	v_mul_f32_e32 v0, 0xbfb8aa3b, v115
	v_exp_f32_e32 v118, v0
	v_mul_f32_e32 v0, 0xbfb8aa3b, v108
	v_exp_f32_e32 v108, v0
	v_mul_f32_e32 v0, 0xbfb8aa3b, v117
	v_exp_f32_e32 v115, v0
	v_lshlrev_b32_e32 v120, 16, v109
	v_mul_f32_e32 v0, 0xbfb8aa3b, v120
	v_and_b32_e32 v109, 0xffff0000, v109
	v_exp_f32_e32 v117, v0
	v_mul_f32_e32 v0, 0xbfb8aa3b, v119
	v_exp_f32_e32 v119, v0
	v_mul_f32_e32 v0, 0xbfb8aa3b, v109
	v_pk_add_f32 v[114:115], v[114:115], 1.0 op_sel_hi:[1,0]
	v_exp_f32_e32 v109, v0
	v_pk_add_f32 v[118:119], v[118:119], 1.0 op_sel_hi:[1,0]
	v_pk_add_f32 v[108:109], v[108:109], 1.0 op_sel_hi:[1,0]
	v_rcp_f32_e32 v115, v115
	s_nop 0
	s_waitcnt vmcnt(0)
	v_lshlrev_b32_e32 v121, 16, v111
	v_rcp_f32_e32 v114, v114
	s_nop 0
	v_mov_b32_e32 v122, v102
	v_mov_b32_e32 v123, v104
	v_lshlrev_b32_e32 v120, 16, v110
	v_pk_fma_f32 v[114:115], v[122:123], v[114:115], v[120:121]
	v_rcp_f32_e32 v119, v119
	s_nop 0
	v_and_b32_e32 v111, 0xffff0000, v111
	v_and_b32_e32 v110, 0xffff0000, v110
	v_rcp_f32_e32 v118, v118
	s_nop 0
	v_mov_b32_e32 v104, v103
	v_pk_fma_f32 v[102:103], v[104:105], v[118:119], v[110:111]
	v_cvt_pk_bf16_f32 v0, v114, v115
	v_cvt_pk_bf16_f32 v102, v102, v103
	v_and_b32_e32 v103, 0xffff0000, v102
	v_lshlrev_b32_e32 v102, 16, v102
	v_lshlrev_b32_e32 v105, 16, v113
	v_lshlrev_b32_e32 v104, 16, v112
	v_and_b32_e32 v111, 0xffff0000, v113
	v_and_b32_e32 v110, 0xffff0000, v112
	v_pk_add_f32 v[112:113], v[116:117], 1.0 op_sel_hi:[1,0]
	v_or_b32_sdwa v103, v103, v0 dst_sel:DWORD dst_unused:UNUSED_PAD src0_sel:DWORD src1_sel:WORD_1
	v_or_b32_sdwa v102, v102, v0 dst_sel:DWORD dst_unused:UNUSED_PAD src0_sel:DWORD src1_sel:WORD_0
	s_nop 0
	v_rcp_f32_e32 v113, v113
	s_nop 0
	s_nop 0
	v_rcp_f32_e32 v112, v112
	s_nop 0
	v_mov_b32_e32 v114, v98
	v_mov_b32_e32 v115, v100
	v_pk_fma_f32 v[104:105], v[114:115], v[112:113], v[104:105]
	v_add_u32_e32 v116, 0x2d800, v157
	v_rcp_f32_e32 v109, v109
	s_nop 0
	s_nop 0
	v_rcp_f32_e32 v108, v108
	s_nop 0
	v_mov_b32_e32 v100, v99
	v_pk_fma_f32 v[98:99], v[100:101], v[108:109], v[110:111]
	v_cvt_pk_bf16_f32 v0, v104, v105
	v_cvt_pk_bf16_f32 v98, v98, v99
	v_and_b32_e32 v99, 0xffff0000, v98
	v_lshlrev_b32_e32 v98, 16, v98
	v_or_b32_sdwa v105, v99, v0 dst_sel:DWORD dst_unused:UNUSED_PAD src0_sel:DWORD src1_sel:WORD_1
	v_or_b32_sdwa v104, v98, v0 dst_sel:DWORD dst_unused:UNUSED_PAD src0_sel:DWORD src1_sel:WORD_0
	v_add_u32_e32 v0, v116, v156
	global_store_dwordx4 v[106:107], v[102:105], off
	v_lshl_add_u64 v[98:99], v[0:1], 1, s[6:7]
	global_load_dwordx4 v[98:101], v[98:99], off
	v_or_b32_e32 v102, 32, v159
	v_mul_lo_u32 v117, v102, s61
	v_add_u32_e32 v0, v0, v117
	s_waitcnt vmcnt(0)
	v_lshlrev_b32_e32 v106, 16, v98
	v_and_b32_e32 v107, 0xffff0000, v98
	v_lshlrev_b32_e32 v109, 16, v99
	v_and_b32_e32 v111, 0xffff0000, v99
	v_lshl_add_u64 v[98:99], v[0:1], 1, s[10:11]
	global_load_dwordx4 v[102:105], v[98:99], off
	v_lshlrev_b32_e32 v108, 16, v100
	v_mul_f32_e32 v0, 0xbfb8aa3b, v106
	v_exp_f32_e32 v106, v0
	v_mul_f32_e32 v0, 0xbfb8aa3b, v108
	v_and_b32_e32 v100, 0xffff0000, v100
	v_exp_f32_e32 v108, v0
	v_mul_f32_e32 v0, 0xbfb8aa3b, v107
	v_exp_f32_e32 v110, v0
	v_mul_f32_e32 v0, 0xbfb8aa3b, v100
	v_exp_f32_e32 v100, v0
	v_mul_f32_e32 v0, 0xbfb8aa3b, v109
	v_exp_f32_e32 v107, v0
	v_lshlrev_b32_e32 v112, 16, v101
	v_mul_f32_e32 v0, 0xbfb8aa3b, v112
	v_and_b32_e32 v101, 0xffff0000, v101
	v_exp_f32_e32 v109, v0
	v_mul_f32_e32 v0, 0xbfb8aa3b, v111
	v_exp_f32_e32 v111, v0
	v_mul_f32_e32 v0, 0xbfb8aa3b, v101
	v_pk_add_f32 v[106:107], v[106:107], 1.0 op_sel_hi:[1,0]
	v_exp_f32_e32 v101, v0
	v_pk_add_f32 v[110:111], v[110:111], 1.0 op_sel_hi:[1,0]
	v_pk_add_f32 v[100:101], v[100:101], 1.0 op_sel_hi:[1,0]
	v_rcp_f32_e32 v107, v107
	s_nop 0
	s_waitcnt vmcnt(0)
	v_lshlrev_b32_e32 v113, 16, v103
	v_rcp_f32_e32 v106, v106
	s_nop 0
	v_mov_b32_e32 v114, v94
	v_mov_b32_e32 v115, v96
	v_lshlrev_b32_e32 v112, 16, v102
	v_pk_fma_f32 v[106:107], v[114:115], v[106:107], v[112:113]
	v_rcp_f32_e32 v111, v111
	s_nop 0
	v_and_b32_e32 v103, 0xffff0000, v103
	v_and_b32_e32 v102, 0xffff0000, v102
	v_rcp_f32_e32 v110, v110
	s_nop 0
	v_mov_b32_e32 v96, v95
	v_pk_fma_f32 v[94:95], v[96:97], v[110:111], v[102:103]
	v_cvt_pk_bf16_f32 v0, v106, v107
	v_cvt_pk_bf16_f32 v94, v94, v95
	v_and_b32_e32 v95, 0xffff0000, v94
	v_lshlrev_b32_e32 v94, 16, v94
	v_lshlrev_b32_e32 v97, 16, v105
	v_lshlrev_b32_e32 v96, 16, v104
	v_and_b32_e32 v103, 0xffff0000, v105
	v_and_b32_e32 v102, 0xffff0000, v104
	v_pk_add_f32 v[104:105], v[108:109], 1.0 op_sel_hi:[1,0]
	v_or_b32_sdwa v95, v95, v0 dst_sel:DWORD dst_unused:UNUSED_PAD src0_sel:DWORD src1_sel:WORD_1
	v_or_b32_sdwa v94, v94, v0 dst_sel:DWORD dst_unused:UNUSED_PAD src0_sel:DWORD src1_sel:WORD_0
	s_nop 0
	v_rcp_f32_e32 v105, v105
	s_nop 0
	s_nop 0
	v_rcp_f32_e32 v104, v104
	s_nop 0
	v_mov_b32_e32 v106, v90
	v_mov_b32_e32 v107, v92
	v_pk_fma_f32 v[96:97], v[106:107], v[104:105], v[96:97]
	v_rcp_f32_e32 v101, v101
	s_nop 0
	s_nop 0
	v_rcp_f32_e32 v100, v100
	s_nop 0
	v_mov_b32_e32 v92, v91
	v_pk_fma_f32 v[90:91], v[92:93], v[100:101], v[102:103]
	v_cvt_pk_bf16_f32 v0, v96, v97
	v_cvt_pk_bf16_f32 v90, v90, v91
	v_and_b32_e32 v91, 0xffff0000, v90
	v_lshlrev_b32_e32 v90, 16, v90
	v_or_b32_sdwa v97, v91, v0 dst_sel:DWORD dst_unused:UNUSED_PAD src0_sel:DWORD src1_sel:WORD_1
	v_or_b32_sdwa v96, v90, v0 dst_sel:DWORD dst_unused:UNUSED_PAD src0_sel:DWORD src1_sel:WORD_0
	v_add_u32_e32 v0, v116, v126
	global_store_dwordx4 v[98:99], v[94:97], off
	v_lshl_add_u64 v[90:91], v[0:1], 1, s[6:7]
	global_load_dwordx4 v[90:93], v[90:91], off
	v_add_u32_e32 v0, v0, v117
	s_waitcnt vmcnt(0)
	v_lshlrev_b32_e32 v98, 16, v90
	v_and_b32_e32 v99, 0xffff0000, v90
	v_lshlrev_b32_e32 v101, 16, v91
	v_and_b32_e32 v103, 0xffff0000, v91
	v_lshl_add_u64 v[90:91], v[0:1], 1, s[10:11]
	global_load_dwordx4 v[94:97], v[90:91], off
	v_lshlrev_b32_e32 v100, 16, v92
	v_mul_f32_e32 v0, 0xbfb8aa3b, v98
	v_exp_f32_e32 v98, v0
	v_mul_f32_e32 v0, 0xbfb8aa3b, v100
	v_and_b32_e32 v92, 0xffff0000, v92
	v_exp_f32_e32 v100, v0
	v_mul_f32_e32 v0, 0xbfb8aa3b, v99
	v_exp_f32_e32 v102, v0
	v_mul_f32_e32 v0, 0xbfb8aa3b, v92
	v_exp_f32_e32 v92, v0
	v_mul_f32_e32 v0, 0xbfb8aa3b, v101
	v_exp_f32_e32 v99, v0
	v_lshlrev_b32_e32 v104, 16, v93
	v_mul_f32_e32 v0, 0xbfb8aa3b, v104
	v_and_b32_e32 v93, 0xffff0000, v93
	v_exp_f32_e32 v101, v0
	v_mul_f32_e32 v0, 0xbfb8aa3b, v103
	v_exp_f32_e32 v103, v0
	v_mul_f32_e32 v0, 0xbfb8aa3b, v93
	v_pk_add_f32 v[98:99], v[98:99], 1.0 op_sel_hi:[1,0]
	v_exp_f32_e32 v93, v0
	v_pk_add_f32 v[102:103], v[102:103], 1.0 op_sel_hi:[1,0]
	v_pk_add_f32 v[92:93], v[92:93], 1.0 op_sel_hi:[1,0]
	v_rcp_f32_e32 v99, v99
	s_nop 0
	s_waitcnt vmcnt(0)
	v_lshlrev_b32_e32 v105, 16, v95
	v_rcp_f32_e32 v98, v98
	s_nop 0
	v_mov_b32_e32 v106, v86
	v_mov_b32_e32 v107, v88
	v_lshlrev_b32_e32 v104, 16, v94
	v_pk_fma_f32 v[98:99], v[106:107], v[98:99], v[104:105]
	v_rcp_f32_e32 v103, v103
	s_nop 0
	v_and_b32_e32 v95, 0xffff0000, v95
	v_and_b32_e32 v94, 0xffff0000, v94
	v_rcp_f32_e32 v102, v102
	s_nop 0
	v_mov_b32_e32 v88, v87
	v_pk_fma_f32 v[86:87], v[88:89], v[102:103], v[94:95]
	v_cvt_pk_bf16_f32 v0, v98, v99
	v_cvt_pk_bf16_f32 v86, v86, v87
	v_and_b32_e32 v87, 0xffff0000, v86
	v_lshlrev_b32_e32 v86, 16, v86
	v_lshlrev_b32_e32 v89, 16, v97
	v_lshlrev_b32_e32 v88, 16, v96
	v_and_b32_e32 v95, 0xffff0000, v97
	v_and_b32_e32 v94, 0xffff0000, v96
	v_pk_add_f32 v[96:97], v[100:101], 1.0 op_sel_hi:[1,0]
	v_or_b32_sdwa v87, v87, v0 dst_sel:DWORD dst_unused:UNUSED_PAD src0_sel:DWORD src1_sel:WORD_1
	v_or_b32_sdwa v86, v86, v0 dst_sel:DWORD dst_unused:UNUSED_PAD src0_sel:DWORD src1_sel:WORD_0
	s_nop 0
	v_rcp_f32_e32 v97, v97
	s_nop 0
	s_nop 0
	v_rcp_f32_e32 v96, v96
	s_nop 0
	v_mov_b32_e32 v98, v82
	v_mov_b32_e32 v99, v84
	v_pk_fma_f32 v[88:89], v[98:99], v[96:97], v[88:89]
	v_add_u32_e32 v100, 0x44400, v157
	v_rcp_f32_e32 v93, v93
	s_nop 0
	s_nop 0
	v_rcp_f32_e32 v92, v92
	s_nop 0
	v_mov_b32_e32 v84, v83
	v_pk_fma_f32 v[82:83], v[84:85], v[92:93], v[94:95]
	v_cvt_pk_bf16_f32 v0, v88, v89
	v_cvt_pk_bf16_f32 v82, v82, v83
	v_and_b32_e32 v83, 0xffff0000, v82
	v_lshlrev_b32_e32 v82, 16, v82
	v_or_b32_sdwa v89, v83, v0 dst_sel:DWORD dst_unused:UNUSED_PAD src0_sel:DWORD src1_sel:WORD_1
	v_or_b32_sdwa v88, v82, v0 dst_sel:DWORD dst_unused:UNUSED_PAD src0_sel:DWORD src1_sel:WORD_0
	v_add_u32_e32 v0, v100, v156
	global_store_dwordx4 v[90:91], v[86:89], off
	v_lshl_add_u64 v[82:83], v[0:1], 1, s[6:7]
	global_load_dwordx4 v[82:85], v[82:83], off
	v_or_b32_e32 v86, 48, v159
	v_mul_lo_u32 v101, v86, s61
	v_add_u32_e32 v0, v0, v101
	s_waitcnt vmcnt(0)
	v_lshlrev_b32_e32 v90, 16, v82
	v_and_b32_e32 v91, 0xffff0000, v82
	v_lshlrev_b32_e32 v93, 16, v83
	v_and_b32_e32 v95, 0xffff0000, v83
	v_lshl_add_u64 v[82:83], v[0:1], 1, s[10:11]
	global_load_dwordx4 v[86:89], v[82:83], off
	v_lshlrev_b32_e32 v92, 16, v84
	v_mul_f32_e32 v0, 0xbfb8aa3b, v90
	v_exp_f32_e32 v90, v0
	v_mul_f32_e32 v0, 0xbfb8aa3b, v92
	v_and_b32_e32 v84, 0xffff0000, v84
	v_exp_f32_e32 v92, v0
	v_mul_f32_e32 v0, 0xbfb8aa3b, v91
	v_exp_f32_e32 v94, v0
	v_mul_f32_e32 v0, 0xbfb8aa3b, v84
	v_exp_f32_e32 v84, v0
	v_mul_f32_e32 v0, 0xbfb8aa3b, v93
	v_exp_f32_e32 v91, v0
	v_lshlrev_b32_e32 v96, 16, v85
	v_mul_f32_e32 v0, 0xbfb8aa3b, v96
	v_and_b32_e32 v85, 0xffff0000, v85
	v_exp_f32_e32 v93, v0
	v_mul_f32_e32 v0, 0xbfb8aa3b, v95
	v_exp_f32_e32 v95, v0
	v_mul_f32_e32 v0, 0xbfb8aa3b, v85
	v_pk_add_f32 v[90:91], v[90:91], 1.0 op_sel_hi:[1,0]
	v_exp_f32_e32 v85, v0
	v_pk_add_f32 v[94:95], v[94:95], 1.0 op_sel_hi:[1,0]
	v_pk_add_f32 v[84:85], v[84:85], 1.0 op_sel_hi:[1,0]
	v_rcp_f32_e32 v91, v91
	s_nop 0
	s_waitcnt vmcnt(0)
	v_lshlrev_b32_e32 v97, 16, v87
	v_rcp_f32_e32 v90, v90
	s_nop 0
	v_mov_b32_e32 v98, v78
	v_mov_b32_e32 v99, v80
	v_lshlrev_b32_e32 v96, 16, v86
	v_pk_fma_f32 v[90:91], v[98:99], v[90:91], v[96:97]
	v_rcp_f32_e32 v95, v95
	s_nop 0
	v_and_b32_e32 v87, 0xffff0000, v87
	v_and_b32_e32 v86, 0xffff0000, v86
	v_rcp_f32_e32 v94, v94
	s_nop 0
	v_mov_b32_e32 v80, v79
	v_pk_fma_f32 v[78:79], v[80:81], v[94:95], v[86:87]
	v_cvt_pk_bf16_f32 v0, v90, v91
	v_cvt_pk_bf16_f32 v78, v78, v79
	v_and_b32_e32 v79, 0xffff0000, v78
	v_lshlrev_b32_e32 v78, 16, v78
	v_lshlrev_b32_e32 v81, 16, v89
	v_lshlrev_b32_e32 v80, 16, v88
	v_and_b32_e32 v87, 0xffff0000, v89
	v_and_b32_e32 v86, 0xffff0000, v88
	v_pk_add_f32 v[88:89], v[92:93], 1.0 op_sel_hi:[1,0]
	v_or_b32_sdwa v79, v79, v0 dst_sel:DWORD dst_unused:UNUSED_PAD src0_sel:DWORD src1_sel:WORD_1
	v_or_b32_sdwa v78, v78, v0 dst_sel:DWORD dst_unused:UNUSED_PAD src0_sel:DWORD src1_sel:WORD_0
	s_nop 0
	v_rcp_f32_e32 v89, v89
	s_nop 0
	s_nop 0
	v_rcp_f32_e32 v88, v88
	s_nop 0
	v_mov_b32_e32 v90, v74
	v_mov_b32_e32 v91, v76
	v_pk_fma_f32 v[80:81], v[90:91], v[88:89], v[80:81]
	v_rcp_f32_e32 v85, v85
	s_nop 0
	s_nop 0
	v_rcp_f32_e32 v84, v84
	s_nop 0
	v_mov_b32_e32 v76, v75
	v_pk_fma_f32 v[74:75], v[76:77], v[84:85], v[86:87]
	v_cvt_pk_bf16_f32 v0, v80, v81
	v_cvt_pk_bf16_f32 v74, v74, v75
	v_and_b32_e32 v75, 0xffff0000, v74
	v_lshlrev_b32_e32 v74, 16, v74
	v_or_b32_sdwa v81, v75, v0 dst_sel:DWORD dst_unused:UNUSED_PAD src0_sel:DWORD src1_sel:WORD_1
	v_or_b32_sdwa v80, v74, v0 dst_sel:DWORD dst_unused:UNUSED_PAD src0_sel:DWORD src1_sel:WORD_0
	v_add_u32_e32 v0, v100, v126
	global_store_dwordx4 v[82:83], v[78:81], off
	v_lshl_add_u64 v[74:75], v[0:1], 1, s[6:7]
	global_load_dwordx4 v[74:77], v[74:75], off
	v_add_u32_e32 v0, v0, v101
	s_waitcnt vmcnt(0)
	v_lshlrev_b32_e32 v82, 16, v74
	v_and_b32_e32 v83, 0xffff0000, v74
	v_lshlrev_b32_e32 v85, 16, v75
	v_and_b32_e32 v87, 0xffff0000, v75
	v_lshl_add_u64 v[74:75], v[0:1], 1, s[10:11]
	global_load_dwordx4 v[78:81], v[74:75], off
	v_lshlrev_b32_e32 v84, 16, v76
	v_mul_f32_e32 v0, 0xbfb8aa3b, v82
	v_exp_f32_e32 v82, v0
	v_mul_f32_e32 v0, 0xbfb8aa3b, v84
	v_and_b32_e32 v76, 0xffff0000, v76
	v_exp_f32_e32 v84, v0
	v_mul_f32_e32 v0, 0xbfb8aa3b, v83
	v_exp_f32_e32 v86, v0
	v_mul_f32_e32 v0, 0xbfb8aa3b, v76
	v_exp_f32_e32 v76, v0
	v_mul_f32_e32 v0, 0xbfb8aa3b, v85
	v_exp_f32_e32 v83, v0
	v_lshlrev_b32_e32 v88, 16, v77
	v_mul_f32_e32 v0, 0xbfb8aa3b, v88
	v_and_b32_e32 v77, 0xffff0000, v77
	v_exp_f32_e32 v85, v0
	v_mul_f32_e32 v0, 0xbfb8aa3b, v87
	v_exp_f32_e32 v87, v0
	v_mul_f32_e32 v0, 0xbfb8aa3b, v77
	v_pk_add_f32 v[82:83], v[82:83], 1.0 op_sel_hi:[1,0]
	v_exp_f32_e32 v77, v0
	v_pk_add_f32 v[86:87], v[86:87], 1.0 op_sel_hi:[1,0]
	v_pk_add_f32 v[76:77], v[76:77], 1.0 op_sel_hi:[1,0]
	v_rcp_f32_e32 v83, v83
	s_nop 0
	s_waitcnt vmcnt(0)
	v_lshlrev_b32_e32 v89, 16, v79
	v_rcp_f32_e32 v82, v82
	s_nop 0
	v_mov_b32_e32 v90, v70
	v_mov_b32_e32 v91, v72
	v_lshlrev_b32_e32 v88, 16, v78
	v_pk_fma_f32 v[82:83], v[90:91], v[82:83], v[88:89]
	v_rcp_f32_e32 v87, v87
	s_nop 0
	v_and_b32_e32 v79, 0xffff0000, v79
	v_and_b32_e32 v78, 0xffff0000, v78
	v_rcp_f32_e32 v86, v86
	s_nop 0
	v_mov_b32_e32 v72, v71
	v_pk_fma_f32 v[70:71], v[72:73], v[86:87], v[78:79]
	v_cvt_pk_bf16_f32 v0, v82, v83
	v_cvt_pk_bf16_f32 v70, v70, v71
	v_and_b32_e32 v71, 0xffff0000, v70
	v_lshlrev_b32_e32 v70, 16, v70
	v_lshlrev_b32_e32 v73, 16, v81
	v_lshlrev_b32_e32 v72, 16, v80
	v_and_b32_e32 v79, 0xffff0000, v81
	v_and_b32_e32 v78, 0xffff0000, v80
	v_pk_add_f32 v[80:81], v[84:85], 1.0 op_sel_hi:[1,0]
	v_or_b32_sdwa v71, v71, v0 dst_sel:DWORD dst_unused:UNUSED_PAD src0_sel:DWORD src1_sel:WORD_1
	v_or_b32_sdwa v70, v70, v0 dst_sel:DWORD dst_unused:UNUSED_PAD src0_sel:DWORD src1_sel:WORD_0
	s_nop 0
	v_rcp_f32_e32 v81, v81
	s_nop 0
	s_nop 0
	v_rcp_f32_e32 v80, v80
	s_nop 0
	v_mov_b32_e32 v82, v66
	v_mov_b32_e32 v83, v68
	v_pk_fma_f32 v[72:73], v[82:83], v[80:81], v[72:73]
	v_add_u32_e32 v84, 0xb6000, v157
	v_rcp_f32_e32 v77, v77
	s_nop 0
	v_add_u32_e32 v85, 0xfff6a000, v158
	v_rcp_f32_e32 v76, v76
	s_nop 0
	v_mov_b32_e32 v68, v67
	v_pk_fma_f32 v[66:67], v[68:69], v[76:77], v[78:79]
	v_cvt_pk_bf16_f32 v0, v72, v73
	v_cvt_pk_bf16_f32 v66, v66, v67
	v_and_b32_e32 v67, 0xffff0000, v66
	v_lshlrev_b32_e32 v66, 16, v66
	v_or_b32_sdwa v73, v67, v0 dst_sel:DWORD dst_unused:UNUSED_PAD src0_sel:DWORD src1_sel:WORD_1
	v_or_b32_sdwa v72, v66, v0 dst_sel:DWORD dst_unused:UNUSED_PAD src0_sel:DWORD src1_sel:WORD_0
	v_add_u32_e32 v0, v84, v156
	global_store_dwordx4 v[74:75], v[70:73], off
	v_lshl_add_u64 v[66:67], v[0:1], 1, s[6:7]
	global_load_dwordx4 v[66:69], v[66:67], off
	v_add_u32_e32 v0, v0, v85
	s_waitcnt vmcnt(0)
	v_lshlrev_b32_e32 v74, 16, v66
	v_and_b32_e32 v75, 0xffff0000, v66
	v_lshlrev_b32_e32 v77, 16, v67
	v_and_b32_e32 v79, 0xffff0000, v67
	v_lshl_add_u64 v[66:67], v[0:1], 1, s[10:11]
	global_load_dwordx4 v[70:73], v[66:67], off
	v_lshlrev_b32_e32 v76, 16, v68
	v_mul_f32_e32 v0, 0xbfb8aa3b, v74
	v_exp_f32_e32 v74, v0
	v_mul_f32_e32 v0, 0xbfb8aa3b, v76
	v_and_b32_e32 v68, 0xffff0000, v68
	v_exp_f32_e32 v76, v0
	v_mul_f32_e32 v0, 0xbfb8aa3b, v75
	v_exp_f32_e32 v78, v0
	v_mul_f32_e32 v0, 0xbfb8aa3b, v68
	v_exp_f32_e32 v68, v0
	v_mul_f32_e32 v0, 0xbfb8aa3b, v77
	v_exp_f32_e32 v75, v0
	v_lshlrev_b32_e32 v80, 16, v69
	v_mul_f32_e32 v0, 0xbfb8aa3b, v80
	v_and_b32_e32 v69, 0xffff0000, v69
	v_exp_f32_e32 v77, v0
	v_mul_f32_e32 v0, 0xbfb8aa3b, v79
	v_exp_f32_e32 v79, v0
	v_mul_f32_e32 v0, 0xbfb8aa3b, v69
	v_pk_add_f32 v[74:75], v[74:75], 1.0 op_sel_hi:[1,0]
	v_exp_f32_e32 v69, v0
	v_pk_add_f32 v[78:79], v[78:79], 1.0 op_sel_hi:[1,0]
	v_pk_add_f32 v[68:69], v[68:69], 1.0 op_sel_hi:[1,0]
	v_rcp_f32_e32 v75, v75
	s_nop 0
	s_waitcnt vmcnt(0)
	v_lshlrev_b32_e32 v81, 16, v71
	v_rcp_f32_e32 v74, v74
	s_nop 0
	v_mov_b32_e32 v82, v62
	v_mov_b32_e32 v83, v64
	v_lshlrev_b32_e32 v80, 16, v70
	v_pk_fma_f32 v[74:75], v[82:83], v[74:75], v[80:81]
	v_rcp_f32_e32 v79, v79
	s_nop 0
	v_and_b32_e32 v71, 0xffff0000, v71
	v_and_b32_e32 v70, 0xffff0000, v70
	v_rcp_f32_e32 v78, v78
	s_nop 0
	v_mov_b32_e32 v64, v63
	v_pk_fma_f32 v[62:63], v[64:65], v[78:79], v[70:71]
	v_cvt_pk_bf16_f32 v0, v74, v75
	v_cvt_pk_bf16_f32 v62, v62, v63
	v_and_b32_e32 v63, 0xffff0000, v62
	v_lshlrev_b32_e32 v62, 16, v62
	v_lshlrev_b32_e32 v65, 16, v73
	v_lshlrev_b32_e32 v64, 16, v72
	v_and_b32_e32 v71, 0xffff0000, v73
	v_and_b32_e32 v70, 0xffff0000, v72
	v_pk_add_f32 v[72:73], v[76:77], 1.0 op_sel_hi:[1,0]
	v_or_b32_sdwa v63, v63, v0 dst_sel:DWORD dst_unused:UNUSED_PAD src0_sel:DWORD src1_sel:WORD_1
	v_or_b32_sdwa v62, v62, v0 dst_sel:DWORD dst_unused:UNUSED_PAD src0_sel:DWORD src1_sel:WORD_0
	s_nop 0
	v_rcp_f32_e32 v73, v73
	s_nop 0
	s_nop 0
	v_rcp_f32_e32 v72, v72
	s_nop 0
	v_mov_b32_e32 v74, v58
	v_mov_b32_e32 v75, v60
	v_pk_fma_f32 v[64:65], v[74:75], v[72:73], v[64:65]
	v_rcp_f32_e32 v69, v69
	s_nop 0
	s_nop 0
	v_rcp_f32_e32 v68, v68
	s_nop 0
	v_mov_b32_e32 v60, v59
	v_pk_fma_f32 v[58:59], v[60:61], v[68:69], v[70:71]
	v_cvt_pk_bf16_f32 v0, v64, v65
	v_cvt_pk_bf16_f32 v58, v58, v59
	v_and_b32_e32 v59, 0xffff0000, v58
	v_lshlrev_b32_e32 v58, 16, v58
	v_or_b32_sdwa v65, v59, v0 dst_sel:DWORD dst_unused:UNUSED_PAD src0_sel:DWORD src1_sel:WORD_1
	v_or_b32_sdwa v64, v58, v0 dst_sel:DWORD dst_unused:UNUSED_PAD src0_sel:DWORD src1_sel:WORD_0
	v_add_u32_e32 v0, v84, v126
	global_store_dwordx4 v[66:67], v[62:65], off
	v_lshl_add_u64 v[58:59], v[0:1], 1, s[6:7]
	global_load_dwordx4 v[58:61], v[58:59], off
	v_add_u32_e32 v0, v0, v85
	s_waitcnt vmcnt(0)
	v_lshlrev_b32_e32 v66, 16, v58
	v_and_b32_e32 v67, 0xffff0000, v58
	v_lshlrev_b32_e32 v69, 16, v59
	v_and_b32_e32 v71, 0xffff0000, v59
	v_lshl_add_u64 v[58:59], v[0:1], 1, s[10:11]
	global_load_dwordx4 v[62:65], v[58:59], off
	v_lshlrev_b32_e32 v68, 16, v60
	v_mul_f32_e32 v0, 0xbfb8aa3b, v66
	v_exp_f32_e32 v66, v0
	v_mul_f32_e32 v0, 0xbfb8aa3b, v68
	v_and_b32_e32 v60, 0xffff0000, v60
	v_exp_f32_e32 v68, v0
	v_mul_f32_e32 v0, 0xbfb8aa3b, v67
	v_exp_f32_e32 v70, v0
	v_mul_f32_e32 v0, 0xbfb8aa3b, v60
	v_exp_f32_e32 v60, v0
	v_mul_f32_e32 v0, 0xbfb8aa3b, v69
	v_exp_f32_e32 v67, v0
	v_lshlrev_b32_e32 v72, 16, v61
	v_mul_f32_e32 v0, 0xbfb8aa3b, v72
	v_and_b32_e32 v61, 0xffff0000, v61
	v_exp_f32_e32 v69, v0
	v_mul_f32_e32 v0, 0xbfb8aa3b, v71
	v_exp_f32_e32 v71, v0
	v_mul_f32_e32 v0, 0xbfb8aa3b, v61
	v_pk_add_f32 v[66:67], v[66:67], 1.0 op_sel_hi:[1,0]
	v_exp_f32_e32 v61, v0
	v_pk_add_f32 v[70:71], v[70:71], 1.0 op_sel_hi:[1,0]
	v_pk_add_f32 v[60:61], v[60:61], 1.0 op_sel_hi:[1,0]
	v_rcp_f32_e32 v67, v67
	s_nop 0
	s_waitcnt vmcnt(0)
	v_lshlrev_b32_e32 v73, 16, v63
	v_rcp_f32_e32 v66, v66
	s_nop 0
	v_mov_b32_e32 v74, v54
	v_mov_b32_e32 v75, v56
	v_lshlrev_b32_e32 v72, 16, v62
	v_pk_fma_f32 v[66:67], v[74:75], v[66:67], v[72:73]
	v_rcp_f32_e32 v71, v71
	s_nop 0
	v_and_b32_e32 v63, 0xffff0000, v63
	v_and_b32_e32 v62, 0xffff0000, v62
	v_rcp_f32_e32 v70, v70
	s_nop 0
	v_mov_b32_e32 v56, v55
	v_pk_fma_f32 v[54:55], v[56:57], v[70:71], v[62:63]
	v_cvt_pk_bf16_f32 v0, v66, v67
	v_cvt_pk_bf16_f32 v54, v54, v55
	v_and_b32_e32 v55, 0xffff0000, v54
	v_lshlrev_b32_e32 v54, 16, v54
	v_lshlrev_b32_e32 v57, 16, v65
	v_lshlrev_b32_e32 v56, 16, v64
	v_and_b32_e32 v63, 0xffff0000, v65
	v_and_b32_e32 v62, 0xffff0000, v64
	v_pk_add_f32 v[64:65], v[68:69], 1.0 op_sel_hi:[1,0]
	v_or_b32_sdwa v55, v55, v0 dst_sel:DWORD dst_unused:UNUSED_PAD src0_sel:DWORD src1_sel:WORD_1
	v_or_b32_sdwa v54, v54, v0 dst_sel:DWORD dst_unused:UNUSED_PAD src0_sel:DWORD src1_sel:WORD_0
	s_nop 0
	v_rcp_f32_e32 v65, v65
	s_nop 0
	s_nop 0
	v_rcp_f32_e32 v64, v64
	s_nop 0
	v_mov_b32_e32 v66, v50
	v_mov_b32_e32 v67, v52
	v_pk_fma_f32 v[56:57], v[66:67], v[64:65], v[56:57]
	v_add_u32_e32 v68, 0xccc00, v157
	v_rcp_f32_e32 v61, v61
	s_nop 0
	v_add_u32_e32 v69, 0xfff57400, v158
	v_rcp_f32_e32 v60, v60
	s_nop 0
	v_mov_b32_e32 v52, v51
	v_pk_fma_f32 v[50:51], v[52:53], v[60:61], v[62:63]
	v_cvt_pk_bf16_f32 v0, v56, v57
	v_cvt_pk_bf16_f32 v50, v50, v51
	v_and_b32_e32 v51, 0xffff0000, v50
	v_lshlrev_b32_e32 v50, 16, v50
	v_or_b32_sdwa v57, v51, v0 dst_sel:DWORD dst_unused:UNUSED_PAD src0_sel:DWORD src1_sel:WORD_1
	v_or_b32_sdwa v56, v50, v0 dst_sel:DWORD dst_unused:UNUSED_PAD src0_sel:DWORD src1_sel:WORD_0
	v_add_u32_e32 v0, v68, v156
	global_store_dwordx4 v[58:59], v[54:57], off
	v_lshl_add_u64 v[50:51], v[0:1], 1, s[6:7]
	global_load_dwordx4 v[50:53], v[50:51], off
	v_add_u32_e32 v0, v0, v69
	s_waitcnt vmcnt(0)
	v_lshlrev_b32_e32 v58, 16, v50
	v_and_b32_e32 v59, 0xffff0000, v50
	v_lshlrev_b32_e32 v61, 16, v51
	v_and_b32_e32 v63, 0xffff0000, v51
	v_lshl_add_u64 v[50:51], v[0:1], 1, s[10:11]
	global_load_dwordx4 v[54:57], v[50:51], off
	v_lshlrev_b32_e32 v60, 16, v52
	v_mul_f32_e32 v0, 0xbfb8aa3b, v58
	v_exp_f32_e32 v58, v0
	v_mul_f32_e32 v0, 0xbfb8aa3b, v60
	v_and_b32_e32 v52, 0xffff0000, v52
	v_exp_f32_e32 v60, v0
	v_mul_f32_e32 v0, 0xbfb8aa3b, v59
	v_exp_f32_e32 v62, v0
	v_mul_f32_e32 v0, 0xbfb8aa3b, v52
	v_exp_f32_e32 v52, v0
	v_mul_f32_e32 v0, 0xbfb8aa3b, v61
	v_exp_f32_e32 v59, v0
	v_lshlrev_b32_e32 v64, 16, v53
	v_mul_f32_e32 v0, 0xbfb8aa3b, v64
	v_and_b32_e32 v53, 0xffff0000, v53
	v_exp_f32_e32 v61, v0
	v_mul_f32_e32 v0, 0xbfb8aa3b, v63
	v_exp_f32_e32 v63, v0
	v_mul_f32_e32 v0, 0xbfb8aa3b, v53
	v_pk_add_f32 v[58:59], v[58:59], 1.0 op_sel_hi:[1,0]
	v_exp_f32_e32 v53, v0
	v_pk_add_f32 v[62:63], v[62:63], 1.0 op_sel_hi:[1,0]
	v_pk_add_f32 v[52:53], v[52:53], 1.0 op_sel_hi:[1,0]
	v_rcp_f32_e32 v59, v59
	s_nop 0
	s_waitcnt vmcnt(0)
	v_lshlrev_b32_e32 v65, 16, v55
	v_rcp_f32_e32 v58, v58
	s_nop 0
	v_mov_b32_e32 v66, v46
	v_mov_b32_e32 v67, v48
	v_lshlrev_b32_e32 v64, 16, v54
	v_pk_fma_f32 v[58:59], v[66:67], v[58:59], v[64:65]
	v_rcp_f32_e32 v63, v63
	s_nop 0
	v_and_b32_e32 v55, 0xffff0000, v55
	v_and_b32_e32 v54, 0xffff0000, v54
	v_rcp_f32_e32 v62, v62
	s_nop 0
	v_mov_b32_e32 v48, v47
	v_pk_fma_f32 v[46:47], v[48:49], v[62:63], v[54:55]
	v_cvt_pk_bf16_f32 v0, v58, v59
	v_cvt_pk_bf16_f32 v46, v46, v47
	v_and_b32_e32 v47, 0xffff0000, v46
	v_lshlrev_b32_e32 v46, 16, v46
	v_lshlrev_b32_e32 v49, 16, v57
	v_lshlrev_b32_e32 v48, 16, v56
	v_and_b32_e32 v55, 0xffff0000, v57
	v_and_b32_e32 v54, 0xffff0000, v56
	v_pk_add_f32 v[56:57], v[60:61], 1.0 op_sel_hi:[1,0]
	v_or_b32_sdwa v47, v47, v0 dst_sel:DWORD dst_unused:UNUSED_PAD src0_sel:DWORD src1_sel:WORD_1
	v_or_b32_sdwa v46, v46, v0 dst_sel:DWORD dst_unused:UNUSED_PAD src0_sel:DWORD src1_sel:WORD_0
	s_nop 0
	v_rcp_f32_e32 v57, v57
	s_nop 0
	s_nop 0
	v_rcp_f32_e32 v56, v56
	s_nop 0
	v_mov_b32_e32 v58, v42
	v_mov_b32_e32 v59, v44
	v_pk_fma_f32 v[48:49], v[58:59], v[56:57], v[48:49]
	v_rcp_f32_e32 v53, v53
	s_nop 0
	s_nop 0
	v_rcp_f32_e32 v52, v52
	s_nop 0
	v_mov_b32_e32 v44, v43
	v_pk_fma_f32 v[42:43], v[44:45], v[52:53], v[54:55]
	v_cvt_pk_bf16_f32 v0, v48, v49
	v_cvt_pk_bf16_f32 v42, v42, v43
	v_and_b32_e32 v43, 0xffff0000, v42
	v_lshlrev_b32_e32 v42, 16, v42
	v_or_b32_sdwa v49, v43, v0 dst_sel:DWORD dst_unused:UNUSED_PAD src0_sel:DWORD src1_sel:WORD_1
	v_or_b32_sdwa v48, v42, v0 dst_sel:DWORD dst_unused:UNUSED_PAD src0_sel:DWORD src1_sel:WORD_0
	v_add_u32_e32 v0, v68, v126
	global_store_dwordx4 v[50:51], v[46:49], off
	v_lshl_add_u64 v[42:43], v[0:1], 1, s[6:7]
	global_load_dwordx4 v[42:45], v[42:43], off
	v_add_u32_e32 v0, v0, v69
	s_waitcnt vmcnt(0)
	v_lshlrev_b32_e32 v50, 16, v42
	v_and_b32_e32 v51, 0xffff0000, v42
	v_lshlrev_b32_e32 v53, 16, v43
	v_and_b32_e32 v55, 0xffff0000, v43
	v_lshl_add_u64 v[42:43], v[0:1], 1, s[10:11]
	global_load_dwordx4 v[46:49], v[42:43], off
	v_lshlrev_b32_e32 v52, 16, v44
	v_mul_f32_e32 v0, 0xbfb8aa3b, v50
	v_exp_f32_e32 v50, v0
	v_mul_f32_e32 v0, 0xbfb8aa3b, v52
	v_and_b32_e32 v44, 0xffff0000, v44
	v_exp_f32_e32 v52, v0
	v_mul_f32_e32 v0, 0xbfb8aa3b, v51
	v_exp_f32_e32 v54, v0
	v_mul_f32_e32 v0, 0xbfb8aa3b, v44
	v_exp_f32_e32 v44, v0
	v_mul_f32_e32 v0, 0xbfb8aa3b, v53
	v_exp_f32_e32 v51, v0
	v_lshlrev_b32_e32 v56, 16, v45
	v_mul_f32_e32 v0, 0xbfb8aa3b, v56
	v_and_b32_e32 v45, 0xffff0000, v45
	v_exp_f32_e32 v53, v0
	v_mul_f32_e32 v0, 0xbfb8aa3b, v55
	v_exp_f32_e32 v55, v0
	v_mul_f32_e32 v0, 0xbfb8aa3b, v45
	v_pk_add_f32 v[50:51], v[50:51], 1.0 op_sel_hi:[1,0]
	v_exp_f32_e32 v45, v0
	v_pk_add_f32 v[54:55], v[54:55], 1.0 op_sel_hi:[1,0]
	v_pk_add_f32 v[44:45], v[44:45], 1.0 op_sel_hi:[1,0]
	v_rcp_f32_e32 v51, v51
	s_nop 0
	s_waitcnt vmcnt(0)
	v_lshlrev_b32_e32 v57, 16, v47
	v_rcp_f32_e32 v50, v50
	s_nop 0
	v_mov_b32_e32 v58, v38
	v_mov_b32_e32 v59, v40
	v_lshlrev_b32_e32 v56, 16, v46
	v_pk_fma_f32 v[50:51], v[58:59], v[50:51], v[56:57]
	v_rcp_f32_e32 v55, v55
	s_nop 0
	v_and_b32_e32 v47, 0xffff0000, v47
	v_and_b32_e32 v46, 0xffff0000, v46
	v_rcp_f32_e32 v54, v54
	s_nop 0
	v_mov_b32_e32 v40, v39
	v_pk_fma_f32 v[38:39], v[40:41], v[54:55], v[46:47]
	v_cvt_pk_bf16_f32 v0, v50, v51
	v_cvt_pk_bf16_f32 v38, v38, v39
	v_and_b32_e32 v39, 0xffff0000, v38
	v_lshlrev_b32_e32 v38, 16, v38
	v_lshlrev_b32_e32 v41, 16, v49
	v_lshlrev_b32_e32 v40, 16, v48
	v_and_b32_e32 v47, 0xffff0000, v49
	v_and_b32_e32 v46, 0xffff0000, v48
	v_pk_add_f32 v[48:49], v[52:53], 1.0 op_sel_hi:[1,0]
	v_or_b32_sdwa v39, v39, v0 dst_sel:DWORD dst_unused:UNUSED_PAD src0_sel:DWORD src1_sel:WORD_1
	v_or_b32_sdwa v38, v38, v0 dst_sel:DWORD dst_unused:UNUSED_PAD src0_sel:DWORD src1_sel:WORD_0
	s_nop 0
	v_rcp_f32_e32 v49, v49
	s_nop 0
	s_nop 0
	v_rcp_f32_e32 v48, v48
	s_nop 0
	v_mov_b32_e32 v50, v34
	v_mov_b32_e32 v51, v36
	v_pk_fma_f32 v[40:41], v[50:51], v[48:49], v[40:41]
	v_add_u32_e32 v52, 0xe3800, v157
	v_rcp_f32_e32 v45, v45
	s_nop 0
	v_add_u32_e32 v53, 0xfff44800, v158
	v_rcp_f32_e32 v44, v44
	s_nop 0
	v_mov_b32_e32 v36, v35
	v_pk_fma_f32 v[34:35], v[36:37], v[44:45], v[46:47]
	v_cvt_pk_bf16_f32 v0, v40, v41
	v_cvt_pk_bf16_f32 v34, v34, v35
	v_and_b32_e32 v35, 0xffff0000, v34
	v_lshlrev_b32_e32 v34, 16, v34
	v_or_b32_sdwa v41, v35, v0 dst_sel:DWORD dst_unused:UNUSED_PAD src0_sel:DWORD src1_sel:WORD_1
	v_or_b32_sdwa v40, v34, v0 dst_sel:DWORD dst_unused:UNUSED_PAD src0_sel:DWORD src1_sel:WORD_0
	v_add_u32_e32 v0, v52, v156
	global_store_dwordx4 v[42:43], v[38:41], off
	v_lshl_add_u64 v[34:35], v[0:1], 1, s[6:7]
	global_load_dwordx4 v[34:37], v[34:35], off
	v_add_u32_e32 v0, v0, v53
	s_waitcnt vmcnt(0)
	v_lshlrev_b32_e32 v42, 16, v34
	v_and_b32_e32 v43, 0xffff0000, v34
	v_lshlrev_b32_e32 v45, 16, v35
	v_and_b32_e32 v47, 0xffff0000, v35
	v_lshl_add_u64 v[34:35], v[0:1], 1, s[10:11]
	global_load_dwordx4 v[38:41], v[34:35], off
	v_lshlrev_b32_e32 v44, 16, v36
	v_mul_f32_e32 v0, 0xbfb8aa3b, v42
	v_exp_f32_e32 v42, v0
	v_mul_f32_e32 v0, 0xbfb8aa3b, v44
	v_and_b32_e32 v36, 0xffff0000, v36
	v_exp_f32_e32 v44, v0
	v_mul_f32_e32 v0, 0xbfb8aa3b, v43
	v_exp_f32_e32 v46, v0
	v_mul_f32_e32 v0, 0xbfb8aa3b, v36
	v_exp_f32_e32 v36, v0
	v_mul_f32_e32 v0, 0xbfb8aa3b, v45
	v_exp_f32_e32 v43, v0
	v_lshlrev_b32_e32 v48, 16, v37
	v_mul_f32_e32 v0, 0xbfb8aa3b, v48
	v_and_b32_e32 v37, 0xffff0000, v37
	v_exp_f32_e32 v45, v0
	v_mul_f32_e32 v0, 0xbfb8aa3b, v47
	v_exp_f32_e32 v47, v0
	v_mul_f32_e32 v0, 0xbfb8aa3b, v37
	v_pk_add_f32 v[42:43], v[42:43], 1.0 op_sel_hi:[1,0]
	v_exp_f32_e32 v37, v0
	v_pk_add_f32 v[46:47], v[46:47], 1.0 op_sel_hi:[1,0]
	v_pk_add_f32 v[36:37], v[36:37], 1.0 op_sel_hi:[1,0]
	v_rcp_f32_e32 v43, v43
	s_nop 0
	s_waitcnt vmcnt(0)
	v_lshlrev_b32_e32 v49, 16, v39
	v_rcp_f32_e32 v42, v42
	s_nop 0
	v_mov_b32_e32 v50, v30
	v_mov_b32_e32 v51, v32
	v_lshlrev_b32_e32 v48, 16, v38
	v_pk_fma_f32 v[42:43], v[50:51], v[42:43], v[48:49]
	v_rcp_f32_e32 v47, v47
	s_nop 0
	v_and_b32_e32 v39, 0xffff0000, v39
	v_and_b32_e32 v38, 0xffff0000, v38
	v_rcp_f32_e32 v46, v46
	s_nop 0
	v_mov_b32_e32 v32, v31
	v_pk_fma_f32 v[30:31], v[32:33], v[46:47], v[38:39]
	v_cvt_pk_bf16_f32 v0, v42, v43
	v_cvt_pk_bf16_f32 v30, v30, v31
	v_and_b32_e32 v31, 0xffff0000, v30
	v_lshlrev_b32_e32 v30, 16, v30
	v_lshlrev_b32_e32 v33, 16, v41
	v_lshlrev_b32_e32 v32, 16, v40
	v_and_b32_e32 v39, 0xffff0000, v41
	v_and_b32_e32 v38, 0xffff0000, v40
	v_pk_add_f32 v[40:41], v[44:45], 1.0 op_sel_hi:[1,0]
	v_or_b32_sdwa v31, v31, v0 dst_sel:DWORD dst_unused:UNUSED_PAD src0_sel:DWORD src1_sel:WORD_1
	v_or_b32_sdwa v30, v30, v0 dst_sel:DWORD dst_unused:UNUSED_PAD src0_sel:DWORD src1_sel:WORD_0
	s_nop 0
	v_rcp_f32_e32 v41, v41
	s_nop 0
	s_nop 0
	v_rcp_f32_e32 v40, v40
	s_nop 0
	v_mov_b32_e32 v42, v26
	v_mov_b32_e32 v43, v28
	v_pk_fma_f32 v[32:33], v[42:43], v[40:41], v[32:33]
	v_rcp_f32_e32 v37, v37
	s_nop 0
	s_nop 0
	v_rcp_f32_e32 v36, v36
	s_nop 0
	v_mov_b32_e32 v28, v27
	v_pk_fma_f32 v[26:27], v[28:29], v[36:37], v[38:39]
	v_cvt_pk_bf16_f32 v0, v32, v33
	v_cvt_pk_bf16_f32 v26, v26, v27
	v_and_b32_e32 v27, 0xffff0000, v26
	v_lshlrev_b32_e32 v26, 16, v26
	v_or_b32_sdwa v33, v27, v0 dst_sel:DWORD dst_unused:UNUSED_PAD src0_sel:DWORD src1_sel:WORD_1
	v_or_b32_sdwa v32, v26, v0 dst_sel:DWORD dst_unused:UNUSED_PAD src0_sel:DWORD src1_sel:WORD_0
	v_add_u32_e32 v0, v52, v126
	global_store_dwordx4 v[34:35], v[30:33], off
	v_lshl_add_u64 v[26:27], v[0:1], 1, s[6:7]
	global_load_dwordx4 v[26:29], v[26:27], off
	v_add_u32_e32 v0, v0, v53
	s_waitcnt vmcnt(0)
	v_lshlrev_b32_e32 v34, 16, v26
	v_and_b32_e32 v35, 0xffff0000, v26
	v_lshlrev_b32_e32 v37, 16, v27
	v_and_b32_e32 v39, 0xffff0000, v27
	v_lshl_add_u64 v[26:27], v[0:1], 1, s[10:11]
	global_load_dwordx4 v[30:33], v[26:27], off
	v_lshlrev_b32_e32 v36, 16, v28
	v_mul_f32_e32 v0, 0xbfb8aa3b, v34
	v_exp_f32_e32 v34, v0
	v_mul_f32_e32 v0, 0xbfb8aa3b, v36
	v_and_b32_e32 v28, 0xffff0000, v28
	v_exp_f32_e32 v36, v0
	v_mul_f32_e32 v0, 0xbfb8aa3b, v35
	v_exp_f32_e32 v38, v0
	v_mul_f32_e32 v0, 0xbfb8aa3b, v28
	v_exp_f32_e32 v28, v0
	v_mul_f32_e32 v0, 0xbfb8aa3b, v37
	v_exp_f32_e32 v35, v0
	v_lshlrev_b32_e32 v40, 16, v29
	v_mul_f32_e32 v0, 0xbfb8aa3b, v40
	v_and_b32_e32 v29, 0xffff0000, v29
	v_exp_f32_e32 v37, v0
	v_mul_f32_e32 v0, 0xbfb8aa3b, v39
	v_exp_f32_e32 v39, v0
	v_mul_f32_e32 v0, 0xbfb8aa3b, v29
	v_pk_add_f32 v[34:35], v[34:35], 1.0 op_sel_hi:[1,0]
	v_exp_f32_e32 v29, v0
	v_pk_add_f32 v[38:39], v[38:39], 1.0 op_sel_hi:[1,0]
	v_pk_add_f32 v[28:29], v[28:29], 1.0 op_sel_hi:[1,0]
	v_rcp_f32_e32 v35, v35
	s_nop 0
	s_waitcnt vmcnt(0)
	v_lshlrev_b32_e32 v41, 16, v31
	v_rcp_f32_e32 v34, v34
	s_nop 0
	v_mov_b32_e32 v42, v22
	v_mov_b32_e32 v43, v24
	v_lshlrev_b32_e32 v40, 16, v30
	v_pk_fma_f32 v[34:35], v[42:43], v[34:35], v[40:41]
	v_rcp_f32_e32 v39, v39
	s_nop 0
	v_and_b32_e32 v31, 0xffff0000, v31
	v_and_b32_e32 v30, 0xffff0000, v30
	v_rcp_f32_e32 v38, v38
	s_nop 0
	v_mov_b32_e32 v24, v23
	v_pk_fma_f32 v[22:23], v[24:25], v[38:39], v[30:31]
	v_cvt_pk_bf16_f32 v0, v34, v35
	v_cvt_pk_bf16_f32 v22, v22, v23
	v_and_b32_e32 v23, 0xffff0000, v22
	v_lshlrev_b32_e32 v22, 16, v22
	v_lshlrev_b32_e32 v25, 16, v33
	v_lshlrev_b32_e32 v24, 16, v32
	v_and_b32_e32 v31, 0xffff0000, v33
	v_and_b32_e32 v30, 0xffff0000, v32
	v_pk_add_f32 v[32:33], v[36:37], 1.0 op_sel_hi:[1,0]
	v_or_b32_sdwa v23, v23, v0 dst_sel:DWORD dst_unused:UNUSED_PAD src0_sel:DWORD src1_sel:WORD_1
	v_or_b32_sdwa v22, v22, v0 dst_sel:DWORD dst_unused:UNUSED_PAD src0_sel:DWORD src1_sel:WORD_0
	s_nop 0
	v_rcp_f32_e32 v33, v33
	s_nop 0
	s_nop 0
	v_rcp_f32_e32 v32, v32
	s_nop 0
	v_mov_b32_e32 v34, v18
	v_mov_b32_e32 v35, v20
	v_pk_fma_f32 v[24:25], v[34:35], v[32:33], v[24:25]
	v_add_u32_e32 v36, 0xfa400, v157
	v_rcp_f32_e32 v29, v29
	s_nop 0
	v_add_u32_e32 v37, 0xfff31c00, v158
	v_rcp_f32_e32 v28, v28
	s_nop 0
	v_mov_b32_e32 v20, v19
	v_pk_fma_f32 v[18:19], v[20:21], v[28:29], v[30:31]
	v_cvt_pk_bf16_f32 v0, v24, v25
	v_cvt_pk_bf16_f32 v18, v18, v19
	v_and_b32_e32 v19, 0xffff0000, v18
	v_lshlrev_b32_e32 v18, 16, v18
	v_or_b32_sdwa v25, v19, v0 dst_sel:DWORD dst_unused:UNUSED_PAD src0_sel:DWORD src1_sel:WORD_1
	v_or_b32_sdwa v24, v18, v0 dst_sel:DWORD dst_unused:UNUSED_PAD src0_sel:DWORD src1_sel:WORD_0
	v_add_u32_e32 v0, v36, v156
	global_store_dwordx4 v[26:27], v[22:25], off
	v_lshl_add_u64 v[18:19], v[0:1], 1, s[6:7]
	global_load_dwordx4 v[18:21], v[18:19], off
	v_add_u32_e32 v0, v0, v37
	s_waitcnt vmcnt(0)
	v_lshlrev_b32_e32 v26, 16, v18
	v_and_b32_e32 v27, 0xffff0000, v18
	v_lshlrev_b32_e32 v29, 16, v19
	v_and_b32_e32 v31, 0xffff0000, v19
	v_lshl_add_u64 v[18:19], v[0:1], 1, s[10:11]
	global_load_dwordx4 v[22:25], v[18:19], off
	v_lshlrev_b32_e32 v28, 16, v20
	v_mul_f32_e32 v0, 0xbfb8aa3b, v26
	v_exp_f32_e32 v26, v0
	v_mul_f32_e32 v0, 0xbfb8aa3b, v28
	v_and_b32_e32 v20, 0xffff0000, v20
	v_exp_f32_e32 v28, v0
	v_mul_f32_e32 v0, 0xbfb8aa3b, v27
	v_exp_f32_e32 v30, v0
	v_mul_f32_e32 v0, 0xbfb8aa3b, v20
	v_exp_f32_e32 v20, v0
	v_mul_f32_e32 v0, 0xbfb8aa3b, v29
	v_exp_f32_e32 v27, v0
	v_lshlrev_b32_e32 v32, 16, v21
	v_mul_f32_e32 v0, 0xbfb8aa3b, v32
	v_and_b32_e32 v21, 0xffff0000, v21
	v_exp_f32_e32 v29, v0
	v_mul_f32_e32 v0, 0xbfb8aa3b, v31
	v_exp_f32_e32 v31, v0
	v_mul_f32_e32 v0, 0xbfb8aa3b, v21
	v_pk_add_f32 v[26:27], v[26:27], 1.0 op_sel_hi:[1,0]
	v_exp_f32_e32 v21, v0
	v_pk_add_f32 v[30:31], v[30:31], 1.0 op_sel_hi:[1,0]
	v_pk_add_f32 v[20:21], v[20:21], 1.0 op_sel_hi:[1,0]
	v_rcp_f32_e32 v27, v27
	s_nop 0
	s_waitcnt vmcnt(0)
	v_lshlrev_b32_e32 v33, 16, v23
	v_rcp_f32_e32 v26, v26
	s_nop 0
	v_mov_b32_e32 v34, v14
	v_mov_b32_e32 v35, v16
	v_lshlrev_b32_e32 v32, 16, v22
	v_pk_fma_f32 v[26:27], v[34:35], v[26:27], v[32:33]
	v_rcp_f32_e32 v31, v31
	s_nop 0
	v_and_b32_e32 v23, 0xffff0000, v23
	v_and_b32_e32 v22, 0xffff0000, v22
	v_rcp_f32_e32 v30, v30
	s_nop 0
	v_mov_b32_e32 v16, v15
	v_pk_fma_f32 v[14:15], v[16:17], v[30:31], v[22:23]
	v_cvt_pk_bf16_f32 v0, v26, v27
	v_cvt_pk_bf16_f32 v14, v14, v15
	v_and_b32_e32 v15, 0xffff0000, v14
	v_lshlrev_b32_e32 v14, 16, v14
	v_lshlrev_b32_e32 v17, 16, v25
	v_lshlrev_b32_e32 v16, 16, v24
	v_and_b32_e32 v23, 0xffff0000, v25
	v_and_b32_e32 v22, 0xffff0000, v24
	v_pk_add_f32 v[24:25], v[28:29], 1.0 op_sel_hi:[1,0]
	v_or_b32_sdwa v15, v15, v0 dst_sel:DWORD dst_unused:UNUSED_PAD src0_sel:DWORD src1_sel:WORD_1
	v_or_b32_sdwa v14, v14, v0 dst_sel:DWORD dst_unused:UNUSED_PAD src0_sel:DWORD src1_sel:WORD_0
	s_nop 0
	v_rcp_f32_e32 v25, v25
	s_nop 0
	s_nop 0
	v_rcp_f32_e32 v24, v24
	s_nop 0
	v_mov_b32_e32 v26, v10
	v_mov_b32_e32 v27, v12
	v_pk_fma_f32 v[16:17], v[26:27], v[24:25], v[16:17]
	v_rcp_f32_e32 v21, v21
	s_nop 0
	s_nop 0
	v_rcp_f32_e32 v20, v20
	s_nop 0
	v_mov_b32_e32 v12, v11
	v_pk_fma_f32 v[10:11], v[12:13], v[20:21], v[22:23]
	v_cvt_pk_bf16_f32 v0, v16, v17
	v_cvt_pk_bf16_f32 v10, v10, v11
	v_and_b32_e32 v11, 0xffff0000, v10
	v_lshlrev_b32_e32 v10, 16, v10
	v_or_b32_sdwa v17, v11, v0 dst_sel:DWORD dst_unused:UNUSED_PAD src0_sel:DWORD src1_sel:WORD_1
	v_or_b32_sdwa v16, v10, v0 dst_sel:DWORD dst_unused:UNUSED_PAD src0_sel:DWORD src1_sel:WORD_0
	v_add_u32_e32 v0, v36, v126
	global_store_dwordx4 v[18:19], v[14:17], off
	v_lshl_add_u64 v[10:11], v[0:1], 1, s[6:7]
	global_load_dwordx4 v[10:13], v[10:11], off
	v_add_u32_e32 v0, v0, v37
	s_waitcnt vmcnt(0)
	v_lshlrev_b32_e32 v18, 16, v10
	v_and_b32_e32 v19, 0xffff0000, v10
	v_lshlrev_b32_e32 v21, 16, v11
	v_and_b32_e32 v23, 0xffff0000, v11
	v_lshl_add_u64 v[10:11], v[0:1], 1, s[10:11]
	global_load_dwordx4 v[14:17], v[10:11], off
	v_lshlrev_b32_e32 v20, 16, v12
	v_mul_f32_e32 v0, 0xbfb8aa3b, v18
	v_exp_f32_e32 v18, v0
	v_mul_f32_e32 v0, 0xbfb8aa3b, v20
	v_and_b32_e32 v12, 0xffff0000, v12
	v_exp_f32_e32 v20, v0
	v_mul_f32_e32 v0, 0xbfb8aa3b, v19
	v_exp_f32_e32 v22, v0
	v_mul_f32_e32 v0, 0xbfb8aa3b, v12
	v_exp_f32_e32 v12, v0
	v_mul_f32_e32 v0, 0xbfb8aa3b, v21
	v_exp_f32_e32 v19, v0
	v_lshlrev_b32_e32 v24, 16, v13
	v_mul_f32_e32 v0, 0xbfb8aa3b, v24
	v_and_b32_e32 v13, 0xffff0000, v13
	v_exp_f32_e32 v21, v0
	v_mul_f32_e32 v0, 0xbfb8aa3b, v23
	v_exp_f32_e32 v23, v0
	v_mul_f32_e32 v0, 0xbfb8aa3b, v13
	v_pk_add_f32 v[18:19], v[18:19], 1.0 op_sel_hi:[1,0]
	v_exp_f32_e32 v13, v0
	v_pk_add_f32 v[22:23], v[22:23], 1.0 op_sel_hi:[1,0]
	v_pk_add_f32 v[12:13], v[12:13], 1.0 op_sel_hi:[1,0]
	v_rcp_f32_e32 v19, v19
	s_nop 0
	s_waitcnt vmcnt(0)
	v_lshlrev_b32_e32 v25, 16, v15
	v_rcp_f32_e32 v18, v18
	s_nop 0
	v_mov_b32_e32 v26, v6
	v_mov_b32_e32 v27, v8
	v_lshlrev_b32_e32 v24, 16, v14
	v_pk_fma_f32 v[18:19], v[26:27], v[18:19], v[24:25]
	v_rcp_f32_e32 v23, v23
	s_nop 0
	v_and_b32_e32 v15, 0xffff0000, v15
	v_and_b32_e32 v14, 0xffff0000, v14
	v_rcp_f32_e32 v22, v22
	s_nop 0
	v_mov_b32_e32 v8, v7
	v_pk_fma_f32 v[6:7], v[8:9], v[22:23], v[14:15]
	v_cvt_pk_bf16_f32 v0, v18, v19
	v_cvt_pk_bf16_f32 v6, v6, v7
	v_and_b32_e32 v7, 0xffff0000, v6
	v_lshlrev_b32_e32 v6, 16, v6
	v_lshlrev_b32_e32 v9, 16, v17
	v_lshlrev_b32_e32 v8, 16, v16
	v_and_b32_e32 v15, 0xffff0000, v17
	v_and_b32_e32 v14, 0xffff0000, v16
	v_pk_add_f32 v[16:17], v[20:21], 1.0 op_sel_hi:[1,0]
	v_or_b32_sdwa v7, v7, v0 dst_sel:DWORD dst_unused:UNUSED_PAD src0_sel:DWORD src1_sel:WORD_1
	v_or_b32_sdwa v6, v6, v0 dst_sel:DWORD dst_unused:UNUSED_PAD src0_sel:DWORD src1_sel:WORD_0
	s_nop 0
	v_rcp_f32_e32 v17, v17
	s_nop 0
	s_nop 0
	v_rcp_f32_e32 v16, v16
	s_nop 0
	v_mov_b32_e32 v18, v2
	v_mov_b32_e32 v19, v4
	v_pk_fma_f32 v[8:9], v[18:19], v[16:17], v[8:9]
	v_rcp_f32_e32 v13, v13
	s_nop 0
	s_mov_b64 s[26:27], s[18:19]
	v_rcp_f32_e32 v12, v12
	s_nop 0
	v_mov_b32_e32 v4, v3
	v_pk_fma_f32 v[2:3], v[4:5], v[12:13], v[14:15]
	v_cvt_pk_bf16_f32 v0, v8, v9
	v_cvt_pk_bf16_f32 v2, v2, v3
	v_and_b32_e32 v3, 0xffff0000, v2
	v_lshlrev_b32_e32 v2, 16, v2
	v_or_b32_sdwa v9, v3, v0 dst_sel:DWORD dst_unused:UNUSED_PAD src0_sel:DWORD src1_sel:WORD_1
	v_or_b32_sdwa v8, v2, v0 dst_sel:DWORD dst_unused:UNUSED_PAD src0_sel:DWORD src1_sel:WORD_0
	s_and_b64 vcc, exec, s[12:13]
	global_store_dwordx4 v[10:11], v[6:9], off
	s_cbranch_vccz .LBB0_1369
	s_waitcnt vmcnt(0)
	v_readlane_b32 s76, v255, 8
	s_mov_b32 s92, 0x3b2aaaab
	s_cmp_gt_u32 s35, 3
	v_readlane_b32 s77, v255, 9
	s_mul_i32 s60, s33, 0x1800
	s_mul_hi_i32 s62, s64, 0x300
	s_mul_i32 s75, s33, 0x16c00
	s_mov_b32 s93, 0x3c800000
	s_cbranch_scc1 .LBB0_1376
	s_barrier
